# attention steady loop: QK accumulators start from a persistent -mhat register block (v238-253) as MFMA SrcC instead of 16 v_mov per step; SGPR-spill VGPRs renumbered v251/v252 to v254/v255
# speedup vs baseline: 1.0078x; 1.0022x over previous
; #define LAS __attribute__((address_space(3)))
; __device__ __forceinline__ unsigned xb_add(unsigned* p, unsigned v) { return __hip_atomic_fetch_add(p, v, __ATOMIC_RELAXED, __HIP_MEMORY_SCOPE_AGENT); }
; __device__ __forceinline__ unsigned xb_xcc_id() { return (unsigned)__builtin_amdgcn_s_getreg((3 << 11) | 20) & 0xFu; }
; __device__ __forceinline__ XcdBarrier xcd_barrier_post(unsigned* bar, volatile LAS unsigned* st) {
;     XcdBarrier b; b.bar = bar; b.x = xb_xcc_id(); b.st = st;
;     if (threadIdx.x == 0) (void)xb_add(&bar[XB_XCNT(b.x)], 1u);
;     return b;
; }
; __global__ void __launch_bounds__(NWAVES * 64, 2) mega_fwd(Args args) {
;     extern __shared__ __attribute__((aligned(16))) unsigned char lds_raw[];
;     cg::grid_group grid = cg::this_grid();
;     LAS unsigned char* lds = (LAS unsigned char*)lds_raw;
;     const int tid = threadIdx.x, lane = tid & 63, wave = __builtin_amdgcn_readfirstlane(tid >> 6);
;     const int G = gridDim.x, bx = blockIdx.x, vcu = (G % 8 == 0) ? (bx % 8) * (G / 8) + bx / 8 : bx;
;     unsigned char* ws = args.ws;
;     const int lo = args.ph_lo, hi = args.ph_hi;
;     volatile LAS unsigned* MISC = (volatile LAS unsigned*)(lds + RING_BYTES + 64);
;     if (tid < 2) MISC[tid] = 0u;
;     __syncthreads();
;     const XcdBarrier bar = xcd_barrier_post((unsigned*)(ws + WS_CTL), MISC);
;     if (lo < 0) grid.sync();
_Z8mega_fwd4Args:
	s_load_dwordx2 s[28:29], s[0:1], 0xf0
	s_load_dwordx4 s[4:7], s[0:1], 0xe0
	s_mov_b32 s20, s2
	s_add_u32 s2, s0, 0x100
	s_addc_u32 s3, s1, 0
	v_and_b32_e32 v208, 0x3ff, v0
	s_waitcnt lgkmcnt(0)
	v_writelane_b32 v255, s4, 0
	v_readfirstlane_b32 s18, v208
	s_nop 0
	v_writelane_b32 v255, s5, 1
	v_writelane_b32 v255, s6, 2
	v_writelane_b32 v255, s7, 3
	s_load_dwordx8 s[4:11], s[0:1], 0xc0
	s_load_dwordx2 s[12:13], s[0:1], 0x100
	s_waitcnt lgkmcnt(0)
	v_writelane_b32 v255, s12, 4
	s_nop 1
	v_writelane_b32 v255, s13, 5
	s_and_b32 s12, s12, 7
	s_cmp_lg_u32 s12, 0
	v_writelane_b32 v255, s20, 6
	s_cbranch_scc1 .LBB0_2
	s_load_dwordx2 s[12:13], s[0:1], 0x100
	s_waitcnt lgkmcnt(0)
	s_ashr_i32 s13, s20, 31
	s_lshr_b32 s13, s13, 29
	s_add_i32 s13, s20, s13
	s_and_b32 s14, s13, -8
	s_ashr_i32 s12, s12, 3
	s_sub_i32 s14, s20, s14
	s_mul_i32 s12, s12, s14
	s_ashr_i32 s13, s13, 3
	s_add_i32 s12, s12, s13
	v_writelane_b32 v255, s12, 6
.LBB0_2:
	s_load_dwordx2 s[36:37], s[0:1], 0xf8
	s_load_dword s12, s[0:1], 0x108
	v_cmp_gt_u32_e32 vcc, 2, v208
	s_waitcnt lgkmcnt(0)
	v_writelane_b32 v255, s12, 7
	s_and_saveexec_b64 s[12:13], vcc
	v_lshl_add_u32 v1, v208, 2, 0
	v_add_u32_e32 v1, 0x20040, v1
	v_mov_b32_e32 v2, 0
	ds_write_b32 v1, v2
	s_or_b64 exec, exec, s[12:13]
	s_waitcnt lgkmcnt(0)
	s_barrier
	s_getreg_b32 s12, hwreg(HW_REG_XCC_ID, 0, 4)
	s_and_b32 s12, s12, 15
	v_writelane_b32 v255, s12, 8
	v_cmp_eq_u32_e64 s[14:15], 0, v208
	s_mov_b64 s[12:13], exec
	s_nop 0
	v_writelane_b32 v255, s14, 9
	s_nop 1
	v_writelane_b32 v255, s15, 10
	s_and_b64 s[14:15], s[12:13], s[14:15]
	s_mov_b64 exec, s[14:15]
	s_cbranch_execz .LBB0_7
	s_mov_b64 s[14:15], exec
	v_mbcnt_lo_u32_b32 v1, s14, 0
	v_mbcnt_hi_u32_b32 v1, s15, v1
	v_cmp_eq_u32_e32 vcc, 0, v1
	s_and_b64 s[16:17], exec, vcc
	s_mov_b64 exec, s[16:17]
	s_cbranch_execz .LBB0_7
	v_readlane_b32 s16, v255, 8
	s_lshl_b32 s16, s16, 8
	s_bcnt1_i32_b64 s14, s[14:15]
	v_mov_b32_e32 v1, s16
	v_mov_b32_e32 v2, s14
	global_atomic_add v1, v2, s[28:29] offset:1024
.LBB0_7:
	s_or_b64 exec, exec, s[12:13]
	s_load_dwordx16 s[40:55], s[0:1], 0x0
	s_cmp_gt_i32 s36, -1
	s_waitcnt lgkmcnt(0)
	v_writelane_b32 v255, s40, 11
	s_nop 1
	v_writelane_b32 v255, s41, 12
	v_writelane_b32 v255, s42, 13
	v_writelane_b32 v255, s43, 14
	v_writelane_b32 v255, s44, 15
	v_writelane_b32 v255, s45, 16
	v_writelane_b32 v255, s46, 17
	v_writelane_b32 v255, s47, 18
	v_writelane_b32 v255, s48, 19
	v_writelane_b32 v255, s49, 20
	v_writelane_b32 v255, s50, 21
	v_writelane_b32 v255, s51, 22
	v_writelane_b32 v255, s52, 23
	v_writelane_b32 v255, s53, 24
	v_writelane_b32 v255, s54, 25
	v_writelane_b32 v255, s55, 26
	s_cbranch_scc1 .LBB0_19
	v_lshrrev_b32_e32 v1, 20, v0
	v_lshrrev_b32_e32 v0, 10, v0
	v_or_b32_e32 v0, v0, v1
	s_movk_i32 s12, 0x3ff
	v_and_or_b32 v0, v0, s12, v208
	v_cmp_eq_u32_e32 vcc, 0, v0
	s_barrier
	s_and_saveexec_b64 s[12:13], vcc
	s_cbranch_execz .LBB0_18
	buffer_wbl2 sc1
	s_waitcnt vmcnt(0)
	s_load_dwordx2 s[2:3], s[2:3], 0x58
	v_mov_b32_e32 v2, 0
	s_mov_b64 s[14:15], exec
	v_mbcnt_lo_u32_b32 v1, s14, 0
	v_mbcnt_hi_u32_b32 v1, s15, v1
	s_waitcnt lgkmcnt(0)
	global_load_dword v0, v2, s[2:3] offset:40
	v_cmp_eq_u32_e32 vcc, 0, v1
	s_and_saveexec_b64 s[16:17], vcc
	s_cbranch_execz .LBB0_11
	s_bcnt1_i32_b64 s14, s[14:15]
	v_mov_b32_e32 v3, s14
	global_atomic_add v3, v2, v3, s[2:3] offset:32 sc0

; #define LAS __attribute__((address_space(3)))
; __device__ __forceinline__ void p0_prologue(const Args& a, LAS unsigned char* lds, int vcu, int G, int wave, int lane) {
;     ...
;     constexpr int T_PW1 = 16 * 64, T_SQ = 16 * 32, T_QKV = 16 * 96, T_GU = 16 * 88, T_DN = 44 * 32, T_PP = 4 * 32;
;     constexpr int NITEMS = T_PW1 + T_SQ + T_QKV + T_SQ + 4 * T_GU + 2 * T_DN + 2 * T_SQ + 2 * T_PP;
;     for (int it = gw; it < NITEMS; it += NGW) {
; __global__ void __launch_bounds__(NWAVES * 64, 2) mega_fwd(Args args) {
;     ...
;     const int tid = threadIdx.x, lane = tid & 63, wave = __builtin_amdgcn_readfirstlane(tid >> 6);
;     const int G = gridDim.x, bx = blockIdx.x, vcu = (G % 8 == 0) ? (bx % 8) * (G / 8) + bx / 8 : bx;
;     unsigned char* ws = args.ws;
;     const int lo = args.ph_lo, hi = args.ph_hi;
;     volatile LAS unsigned* MISC = (volatile LAS unsigned*)(lds + RING_BYTES + 64);
;     if (tid < 2) MISC[tid] = 0u;
;     __syncthreads();
;     const XcdBarrier bar = xcd_barrier_post((unsigned*)(ws + WS_CTL), MISC);
;     if (lo < 0) grid.sync();
;     ...
;     bf16* HBA = (bf16*)(ws + WS_HBA); bf16* HBB = (bf16*)(ws + WS_HBB); float* SSA = (float*)(ws + WS_SSA); float* SSB = (float*)(ws + WS_SSB);
;     float* H = args.out;
;     typedef pg8::StaticOrder SO;
;     ...
;     if (IN(0)) { p0_prologue(args, lds, vcu, G, wave, lane); }
.LBB0_19:
	s_load_dwordx16 s[40:55], s[0:1], 0x40
	v_and_b32_e32 v209, 63, v208
	s_waitcnt lgkmcnt(0)
	v_writelane_b32 v255, s40, 27
	s_nop 1
	v_writelane_b32 v255, s41, 28
	v_writelane_b32 v255, s42, 29
	v_writelane_b32 v255, s43, 30
	v_writelane_b32 v255, s44, 31
	v_writelane_b32 v255, s45, 32
	v_writelane_b32 v255, s46, 33
	v_writelane_b32 v255, s47, 34
	v_writelane_b32 v255, s48, 35
	v_writelane_b32 v255, s49, 36
	v_writelane_b32 v255, s50, 37
	v_writelane_b32 v255, s51, 38
	v_writelane_b32 v255, s52, 39
	v_writelane_b32 v255, s53, 40
	v_writelane_b32 v255, s54, 41
	v_writelane_b32 v255, s55, 42
	s_load_dwordx16 s[40:55], s[0:1], 0x80
	s_lshr_b32 s0, s18, 6
	s_add_u32 s34, s28, 0x6000000
	s_addc_u32 s35, s29, 0
	s_cmp_lt_i32 s36, 1
	s_waitcnt lgkmcnt(0)
	v_writelane_b32 v255, s40, 43
	s_nop 1
	v_writelane_b32 v255, s41, 44
	v_writelane_b32 v255, s42, 45
	v_writelane_b32 v255, s43, 46
	v_writelane_b32 v255, s44, 47
	v_writelane_b32 v255, s45, 48
	v_writelane_b32 v255, s46, 49
	v_writelane_b32 v255, s47, 50
	v_writelane_b32 v255, s48, 51
	v_writelane_b32 v255, s49, 52
	v_writelane_b32 v255, s50, 53
	v_writelane_b32 v255, s51, 54
	v_writelane_b32 v255, s52, 55
	v_writelane_b32 v255, s53, 56
	v_writelane_b32 v255, s54, 57
	v_writelane_b32 v255, s55, 58
	v_writelane_b32 v255, s0, 59
	s_cselect_b64 s[0:1], -1, 0
	s_cmp_gt_i32 s37, 0
	s_cselect_b64 s[2:3], -1, 0
	s_and_b64 s[0:1], s[0:1], s[2:3]
	s_andn2_b64 vcc, exec, s[0:1]
	s_cbranch_vccnz .LBB0_414
	v_readlane_b32 s2, v255, 6
	s_lshl_b32 s2, s2, 3
	v_readlane_b32 s3, v255, 59
	s_add_i32 s12, s2, s3
	v_readlane_b32 s2, v255, 4
	s_lshl_b32 s14, s2, 3
	s_cmpk_gt_i32 s12, 0x33ff
	v_readlane_b32 s3, v255, 5
	s_cbranch_scc1 .LBB0_395
; #define LAS __attribute__((address_space(3)))
; #define TR(cnt, W, K_, N_, DST, MODE, GAIN) if (r < (cnt)) { transpose_item((W), (K_), (N_), (bf16*)(ws + (DST)), (MODE), (GAIN), scr, r, lane); continue; } r -= (cnt);
; __device__ __forceinline__ void transpose_item(const float* W, int K, int N, bf16* WT, int mode, const float* gain, LAS float* scr, int item, int lane) {
;     const int nblk = N / 32, kb = item / nblk, nb = item % nblk, k0 = 64 * kb, n0 = 32 * nb;
; #pragma unroll
;     for (int i = 0; i < 32; ++i) { const int kk = 2 * i + (lane >> 5); float w = W[(size_t)(k0 + kk) * N + n0 + (lane & 31)]; if (gain) w *= gain[k0 + kk]; scr[kk * 33 + (lane & 31)] = w; }
; __device__ __forceinline__ void p0_prologue(const Args& a, LAS unsigned char* lds, int vcu, int G, int wave, int lane) {
;     unsigned char* ws = a.ws;
;     LAS float* scr = (LAS float*)(lds + wave * 16384);
;     const int gw = vcu * NWAVES + wave, NGW = G * NWAVES;
;     constexpr int T_PW1 = 16 * 64, T_SQ = 16 * 32, T_QKV = 16 * 96, T_GU = 16 * 88, T_DN = 44 * 32, T_PP = 4 * 32;
;     constexpr int NITEMS = T_PW1 + T_SQ + T_QKV + T_SQ + 4 * T_GU + 2 * T_DN + 2 * T_SQ + 2 * T_PP;
;     for (int it = gw; it < NITEMS; it += NGW) {
;         int r = it;
;     ...
;         TR(T_PW1, a.in[I_CW1], D, 2 * D, WS_WPW1, 3, a.in[I_CNG])
;         TR(T_SQ, a.in[I_CW2], D, D, WS_WPW2, 0, (const float*)nullptr)
;         TR(T_QKV, a.in[I_AWQKV], D, 3 * D, WS_WQKV, 4, a.in[I_ANG])
;         TR(T_SQ, a.in[I_AWO], D, D, WS_WO, 0, (const float*)nullptr)
;         TR(T_GU, a.in[I_FWG], D, DFF, WS_WGU0, 1, a.in[I_FNG])
;         TR(T_GU, a.in[I_FWU], D, DFF, WS_WGU0, 2, a.in[I_FNG])
;         TR(T_GU, a.in[I_FWG] + (size_t)D * DFF, D, DFF, WS_WGU1, 1, a.in[I_FNG] + D)
;         TR(T_GU, a.in[I_FWU] + (size_t)D * DFF, D, DFF, WS_WGU1, 2, a.in[I_FNG] + D)
;         TR(T_DN, a.in[I_FWD], DFF, D, WS_WD0, 0, (const float*)nullptr)
;         TR(T_DN, a.in[I_FWD] + (size_t)D * DFF, DFF, D, WS_WD1, 0, (const float*)nullptr)
;         TR(T_SQ, a.in[I_PWG], D, D, WS_WPG0, 0, a.in[I_PNG])
;         TR(T_SQ, a.in[I_PWG] + (size_t)D * D, D, D, WS_WPG1, 0, a.in[I_PNG] + D)
;         TR(T_PP, a.in[I_PWP], PLE, D, WS_WPP0, 0, (const float*)nullptr)
;         TR(T_PP, a.in[I_PWP] + (size_t)PLE * D, PLE, D, WS_WPP1, 0, (const float*)nullptr)
	v_readlane_b32 s2, v255, 59
	s_lshl_b32 s2, s2, 14
	s_add_i32 s2, s2, 0
	s_add_u32 s3, s28, 0x3d00000
	v_writelane_b32 v255, s3, 60
	s_addc_u32 s3, s29, 0
	v_and_b32_e32 v1, 31, v208
	v_writelane_b32 v255, s3, 61
	v_lshrrev_b32_e32 v0, 5, v209
	v_lshlrev_b32_e32 v2, 2, v1
	s_movk_i32 s3, 0x84
	v_mov_b32_e32 v1, 0x108
	v_mad_u32_u24 v39, v0, s3, v1
	v_mov_b32_e32 v1, 0x210
	v_mad_u32_u24 v40, v0, s3, v1
	v_mov_b32_e32 v1, 0x318
	v_mad_u32_u24 v41, v0, s3, v1
	v_mov_b32_e32 v1, 0x420
	v_mad_u32_u24 v42, v0, s3, v1
	v_mov_b32_e32 v1, 0x528
	v_mad_u32_u24 v43, v0, s3, v1
	v_mov_b32_e32 v1, 0x630
	v_mad_u32_u24 v44, v0, s3, v1
	v_mov_b32_e32 v1, 0x738
	v_mad_u32_u24 v45, v0, s3, v1
	v_mov_b32_e32 v1, 0x840
	v_mad_u32_u24 v46, v0, s3, v1
	v_mov_b32_e32 v1, 0x948
	v_mad_u32_u24 v47, v0, s3, v1
	v_mov_b32_e32 v1, 0xa50
	v_mad_u32_u24 v48, v0, s3, v1
	v_mov_b32_e32 v1, 0xb58
	v_mad_u32_u24 v49, v0, s3, v1
	v_mov_b32_e32 v1, 0xc60
	v_mad_u32_u24 v50, v0, s3, v1
	v_mov_b32_e32 v1, 0xd68
	v_mad_u32_u24 v51, v0, s3, v1
	v_mov_b32_e32 v1, 0xe70
	v_mad_u32_u24 v52, v0, s3, v1
	v_mov_b32_e32 v1, 0xf78
	v_mad_u32_u24 v53, v0, s3, v1
	v_mov_b32_e32 v1, 0x1080
	v_mad_u32_u24 v54, v0, s3, v1
	v_mov_b32_e32 v1, 0x1188
	v_mad_u32_u24 v55, v0, s3, v1
	v_mov_b32_e32 v1, 0x1290
	v_mad_u32_u24 v56, v0, s3, v1
	v_mov_b32_e32 v1, 0x1398
	v_mad_u32_u24 v57, v0, s3, v1
	v_mov_b32_e32 v1, 0x14a0
	v_mad_u32_u24 v58, v0, s3, v1
	v_mov_b32_e32 v1, 0x15a8
	v_mad_u32_u24 v59, v0, s3, v1
	v_mov_b32_e32 v1, 0x16b0
	v_mad_u32_u24 v60, v0, s3, v1
	v_mov_b32_e32 v1, 0x17b8
	v_mad_u32_u24 v61, v0, s3, v1
	v_mov_b32_e32 v1, 0x18c0
	v_mad_u32_u24 v62, v0, s3, v1
	v_lshlrev_b32_e32 v1, 3, v208
	v_lshrrev_b32_e32 v63, 3, v209
	v_and_b32_e32 v3, 56, v1
	v_mul_u32_u24_e32 v3, 0x84, v3
	v_lshlrev_b32_e32 v66, 2, v63
	s_add_u32 s80, s28, 0x3c00000
	v_readlane_b32 s16, v255, 0
	v_add3_u32 v67, s2, v3, v66
	s_addc_u32 s81, s29, 0
	v_mov_b32_e32 v3, 0
	v_readlane_b32 s17, v255, 1
	v_add_u32_e32 v36, s2, v2
	s_add_u32 s82, s28, 0x3a00000
	v_lshl_add_u64 v[4:5], s[16:17], 0, v[2:3]
	v_readlane_b32 s40, v255, 43
	s_mov_b64 s[2:3], 0x100000
	s_addc_u32 s83, s29, 0
	v_lshl_add_u64 v[6:7], s[10:11], 0, v[2:3]
	v_readlane_b32 s54, v255, 57
	v_readlane_b32 s55, v255, 58
	v_lshl_add_u64 v[14:15], v[4:5], 0, s[2:3]
	s_mov_b64 s[2:3], 0x400000
	s_add_u32 s92, s28, 0x3800000
	v_lshl_add_u64 v[8:9], s[6:7], 0, v[2:3]
	v_lshl_add_u64 v[10:11], s[4:5], 0, v[2:3]
	v_lshl_add_u64 v[12:13], s[54:55], 0, v[2:3]
	v_lshl_add_u64 v[16:17], v[6:7], 0, s[2:3]
	s_mov_b64 s[2:3], 0xb00000
	v_bfe_u32 v64, v1, 5, 1
	v_lshlrev_b32_e32 v1, 4, v208
	v_lshl_add_u64 v[18:19], v[8:9], 0, s[2:3]
	v_lshl_add_u64 v[20:21], v[10:11], 0, s[2:3]
	v_lshl_add_u64 v[22:23], v[12:13], 0, s[2:3]
	s_addc_u32 s2, s29, 0
	v_and_b32_e32 v65, 48, v1
	v_lshlrev_b32_e32 v1, 6, v63
	v_readlane_b32 s18, v255, 2
	v_readlane_b32 s19, v255, 3
	v_readlane_b32 s41, v255, 44
	v_readlane_b32 s42, v255, 45
	v_readlane_b32 s43, v255, 46
	v_readlane_b32 s44, v255, 47
	v_readlane_b32 s45, v255, 48
	v_readlane_b32 s46, v255, 49
	v_readlane_b32 s47, v255, 50
	v_readlane_b32 s48, v255, 51
	v_readlane_b32 s49, v255, 52
	v_readlane_b32 s50, v255, 53
	v_readlane_b32 s51, v255, 54
	v_readlane_b32 s52, v255, 55
	v_readlane_b32 s53, v255, 56
	v_writelane_b32 v255, s2, 62
	s_movk_i32 s2, 0xc0
	v_and_or_b32 v68, v1, s2, v65
	s_movk_i32 s2, 0x100
	v_or3_b32 v69, v65, v1, s2
	s_add_u32 s2, s28, 0x3200000
	v_writelane_b32 v255, s2, 63
	s_addc_u32 s2, s29, 0
	v_writelane_b32 v254, s2, 0
	s_add_u32 s2, s28, 0x2c00000
	v_writelane_b32 v254, s2, 1
	s_addc_u32 s2, s29, 0
	v_writelane_b32 v254, s2, 3
	s_add_u32 s2, s28, 0x2100000
	v_writelane_b32 v254, s2, 4
	s_addc_u32 s2, s29, 0
	v_writelane_b32 v254, s2, 6
	s_add_u32 s2, s28, 0x1600000
	s_addc_u32 s3, s29, 0
	s_add_u32 s10, s28, 0x1400000
	s_addc_u32 s89, s29, 0
	s_add_u32 s4, s28, 0xe00000
	s_addc_u32 s5, s29, 0
	s_add_u32 s90, s28, 0xc00000
	s_addc_u32 s91, s29, 0
	s_add_u32 s94, s28, 0x800000
	s_addc_u32 s95, s29, 0
	s_add_u32 s6, s8, 0x1000
	s_addc_u32 s7, s9, 0
	s_cmp_lg_u64 s[8:9], 0
	s_cselect_b64 s[26:27], -1, 0
	s_add_u32 s16, s52, 0x1000
	s_addc_u32 s17, s53, 0
	s_cmp_lg_u64 s[52:53], 0
	v_readlane_b32 s52, v255, 27
	v_readlane_b32 s64, v255, 39
	v_readlane_b32 s65, v255, 40
	v_readlane_b32 s66, v255, 41
	v_readlane_b32 s67, v255, 42
	v_readlane_b32 s58, v255, 33
	v_readlane_b32 s59, v255, 34
	v_readlane_b32 s64, v255, 11
	s_cselect_b64 s[24:25], -1, 0
	s_cmp_lg_u64 s[58:59], 0
	v_readlane_b32 s68, v255, 15
	v_readlane_b32 s69, v255, 16
	v_readlane_b32 s54, v255, 29
	v_readlane_b32 s55, v255, 30
	v_readlane_b32 s57, v255, 32
	v_readlane_b32 s60, v255, 35
	v_readlane_b32 s61, v255, 36
	v_readlane_b32 s62, v255, 37
	s_cselect_b64 s[30:31], -1, 0
	v_readlane_b32 s70, v255, 17
	v_readlane_b32 s71, v255, 18
	s_cmp_lg_u64 s[68:69], 0
	v_mul_u32_u24_e32 v37, 0x84, v0
	v_or_b32_e32 v38, 2, v0
	v_or_b32_e32 v70, 4, v0
	v_or_b32_e32 v71, 6, v0
	v_or_b32_e32 v72, 8, v0
	v_or_b32_e32 v73, 10, v0
	v_or_b32_e32 v74, 12, v0
	v_or_b32_e32 v75, 14, v0
	v_or_b32_e32 v76, 16, v0
	v_or_b32_e32 v77, 18, v0
	v_or_b32_e32 v78, 20, v0
	v_or_b32_e32 v79, 22, v0
	v_or_b32_e32 v80, 24, v0
	v_or_b32_e32 v81, 26, v0
	v_or_b32_e32 v82, 28, v0
	v_or_b32_e32 v83, 30, v0
	v_or_b32_e32 v84, 32, v0
	v_or_b32_e32 v85, 34, v0
	v_or_b32_e32 v86, 36, v0
	v_or_b32_e32 v87, 38, v0
	v_or_b32_e32 v88, 40, v0
	v_or_b32_e32 v89, 42, v0
	v_or_b32_e32 v90, 44, v0
	v_or_b32_e32 v91, 46, v0
	v_or_b32_e32 v92, 48, v0
	s_mov_b32 s62, s10
	s_mov_b32 s59, s3
	s_mov_b32 s58, s2
	v_or_b32_e32 v93, 50, v0
	v_or_b32_e32 v94, 52, v0
	v_mov_b32_e32 v1, v3
	v_or_b32_e32 v95, 54, v0
	v_or_b32_e32 v96, 56, v0
	v_or_b32_e32 v97, 58, v0
	v_or_b32_e32 v98, 60, v0
	v_or_b32_e32 v99, 62, v0
	v_and_b32_e32 v100, 16, v66
	v_or_b32_e32 v101, 8, v63
	v_or_b32_e32 v102, 16, v63
	v_or_b32_e32 v103, 24, v63
	v_mov_b32_e32 v104, 0xf07
	v_mov_b32_e32 v105, 0xf0f
	v_mov_b32_e32 v106, 0xf17
	v_mov_b32_e32 v107, 0xf1f
	v_lshl_add_u64 v[24:25], s[48:49], 0, v[2:3]
	v_lshl_add_u64 v[26:27], s[60:61], 0, v[2:3]
	v_lshl_add_u64 v[28:29], s[54:55], 0, v[2:3]
	v_lshl_add_u64 v[30:31], s[70:71], 0, v[2:3]
	s_cselect_b64 s[38:39], -1, 0
	s_lshl_b32 s10, s12, 5
	s_lshl_b32 s11, s14, 5
	s_lshl_b32 s96, s12, 6
	s_lshl_b32 s97, s14, 6
	s_lshl_b32 s13, s12, 2
	s_lshl_b32 s15, s14, 2
	s_movk_i32 s33, 0x7fff
	s_mov_b32 s86, 0xffff0000
	s_movk_i32 s87, 0x2c00
	s_movk_i32 s93, 0x3000
	s_mov_b32 s88, s12
	s_mov_b32 s57, 0
	v_readlane_b32 s53, v255, 28
	v_readlane_b32 s56, v255, 31
	v_readlane_b32 s63, v255, 38
	v_readlane_b32 s65, v255, 12
	v_readlane_b32 s66, v255, 13
	v_readlane_b32 s67, v255, 14
	v_readlane_b32 s72, v255, 19
	v_readlane_b32 s73, v255, 20
	v_readlane_b32 s74, v255, 21
	v_readlane_b32 s75, v255, 22
	v_readlane_b32 s76, v255, 23
	v_readlane_b32 s77, v255, 24
	v_readlane_b32 s78, v255, 25
	v_readlane_b32 s79, v255, 26
	s_branch .LBB0_24

; #define LAS __attribute__((address_space(3)))
; #define TR(cnt, W, K_, N_, DST, MODE, GAIN) if (r < (cnt)) { transpose_item((W), (K_), (N_), (bf16*)(ws + (DST)), (MODE), (GAIN), scr, r, lane); continue; } r -= (cnt);
; __device__ __forceinline__ void transpose_item(const float* W, int K, int N, bf16* WT, int mode, const float* gain, LAS float* scr, int item, int lane) {
;     const int nblk = N / 32, kb = item / nblk, nb = item % nblk, k0 = 64 * kb, n0 = 32 * nb;
; #pragma unroll
;     for (int i = 0; i < 32; ++i) { const int kk = 2 * i + (lane >> 5); float w = W[(size_t)(k0 + kk) * N + n0 + (lane & 31)]; if (gain) w *= gain[k0 + kk]; scr[kk * 33 + (lane & 31)] = w; }
; __device__ __forceinline__ void p0_prologue(const Args& a, LAS unsigned char* lds, int vcu, int G, int wave, int lane) {
;     ...
;     for (int it = gw; it < NITEMS; it += NGW) {
;         int r = it;
;     ...
;         TR(T_PW1, a.in[I_CW1], D, 2 * D, WS_WPW1, 3, a.in[I_CNG])
;         TR(T_SQ, a.in[I_CW2], D, D, WS_WPW2, 0, (const float*)nullptr)
;         TR(T_QKV, a.in[I_AWQKV], D, 3 * D, WS_WQKV, 4, a.in[I_ANG])
;         TR(T_SQ, a.in[I_AWO], D, D, WS_WO, 0, (const float*)nullptr)
;         TR(T_GU, a.in[I_FWG], D, DFF, WS_WGU0, 1, a.in[I_FNG])
;         TR(T_GU, a.in[I_FWU], D, DFF, WS_WGU0, 2, a.in[I_FNG])
;         TR(T_GU, a.in[I_FWG] + (size_t)D * DFF, D, DFF, WS_WGU1, 1, a.in[I_FNG] + D)
;         TR(T_GU, a.in[I_FWU] + (size_t)D * DFF, D, DFF, WS_WGU1, 2, a.in[I_FNG] + D)
;         TR(T_DN, a.in[I_FWD], DFF, D, WS_WD0, 0, (const float*)nullptr)
;         TR(T_DN, a.in[I_FWD] + (size_t)D * DFF, DFF, D, WS_WD1, 0, (const float*)nullptr)
;         TR(T_SQ, a.in[I_PWG], D, D, WS_WPG0, 0, a.in[I_PNG])
;         TR(T_SQ, a.in[I_PWG] + (size_t)D * D, D, D, WS_WPG1, 0, a.in[I_PNG] + D)
;         TR(T_PP, a.in[I_PWP], PLE, D, WS_WPP0, 0, (const float*)nullptr)
;         TR(T_PP, a.in[I_PWP] + (size_t)PLE * D, PLE, D, WS_WPP1, 0, (const float*)nullptr)
.LBB0_24:
	s_cmpk_gt_i32 s88, 0x3ff
	s_mov_b64 s[2:3], -1
	s_cbranch_scc0 .LBB0_330
	s_cmpk_gt_u32 s88, 0x5ff
	s_cbranch_scc0 .LBB0_327
	s_cmpk_gt_u32 s88, 0xbff
	s_cbranch_scc0 .LBB0_260
	s_cmpk_gt_u32 s88, 0xdff
	s_cbranch_scc0 .LBB0_257
	s_cmpk_gt_u32 s88, 0x137f
	s_cbranch_scc0 .LBB0_190
	s_cmpk_gt_u32 s88, 0x18ff
	s_cbranch_scc0 .LBB0_123
	s_cmpk_gt_u32 s88, 0x1e7f
	s_cbranch_scc0 .LBB0_120
	s_cmpk_gt_u32 s88, 0x23ff
	s_cbranch_scc0 .LBB0_117
	s_cmpk_gt_u32 s88, 0x297f
	s_cbranch_scc0 .LBB0_114
	s_cmpk_gt_u32 s88, 0x2eff
	s_cbranch_scc0 .LBB0_111
	s_cmpk_gt_u32 s88, 0x30ff
	s_cbranch_scc0 .LBB0_44
	s_cmpk_gt_u32 s88, 0x32ff
	s_cbranch_scc0 .LBB0_41
	s_bfe_u32 s18, s88, 0x30005
	s_cmpk_gt_u32 s88, 0x337f
	s_cbranch_scc0 .LBB0_38
	s_xor_b32 s2, s18, 4
	s_lshl_b32 s3, s2, 6
	s_and_b32 s19, s10, 0x3e0
	s_lshl_b32 s56, s19, 2
	v_or_b32_e32 v2, s3, v0
	v_lshl_add_u64 v[32:33], v[14:15], 0, s[56:57]
	v_lshlrev_b32_e32 v2, 12, v2
	v_lshl_add_u64 v[34:35], v[32:33], 0, v[2:3]
	v_or_b32_e32 v2, s3, v38
	v_lshlrev_b32_e32 v2, 12, v2
	global_load_dword v108, v[34:35], off
	v_lshl_add_u64 v[34:35], v[32:33], 0, v[2:3]
	v_or_b32_e32 v2, s3, v70
	v_lshlrev_b32_e32 v2, 12, v2
	global_load_dword v109, v[34:35], off
	v_lshl_add_u64 v[34:35], v[32:33], 0, v[2:3]
	v_or_b32_e32 v2, s3, v71
	v_lshlrev_b32_e32 v2, 12, v2
	global_load_dword v110, v[34:35], off
	v_lshl_add_u64 v[34:35], v[32:33], 0, v[2:3]
	v_or_b32_e32 v2, s3, v72
	v_lshlrev_b32_e32 v2, 12, v2
	global_load_dword v111, v[34:35], off
	v_lshl_add_u64 v[34:35], v[32:33], 0, v[2:3]
	v_or_b32_e32 v2, s3, v73
	v_lshlrev_b32_e32 v2, 12, v2
	global_load_dword v112, v[34:35], off
	v_lshl_add_u64 v[34:35], v[32:33], 0, v[2:3]
	v_or_b32_e32 v2, s3, v74
	v_lshlrev_b32_e32 v2, 12, v2
	global_load_dword v113, v[34:35], off
	v_lshl_add_u64 v[34:35], v[32:33], 0, v[2:3]
	v_or_b32_e32 v2, s3, v75
	v_lshlrev_b32_e32 v2, 12, v2
	global_load_dword v114, v[34:35], off
	v_lshl_add_u64 v[34:35], v[32:33], 0, v[2:3]
	v_or_b32_e32 v2, s3, v76
	v_lshlrev_b32_e32 v2, 12, v2
	global_load_dword v115, v[34:35], off
	v_lshl_add_u64 v[34:35], v[32:33], 0, v[2:3]
	v_or_b32_e32 v2, s3, v77
	v_lshlrev_b32_e32 v2, 12, v2
	global_load_dword v116, v[34:35], off
	v_lshl_add_u64 v[34:35], v[32:33], 0, v[2:3]
	v_or_b32_e32 v2, s3, v78
	v_lshlrev_b32_e32 v2, 12, v2
	global_load_dword v117, v[34:35], off
	v_lshl_add_u64 v[34:35], v[32:33], 0, v[2:3]
	v_or_b32_e32 v2, s3, v79
	v_lshlrev_b32_e32 v2, 12, v2
	global_load_dword v118, v[34:35], off
	v_lshl_add_u64 v[34:35], v[32:33], 0, v[2:3]
	v_or_b32_e32 v2, s3, v80
	v_lshlrev_b32_e32 v2, 12, v2
	global_load_dword v119, v[34:35], off
	v_lshl_add_u64 v[34:35], v[32:33], 0, v[2:3]
	v_or_b32_e32 v2, s3, v81
	v_lshlrev_b32_e32 v2, 12, v2
	global_load_dword v120, v[34:35], off
	v_lshl_add_u64 v[34:35], v[32:33], 0, v[2:3]
	v_or_b32_e32 v2, s3, v82
	v_lshlrev_b32_e32 v2, 12, v2
	global_load_dword v121, v[34:35], off
	v_lshl_add_u64 v[34:35], v[32:33], 0, v[2:3]
	v_or_b32_e32 v2, s3, v83
	v_lshlrev_b32_e32 v2, 12, v2
	global_load_dword v122, v[34:35], off
	v_lshl_add_u64 v[34:35], v[32:33], 0, v[2:3]
	v_or_b32_e32 v2, s3, v84
	v_lshlrev_b32_e32 v2, 12, v2
	global_load_dword v123, v[34:35], off
	v_lshl_add_u64 v[34:35], v[32:33], 0, v[2:3]
	v_or_b32_e32 v2, s3, v85
	v_lshlrev_b32_e32 v2, 12, v2
	global_load_dword v124, v[34:35], off
	v_lshl_add_u64 v[34:35], v[32:33], 0, v[2:3]
	v_or_b32_e32 v2, s3, v86
	v_lshlrev_b32_e32 v2, 12, v2
	global_load_dword v125, v[34:35], off
	v_lshl_add_u64 v[34:35], v[32:33], 0, v[2:3]
	v_or_b32_e32 v2, s3, v87
	v_lshlrev_b32_e32 v2, 12, v2
	global_load_dword v126, v[34:35], off
	v_lshl_add_u64 v[34:35], v[32:33], 0, v[2:3]
	v_or_b32_e32 v2, s3, v88
	v_lshlrev_b32_e32 v2, 12, v2
	global_load_dword v127, v[34:35], off
	v_lshl_add_u64 v[34:35], v[32:33], 0, v[2:3]
	v_or_b32_e32 v2, s3, v89
	v_lshlrev_b32_e32 v2, 12, v2
	global_load_dword v128, v[34:35], off
	v_lshl_add_u64 v[34:35], v[32:33], 0, v[2:3]
	v_or_b32_e32 v2, s3, v90
	v_lshlrev_b32_e32 v2, 12, v2
	global_load_dword v129, v[34:35], off
	v_lshl_add_u64 v[34:35], v[32:33], 0, v[2:3]
	v_or_b32_e32 v2, s3, v91
	v_lshlrev_b32_e32 v2, 12, v2
	global_load_dword v130, v[34:35], off
	v_lshl_add_u64 v[34:35], v[32:33], 0, v[2:3]
	v_or_b32_e32 v2, s3, v92
	v_lshlrev_b32_e32 v2, 12, v2
	global_load_dword v131, v[34:35], off
	v_lshl_add_u64 v[34:35], v[32:33], 0, v[2:3]
	v_or_b32_e32 v2, s3, v93
	v_lshlrev_b32_e32 v2, 12, v2
	global_load_dword v132, v[34:35], off
	v_lshl_add_u64 v[34:35], v[32:33], 0, v[2:3]
	v_or_b32_e32 v2, s3, v94
	v_lshlrev_b32_e32 v2, 12, v2
	global_load_dword v133, v[34:35], off
	v_lshl_add_u64 v[34:35], v[32:33], 0, v[2:3]
	v_or_b32_e32 v2, s3, v95
	v_lshlrev_b32_e32 v2, 12, v2
	global_load_dword v134, v[34:35], off
	v_lshl_add_u64 v[34:35], v[32:33], 0, v[2:3]
	v_or_b32_e32 v2, s3, v96
	v_lshlrev_b32_e32 v2, 12, v2
	global_load_dword v135, v[34:35], off
	v_lshl_add_u64 v[34:35], v[32:33], 0, v[2:3]
	v_or_b32_e32 v2, s3, v97
	v_lshlrev_b32_e32 v2, 12, v2
	global_load_dword v136, v[34:35], off
	v_lshl_add_u64 v[34:35], v[32:33], 0, v[2:3]
	v_or_b32_e32 v2, s3, v98
	v_lshlrev_b32_e32 v2, 12, v2
	global_load_dword v137, v[34:35], off
	v_lshl_add_u64 v[34:35], v[32:33], 0, v[2:3]
	v_or_b32_e32 v2, s3, v99
	v_lshlrev_b32_e32 v2, 12, v2
	v_lshl_add_u64 v[32:33], v[32:33], 0, v[2:3]
	global_load_dword v34, v[34:35], off
	s_and_b32 s3, s10, 0x60
	global_load_dword v2, v[32:33], off
	v_add_u32_e32 v32, v36, v37
	s_waitcnt vmcnt(30)
	ds_write2_b32 v32, v108, v109 offset1:66
	s_waitcnt vmcnt(28)
	ds_write2_b32 v32, v110, v111 offset0:132 offset1:198
	v_add_u32_e32 v32, 0x400, v32
	s_waitcnt vmcnt(26)
; #define GAS __attribute__((address_space(1)))
; #define LAS __attribute__((address_space(3)))
; #define LDS_WAIT() asm volatile("s_waitcnt lgkmcnt(0)" ::: "memory")
; __device__ __forceinline__ unsigned pk2(float lo, float hi) { return f2bf(lo) | (f2bf(hi) << 16); }
; __device__ __forceinline__ void transpose_item(const float* W, int K, int N, bf16* WT, int mode, const float* gain, LAS float* scr, int item, int lane) {
;     ...
;     for (int i = 0; i < 32; ++i) { const int kk = 2 * i + (lane >> 5); float w = W[(size_t)(k0 + kk) * N + n0 + (lane & 31)]; if (gain) w *= gain[k0 + kk]; scr[kk * 33 + (lane & 31)] = w; }
;     LDS_WAIT(); asm volatile("" ::: "memory");
;     const int c = lane & 7;
; #pragma unroll
;     for (int j = 0; j < 4; ++j) { const int n = (lane >> 3) + 8 * j; const LAS float* s = scr + (8 * c) * 33 + n;
;         v4u o; o.x = pk2(s[0 * 33], s[1 * 33]); o.y = pk2(s[2 * 33], s[3 * 33]); o.z = pk2(s[4 * 33], s[5 * 33]); o.w = pk2(s[6 * 33], s[7 * 33]);
;         const int p_ = dst_row(mode, n0 + n), pl_ = p_ & 127, x_ = pl_ & 31, R_ = (pl_ & ~31) + 16 * ((x_ >> 2) & 1) + 4 * (x_ >> 3) + (x_ & 3);
;         *(GAS v4u*)((GAS unsigned char*)WT + ((size_t)(p_ >> 7) * (K / 64) + (k0 >> 6)) * 16384 + pg8::lds_byte(R_, 8 * c)) = o; }
	ds_write2_b32 v32, v112, v113 offset0:8 offset1:74
	v_add_u32_e32 v32, v36, v44
	s_waitcnt vmcnt(24)
	ds_write2_b32 v32, v114, v115 offset1:66
	s_waitcnt vmcnt(22)
	ds_write2_b32 v32, v116, v117 offset0:132 offset1:198
	v_add_u32_e32 v32, 0x400, v32
	s_waitcnt vmcnt(20)
	ds_write2_b32 v32, v118, v119 offset0:8 offset1:74
	v_add_u32_e32 v32, v36, v50
	s_waitcnt vmcnt(18)
	ds_write2_b32 v32, v120, v121 offset1:66
	s_waitcnt vmcnt(16)
	ds_write2_b32 v32, v122, v123 offset0:132 offset1:198
	v_add_u32_e32 v32, 0x400, v32
	s_waitcnt vmcnt(14)
	ds_write2_b32 v32, v124, v125 offset0:8 offset1:74
	v_add_u32_e32 v32, v36, v56
	s_waitcnt vmcnt(12)
	ds_write2_b32 v32, v126, v127 offset1:66
	s_waitcnt vmcnt(10)
	ds_write2_b32 v32, v128, v129 offset0:132 offset1:198
	v_add_u32_e32 v32, 0x400, v32
	s_waitcnt vmcnt(8)
	ds_write2_b32 v32, v130, v131 offset0:8 offset1:74
	v_add_u32_e32 v32, v36, v62
	s_waitcnt vmcnt(6)
	ds_write2_b32 v32, v132, v133 offset1:66
	s_waitcnt vmcnt(4)
	ds_write2_b32 v32, v134, v135 offset0:132 offset1:198
	v_add_u32_e32 v32, 0x400, v32
	s_waitcnt vmcnt(2)
	ds_write2_b32 v32, v136, v137 offset0:8 offset1:74
	s_waitcnt vmcnt(0)
	ds_write2_b32 v32, v34, v2 offset0:140 offset1:206
	s_waitcnt lgkmcnt(0)
	ds_read2_b32 v[108:109], v67 offset1:8
	ds_read2_b32 v[110:111], v67 offset0:33 offset1:41
	ds_read2_b32 v[112:113], v67 offset0:66 offset1:74
	ds_read2_b32 v[114:115], v67 offset0:99 offset1:107
	ds_read2_b32 v[116:117], v67 offset0:132 offset1:140
	s_waitcnt lgkmcnt(4)
	v_bfe_u32 v2, v108, 16, 1
	v_add3_u32 v2, v108, v2, s33
	s_waitcnt lgkmcnt(3)
	v_bfe_u32 v32, v110, 16, 1
	v_lshrrev_b32_e32 v2, 16, v2
	v_add3_u32 v32, v110, v32, s33
	ds_read2_b32 v[118:119], v67 offset0:165 offset1:173
	v_and_or_b32 v32, v32, s86, v2
	s_waitcnt lgkmcnt(3)
	v_bfe_u32 v2, v112, 16, 1
	v_add3_u32 v2, v112, v2, s33
	s_waitcnt lgkmcnt(2)
	v_bfe_u32 v33, v114, 16, 1
	ds_read2_b32 v[120:121], v67 offset0:198 offset1:206
	v_lshrrev_b32_e32 v2, 16, v2
	v_add3_u32 v33, v114, v33, s33
	ds_read2_b32 v[122:123], v67 offset0:231 offset1:239
	v_and_or_b32 v33, v33, s86, v2
	s_waitcnt lgkmcnt(3)
	v_bfe_u32 v2, v116, 16, 1
	v_add3_u32 v2, v116, v2, s33
	s_waitcnt lgkmcnt(2)
	v_bfe_u32 v34, v118, 16, 1
	v_lshrrev_b32_e32 v2, 16, v2
	v_add3_u32 v34, v118, v34, s33
	v_and_or_b32 v34, v34, s86, v2
	s_waitcnt lgkmcnt(1)
	v_bfe_u32 v2, v120, 16, 1
	v_add3_u32 v2, v120, v2, s33
	s_waitcnt lgkmcnt(0)
	v_bfe_u32 v35, v122, 16, 1
	v_lshrrev_b32_e32 v2, 16, v2
	v_add3_u32 v35, v122, v35, s33
	v_and_or_b32 v35, v35, s86, v2
	v_or_b32_e32 v2, s3, v100
	s_and_b32 s3, s88, 28
	s_add_i32 s2, s2, s3
	v_lshrrev_b32_e32 v2, 3, v2
	s_lshl_b32 s2, s2, 14
	v_readlane_b32 s3, v255, 60
	v_or_b32_e32 v2, v2, v64
	s_add_u32 s2, s3, s2
	v_readlane_b32 s3, v255, 61
	v_lshlrev_b32_e32 v2, 10, v2
	s_addc_u32 s3, s3, 0
	v_or_b32_e32 v124, v2, v68
	v_bfe_u32 v108, v123, 16, 1
	v_add3_u32 v110, v123, v108, s33
	global_store_dwordx4 v124, v[32:35], s[2:3]
	v_or_b32_e32 v2, v2, v69
	ds_read2_b32 v[122:123], v67 offset0:247 offset1:255
	v_bfe_u32 v32, v109, 16, 1
	v_add3_u32 v32, v109, v32, s33
	v_bfe_u32 v33, v111, 16, 1
	v_lshrrev_b32_e32 v32, 16, v32
	v_add3_u32 v33, v111, v33, s33
	v_and_or_b32 v32, v33, s86, v32
	v_bfe_u32 v33, v113, 16, 1
	v_add3_u32 v33, v113, v33, s33
	v_bfe_u32 v34, v115, 16, 1
	v_lshrrev_b32_e32 v33, 16, v33
	v_add3_u32 v34, v115, v34, s33
	v_and_or_b32 v33, v34, s86, v33
	v_bfe_u32 v34, v117, 16, 1
	v_add3_u32 v34, v117, v34, s33
	v_bfe_u32 v35, v119, 16, 1
	v_lshrrev_b32_e32 v34, 16, v34
	v_add3_u32 v35, v119, v35, s33
	v_and_or_b32 v34, v35, s86, v34
	v_bfe_u32 v35, v121, 16, 1
	v_add3_u32 v35, v121, v35, s33
	v_lshrrev_b32_e32 v35, 16, v35
	ds_read2_b32 v[108:109], v67 offset0:16 offset1:24
	v_and_or_b32 v35, v110, s86, v35
	ds_read2_b32 v[110:111], v67 offset0:49 offset1:57
	ds_read2_b32 v[112:113], v67 offset0:82 offset1:90
	ds_read2_b32 v[114:115], v67 offset0:115 offset1:123
	global_store_dwordx4 v2, v[32:35], s[2:3]
	s_waitcnt lgkmcnt(3)
	v_bfe_u32 v2, v108, 16, 1
	v_add3_u32 v2, v108, v2, s33
	s_waitcnt lgkmcnt(2)
	v_bfe_u32 v32, v110, 16, 1
	ds_read2_b32 v[116:117], v67 offset0:148 offset1:156
	v_lshrrev_b32_e32 v2, 16, v2
	v_add3_u32 v32, v110, v32, s33
	ds_read2_b32 v[118:119], v67 offset0:181 offset1:189
	v_and_or_b32 v32, v32, s86, v2
	s_waitcnt lgkmcnt(3)
	v_bfe_u32 v2, v112, 16, 1
	v_add3_u32 v2, v112, v2, s33
	s_waitcnt lgkmcnt(2)
	v_bfe_u32 v33, v114, 16, 1
	ds_read2_b32 v[120:121], v67 offset0:214 offset1:222
	v_lshrrev_b32_e32 v2, 16, v2
	v_add3_u32 v33, v114, v33, s33
	v_and_or_b32 v33, v33, s86, v2
	s_waitcnt lgkmcnt(2)
	v_bfe_u32 v2, v116, 16, 1
	v_add3_u32 v2, v116, v2, s33
	s_waitcnt lgkmcnt(1)
	v_bfe_u32 v34, v118, 16, 1
	v_lshrrev_b32_e32 v2, 16, v2
	v_add3_u32 v34, v118, v34, s33
	v_and_or_b32 v34, v34, s86, v2
	s_waitcnt lgkmcnt(0)
	v_bfe_u32 v2, v120, 16, 1
	v_add3_u32 v2, v120, v2, s33
	v_bfe_u32 v35, v122, 16, 1
	v_lshrrev_b32_e32 v2, 16, v2
	v_add3_u32 v35, v122, v35, s33
	v_and_or_b32 v35, v35, s86, v2
	v_xor_b32_e32 v2, 32, v124
	v_lshl_add_u64 v[124:125], s[2:3], 0, v[2:3]
	global_store_dwordx4 v[124:125], v[32:35], off offset:512
	v_bfe_u32 v2, v111, 16, 1
	v_add3_u32 v2, v111, v2, s33
	v_bfe_u32 v32, v109, 16, 1
	v_add3_u32 v32, v109, v32, s33
	v_lshrrev_b32_e32 v32, 16, v32
	v_bfe_u32 v33, v113, 16, 1
	v_and_or_b32 v32, v2, s86, v32
	v_bfe_u32 v2, v115, 16, 1
	v_add3_u32 v33, v113, v33, s33
	v_add3_u32 v2, v115, v2, s33
	v_lshrrev_b32_e32 v33, 16, v33
	v_bfe_u32 v34, v117, 16, 1
	v_and_or_b32 v33, v2, s86, v33
	v_bfe_u32 v2, v119, 16, 1
	v_add3_u32 v34, v117, v34, s33
	v_add3_u32 v2, v119, v2, s33
	v_lshrrev_b32_e32 v34, 16, v34
	v_bfe_u32 v35, v121, 16, 1
	v_and_or_b32 v34, v2, s86, v34
	v_bfe_u32 v2, v123, 16, 1
	v_add3_u32 v35, v121, v35, s33
	v_add3_u32 v2, v123, v2, s33
	v_lshrrev_b32_e32 v35, 16, v35
	v_and_or_b32 v35, v2, s86, v35
	global_store_dwordx4 v[124:125], v[32:35], off offset:768
	s_waitcnt lgkmcnt(0)
	s_mov_b64 s[2:3], 0

; #define GAS __attribute__((address_space(1)))
; #define LAS __attribute__((address_space(3)))
; #define LDS_WAIT() asm volatile("s_waitcnt lgkmcnt(0)" ::: "memory")
; __device__ __forceinline__ unsigned pk2(float lo, float hi) { return f2bf(lo) | (f2bf(hi) << 16); }
; __device__ __forceinline__ void transpose_item(const float* W, int K, int N, bf16* WT, int mode, const float* gain, LAS float* scr, int item, int lane) {
;     ...
;     LDS_WAIT(); asm volatile("" ::: "memory");
;     const int c = lane & 7;
; #pragma unroll
;     for (int j = 0; j < 4; ++j) { const int n = (lane >> 3) + 8 * j; const LAS float* s = scr + (8 * c) * 33 + n;
;         v4u o; o.x = pk2(s[0 * 33], s[1 * 33]); o.y = pk2(s[2 * 33], s[3 * 33]); o.z = pk2(s[4 * 33], s[5 * 33]); o.w = pk2(s[6 * 33], s[7 * 33]);
;         const int p_ = dst_row(mode, n0 + n), pl_ = p_ & 127, x_ = pl_ & 31, R_ = (pl_ & ~31) + 16 * ((x_ >> 2) & 1) + 4 * (x_ >> 3) + (x_ & 3);
;         *(GAS v4u*)((GAS unsigned char*)WT + ((size_t)(p_ >> 7) * (K / 64) + (k0 >> 6)) * 16384 + pg8::lds_byte(R_, 8 * c)) = o; }
.LBB0_109:
	s_waitcnt vmcnt(0)
	ds_write_b32 v35, v2 offset:1848
	s_waitcnt lgkmcnt(0)
	ds_read2_b32 v[108:109], v67 offset1:8
	ds_read2_b32 v[110:111], v67 offset0:33 offset1:41
	ds_read2_b32 v[112:113], v67 offset0:66 offset1:74
	ds_read2_b32 v[114:115], v67 offset0:99 offset1:107
	ds_read2_b32 v[116:117], v67 offset0:132 offset1:140
	s_waitcnt lgkmcnt(4)
	v_bfe_u32 v2, v108, 16, 1
	s_waitcnt lgkmcnt(3)
	v_bfe_u32 v32, v110, 16, 1
	v_add3_u32 v2, v108, v2, s33
	v_add3_u32 v32, v110, v32, s33
	v_lshrrev_b32_e32 v2, 16, v2
	ds_read2_b32 v[118:119], v67 offset0:165 offset1:173
	v_and_or_b32 v32, v32, s86, v2
	s_waitcnt lgkmcnt(3)
	v_bfe_u32 v2, v112, 16, 1
	v_add3_u32 v2, v112, v2, s33
	s_waitcnt lgkmcnt(2)
	v_bfe_u32 v33, v114, 16, 1
	ds_read2_b32 v[120:121], v67 offset0:198 offset1:206
	v_lshrrev_b32_e32 v2, 16, v2
	v_add3_u32 v33, v114, v33, s33
	ds_read2_b32 v[122:123], v67 offset0:231 offset1:239
	v_and_or_b32 v33, v33, s86, v2
	s_waitcnt lgkmcnt(3)
	v_bfe_u32 v2, v116, 16, 1
	v_add3_u32 v2, v116, v2, s33
	s_waitcnt lgkmcnt(2)
	v_bfe_u32 v34, v118, 16, 1
	v_lshrrev_b32_e32 v2, 16, v2
	v_add3_u32 v34, v118, v34, s33
	v_and_or_b32 v34, v34, s86, v2
	s_waitcnt lgkmcnt(1)
	v_bfe_u32 v2, v120, 16, 1
	v_add3_u32 v2, v120, v2, s33
	s_waitcnt lgkmcnt(0)
	v_bfe_u32 v35, v122, 16, 1
	v_lshrrev_b32_e32 v2, 16, v2
	v_add3_u32 v35, v122, v35, s33
	s_and_b32 s2, s10, 0x60
	v_and_or_b32 v35, v35, s86, v2
	v_or_b32_e32 v2, s2, v100
	s_and_b32 s2, s13, 0x70
	s_add_i32 s18, s18, s2
	v_lshrrev_b32_e32 v2, 3, v2
	s_lshl_b32 s2, s18, 14
	v_or_b32_e32 v2, v2, v64
	s_add_u32 s2, s92, s2
	v_readlane_b32 s3, v255, 62
	v_lshlrev_b32_e32 v2, 10, v2
	s_addc_u32 s3, s3, 0
	v_or_b32_e32 v124, v2, v68
	v_bfe_u32 v108, v123, 16, 1
	v_add3_u32 v110, v123, v108, s33
	global_store_dwordx4 v124, v[32:35], s[2:3]
	v_or_b32_e32 v2, v2, v69
	ds_read2_b32 v[122:123], v67 offset0:247 offset1:255
	v_bfe_u32 v32, v109, 16, 1
	v_add3_u32 v32, v109, v32, s33
	v_bfe_u32 v33, v111, 16, 1
	v_lshrrev_b32_e32 v32, 16, v32
	v_add3_u32 v33, v111, v33, s33
	v_and_or_b32 v32, v33, s86, v32
	v_bfe_u32 v33, v113, 16, 1
	v_add3_u32 v33, v113, v33, s33
	v_bfe_u32 v34, v115, 16, 1
	v_lshrrev_b32_e32 v33, 16, v33
	v_add3_u32 v34, v115, v34, s33
	v_and_or_b32 v33, v34, s86, v33
	v_bfe_u32 v34, v117, 16, 1
	v_add3_u32 v34, v117, v34, s33
	v_bfe_u32 v35, v119, 16, 1
	v_lshrrev_b32_e32 v34, 16, v34
	v_add3_u32 v35, v119, v35, s33
	v_and_or_b32 v34, v35, s86, v34
	v_bfe_u32 v35, v121, 16, 1
	v_add3_u32 v35, v121, v35, s33
	v_lshrrev_b32_e32 v35, 16, v35
	ds_read2_b32 v[108:109], v67 offset0:16 offset1:24
	v_and_or_b32 v35, v110, s86, v35
	ds_read2_b32 v[110:111], v67 offset0:49 offset1:57
	ds_read2_b32 v[112:113], v67 offset0:82 offset1:90
	ds_read2_b32 v[114:115], v67 offset0:115 offset1:123
	global_store_dwordx4 v2, v[32:35], s[2:3]
	s_waitcnt lgkmcnt(3)
	v_bfe_u32 v2, v108, 16, 1
	v_add3_u32 v2, v108, v2, s33
	s_waitcnt lgkmcnt(2)
	v_bfe_u32 v32, v110, 16, 1
	ds_read2_b32 v[116:117], v67 offset0:148 offset1:156
	v_lshrrev_b32_e32 v2, 16, v2
	v_add3_u32 v32, v110, v32, s33
	ds_read2_b32 v[118:119], v67 offset0:181 offset1:189
	v_and_or_b32 v32, v32, s86, v2
	s_waitcnt lgkmcnt(3)
	v_bfe_u32 v2, v112, 16, 1
	v_add3_u32 v2, v112, v2, s33
	s_waitcnt lgkmcnt(2)
	v_bfe_u32 v33, v114, 16, 1
	ds_read2_b32 v[120:121], v67 offset0:214 offset1:222
	v_lshrrev_b32_e32 v2, 16, v2
	v_add3_u32 v33, v114, v33, s33
	v_and_or_b32 v33, v33, s86, v2
	s_waitcnt lgkmcnt(2)
	v_bfe_u32 v2, v116, 16, 1
	v_add3_u32 v2, v116, v2, s33
	s_waitcnt lgkmcnt(1)
	v_bfe_u32 v34, v118, 16, 1
	v_lshrrev_b32_e32 v2, 16, v2
	v_add3_u32 v34, v118, v34, s33
	v_and_or_b32 v34, v34, s86, v2
	s_waitcnt lgkmcnt(0)
	v_bfe_u32 v2, v120, 16, 1
	v_add3_u32 v2, v120, v2, s33
	v_bfe_u32 v35, v122, 16, 1
	v_lshrrev_b32_e32 v2, 16, v2
	v_add3_u32 v35, v122, v35, s33
	v_and_or_b32 v35, v35, s86, v2
	v_xor_b32_e32 v2, 32, v124
	v_lshl_add_u64 v[124:125], s[2:3], 0, v[2:3]
	global_store_dwordx4 v[124:125], v[32:35], off offset:512
	v_bfe_u32 v2, v111, 16, 1
	v_add3_u32 v2, v111, v2, s33
	v_bfe_u32 v32, v109, 16, 1
	v_add3_u32 v32, v109, v32, s33
	v_lshrrev_b32_e32 v32, 16, v32
	v_bfe_u32 v33, v113, 16, 1
	v_and_or_b32 v32, v2, s86, v32
	v_bfe_u32 v2, v115, 16, 1
	v_add3_u32 v33, v113, v33, s33
	v_add3_u32 v2, v115, v2, s33
	v_lshrrev_b32_e32 v33, 16, v33
	v_bfe_u32 v34, v117, 16, 1
	v_and_or_b32 v33, v2, s86, v33
	v_bfe_u32 v2, v119, 16, 1
	v_add3_u32 v34, v117, v34, s33
	v_add3_u32 v2, v119, v2, s33
	v_lshrrev_b32_e32 v34, 16, v34
	v_bfe_u32 v35, v121, 16, 1
	v_and_or_b32 v34, v2, s86, v34
	v_bfe_u32 v2, v123, 16, 1
	v_add3_u32 v35, v121, v35, s33
	v_add3_u32 v2, v123, v2, s33
	v_lshrrev_b32_e32 v35, 16, v35
	v_and_or_b32 v35, v2, s86, v35
	global_store_dwordx4 v[124:125], v[32:35], off offset:768
	s_waitcnt lgkmcnt(0)

; #define LAS __attribute__((address_space(3)))
; #define TR(cnt, W, K_, N_, DST, MODE, GAIN) if (r < (cnt)) { transpose_item((W), (K_), (N_), (bf16*)(ws + (DST)), (MODE), (GAIN), scr, r, lane); continue; } r -= (cnt);
; __device__ __forceinline__ void transpose_item(const float* W, int K, int N, bf16* WT, int mode, const float* gain, LAS float* scr, int item, int lane) {
;     const int nblk = N / 32, kb = item / nblk, nb = item % nblk, k0 = 64 * kb, n0 = 32 * nb;
; #pragma unroll
;     for (int i = 0; i < 32; ++i) { const int kk = 2 * i + (lane >> 5); float w = W[(size_t)(k0 + kk) * N + n0 + (lane & 31)]; if (gain) w *= gain[k0 + kk]; scr[kk * 33 + (lane & 31)] = w; }
; __device__ __forceinline__ void p0_prologue(const Args& a, LAS unsigned char* lds, int vcu, int G, int wave, int lane) {
;     ...
;         TR(T_DN, a.in[I_FWD] + (size_t)D * DFF, DFF, D, WS_WD1, 0, (const float*)nullptr)
.LBB0_111:
	s_andn2_b64 vcc, exec, s[2:3]
	s_cbranch_vccnz .LBB0_113
	s_add_i32 s2, s88, 0xd680
	s_bfe_u32 s2, s2, 0xb0005
	s_lshl_b32 s3, s2, 6
	s_and_b32 s18, s10, 0x3e0
	s_lshl_b32 s56, s18, 2
	v_or_b32_e32 v2, s3, v0
	v_lshl_add_u64 v[32:33], v[18:19], 0, s[56:57]
	v_lshlrev_b32_e32 v2, 12, v2
	v_lshl_add_u64 v[34:35], v[32:33], 0, v[2:3]
	v_or_b32_e32 v2, s3, v38
	v_lshlrev_b32_e32 v2, 12, v2
	global_load_dword v108, v[34:35], off
	v_lshl_add_u64 v[34:35], v[32:33], 0, v[2:3]
	v_or_b32_e32 v2, s3, v70
	v_lshlrev_b32_e32 v2, 12, v2
	global_load_dword v109, v[34:35], off
	v_lshl_add_u64 v[34:35], v[32:33], 0, v[2:3]
	v_or_b32_e32 v2, s3, v71
	v_lshlrev_b32_e32 v2, 12, v2
	global_load_dword v110, v[34:35], off
	v_lshl_add_u64 v[34:35], v[32:33], 0, v[2:3]
	v_or_b32_e32 v2, s3, v72
	v_lshlrev_b32_e32 v2, 12, v2
	global_load_dword v111, v[34:35], off
	v_lshl_add_u64 v[34:35], v[32:33], 0, v[2:3]
	v_or_b32_e32 v2, s3, v73
	v_lshlrev_b32_e32 v2, 12, v2
	global_load_dword v112, v[34:35], off
	v_lshl_add_u64 v[34:35], v[32:33], 0, v[2:3]
	v_or_b32_e32 v2, s3, v74
	v_lshlrev_b32_e32 v2, 12, v2
	global_load_dword v113, v[34:35], off
	v_lshl_add_u64 v[34:35], v[32:33], 0, v[2:3]
	v_or_b32_e32 v2, s3, v75
	v_lshlrev_b32_e32 v2, 12, v2
	global_load_dword v114, v[34:35], off
	v_lshl_add_u64 v[34:35], v[32:33], 0, v[2:3]
	v_or_b32_e32 v2, s3, v76
	v_lshlrev_b32_e32 v2, 12, v2
	global_load_dword v115, v[34:35], off
	v_lshl_add_u64 v[34:35], v[32:33], 0, v[2:3]
	v_or_b32_e32 v2, s3, v77
	v_lshlrev_b32_e32 v2, 12, v2
	global_load_dword v116, v[34:35], off
	v_lshl_add_u64 v[34:35], v[32:33], 0, v[2:3]
	v_or_b32_e32 v2, s3, v78
	v_lshlrev_b32_e32 v2, 12, v2
	global_load_dword v117, v[34:35], off
	v_lshl_add_u64 v[34:35], v[32:33], 0, v[2:3]
	v_or_b32_e32 v2, s3, v79
	v_lshlrev_b32_e32 v2, 12, v2
	global_load_dword v118, v[34:35], off
	v_lshl_add_u64 v[34:35], v[32:33], 0, v[2:3]
	v_or_b32_e32 v2, s3, v80
	v_lshlrev_b32_e32 v2, 12, v2
	global_load_dword v119, v[34:35], off
	v_lshl_add_u64 v[34:35], v[32:33], 0, v[2:3]
	v_or_b32_e32 v2, s3, v81
	v_lshlrev_b32_e32 v2, 12, v2
	global_load_dword v120, v[34:35], off
	v_lshl_add_u64 v[34:35], v[32:33], 0, v[2:3]
	v_or_b32_e32 v2, s3, v82
	v_lshlrev_b32_e32 v2, 12, v2
	global_load_dword v121, v[34:35], off
	v_lshl_add_u64 v[34:35], v[32:33], 0, v[2:3]
	v_or_b32_e32 v2, s3, v83
	v_lshlrev_b32_e32 v2, 12, v2
	global_load_dword v122, v[34:35], off
	v_lshl_add_u64 v[34:35], v[32:33], 0, v[2:3]
	v_or_b32_e32 v2, s3, v84
	v_lshlrev_b32_e32 v2, 12, v2
	global_load_dword v123, v[34:35], off
	v_lshl_add_u64 v[34:35], v[32:33], 0, v[2:3]
	v_or_b32_e32 v2, s3, v85
	v_lshlrev_b32_e32 v2, 12, v2
	global_load_dword v124, v[34:35], off
	v_lshl_add_u64 v[34:35], v[32:33], 0, v[2:3]
	v_or_b32_e32 v2, s3, v86
	v_lshlrev_b32_e32 v2, 12, v2
	global_load_dword v125, v[34:35], off
	v_lshl_add_u64 v[34:35], v[32:33], 0, v[2:3]
	v_or_b32_e32 v2, s3, v87
	v_lshlrev_b32_e32 v2, 12, v2
	global_load_dword v126, v[34:35], off
	v_lshl_add_u64 v[34:35], v[32:33], 0, v[2:3]
	v_or_b32_e32 v2, s3, v88
	v_lshlrev_b32_e32 v2, 12, v2
	global_load_dword v127, v[34:35], off
	v_lshl_add_u64 v[34:35], v[32:33], 0, v[2:3]
	v_or_b32_e32 v2, s3, v89
	v_lshlrev_b32_e32 v2, 12, v2
	global_load_dword v128, v[34:35], off
	v_lshl_add_u64 v[34:35], v[32:33], 0, v[2:3]
	v_or_b32_e32 v2, s3, v90
	v_lshlrev_b32_e32 v2, 12, v2
	global_load_dword v129, v[34:35], off
	v_lshl_add_u64 v[34:35], v[32:33], 0, v[2:3]
	v_or_b32_e32 v2, s3, v91
	v_lshlrev_b32_e32 v2, 12, v2
	global_load_dword v130, v[34:35], off
	v_lshl_add_u64 v[34:35], v[32:33], 0, v[2:3]
	v_or_b32_e32 v2, s3, v92
	v_lshlrev_b32_e32 v2, 12, v2
	global_load_dword v131, v[34:35], off
	v_lshl_add_u64 v[34:35], v[32:33], 0, v[2:3]
	v_or_b32_e32 v2, s3, v93
	v_lshlrev_b32_e32 v2, 12, v2
	global_load_dword v132, v[34:35], off
	v_lshl_add_u64 v[34:35], v[32:33], 0, v[2:3]
	v_or_b32_e32 v2, s3, v94
	v_lshlrev_b32_e32 v2, 12, v2
	global_load_dword v133, v[34:35], off
	v_lshl_add_u64 v[34:35], v[32:33], 0, v[2:3]
	v_or_b32_e32 v2, s3, v95
	v_lshlrev_b32_e32 v2, 12, v2
	global_load_dword v134, v[34:35], off
	v_lshl_add_u64 v[34:35], v[32:33], 0, v[2:3]
	v_or_b32_e32 v2, s3, v96
	v_lshlrev_b32_e32 v2, 12, v2
	global_load_dword v135, v[34:35], off
	v_lshl_add_u64 v[34:35], v[32:33], 0, v[2:3]
	v_or_b32_e32 v2, s3, v97
	v_lshlrev_b32_e32 v2, 12, v2
	global_load_dword v136, v[34:35], off
	v_lshl_add_u64 v[34:35], v[32:33], 0, v[2:3]
	v_or_b32_e32 v2, s3, v98
	v_lshlrev_b32_e32 v2, 12, v2
	global_load_dword v137, v[34:35], off
	v_lshl_add_u64 v[34:35], v[32:33], 0, v[2:3]
	v_or_b32_e32 v2, s3, v99
	v_lshlrev_b32_e32 v2, 12, v2
	v_lshl_add_u64 v[32:33], v[32:33], 0, v[2:3]
	global_load_dword v34, v[34:35], off
	s_and_b32 s3, s10, 0x60
	global_load_dword v2, v[32:33], off
	v_add_u32_e32 v32, v36, v37
	s_waitcnt vmcnt(30)
	ds_write2_b32 v32, v108, v109 offset1:66
	s_waitcnt vmcnt(28)
	ds_write2_b32 v32, v110, v111 offset0:132 offset1:198
	v_add_u32_e32 v32, 0x400, v32
	s_waitcnt vmcnt(26)
	ds_write2_b32 v32, v112, v113 offset0:8 offset1:74
	v_add_u32_e32 v32, v36, v44
	s_waitcnt vmcnt(24)
	ds_write2_b32 v32, v114, v115 offset1:66
	s_waitcnt vmcnt(22)
	ds_write2_b32 v32, v116, v117 offset0:132 offset1:198
	v_add_u32_e32 v32, 0x400, v32
	s_waitcnt vmcnt(20)
	ds_write2_b32 v32, v118, v119 offset0:8 offset1:74
	v_add_u32_e32 v32, v36, v50
	s_waitcnt vmcnt(18)
	ds_write2_b32 v32, v120, v121 offset1:66
	s_waitcnt vmcnt(16)
; #define GAS __attribute__((address_space(1)))
; #define LAS __attribute__((address_space(3)))
; #define LDS_WAIT() asm volatile("s_waitcnt lgkmcnt(0)" ::: "memory")
; __device__ __forceinline__ unsigned pk2(float lo, float hi) { return f2bf(lo) | (f2bf(hi) << 16); }
; __device__ __forceinline__ void transpose_item(const float* W, int K, int N, bf16* WT, int mode, const float* gain, LAS float* scr, int item, int lane) {
;     ...
;     LDS_WAIT(); asm volatile("" ::: "memory");
;     const int c = lane & 7;
; #pragma unroll
;     for (int j = 0; j < 4; ++j) { const int n = (lane >> 3) + 8 * j; const LAS float* s = scr + (8 * c) * 33 + n;
;         v4u o; o.x = pk2(s[0 * 33], s[1 * 33]); o.y = pk2(s[2 * 33], s[3 * 33]); o.z = pk2(s[4 * 33], s[5 * 33]); o.w = pk2(s[6 * 33], s[7 * 33]);
;         const int p_ = dst_row(mode, n0 + n), pl_ = p_ & 127, x_ = pl_ & 31, R_ = (pl_ & ~31) + 16 * ((x_ >> 2) & 1) + 4 * (x_ >> 3) + (x_ & 3);
;         *(GAS v4u*)((GAS unsigned char*)WT + ((size_t)(p_ >> 7) * (K / 64) + (k0 >> 6)) * 16384 + pg8::lds_byte(R_, 8 * c)) = o; }
	ds_write2_b32 v32, v122, v123 offset0:132 offset1:198
	v_add_u32_e32 v32, 0x400, v32
	s_waitcnt vmcnt(14)
	ds_write2_b32 v32, v124, v125 offset0:8 offset1:74
	v_add_u32_e32 v32, v36, v56
	s_waitcnt vmcnt(12)
	ds_write2_b32 v32, v126, v127 offset1:66
	s_waitcnt vmcnt(10)
	ds_write2_b32 v32, v128, v129 offset0:132 offset1:198
	v_add_u32_e32 v32, 0x400, v32
	s_waitcnt vmcnt(8)
	ds_write2_b32 v32, v130, v131 offset0:8 offset1:74
	v_add_u32_e32 v32, v36, v62
	s_waitcnt vmcnt(6)
	ds_write2_b32 v32, v132, v133 offset1:66
	s_waitcnt vmcnt(4)
	ds_write2_b32 v32, v134, v135 offset0:132 offset1:198
	v_add_u32_e32 v32, 0x400, v32
	s_waitcnt vmcnt(2)
	ds_write2_b32 v32, v136, v137 offset0:8 offset1:74
	s_waitcnt vmcnt(0)
	ds_write2_b32 v32, v34, v2 offset0:140 offset1:206
	s_waitcnt lgkmcnt(0)
	ds_read2_b32 v[108:109], v67 offset1:8
	ds_read2_b32 v[110:111], v67 offset0:33 offset1:41
	ds_read2_b32 v[112:113], v67 offset0:66 offset1:74
	ds_read2_b32 v[114:115], v67 offset0:99 offset1:107
	ds_read2_b32 v[116:117], v67 offset0:132 offset1:140
	s_waitcnt lgkmcnt(4)
	v_bfe_u32 v2, v108, 16, 1
	v_add3_u32 v2, v108, v2, s33
	s_waitcnt lgkmcnt(3)
	v_bfe_u32 v32, v110, 16, 1
	v_lshrrev_b32_e32 v2, 16, v2
	v_add3_u32 v32, v110, v32, s33
	ds_read2_b32 v[118:119], v67 offset0:165 offset1:173
	v_and_or_b32 v32, v32, s86, v2
	s_waitcnt lgkmcnt(3)
	v_bfe_u32 v2, v112, 16, 1
	v_add3_u32 v2, v112, v2, s33
	s_waitcnt lgkmcnt(2)
	v_bfe_u32 v33, v114, 16, 1
	ds_read2_b32 v[120:121], v67 offset0:198 offset1:206
	v_lshrrev_b32_e32 v2, 16, v2
	v_add3_u32 v33, v114, v33, s33
	ds_read2_b32 v[122:123], v67 offset0:231 offset1:239
	v_and_or_b32 v33, v33, s86, v2
	s_waitcnt lgkmcnt(3)
	v_bfe_u32 v2, v116, 16, 1
	v_add3_u32 v2, v116, v2, s33
	s_waitcnt lgkmcnt(2)
	v_bfe_u32 v34, v118, 16, 1
	v_lshrrev_b32_e32 v2, 16, v2
	v_add3_u32 v34, v118, v34, s33
	v_and_or_b32 v34, v34, s86, v2
	s_waitcnt lgkmcnt(1)
	v_bfe_u32 v2, v120, 16, 1
	v_add3_u32 v2, v120, v2, s33
	s_waitcnt lgkmcnt(0)
	v_bfe_u32 v35, v122, 16, 1
	v_lshrrev_b32_e32 v2, 16, v2
	v_add3_u32 v35, v122, v35, s33
	v_and_or_b32 v35, v35, s86, v2
	v_or_b32_e32 v2, s3, v100
	s_bfe_u32 s3, s10, 0x30007
	s_mul_i32 s3, s3, 44
	s_add_i32 s3, s3, s2
	v_lshrrev_b32_e32 v2, 3, v2
	s_lshl_b32 s2, s3, 14
	v_readlane_b32 s3, v255, 63
	v_or_b32_e32 v2, v2, v64
	s_add_u32 s2, s3, s2
	v_readlane_b32 s3, v254, 0
	v_lshlrev_b32_e32 v2, 10, v2
	s_addc_u32 s3, s3, 0
	v_or_b32_e32 v124, v2, v68
	v_bfe_u32 v108, v123, 16, 1
	v_add3_u32 v110, v123, v108, s33
	global_store_dwordx4 v124, v[32:35], s[2:3]
	v_or_b32_e32 v2, v2, v69
	ds_read2_b32 v[122:123], v67 offset0:247 offset1:255
	v_bfe_u32 v32, v109, 16, 1
	v_add3_u32 v32, v109, v32, s33
	v_bfe_u32 v33, v111, 16, 1
	v_lshrrev_b32_e32 v32, 16, v32
	v_add3_u32 v33, v111, v33, s33
	v_and_or_b32 v32, v33, s86, v32
	v_bfe_u32 v33, v113, 16, 1
	v_add3_u32 v33, v113, v33, s33
	v_bfe_u32 v34, v115, 16, 1
	v_lshrrev_b32_e32 v33, 16, v33
	v_add3_u32 v34, v115, v34, s33
	v_and_or_b32 v33, v34, s86, v33
	v_bfe_u32 v34, v117, 16, 1
	v_add3_u32 v34, v117, v34, s33
	v_bfe_u32 v35, v119, 16, 1
	v_lshrrev_b32_e32 v34, 16, v34
	v_add3_u32 v35, v119, v35, s33
	v_and_or_b32 v34, v35, s86, v34
	v_bfe_u32 v35, v121, 16, 1
	v_add3_u32 v35, v121, v35, s33
	v_lshrrev_b32_e32 v35, 16, v35
	ds_read2_b32 v[108:109], v67 offset0:16 offset1:24
	v_and_or_b32 v35, v110, s86, v35
	ds_read2_b32 v[110:111], v67 offset0:49 offset1:57
	ds_read2_b32 v[112:113], v67 offset0:82 offset1:90
	ds_read2_b32 v[114:115], v67 offset0:115 offset1:123
	global_store_dwordx4 v2, v[32:35], s[2:3]
	s_waitcnt lgkmcnt(3)
	v_bfe_u32 v2, v108, 16, 1
	v_add3_u32 v2, v108, v2, s33
	s_waitcnt lgkmcnt(2)
	v_bfe_u32 v32, v110, 16, 1
	ds_read2_b32 v[116:117], v67 offset0:148 offset1:156
	v_lshrrev_b32_e32 v2, 16, v2
	v_add3_u32 v32, v110, v32, s33
	ds_read2_b32 v[118:119], v67 offset0:181 offset1:189
	v_and_or_b32 v32, v32, s86, v2
	s_waitcnt lgkmcnt(3)
	v_bfe_u32 v2, v112, 16, 1
	v_add3_u32 v2, v112, v2, s33
	s_waitcnt lgkmcnt(2)
	v_bfe_u32 v33, v114, 16, 1
	ds_read2_b32 v[120:121], v67 offset0:214 offset1:222
	v_lshrrev_b32_e32 v2, 16, v2
	v_add3_u32 v33, v114, v33, s33
	v_and_or_b32 v33, v33, s86, v2
	s_waitcnt lgkmcnt(2)
	v_bfe_u32 v2, v116, 16, 1
	v_add3_u32 v2, v116, v2, s33
	s_waitcnt lgkmcnt(1)
	v_bfe_u32 v34, v118, 16, 1
	v_lshrrev_b32_e32 v2, 16, v2
	v_add3_u32 v34, v118, v34, s33
	v_and_or_b32 v34, v34, s86, v2
	s_waitcnt lgkmcnt(0)
	v_bfe_u32 v2, v120, 16, 1
	v_add3_u32 v2, v120, v2, s33
	v_bfe_u32 v35, v122, 16, 1
	v_lshrrev_b32_e32 v2, 16, v2
	v_add3_u32 v35, v122, v35, s33
	v_and_or_b32 v35, v35, s86, v2
	v_xor_b32_e32 v2, 32, v124
	v_lshl_add_u64 v[124:125], s[2:3], 0, v[2:3]
	global_store_dwordx4 v[124:125], v[32:35], off offset:512
	v_bfe_u32 v2, v111, 16, 1
	v_add3_u32 v2, v111, v2, s33
	v_bfe_u32 v32, v109, 16, 1
	v_add3_u32 v32, v109, v32, s33
	v_lshrrev_b32_e32 v32, 16, v32
	v_bfe_u32 v33, v113, 16, 1
	v_and_or_b32 v32, v2, s86, v32
	v_bfe_u32 v2, v115, 16, 1
	v_add3_u32 v33, v113, v33, s33
	v_add3_u32 v2, v115, v2, s33
	v_lshrrev_b32_e32 v33, 16, v33
	v_bfe_u32 v34, v117, 16, 1
	v_and_or_b32 v33, v2, s86, v33
	v_bfe_u32 v2, v119, 16, 1
	v_add3_u32 v34, v117, v34, s33
	v_add3_u32 v2, v119, v2, s33
	v_lshrrev_b32_e32 v34, 16, v34
	v_bfe_u32 v35, v121, 16, 1
	v_and_or_b32 v34, v2, s86, v34
	v_bfe_u32 v2, v123, 16, 1
	v_add3_u32 v35, v121, v35, s33
	v_add3_u32 v2, v123, v2, s33
	v_lshrrev_b32_e32 v35, 16, v35
	v_and_or_b32 v35, v2, s86, v35
	global_store_dwordx4 v[124:125], v[32:35], off offset:768
	s_waitcnt lgkmcnt(0)

; #define LAS __attribute__((address_space(3)))
; #define TR(cnt, W, K_, N_, DST, MODE, GAIN) if (r < (cnt)) { transpose_item((W), (K_), (N_), (bf16*)(ws + (DST)), (MODE), (GAIN), scr, r, lane); continue; } r -= (cnt);
; __device__ __forceinline__ void transpose_item(const float* W, int K, int N, bf16* WT, int mode, const float* gain, LAS float* scr, int item, int lane) {
;     const int nblk = N / 32, kb = item / nblk, nb = item % nblk, k0 = 64 * kb, n0 = 32 * nb;
; #pragma unroll
;     for (int i = 0; i < 32; ++i) { const int kk = 2 * i + (lane >> 5); float w = W[(size_t)(k0 + kk) * N + n0 + (lane & 31)]; if (gain) w *= gain[k0 + kk]; scr[kk * 33 + (lane & 31)] = w; }
; __device__ __forceinline__ void p0_prologue(const Args& a, LAS unsigned char* lds, int vcu, int G, int wave, int lane) {
;     ...
;         TR(T_DN, a.in[I_FWD], DFF, D, WS_WD0, 0, (const float*)nullptr)
.LBB0_114:
	s_andn2_b64 vcc, exec, s[2:3]
	s_cbranch_vccnz .LBB0_116
	s_add_i32 s2, s88, 0xdc00
	s_bfe_u32 s2, s2, 0xb0005
	s_lshl_b32 s3, s2, 6
	s_and_b32 s18, s10, 0x3e0
	s_lshl_b32 s56, s18, 2
	v_or_b32_e32 v2, s3, v0
	v_lshl_add_u64 v[32:33], v[8:9], 0, s[56:57]
	v_lshlrev_b32_e32 v2, 12, v2
	v_lshl_add_u64 v[34:35], v[32:33], 0, v[2:3]
	v_or_b32_e32 v2, s3, v38
	v_lshlrev_b32_e32 v2, 12, v2
	global_load_dword v108, v[34:35], off
	v_lshl_add_u64 v[34:35], v[32:33], 0, v[2:3]
	v_or_b32_e32 v2, s3, v70
	v_lshlrev_b32_e32 v2, 12, v2
	global_load_dword v109, v[34:35], off
	v_lshl_add_u64 v[34:35], v[32:33], 0, v[2:3]
	v_or_b32_e32 v2, s3, v71
	v_lshlrev_b32_e32 v2, 12, v2
	global_load_dword v110, v[34:35], off
	v_lshl_add_u64 v[34:35], v[32:33], 0, v[2:3]
	v_or_b32_e32 v2, s3, v72
	v_lshlrev_b32_e32 v2, 12, v2
	global_load_dword v111, v[34:35], off
	v_lshl_add_u64 v[34:35], v[32:33], 0, v[2:3]
	v_or_b32_e32 v2, s3, v73
	v_lshlrev_b32_e32 v2, 12, v2
	global_load_dword v112, v[34:35], off
	v_lshl_add_u64 v[34:35], v[32:33], 0, v[2:3]
	v_or_b32_e32 v2, s3, v74
	v_lshlrev_b32_e32 v2, 12, v2
	global_load_dword v113, v[34:35], off
	v_lshl_add_u64 v[34:35], v[32:33], 0, v[2:3]
	v_or_b32_e32 v2, s3, v75
	v_lshlrev_b32_e32 v2, 12, v2
	global_load_dword v114, v[34:35], off
	v_lshl_add_u64 v[34:35], v[32:33], 0, v[2:3]
	v_or_b32_e32 v2, s3, v76
	v_lshlrev_b32_e32 v2, 12, v2
	global_load_dword v115, v[34:35], off
	v_lshl_add_u64 v[34:35], v[32:33], 0, v[2:3]
	v_or_b32_e32 v2, s3, v77
	v_lshlrev_b32_e32 v2, 12, v2
	global_load_dword v116, v[34:35], off
	v_lshl_add_u64 v[34:35], v[32:33], 0, v[2:3]
	v_or_b32_e32 v2, s3, v78
	v_lshlrev_b32_e32 v2, 12, v2
	global_load_dword v117, v[34:35], off
	v_lshl_add_u64 v[34:35], v[32:33], 0, v[2:3]
	v_or_b32_e32 v2, s3, v79
	v_lshlrev_b32_e32 v2, 12, v2
	global_load_dword v118, v[34:35], off
	v_lshl_add_u64 v[34:35], v[32:33], 0, v[2:3]
	v_or_b32_e32 v2, s3, v80
	v_lshlrev_b32_e32 v2, 12, v2
	global_load_dword v119, v[34:35], off
	v_lshl_add_u64 v[34:35], v[32:33], 0, v[2:3]
	v_or_b32_e32 v2, s3, v81
	v_lshlrev_b32_e32 v2, 12, v2
	global_load_dword v120, v[34:35], off
	v_lshl_add_u64 v[34:35], v[32:33], 0, v[2:3]
	v_or_b32_e32 v2, s3, v82
	v_lshlrev_b32_e32 v2, 12, v2
	global_load_dword v121, v[34:35], off
	v_lshl_add_u64 v[34:35], v[32:33], 0, v[2:3]
	v_or_b32_e32 v2, s3, v83
	v_lshlrev_b32_e32 v2, 12, v2
	global_load_dword v122, v[34:35], off
	v_lshl_add_u64 v[34:35], v[32:33], 0, v[2:3]
	v_or_b32_e32 v2, s3, v84
	v_lshlrev_b32_e32 v2, 12, v2
	global_load_dword v123, v[34:35], off
	v_lshl_add_u64 v[34:35], v[32:33], 0, v[2:3]
	v_or_b32_e32 v2, s3, v85
	v_lshlrev_b32_e32 v2, 12, v2
	global_load_dword v124, v[34:35], off
	v_lshl_add_u64 v[34:35], v[32:33], 0, v[2:3]
	v_or_b32_e32 v2, s3, v86
	v_lshlrev_b32_e32 v2, 12, v2
	global_load_dword v125, v[34:35], off
	v_lshl_add_u64 v[34:35], v[32:33], 0, v[2:3]
	v_or_b32_e32 v2, s3, v87
	v_lshlrev_b32_e32 v2, 12, v2
	global_load_dword v126, v[34:35], off
	v_lshl_add_u64 v[34:35], v[32:33], 0, v[2:3]
	v_or_b32_e32 v2, s3, v88
	v_lshlrev_b32_e32 v2, 12, v2
	global_load_dword v127, v[34:35], off
	v_lshl_add_u64 v[34:35], v[32:33], 0, v[2:3]
	v_or_b32_e32 v2, s3, v89
	v_lshlrev_b32_e32 v2, 12, v2
	global_load_dword v128, v[34:35], off
	v_lshl_add_u64 v[34:35], v[32:33], 0, v[2:3]
	v_or_b32_e32 v2, s3, v90
	v_lshlrev_b32_e32 v2, 12, v2
	global_load_dword v129, v[34:35], off
	v_lshl_add_u64 v[34:35], v[32:33], 0, v[2:3]
	v_or_b32_e32 v2, s3, v91
	v_lshlrev_b32_e32 v2, 12, v2
	global_load_dword v130, v[34:35], off
	v_lshl_add_u64 v[34:35], v[32:33], 0, v[2:3]
	v_or_b32_e32 v2, s3, v92
	v_lshlrev_b32_e32 v2, 12, v2
	global_load_dword v131, v[34:35], off
	v_lshl_add_u64 v[34:35], v[32:33], 0, v[2:3]
	v_or_b32_e32 v2, s3, v93
	v_lshlrev_b32_e32 v2, 12, v2
	global_load_dword v132, v[34:35], off
	v_lshl_add_u64 v[34:35], v[32:33], 0, v[2:3]
	v_or_b32_e32 v2, s3, v94
	v_lshlrev_b32_e32 v2, 12, v2
	global_load_dword v133, v[34:35], off
	v_lshl_add_u64 v[34:35], v[32:33], 0, v[2:3]
	v_or_b32_e32 v2, s3, v95
	v_lshlrev_b32_e32 v2, 12, v2
	global_load_dword v134, v[34:35], off
	v_lshl_add_u64 v[34:35], v[32:33], 0, v[2:3]
	v_or_b32_e32 v2, s3, v96
	v_lshlrev_b32_e32 v2, 12, v2
	global_load_dword v135, v[34:35], off
	v_lshl_add_u64 v[34:35], v[32:33], 0, v[2:3]
	v_or_b32_e32 v2, s3, v97
	v_lshlrev_b32_e32 v2, 12, v2
	global_load_dword v136, v[34:35], off
	v_lshl_add_u64 v[34:35], v[32:33], 0, v[2:3]
	v_or_b32_e32 v2, s3, v98
	v_lshlrev_b32_e32 v2, 12, v2
	global_load_dword v137, v[34:35], off
	v_lshl_add_u64 v[34:35], v[32:33], 0, v[2:3]
	v_or_b32_e32 v2, s3, v99
	v_lshlrev_b32_e32 v2, 12, v2
	v_lshl_add_u64 v[32:33], v[32:33], 0, v[2:3]
	global_load_dword v34, v[34:35], off
	s_and_b32 s3, s10, 0x60
	global_load_dword v2, v[32:33], off
	v_add_u32_e32 v32, v36, v37
	s_waitcnt vmcnt(30)
	ds_write2_b32 v32, v108, v109 offset1:66
	s_waitcnt vmcnt(28)
	ds_write2_b32 v32, v110, v111 offset0:132 offset1:198
	v_add_u32_e32 v32, 0x400, v32
	s_waitcnt vmcnt(26)
	ds_write2_b32 v32, v112, v113 offset0:8 offset1:74
	v_add_u32_e32 v32, v36, v44
	s_waitcnt vmcnt(24)
	ds_write2_b32 v32, v114, v115 offset1:66
	s_waitcnt vmcnt(22)
	ds_write2_b32 v32, v116, v117 offset0:132 offset1:198
	v_add_u32_e32 v32, 0x400, v32
	s_waitcnt vmcnt(20)
	ds_write2_b32 v32, v118, v119 offset0:8 offset1:74
	v_add_u32_e32 v32, v36, v50
	s_waitcnt vmcnt(18)
	ds_write2_b32 v32, v120, v121 offset1:66
	s_waitcnt vmcnt(16)
; #define GAS __attribute__((address_space(1)))
; #define LAS __attribute__((address_space(3)))
; #define LDS_WAIT() asm volatile("s_waitcnt lgkmcnt(0)" ::: "memory")
; __device__ __forceinline__ unsigned pk2(float lo, float hi) { return f2bf(lo) | (f2bf(hi) << 16); }
; __device__ __forceinline__ void transpose_item(const float* W, int K, int N, bf16* WT, int mode, const float* gain, LAS float* scr, int item, int lane) {
;     ...
;     LDS_WAIT(); asm volatile("" ::: "memory");
;     const int c = lane & 7;
; #pragma unroll
;     for (int j = 0; j < 4; ++j) { const int n = (lane >> 3) + 8 * j; const LAS float* s = scr + (8 * c) * 33 + n;
;         v4u o; o.x = pk2(s[0 * 33], s[1 * 33]); o.y = pk2(s[2 * 33], s[3 * 33]); o.z = pk2(s[4 * 33], s[5 * 33]); o.w = pk2(s[6 * 33], s[7 * 33]);
;         const int p_ = dst_row(mode, n0 + n), pl_ = p_ & 127, x_ = pl_ & 31, R_ = (pl_ & ~31) + 16 * ((x_ >> 2) & 1) + 4 * (x_ >> 3) + (x_ & 3);
;         *(GAS v4u*)((GAS unsigned char*)WT + ((size_t)(p_ >> 7) * (K / 64) + (k0 >> 6)) * 16384 + pg8::lds_byte(R_, 8 * c)) = o; }
	ds_write2_b32 v32, v122, v123 offset0:132 offset1:198
	v_add_u32_e32 v32, 0x400, v32
	s_waitcnt vmcnt(14)
	ds_write2_b32 v32, v124, v125 offset0:8 offset1:74
	v_add_u32_e32 v32, v36, v56
	s_waitcnt vmcnt(12)
	ds_write2_b32 v32, v126, v127 offset1:66
	s_waitcnt vmcnt(10)
	ds_write2_b32 v32, v128, v129 offset0:132 offset1:198
	v_add_u32_e32 v32, 0x400, v32
	s_waitcnt vmcnt(8)
	ds_write2_b32 v32, v130, v131 offset0:8 offset1:74
	v_add_u32_e32 v32, v36, v62
	s_waitcnt vmcnt(6)
	ds_write2_b32 v32, v132, v133 offset1:66
	s_waitcnt vmcnt(4)
	ds_write2_b32 v32, v134, v135 offset0:132 offset1:198
	v_add_u32_e32 v32, 0x400, v32
	s_waitcnt vmcnt(2)
	ds_write2_b32 v32, v136, v137 offset0:8 offset1:74
	s_waitcnt vmcnt(0)
	ds_write2_b32 v32, v34, v2 offset0:140 offset1:206
	s_waitcnt lgkmcnt(0)
	ds_read2_b32 v[108:109], v67 offset1:8
	ds_read2_b32 v[110:111], v67 offset0:33 offset1:41
	ds_read2_b32 v[112:113], v67 offset0:66 offset1:74
	ds_read2_b32 v[114:115], v67 offset0:99 offset1:107
	ds_read2_b32 v[116:117], v67 offset0:132 offset1:140
	s_waitcnt lgkmcnt(4)
	v_bfe_u32 v2, v108, 16, 1
	v_add3_u32 v2, v108, v2, s33
	s_waitcnt lgkmcnt(3)
	v_bfe_u32 v32, v110, 16, 1
	v_lshrrev_b32_e32 v2, 16, v2
	v_add3_u32 v32, v110, v32, s33
	ds_read2_b32 v[118:119], v67 offset0:165 offset1:173
	v_and_or_b32 v32, v32, s86, v2
	s_waitcnt lgkmcnt(3)
	v_bfe_u32 v2, v112, 16, 1
	v_add3_u32 v2, v112, v2, s33
	s_waitcnt lgkmcnt(2)
	v_bfe_u32 v33, v114, 16, 1
	ds_read2_b32 v[120:121], v67 offset0:198 offset1:206
	v_lshrrev_b32_e32 v2, 16, v2
	v_add3_u32 v33, v114, v33, s33
	ds_read2_b32 v[122:123], v67 offset0:231 offset1:239
	v_and_or_b32 v33, v33, s86, v2
	s_waitcnt lgkmcnt(3)
	v_bfe_u32 v2, v116, 16, 1
	v_add3_u32 v2, v116, v2, s33
	s_waitcnt lgkmcnt(2)
	v_bfe_u32 v34, v118, 16, 1
	v_lshrrev_b32_e32 v2, 16, v2
	v_add3_u32 v34, v118, v34, s33
	v_and_or_b32 v34, v34, s86, v2
	s_waitcnt lgkmcnt(1)
	v_bfe_u32 v2, v120, 16, 1
	v_add3_u32 v2, v120, v2, s33
	s_waitcnt lgkmcnt(0)
	v_bfe_u32 v35, v122, 16, 1
	v_lshrrev_b32_e32 v2, 16, v2
	v_add3_u32 v35, v122, v35, s33
	v_and_or_b32 v35, v35, s86, v2
	v_or_b32_e32 v2, s3, v100
	s_bfe_u32 s3, s10, 0x30007
	s_mul_i32 s3, s3, 44
	s_add_i32 s3, s3, s2
	v_lshrrev_b32_e32 v2, 3, v2
	s_lshl_b32 s2, s3, 14
	v_readlane_b32 s3, v254, 1
	v_or_b32_e32 v2, v2, v64
	s_add_u32 s2, s3, s2
	v_readlane_b32 s3, v254, 3
	v_lshlrev_b32_e32 v2, 10, v2
	s_addc_u32 s3, s3, 0
	v_or_b32_e32 v124, v2, v68
	v_bfe_u32 v108, v123, 16, 1
	v_add3_u32 v110, v123, v108, s33
	global_store_dwordx4 v124, v[32:35], s[2:3]
	v_or_b32_e32 v2, v2, v69
	ds_read2_b32 v[122:123], v67 offset0:247 offset1:255
	v_bfe_u32 v32, v109, 16, 1
	v_add3_u32 v32, v109, v32, s33
	v_bfe_u32 v33, v111, 16, 1
	v_lshrrev_b32_e32 v32, 16, v32
	v_add3_u32 v33, v111, v33, s33
	v_and_or_b32 v32, v33, s86, v32
	v_bfe_u32 v33, v113, 16, 1
	v_add3_u32 v33, v113, v33, s33
	v_bfe_u32 v34, v115, 16, 1
	v_lshrrev_b32_e32 v33, 16, v33
	v_add3_u32 v34, v115, v34, s33
	v_and_or_b32 v33, v34, s86, v33
	v_bfe_u32 v34, v117, 16, 1
	v_add3_u32 v34, v117, v34, s33
	v_bfe_u32 v35, v119, 16, 1
	v_lshrrev_b32_e32 v34, 16, v34
	v_add3_u32 v35, v119, v35, s33
	v_and_or_b32 v34, v35, s86, v34
	v_bfe_u32 v35, v121, 16, 1
	v_add3_u32 v35, v121, v35, s33
	v_lshrrev_b32_e32 v35, 16, v35
	ds_read2_b32 v[108:109], v67 offset0:16 offset1:24
	v_and_or_b32 v35, v110, s86, v35
	ds_read2_b32 v[110:111], v67 offset0:49 offset1:57
	ds_read2_b32 v[112:113], v67 offset0:82 offset1:90
	ds_read2_b32 v[114:115], v67 offset0:115 offset1:123
	global_store_dwordx4 v2, v[32:35], s[2:3]
	s_waitcnt lgkmcnt(3)
	v_bfe_u32 v2, v108, 16, 1
	v_add3_u32 v2, v108, v2, s33
	s_waitcnt lgkmcnt(2)
	v_bfe_u32 v32, v110, 16, 1
	ds_read2_b32 v[116:117], v67 offset0:148 offset1:156
	v_lshrrev_b32_e32 v2, 16, v2
	v_add3_u32 v32, v110, v32, s33
	ds_read2_b32 v[118:119], v67 offset0:181 offset1:189
	v_and_or_b32 v32, v32, s86, v2
	s_waitcnt lgkmcnt(3)
	v_bfe_u32 v2, v112, 16, 1
	v_add3_u32 v2, v112, v2, s33
	s_waitcnt lgkmcnt(2)
	v_bfe_u32 v33, v114, 16, 1
	ds_read2_b32 v[120:121], v67 offset0:214 offset1:222
	v_lshrrev_b32_e32 v2, 16, v2
	v_add3_u32 v33, v114, v33, s33
	v_and_or_b32 v33, v33, s86, v2
	s_waitcnt lgkmcnt(2)
	v_bfe_u32 v2, v116, 16, 1
	v_add3_u32 v2, v116, v2, s33
	s_waitcnt lgkmcnt(1)
	v_bfe_u32 v34, v118, 16, 1
	v_lshrrev_b32_e32 v2, 16, v2
	v_add3_u32 v34, v118, v34, s33
	v_and_or_b32 v34, v34, s86, v2
	s_waitcnt lgkmcnt(0)
	v_bfe_u32 v2, v120, 16, 1
	v_add3_u32 v2, v120, v2, s33
	v_bfe_u32 v35, v122, 16, 1
	v_lshrrev_b32_e32 v2, 16, v2
	v_add3_u32 v35, v122, v35, s33
	v_and_or_b32 v35, v35, s86, v2
	v_xor_b32_e32 v2, 32, v124
	v_lshl_add_u64 v[124:125], s[2:3], 0, v[2:3]
	global_store_dwordx4 v[124:125], v[32:35], off offset:512
	v_bfe_u32 v2, v111, 16, 1
	v_add3_u32 v2, v111, v2, s33
	v_bfe_u32 v32, v109, 16, 1
	v_add3_u32 v32, v109, v32, s33
	v_lshrrev_b32_e32 v32, 16, v32
	v_bfe_u32 v33, v113, 16, 1
	v_and_or_b32 v32, v2, s86, v32
	v_bfe_u32 v2, v115, 16, 1
	v_add3_u32 v33, v113, v33, s33
	v_add3_u32 v2, v115, v2, s33
	v_lshrrev_b32_e32 v33, 16, v33
	v_bfe_u32 v34, v117, 16, 1
	v_and_or_b32 v33, v2, s86, v33
	v_bfe_u32 v2, v119, 16, 1
	v_add3_u32 v34, v117, v34, s33
	v_add3_u32 v2, v119, v2, s33
	v_lshrrev_b32_e32 v34, 16, v34
	v_bfe_u32 v35, v121, 16, 1
	v_and_or_b32 v34, v2, s86, v34
	v_bfe_u32 v2, v123, 16, 1
	v_add3_u32 v35, v121, v35, s33
	v_add3_u32 v2, v123, v2, s33
	v_lshrrev_b32_e32 v35, 16, v35
	v_and_or_b32 v35, v2, s86, v35
	global_store_dwordx4 v[124:125], v[32:35], off offset:768
	s_waitcnt lgkmcnt(0)

; #define LAS __attribute__((address_space(3)))
; #define LDS_WAIT() asm volatile("s_waitcnt lgkmcnt(0)" ::: "memory")
; #define TR(cnt, W, K_, N_, DST, MODE, GAIN) if (r < (cnt)) { transpose_item((W), (K_), (N_), (bf16*)(ws + (DST)), (MODE), (GAIN), scr, r, lane); continue; } r -= (cnt);
; __device__ __forceinline__ void transpose_item(const float* W, int K, int N, bf16* WT, int mode, const float* gain, LAS float* scr, int item, int lane) {
;     const int nblk = N / 32, kb = item / nblk, nb = item % nblk, k0 = 64 * kb, n0 = 32 * nb;
; #pragma unroll
;     for (int i = 0; i < 32; ++i) { const int kk = 2 * i + (lane >> 5); float w = W[(size_t)(k0 + kk) * N + n0 + (lane & 31)]; if (gain) w *= gain[k0 + kk]; scr[kk * 33 + (lane & 31)] = w; }
;     LDS_WAIT(); asm volatile("" ::: "memory");
; __device__ __forceinline__ void p0_prologue(const Args& a, LAS unsigned char* lds, int vcu, int G, int wave, int lane) {
;     ...
;         TR(T_GU, a.in[I_FWU] + (size_t)D * DFF, D, DFF, WS_WGU1, 2, a.in[I_FNG] + D)
.LBB0_117:
	s_andn2_b64 vcc, exec, s[2:3]
	s_cbranch_vccnz .LBB0_119
	s_add_i32 s3, s88, 0xe180
	s_and_b32 s2, s3, 0xffff
	s_mul_i32 s2, s2, 0xba2f
	s_lshr_b32 s18, s2, 16
	s_lshr_b32 s2, s2, 22
	s_mul_i32 s19, s2, 0x58
	s_sub_i32 s3, s3, s19
	s_and_b32 s3, s3, 0xffff
	s_and_b32 s19, s18, 0xffc0
	s_lshl_b32 s56, s3, 7
	v_lshl_add_u64 v[32:33], v[20:21], 0, s[56:57]
	v_or_b32_e32 v2, s19, v0
	v_mad_u64_u32 v[34:35], s[22:23], v2, s87, v[32:33]
	v_lshlrev_b32_e32 v2, 2, v2
	global_load_dword v34, v[34:35], off
	v_or_b32_e32 v109, s19, v38
	global_load_dword v2, v2, s[16:17]
	v_add_u32_e32 v108, v36, v37
	s_lshl_b32 s18, s3, 5
	s_lshl_b32 s3, s3, 3
	s_and_b32 s18, s18, 0x60
	s_and_b32 s3, s3, 0x3e0
	s_add_i32 s2, s2, s3
	s_lshl_b32 s2, s2, 14
	s_add_i32 s2, s2, 0x40000
	v_readlane_b32 s3, v254, 4
	s_add_u32 s2, s3, s2
	v_readlane_b32 s3, v254, 6
	s_addc_u32 s3, s3, 0
	s_waitcnt vmcnt(0)
	v_mul_f32_e32 v2, v34, v2
	v_mad_u64_u32 v[34:35], s[22:23], v109, s87, v[32:33]
	global_load_dword v34, v[34:35], off
	v_lshlrev_b32_e32 v35, 2, v109
	global_load_dword v35, v35, s[16:17]
	v_or_b32_e32 v109, s19, v71
	s_waitcnt vmcnt(0)
	v_mul_f32_e32 v34, v34, v35
	ds_write2_b32 v108, v2, v34 offset1:66
	v_or_b32_e32 v2, s19, v70
	v_mad_u64_u32 v[34:35], s[22:23], v2, s87, v[32:33]
	v_lshlrev_b32_e32 v2, 2, v2
	global_load_dword v34, v[34:35], off
	s_nop 0
	global_load_dword v2, v2, s[16:17]
	s_waitcnt vmcnt(0)
	v_mul_f32_e32 v2, v34, v2
	v_mad_u64_u32 v[34:35], s[22:23], v109, s87, v[32:33]
	global_load_dword v34, v[34:35], off
	v_lshlrev_b32_e32 v35, 2, v109
	global_load_dword v35, v35, s[16:17]
	v_or_b32_e32 v109, s19, v73
	s_waitcnt vmcnt(0)
	v_mul_f32_e32 v34, v34, v35
	ds_write2_b32 v108, v2, v34 offset0:132 offset1:198
	v_or_b32_e32 v2, s19, v72
	v_mad_u64_u32 v[34:35], s[22:23], v2, s87, v[32:33]
	v_lshlrev_b32_e32 v2, 2, v2
	global_load_dword v34, v[34:35], off
	s_nop 0
	global_load_dword v2, v2, s[16:17]
	s_waitcnt vmcnt(0)
	v_mul_f32_e32 v2, v34, v2
	v_mad_u64_u32 v[34:35], s[22:23], v109, s87, v[32:33]
	global_load_dword v34, v[34:35], off
	v_lshlrev_b32_e32 v35, 2, v109
	global_load_dword v35, v35, s[16:17]
	v_or_b32_e32 v109, s19, v75
	s_waitcnt vmcnt(0)
	v_mul_f32_e32 v34, v34, v35
	v_add_u32_e32 v35, 0x400, v108
	ds_write2_b32 v35, v2, v34 offset0:8 offset1:74
	v_or_b32_e32 v2, s19, v74
	v_mad_u64_u32 v[34:35], s[22:23], v2, s87, v[32:33]
	v_lshlrev_b32_e32 v2, 2, v2
	global_load_dword v34, v[34:35], off
	v_add_u32_e32 v108, v36, v44
	global_load_dword v2, v2, s[16:17]
	s_waitcnt vmcnt(0)
	v_mul_f32_e32 v2, v34, v2
	v_mad_u64_u32 v[34:35], s[22:23], v109, s87, v[32:33]
	global_load_dword v34, v[34:35], off
	v_lshlrev_b32_e32 v35, 2, v109
	global_load_dword v35, v35, s[16:17]
	v_or_b32_e32 v109, s19, v77
	s_waitcnt vmcnt(0)
	v_mul_f32_e32 v34, v34, v35
	ds_write2_b32 v108, v2, v34 offset1:66
	v_or_b32_e32 v2, s19, v76
	v_mad_u64_u32 v[34:35], s[22:23], v2, s87, v[32:33]
	v_lshlrev_b32_e32 v2, 2, v2
	global_load_dword v34, v[34:35], off
	s_nop 0
	global_load_dword v2, v2, s[16:17]
	s_waitcnt vmcnt(0)
	v_mul_f32_e32 v2, v34, v2
	v_mad_u64_u32 v[34:35], s[22:23], v109, s87, v[32:33]
	global_load_dword v34, v[34:35], off
	v_lshlrev_b32_e32 v35, 2, v109
	global_load_dword v35, v35, s[16:17]
	v_or_b32_e32 v109, s19, v79
	s_waitcnt vmcnt(0)
	v_mul_f32_e32 v34, v34, v35
	ds_write2_b32 v108, v2, v34 offset0:132 offset1:198
	v_or_b32_e32 v2, s19, v78
	v_mad_u64_u32 v[34:35], s[22:23], v2, s87, v[32:33]
	v_lshlrev_b32_e32 v2, 2, v2
	global_load_dword v34, v[34:35], off
	s_nop 0
	global_load_dword v2, v2, s[16:17]
	s_waitcnt vmcnt(0)
	v_mul_f32_e32 v2, v34, v2
	v_mad_u64_u32 v[34:35], s[22:23], v109, s87, v[32:33]
	global_load_dword v34, v[34:35], off
	v_lshlrev_b32_e32 v35, 2, v109
	global_load_dword v35, v35, s[16:17]
	v_or_b32_e32 v109, s19, v81
	s_waitcnt vmcnt(0)
	v_mul_f32_e32 v34, v34, v35
	v_add_u32_e32 v35, 0x400, v108
	ds_write2_b32 v35, v2, v34 offset0:8 offset1:74
	v_or_b32_e32 v2, s19, v80
	v_mad_u64_u32 v[34:35], s[22:23], v2, s87, v[32:33]
	v_lshlrev_b32_e32 v2, 2, v2
	global_load_dword v34, v[34:35], off
	v_add_u32_e32 v108, v36, v50
	global_load_dword v2, v2, s[16:17]
	s_waitcnt vmcnt(0)
	v_mul_f32_e32 v2, v34, v2
	v_mad_u64_u32 v[34:35], s[22:23], v109, s87, v[32:33]
	global_load_dword v34, v[34:35], off
	v_lshlrev_b32_e32 v35, 2, v109
	global_load_dword v35, v35, s[16:17]
	v_or_b32_e32 v109, s19, v83
	s_waitcnt vmcnt(0)
	v_mul_f32_e32 v34, v34, v35
	ds_write2_b32 v108, v2, v34 offset1:66
	v_or_b32_e32 v2, s19, v82
	v_mad_u64_u32 v[34:35], s[22:23], v2, s87, v[32:33]
	v_lshlrev_b32_e32 v2, 2, v2
	global_load_dword v34, v[34:35], off
	s_nop 0
	global_load_dword v2, v2, s[16:17]
	s_waitcnt vmcnt(0)
	v_mul_f32_e32 v2, v34, v2
	v_mad_u64_u32 v[34:35], s[22:23], v109, s87, v[32:33]
	global_load_dword v34, v[34:35], off
	v_lshlrev_b32_e32 v35, 2, v109
	global_load_dword v35, v35, s[16:17]
	v_or_b32_e32 v109, s19, v85
	s_waitcnt vmcnt(0)
	v_mul_f32_e32 v34, v34, v35
	ds_write2_b32 v108, v2, v34 offset0:132 offset1:198
	v_or_b32_e32 v2, s19, v84
	v_mad_u64_u32 v[34:35], s[22:23], v2, s87, v[32:33]
	v_lshlrev_b32_e32 v2, 2, v2
	global_load_dword v34, v[34:35], off
	s_nop 0
	global_load_dword v2, v2, s[16:17]
	s_waitcnt vmcnt(0)
	v_mul_f32_e32 v2, v34, v2
	v_mad_u64_u32 v[34:35], s[22:23], v109, s87, v[32:33]
	global_load_dword v34, v[34:35], off
	v_lshlrev_b32_e32 v35, 2, v109
	global_load_dword v35, v35, s[16:17]
	v_or_b32_e32 v109, s19, v87
	s_waitcnt vmcnt(0)
	v_mul_f32_e32 v34, v34, v35
	v_add_u32_e32 v35, 0x400, v108
	ds_write2_b32 v35, v2, v34 offset0:8 offset1:74
	v_or_b32_e32 v2, s19, v86
	v_mad_u64_u32 v[34:35], s[22:23], v2, s87, v[32:33]
	v_lshlrev_b32_e32 v2, 2, v2
	global_load_dword v34, v[34:35], off
	v_add_u32_e32 v108, v36, v56
	global_load_dword v2, v2, s[16:17]
	s_waitcnt vmcnt(0)
; #define LAS __attribute__((address_space(3)))
; #define LDS_WAIT() asm volatile("s_waitcnt lgkmcnt(0)" ::: "memory")
; __device__ __forceinline__ void transpose_item(const float* W, int K, int N, bf16* WT, int mode, const float* gain, LAS float* scr, int item, int lane) {
;     ...
;     for (int i = 0; i < 32; ++i) { const int kk = 2 * i + (lane >> 5); float w = W[(size_t)(k0 + kk) * N + n0 + (lane & 31)]; if (gain) w *= gain[k0 + kk]; scr[kk * 33 + (lane & 31)] = w; }
;     LDS_WAIT(); asm volatile("" ::: "memory");
;     const int c = lane & 7;
; #pragma unroll
;     for (int j = 0; j < 4; ++j) { const int n = (lane >> 3) + 8 * j; const LAS float* s = scr + (8 * c) * 33 + n;
	v_mul_f32_e32 v2, v34, v2
	v_mad_u64_u32 v[34:35], s[22:23], v109, s87, v[32:33]
	global_load_dword v34, v[34:35], off
	v_lshlrev_b32_e32 v35, 2, v109
	global_load_dword v35, v35, s[16:17]
	v_or_b32_e32 v109, s19, v89
	s_waitcnt vmcnt(0)
	v_mul_f32_e32 v34, v34, v35
	ds_write2_b32 v108, v2, v34 offset1:66
	v_or_b32_e32 v2, s19, v88
	v_mad_u64_u32 v[34:35], s[22:23], v2, s87, v[32:33]
	v_lshlrev_b32_e32 v2, 2, v2
	global_load_dword v34, v[34:35], off
	s_nop 0
	global_load_dword v2, v2, s[16:17]
	s_waitcnt vmcnt(0)
	v_mul_f32_e32 v2, v34, v2
	v_mad_u64_u32 v[34:35], s[22:23], v109, s87, v[32:33]
	global_load_dword v34, v[34:35], off
	v_lshlrev_b32_e32 v35, 2, v109
	global_load_dword v35, v35, s[16:17]
	v_or_b32_e32 v109, s19, v91
	s_waitcnt vmcnt(0)
	v_mul_f32_e32 v34, v34, v35
	ds_write2_b32 v108, v2, v34 offset0:132 offset1:198
	v_or_b32_e32 v2, s19, v90
	v_mad_u64_u32 v[34:35], s[22:23], v2, s87, v[32:33]
	v_lshlrev_b32_e32 v2, 2, v2
	global_load_dword v34, v[34:35], off
	s_nop 0
	global_load_dword v2, v2, s[16:17]
	s_waitcnt vmcnt(0)
	v_mul_f32_e32 v2, v34, v2
	v_mad_u64_u32 v[34:35], s[22:23], v109, s87, v[32:33]
	global_load_dword v34, v[34:35], off
	v_lshlrev_b32_e32 v35, 2, v109
	global_load_dword v35, v35, s[16:17]
	v_or_b32_e32 v109, s19, v93
	s_waitcnt vmcnt(0)
	v_mul_f32_e32 v34, v34, v35
	v_add_u32_e32 v35, 0x400, v108
	ds_write2_b32 v35, v2, v34 offset0:8 offset1:74
	v_or_b32_e32 v2, s19, v92
	v_mad_u64_u32 v[34:35], s[22:23], v2, s87, v[32:33]
	v_lshlrev_b32_e32 v2, 2, v2
	global_load_dword v34, v[34:35], off
	v_add_u32_e32 v108, v36, v62
	global_load_dword v2, v2, s[16:17]
	s_waitcnt vmcnt(0)
	v_mul_f32_e32 v2, v34, v2
	v_mad_u64_u32 v[34:35], s[22:23], v109, s87, v[32:33]
	global_load_dword v34, v[34:35], off
	v_lshlrev_b32_e32 v35, 2, v109
	global_load_dword v35, v35, s[16:17]
	v_or_b32_e32 v109, s19, v95
	s_waitcnt vmcnt(0)
	v_mul_f32_e32 v34, v34, v35
	ds_write2_b32 v108, v2, v34 offset1:66
	v_or_b32_e32 v2, s19, v94
	v_mad_u64_u32 v[34:35], s[22:23], v2, s87, v[32:33]
	v_lshlrev_b32_e32 v2, 2, v2
	global_load_dword v34, v[34:35], off
	s_nop 0
	global_load_dword v2, v2, s[16:17]
	s_waitcnt vmcnt(0)
	v_mul_f32_e32 v2, v34, v2
	v_mad_u64_u32 v[34:35], s[22:23], v109, s87, v[32:33]
	global_load_dword v34, v[34:35], off
	v_lshlrev_b32_e32 v35, 2, v109
	global_load_dword v35, v35, s[16:17]
	v_or_b32_e32 v109, s19, v97
	s_waitcnt vmcnt(0)
	v_mul_f32_e32 v34, v34, v35
	ds_write2_b32 v108, v2, v34 offset0:132 offset1:198
	v_or_b32_e32 v2, s19, v96
	v_mad_u64_u32 v[34:35], s[22:23], v2, s87, v[32:33]
	v_lshlrev_b32_e32 v2, 2, v2
	global_load_dword v34, v[34:35], off
	v_add_u32_e32 v108, 0x400, v108
	global_load_dword v2, v2, s[16:17]
	s_waitcnt vmcnt(0)
	v_mul_f32_e32 v2, v34, v2
	v_mad_u64_u32 v[34:35], s[22:23], v109, s87, v[32:33]
	global_load_dword v34, v[34:35], off
	v_lshlrev_b32_e32 v35, 2, v109
	global_load_dword v35, v35, s[16:17]
	s_waitcnt vmcnt(0)
	v_mul_f32_e32 v34, v34, v35
	ds_write2_b32 v108, v2, v34 offset0:8 offset1:74
	v_or_b32_e32 v2, s19, v98
	v_mad_u64_u32 v[34:35], s[22:23], v2, s87, v[32:33]
	v_lshlrev_b32_e32 v2, 2, v2
	global_load_dword v34, v[34:35], off
	s_nop 0
	global_load_dword v2, v2, s[16:17]
	s_waitcnt vmcnt(0)
	v_mul_f32_e32 v2, v34, v2
	v_or_b32_e32 v34, s19, v99
	v_mad_u64_u32 v[32:33], s[22:23], v34, s87, v[32:33]
	global_load_dword v32, v[32:33], off
	v_lshlrev_b32_e32 v33, 2, v34
	global_load_dword v33, v33, s[16:17]
	s_waitcnt vmcnt(0)
	v_mul_f32_e32 v32, v32, v33
	ds_write2_b32 v108, v2, v32 offset0:140 offset1:206
	s_waitcnt lgkmcnt(0)
	ds_read2_b32 v[108:109], v67 offset0:33 offset1:41
	ds_read2_b32 v[110:111], v67 offset1:8
	ds_read2_b32 v[112:113], v67 offset0:66 offset1:74
	ds_read2_b32 v[114:115], v67 offset0:99 offset1:107
	ds_read2_b32 v[116:117], v67 offset0:132 offset1:140
	ds_read2_b32 v[118:119], v67 offset0:165 offset1:173
	ds_read2_b32 v[120:121], v67 offset0:198 offset1:206
	ds_read2_b32 v[122:123], v67 offset0:231 offset1:239
	s_waitcnt lgkmcnt(7)
	v_bfe_u32 v32, v108, 16, 1
	s_waitcnt lgkmcnt(6)
; #define GAS __attribute__((address_space(1)))
; #define LAS __attribute__((address_space(3)))
; __device__ __forceinline__ unsigned pk2(float lo, float hi) { return f2bf(lo) | (f2bf(hi) << 16); }
; __device__ __forceinline__ void transpose_item(const float* W, int K, int N, bf16* WT, int mode, const float* gain, LAS float* scr, int item, int lane) {
;     ...
;     for (int j = 0; j < 4; ++j) { const int n = (lane >> 3) + 8 * j; const LAS float* s = scr + (8 * c) * 33 + n;
;         v4u o; o.x = pk2(s[0 * 33], s[1 * 33]); o.y = pk2(s[2 * 33], s[3 * 33]); o.z = pk2(s[4 * 33], s[5 * 33]); o.w = pk2(s[6 * 33], s[7 * 33]);
;         const int p_ = dst_row(mode, n0 + n), pl_ = p_ & 127, x_ = pl_ & 31, R_ = (pl_ & ~31) + 16 * ((x_ >> 2) & 1) + 4 * (x_ >> 3) + (x_ & 3);
;         *(GAS v4u*)((GAS unsigned char*)WT + ((size_t)(p_ >> 7) * (K / 64) + (k0 >> 6)) * 16384 + pg8::lds_byte(R_, 8 * c)) = o; }
	v_bfe_u32 v2, v110, 16, 1
	v_add3_u32 v2, v110, v2, s33
	v_lshrrev_b32_e32 v2, 16, v2
	v_add3_u32 v32, v108, v32, s33
	v_and_or_b32 v32, v32, s86, v2
	s_waitcnt lgkmcnt(5)
	v_bfe_u32 v2, v112, 16, 1
	v_add3_u32 v2, v112, v2, s33
	s_waitcnt lgkmcnt(4)
	v_bfe_u32 v33, v114, 16, 1
	v_lshrrev_b32_e32 v2, 16, v2
	v_add3_u32 v33, v114, v33, s33
	v_and_or_b32 v33, v33, s86, v2
	s_waitcnt lgkmcnt(3)
	v_bfe_u32 v2, v116, 16, 1
	v_add3_u32 v2, v116, v2, s33
	s_waitcnt lgkmcnt(2)
	v_bfe_u32 v34, v118, 16, 1
	v_lshrrev_b32_e32 v2, 16, v2
	v_add3_u32 v34, v118, v34, s33
	v_and_or_b32 v34, v34, s86, v2
	s_waitcnt lgkmcnt(1)
	v_bfe_u32 v2, v120, 16, 1
	v_add3_u32 v2, v120, v2, s33
	s_waitcnt lgkmcnt(0)
	v_bfe_u32 v35, v122, 16, 1
	v_lshrrev_b32_e32 v2, 16, v2
	v_add3_u32 v35, v122, v35, s33
	v_and_or_b32 v35, v35, s86, v2
	v_or_b32_e32 v2, s18, v100
	v_lshrrev_b32_e32 v2, 3, v2
	v_or_b32_e32 v2, v2, v64
	v_lshlrev_b32_e32 v2, 10, v2
	v_or_b32_e32 v124, v2, v68
	global_store_dwordx4 v124, v[32:35], s[2:3]
	v_bfe_u32 v108, v123, 16, 1
	v_add3_u32 v108, v123, v108, s33
	v_bfe_u32 v32, v111, 16, 1
	v_add3_u32 v32, v111, v32, s33
	v_bfe_u32 v33, v109, 16, 1
	v_lshrrev_b32_e32 v32, 16, v32
	v_add3_u32 v33, v109, v33, s33
	v_and_or_b32 v32, v33, s86, v32
	v_bfe_u32 v33, v113, 16, 1
	v_add3_u32 v33, v113, v33, s33
	v_bfe_u32 v34, v115, 16, 1
	v_lshrrev_b32_e32 v33, 16, v33
	v_add3_u32 v34, v115, v34, s33
	v_and_or_b32 v33, v34, s86, v33
	v_bfe_u32 v34, v117, 16, 1
	v_add3_u32 v34, v117, v34, s33
	v_bfe_u32 v35, v119, 16, 1
	v_lshrrev_b32_e32 v34, 16, v34
	v_add3_u32 v35, v119, v35, s33
	v_and_or_b32 v34, v35, s86, v34
	v_bfe_u32 v35, v121, 16, 1
	v_add3_u32 v35, v121, v35, s33
	v_lshrrev_b32_e32 v35, 16, v35
	v_and_or_b32 v35, v108, s86, v35
	v_or_b32_e32 v2, v2, v69
	global_store_dwordx4 v2, v[32:35], s[2:3]
	ds_read2_b32 v[108:109], v67 offset0:16 offset1:24
	ds_read2_b32 v[110:111], v67 offset0:49 offset1:57
	ds_read2_b32 v[112:113], v67 offset0:82 offset1:90
	ds_read2_b32 v[114:115], v67 offset0:115 offset1:123
	ds_read2_b32 v[116:117], v67 offset0:148 offset1:156
	ds_read2_b32 v[118:119], v67 offset0:181 offset1:189
	ds_read2_b32 v[120:121], v67 offset0:214 offset1:222
	ds_read2_b32 v[122:123], v67 offset0:247 offset1:255
	s_waitcnt lgkmcnt(7)
	v_bfe_u32 v2, v108, 16, 1
	v_add3_u32 v2, v108, v2, s33
	s_waitcnt lgkmcnt(6)
	v_bfe_u32 v32, v110, 16, 1
	v_lshrrev_b32_e32 v2, 16, v2
	v_add3_u32 v32, v110, v32, s33
	v_and_or_b32 v32, v32, s86, v2
	s_waitcnt lgkmcnt(5)
	v_bfe_u32 v2, v112, 16, 1
	v_add3_u32 v2, v112, v2, s33
	s_waitcnt lgkmcnt(4)
	v_bfe_u32 v33, v114, 16, 1
	v_lshrrev_b32_e32 v2, 16, v2
	v_add3_u32 v33, v114, v33, s33
	v_and_or_b32 v33, v33, s86, v2
	s_waitcnt lgkmcnt(3)
	v_bfe_u32 v2, v116, 16, 1
	v_add3_u32 v2, v116, v2, s33
	s_waitcnt lgkmcnt(2)
	v_bfe_u32 v34, v118, 16, 1
	v_lshrrev_b32_e32 v2, 16, v2
	v_add3_u32 v34, v118, v34, s33
	v_and_or_b32 v34, v34, s86, v2
	s_waitcnt lgkmcnt(1)
	v_bfe_u32 v2, v120, 16, 1
	v_add3_u32 v2, v120, v2, s33
	s_waitcnt lgkmcnt(0)
	v_bfe_u32 v35, v122, 16, 1
	v_lshrrev_b32_e32 v2, 16, v2
	v_add3_u32 v35, v122, v35, s33
	v_and_or_b32 v35, v35, s86, v2
	v_xor_b32_e32 v2, 32, v124
	v_lshl_add_u64 v[124:125], s[2:3], 0, v[2:3]
	global_store_dwordx4 v[124:125], v[32:35], off offset:512
	v_bfe_u32 v2, v111, 16, 1
	v_add3_u32 v2, v111, v2, s33
	v_bfe_u32 v32, v109, 16, 1
	v_add3_u32 v32, v109, v32, s33
	v_lshrrev_b32_e32 v32, 16, v32
	v_bfe_u32 v33, v113, 16, 1
	v_and_or_b32 v32, v2, s86, v32
	v_bfe_u32 v2, v115, 16, 1
	v_add3_u32 v33, v113, v33, s33
	v_add3_u32 v2, v115, v2, s33
	v_lshrrev_b32_e32 v33, 16, v33
	v_bfe_u32 v34, v117, 16, 1
	v_and_or_b32 v33, v2, s86, v33
	v_bfe_u32 v2, v119, 16, 1
	v_add3_u32 v34, v117, v34, s33
	v_add3_u32 v2, v119, v2, s33
	v_lshrrev_b32_e32 v34, 16, v34
	v_bfe_u32 v35, v121, 16, 1
	v_and_or_b32 v34, v2, s86, v34
	v_bfe_u32 v2, v123, 16, 1
	v_add3_u32 v35, v121, v35, s33
	v_add3_u32 v2, v123, v2, s33
	v_lshrrev_b32_e32 v35, 16, v35
	v_and_or_b32 v35, v2, s86, v35
	global_store_dwordx4 v[124:125], v[32:35], off offset:768
	s_waitcnt lgkmcnt(0)

; #define LAS __attribute__((address_space(3)))
; #define LDS_WAIT() asm volatile("s_waitcnt lgkmcnt(0)" ::: "memory")
; #define TR(cnt, W, K_, N_, DST, MODE, GAIN) if (r < (cnt)) { transpose_item((W), (K_), (N_), (bf16*)(ws + (DST)), (MODE), (GAIN), scr, r, lane); continue; } r -= (cnt);
; __device__ __forceinline__ void transpose_item(const float* W, int K, int N, bf16* WT, int mode, const float* gain, LAS float* scr, int item, int lane) {
;     const int nblk = N / 32, kb = item / nblk, nb = item % nblk, k0 = 64 * kb, n0 = 32 * nb;
; #pragma unroll
;     for (int i = 0; i < 32; ++i) { const int kk = 2 * i + (lane >> 5); float w = W[(size_t)(k0 + kk) * N + n0 + (lane & 31)]; if (gain) w *= gain[k0 + kk]; scr[kk * 33 + (lane & 31)] = w; }
;     LDS_WAIT(); asm volatile("" ::: "memory");
; __device__ __forceinline__ void p0_prologue(const Args& a, LAS unsigned char* lds, int vcu, int G, int wave, int lane) {
;     ...
;         TR(T_GU, a.in[I_FWG] + (size_t)D * DFF, D, DFF, WS_WGU1, 1, a.in[I_FNG] + D)
.LBB0_120:
	s_andn2_b64 vcc, exec, s[2:3]
	s_cbranch_vccnz .LBB0_122
	s_add_i32 s3, s88, 0xe700
	s_and_b32 s2, s3, 0xffff
	s_mul_i32 s2, s2, 0xba2f
	s_lshr_b32 s19, s2, 16
	s_lshr_b32 s2, s2, 22
	s_mul_i32 s18, s2, 0x58
	s_sub_i32 s3, s3, s18
	s_and_b32 s18, s3, 0xffff
	s_and_b32 s19, s19, 0xffc0
	s_lshl_b32 s56, s18, 7
	v_lshl_add_u64 v[32:33], v[22:23], 0, s[56:57]
	v_or_b32_e32 v2, s19, v0
	v_mad_u64_u32 v[34:35], s[22:23], v2, s87, v[32:33]
	v_lshlrev_b32_e32 v2, 2, v2
	global_load_dword v34, v[34:35], off
	v_or_b32_e32 v109, s19, v38
	global_load_dword v2, v2, s[16:17]
	v_add_u32_e32 v108, v36, v37
	s_lshl_b32 s3, s18, 5
	s_lshl_b32 s18, s18, 3
	s_and_b32 s3, s3, 0x60
	s_and_b32 s18, s18, 0x3e0
	s_add_i32 s18, s18, s2
	s_lshl_b32 s2, s18, 14
	s_waitcnt vmcnt(0)
	v_mul_f32_e32 v2, v34, v2
	v_mad_u64_u32 v[34:35], s[22:23], v109, s87, v[32:33]
	global_load_dword v34, v[34:35], off
	v_lshlrev_b32_e32 v35, 2, v109
	global_load_dword v35, v35, s[16:17]
	v_or_b32_e32 v109, s19, v71
	s_waitcnt vmcnt(0)
	v_mul_f32_e32 v34, v34, v35
	ds_write2_b32 v108, v2, v34 offset1:66
	v_or_b32_e32 v2, s19, v70
	v_mad_u64_u32 v[34:35], s[22:23], v2, s87, v[32:33]
	v_lshlrev_b32_e32 v2, 2, v2
	global_load_dword v34, v[34:35], off
	s_nop 0
	global_load_dword v2, v2, s[16:17]
	s_waitcnt vmcnt(0)
	v_mul_f32_e32 v2, v34, v2
	v_mad_u64_u32 v[34:35], s[22:23], v109, s87, v[32:33]
	global_load_dword v34, v[34:35], off
	v_lshlrev_b32_e32 v35, 2, v109
	global_load_dword v35, v35, s[16:17]
	v_or_b32_e32 v109, s19, v73
	s_waitcnt vmcnt(0)
	v_mul_f32_e32 v34, v34, v35
	ds_write2_b32 v108, v2, v34 offset0:132 offset1:198
	v_or_b32_e32 v2, s19, v72
	v_mad_u64_u32 v[34:35], s[22:23], v2, s87, v[32:33]
	v_lshlrev_b32_e32 v2, 2, v2
	global_load_dword v34, v[34:35], off
	s_nop 0
	global_load_dword v2, v2, s[16:17]
	s_waitcnt vmcnt(0)
	v_mul_f32_e32 v2, v34, v2
	v_mad_u64_u32 v[34:35], s[22:23], v109, s87, v[32:33]
	global_load_dword v34, v[34:35], off
	v_lshlrev_b32_e32 v35, 2, v109
	global_load_dword v35, v35, s[16:17]
	v_or_b32_e32 v109, s19, v75
	s_waitcnt vmcnt(0)
	v_mul_f32_e32 v34, v34, v35
	v_add_u32_e32 v35, 0x400, v108
	ds_write2_b32 v35, v2, v34 offset0:8 offset1:74
	v_or_b32_e32 v2, s19, v74
	v_mad_u64_u32 v[34:35], s[22:23], v2, s87, v[32:33]
	v_lshlrev_b32_e32 v2, 2, v2
	global_load_dword v34, v[34:35], off
	v_add_u32_e32 v108, v36, v44
	global_load_dword v2, v2, s[16:17]
	s_waitcnt vmcnt(0)
	v_mul_f32_e32 v2, v34, v2
	v_mad_u64_u32 v[34:35], s[22:23], v109, s87, v[32:33]
	global_load_dword v34, v[34:35], off
	v_lshlrev_b32_e32 v35, 2, v109
	global_load_dword v35, v35, s[16:17]
	v_or_b32_e32 v109, s19, v77
	s_waitcnt vmcnt(0)
	v_mul_f32_e32 v34, v34, v35
	ds_write2_b32 v108, v2, v34 offset1:66
	v_or_b32_e32 v2, s19, v76
	v_mad_u64_u32 v[34:35], s[22:23], v2, s87, v[32:33]
	v_lshlrev_b32_e32 v2, 2, v2
	global_load_dword v34, v[34:35], off
	s_nop 0
	global_load_dword v2, v2, s[16:17]
	s_waitcnt vmcnt(0)
	v_mul_f32_e32 v2, v34, v2
	v_mad_u64_u32 v[34:35], s[22:23], v109, s87, v[32:33]
	global_load_dword v34, v[34:35], off
	v_lshlrev_b32_e32 v35, 2, v109
	global_load_dword v35, v35, s[16:17]
	v_or_b32_e32 v109, s19, v79
	s_waitcnt vmcnt(0)
	v_mul_f32_e32 v34, v34, v35
	ds_write2_b32 v108, v2, v34 offset0:132 offset1:198
	v_or_b32_e32 v2, s19, v78
	v_mad_u64_u32 v[34:35], s[22:23], v2, s87, v[32:33]
	v_lshlrev_b32_e32 v2, 2, v2
	global_load_dword v34, v[34:35], off
	s_nop 0
	global_load_dword v2, v2, s[16:17]
	s_waitcnt vmcnt(0)
	v_mul_f32_e32 v2, v34, v2
	v_mad_u64_u32 v[34:35], s[22:23], v109, s87, v[32:33]
	global_load_dword v34, v[34:35], off
	v_lshlrev_b32_e32 v35, 2, v109
	global_load_dword v35, v35, s[16:17]
	v_or_b32_e32 v109, s19, v81
	s_waitcnt vmcnt(0)
	v_mul_f32_e32 v34, v34, v35
	v_add_u32_e32 v35, 0x400, v108
	ds_write2_b32 v35, v2, v34 offset0:8 offset1:74
	v_or_b32_e32 v2, s19, v80
	v_mad_u64_u32 v[34:35], s[22:23], v2, s87, v[32:33]
	v_lshlrev_b32_e32 v2, 2, v2
	global_load_dword v34, v[34:35], off
	v_add_u32_e32 v108, v36, v50
	global_load_dword v2, v2, s[16:17]
	s_waitcnt vmcnt(0)
	v_mul_f32_e32 v2, v34, v2
	v_mad_u64_u32 v[34:35], s[22:23], v109, s87, v[32:33]
	global_load_dword v34, v[34:35], off
	v_lshlrev_b32_e32 v35, 2, v109
	global_load_dword v35, v35, s[16:17]
	v_or_b32_e32 v109, s19, v83
	s_waitcnt vmcnt(0)
	v_mul_f32_e32 v34, v34, v35
	ds_write2_b32 v108, v2, v34 offset1:66
	v_or_b32_e32 v2, s19, v82
	v_mad_u64_u32 v[34:35], s[22:23], v2, s87, v[32:33]
	v_lshlrev_b32_e32 v2, 2, v2
	global_load_dword v34, v[34:35], off
	s_nop 0
	global_load_dword v2, v2, s[16:17]
	s_waitcnt vmcnt(0)
	v_mul_f32_e32 v2, v34, v2
	v_mad_u64_u32 v[34:35], s[22:23], v109, s87, v[32:33]
	global_load_dword v34, v[34:35], off
	v_lshlrev_b32_e32 v35, 2, v109
	global_load_dword v35, v35, s[16:17]
	v_or_b32_e32 v109, s19, v85
	s_waitcnt vmcnt(0)
	v_mul_f32_e32 v34, v34, v35
	ds_write2_b32 v108, v2, v34 offset0:132 offset1:198
	v_or_b32_e32 v2, s19, v84
	v_mad_u64_u32 v[34:35], s[22:23], v2, s87, v[32:33]
	v_lshlrev_b32_e32 v2, 2, v2
	global_load_dword v34, v[34:35], off
	s_nop 0
	global_load_dword v2, v2, s[16:17]
	s_waitcnt vmcnt(0)
	v_mul_f32_e32 v2, v34, v2
	v_mad_u64_u32 v[34:35], s[22:23], v109, s87, v[32:33]
	global_load_dword v34, v[34:35], off
	v_lshlrev_b32_e32 v35, 2, v109
	global_load_dword v35, v35, s[16:17]
	v_or_b32_e32 v109, s19, v87
	s_waitcnt vmcnt(0)
	v_mul_f32_e32 v34, v34, v35
	v_add_u32_e32 v35, 0x400, v108
	ds_write2_b32 v35, v2, v34 offset0:8 offset1:74
	v_or_b32_e32 v2, s19, v86
	v_mad_u64_u32 v[34:35], s[22:23], v2, s87, v[32:33]
	v_lshlrev_b32_e32 v2, 2, v2
	global_load_dword v34, v[34:35], off
	v_add_u32_e32 v108, v36, v56
	global_load_dword v2, v2, s[16:17]
	s_waitcnt vmcnt(0)
; #define LAS __attribute__((address_space(3)))
; #define LDS_WAIT() asm volatile("s_waitcnt lgkmcnt(0)" ::: "memory")
; __device__ __forceinline__ void transpose_item(const float* W, int K, int N, bf16* WT, int mode, const float* gain, LAS float* scr, int item, int lane) {
;     ...
;     for (int i = 0; i < 32; ++i) { const int kk = 2 * i + (lane >> 5); float w = W[(size_t)(k0 + kk) * N + n0 + (lane & 31)]; if (gain) w *= gain[k0 + kk]; scr[kk * 33 + (lane & 31)] = w; }
;     LDS_WAIT(); asm volatile("" ::: "memory");
;     const int c = lane & 7;
; #pragma unroll
;     for (int j = 0; j < 4; ++j) { const int n = (lane >> 3) + 8 * j; const LAS float* s = scr + (8 * c) * 33 + n;
	v_mul_f32_e32 v2, v34, v2
	v_mad_u64_u32 v[34:35], s[22:23], v109, s87, v[32:33]
	global_load_dword v34, v[34:35], off
	v_lshlrev_b32_e32 v35, 2, v109
	global_load_dword v35, v35, s[16:17]
	v_or_b32_e32 v109, s19, v89
	s_waitcnt vmcnt(0)
	v_mul_f32_e32 v34, v34, v35
	ds_write2_b32 v108, v2, v34 offset1:66
	v_or_b32_e32 v2, s19, v88
	v_mad_u64_u32 v[34:35], s[22:23], v2, s87, v[32:33]
	v_lshlrev_b32_e32 v2, 2, v2
	global_load_dword v34, v[34:35], off
	s_nop 0
	global_load_dword v2, v2, s[16:17]
	s_waitcnt vmcnt(0)
	v_mul_f32_e32 v2, v34, v2
	v_mad_u64_u32 v[34:35], s[22:23], v109, s87, v[32:33]
	global_load_dword v34, v[34:35], off
	v_lshlrev_b32_e32 v35, 2, v109
	global_load_dword v35, v35, s[16:17]
	v_or_b32_e32 v109, s19, v91
	s_waitcnt vmcnt(0)
	v_mul_f32_e32 v34, v34, v35
	ds_write2_b32 v108, v2, v34 offset0:132 offset1:198
	v_or_b32_e32 v2, s19, v90
	v_mad_u64_u32 v[34:35], s[22:23], v2, s87, v[32:33]
	v_lshlrev_b32_e32 v2, 2, v2
	global_load_dword v34, v[34:35], off
	s_nop 0
	global_load_dword v2, v2, s[16:17]
	s_waitcnt vmcnt(0)
	v_mul_f32_e32 v2, v34, v2
	v_mad_u64_u32 v[34:35], s[22:23], v109, s87, v[32:33]
	global_load_dword v34, v[34:35], off
	v_lshlrev_b32_e32 v35, 2, v109
	global_load_dword v35, v35, s[16:17]
	v_or_b32_e32 v109, s19, v93
	s_waitcnt vmcnt(0)
	v_mul_f32_e32 v34, v34, v35
	v_add_u32_e32 v35, 0x400, v108
	ds_write2_b32 v35, v2, v34 offset0:8 offset1:74
	v_or_b32_e32 v2, s19, v92
	v_mad_u64_u32 v[34:35], s[22:23], v2, s87, v[32:33]
	v_lshlrev_b32_e32 v2, 2, v2
	global_load_dword v34, v[34:35], off
	v_add_u32_e32 v108, v36, v62
	global_load_dword v2, v2, s[16:17]
	s_waitcnt vmcnt(0)
	v_mul_f32_e32 v2, v34, v2
	v_mad_u64_u32 v[34:35], s[22:23], v109, s87, v[32:33]
	global_load_dword v34, v[34:35], off
	v_lshlrev_b32_e32 v35, 2, v109
	global_load_dword v35, v35, s[16:17]
	v_or_b32_e32 v109, s19, v95
	s_waitcnt vmcnt(0)
	v_mul_f32_e32 v34, v34, v35
	ds_write2_b32 v108, v2, v34 offset1:66
	v_or_b32_e32 v2, s19, v94
	v_mad_u64_u32 v[34:35], s[22:23], v2, s87, v[32:33]
	v_lshlrev_b32_e32 v2, 2, v2
	global_load_dword v34, v[34:35], off
	s_nop 0
	global_load_dword v2, v2, s[16:17]
	s_waitcnt vmcnt(0)
	v_mul_f32_e32 v2, v34, v2
	v_mad_u64_u32 v[34:35], s[22:23], v109, s87, v[32:33]
	global_load_dword v34, v[34:35], off
	v_lshlrev_b32_e32 v35, 2, v109
	global_load_dword v35, v35, s[16:17]
	v_or_b32_e32 v109, s19, v97
	s_waitcnt vmcnt(0)
	v_mul_f32_e32 v34, v34, v35
	ds_write2_b32 v108, v2, v34 offset0:132 offset1:198
	v_or_b32_e32 v2, s19, v96
	v_mad_u64_u32 v[34:35], s[22:23], v2, s87, v[32:33]
	v_lshlrev_b32_e32 v2, 2, v2
	global_load_dword v34, v[34:35], off
	v_add_u32_e32 v108, 0x400, v108
	global_load_dword v2, v2, s[16:17]
	s_waitcnt vmcnt(0)
	v_mul_f32_e32 v2, v34, v2
	v_mad_u64_u32 v[34:35], s[22:23], v109, s87, v[32:33]
	global_load_dword v34, v[34:35], off
	v_lshlrev_b32_e32 v35, 2, v109
	global_load_dword v35, v35, s[16:17]
	s_waitcnt vmcnt(0)
	v_mul_f32_e32 v34, v34, v35
	ds_write2_b32 v108, v2, v34 offset0:8 offset1:74
	v_or_b32_e32 v2, s19, v98
	v_mad_u64_u32 v[34:35], s[22:23], v2, s87, v[32:33]
	v_lshlrev_b32_e32 v2, 2, v2
	global_load_dword v34, v[34:35], off
	s_nop 0
	global_load_dword v2, v2, s[16:17]
	s_waitcnt vmcnt(0)
	v_mul_f32_e32 v2, v34, v2
	v_or_b32_e32 v34, s19, v99
	v_mad_u64_u32 v[32:33], s[22:23], v34, s87, v[32:33]
	global_load_dword v32, v[32:33], off
	v_lshlrev_b32_e32 v33, 2, v34
	global_load_dword v33, v33, s[16:17]
	s_waitcnt vmcnt(0)
	v_mul_f32_e32 v32, v32, v33
	ds_write2_b32 v108, v2, v32 offset0:140 offset1:206
	s_waitcnt lgkmcnt(0)
	ds_read2_b32 v[108:109], v67 offset0:33 offset1:41
	ds_read2_b32 v[110:111], v67 offset1:8
	ds_read2_b32 v[112:113], v67 offset0:66 offset1:74
	ds_read2_b32 v[114:115], v67 offset0:99 offset1:107
	ds_read2_b32 v[116:117], v67 offset0:132 offset1:140
	ds_read2_b32 v[118:119], v67 offset0:165 offset1:173
	ds_read2_b32 v[120:121], v67 offset0:198 offset1:206
	ds_read2_b32 v[122:123], v67 offset0:231 offset1:239
	s_waitcnt lgkmcnt(7)
	v_bfe_u32 v32, v108, 16, 1
	s_waitcnt lgkmcnt(6)
; #define GAS __attribute__((address_space(1)))
; #define LAS __attribute__((address_space(3)))
; __device__ __forceinline__ unsigned f2bf(float f) { unsigned u = __builtin_bit_cast(unsigned, f); return (u + 0x7fffu + ((u >> 16) & 1u)) >> 16; }
; __device__ __forceinline__ unsigned pk2(float lo, float hi) { return f2bf(lo) | (f2bf(hi) << 16); }
; __device__ __forceinline__ void transpose_item(const float* W, int K, int N, bf16* WT, int mode, const float* gain, LAS float* scr, int item, int lane) {
;     ...
;     const int c = lane & 7;
; #pragma unroll
;     for (int j = 0; j < 4; ++j) { const int n = (lane >> 3) + 8 * j; const LAS float* s = scr + (8 * c) * 33 + n;
;         v4u o; o.x = pk2(s[0 * 33], s[1 * 33]); o.y = pk2(s[2 * 33], s[3 * 33]); o.z = pk2(s[4 * 33], s[5 * 33]); o.w = pk2(s[6 * 33], s[7 * 33]);
;         const int p_ = dst_row(mode, n0 + n), pl_ = p_ & 127, x_ = pl_ & 31, R_ = (pl_ & ~31) + 16 * ((x_ >> 2) & 1) + 4 * (x_ >> 3) + (x_ & 3);
;         *(GAS v4u*)((GAS unsigned char*)WT + ((size_t)(p_ >> 7) * (K / 64) + (k0 >> 6)) * 16384 + pg8::lds_byte(R_, 8 * c)) = o; }
	v_bfe_u32 v2, v110, 16, 1
	v_add3_u32 v2, v110, v2, s33
	v_lshrrev_b32_e32 v2, 16, v2
	v_add3_u32 v32, v108, v32, s33
	v_and_or_b32 v32, v32, s86, v2
	s_waitcnt lgkmcnt(5)
	v_bfe_u32 v2, v112, 16, 1
	v_add3_u32 v2, v112, v2, s33
	s_waitcnt lgkmcnt(4)
	v_bfe_u32 v33, v114, 16, 1
	v_lshrrev_b32_e32 v2, 16, v2
	v_add3_u32 v33, v114, v33, s33
	v_and_or_b32 v33, v33, s86, v2
	s_waitcnt lgkmcnt(3)
	v_bfe_u32 v2, v116, 16, 1
	v_add3_u32 v2, v116, v2, s33
	s_waitcnt lgkmcnt(2)
	v_bfe_u32 v34, v118, 16, 1
	v_lshrrev_b32_e32 v2, 16, v2
	v_add3_u32 v34, v118, v34, s33
	v_and_or_b32 v34, v34, s86, v2
	s_waitcnt lgkmcnt(1)
	v_bfe_u32 v2, v120, 16, 1
	v_add3_u32 v2, v120, v2, s33
	s_waitcnt lgkmcnt(0)
	v_bfe_u32 v35, v122, 16, 1
	v_lshrrev_b32_e32 v2, 16, v2
	v_add3_u32 v35, v122, v35, s33
	v_and_or_b32 v35, v35, s86, v2
	v_or_b32_e32 v2, s3, v100
	v_lshrrev_b32_e32 v2, 3, v2
	v_readlane_b32 s3, v254, 4
	v_or_b32_e32 v2, v2, v64
	s_add_u32 s2, s3, s2
	v_readlane_b32 s3, v254, 6
	v_lshlrev_b32_e32 v2, 10, v2
	s_addc_u32 s3, s3, 0
	v_or_b32_e32 v124, v2, v68
	v_bfe_u32 v108, v123, 16, 1
	v_add3_u32 v108, v123, v108, s33
	global_store_dwordx4 v124, v[32:35], s[2:3]
	v_or_b32_e32 v2, v2, v69
	s_nop 0
	v_bfe_u32 v32, v111, 16, 1
	v_add3_u32 v32, v111, v32, s33
	v_bfe_u32 v33, v109, 16, 1
	v_lshrrev_b32_e32 v32, 16, v32
	v_add3_u32 v33, v109, v33, s33
	v_and_or_b32 v32, v33, s86, v32
	v_bfe_u32 v33, v113, 16, 1
	v_add3_u32 v33, v113, v33, s33
	v_bfe_u32 v34, v115, 16, 1
	v_lshrrev_b32_e32 v33, 16, v33
	v_add3_u32 v34, v115, v34, s33
	v_and_or_b32 v33, v34, s86, v33
	v_bfe_u32 v34, v117, 16, 1
	v_add3_u32 v34, v117, v34, s33
	v_bfe_u32 v35, v119, 16, 1
	v_lshrrev_b32_e32 v34, 16, v34
	v_add3_u32 v35, v119, v35, s33
	v_and_or_b32 v34, v35, s86, v34
	v_bfe_u32 v35, v121, 16, 1
	v_add3_u32 v35, v121, v35, s33
	v_lshrrev_b32_e32 v35, 16, v35
	v_and_or_b32 v35, v108, s86, v35
	global_store_dwordx4 v2, v[32:35], s[2:3]
	ds_read2_b32 v[108:109], v67 offset0:16 offset1:24
	ds_read2_b32 v[110:111], v67 offset0:49 offset1:57
	ds_read2_b32 v[112:113], v67 offset0:82 offset1:90
	ds_read2_b32 v[114:115], v67 offset0:115 offset1:123
	ds_read2_b32 v[116:117], v67 offset0:148 offset1:156
	ds_read2_b32 v[118:119], v67 offset0:181 offset1:189
	ds_read2_b32 v[120:121], v67 offset0:214 offset1:222
	ds_read2_b32 v[122:123], v67 offset0:247 offset1:255
	s_waitcnt lgkmcnt(7)
	v_bfe_u32 v2, v108, 16, 1
	v_add3_u32 v2, v108, v2, s33
	s_waitcnt lgkmcnt(6)
	v_bfe_u32 v32, v110, 16, 1
	v_lshrrev_b32_e32 v2, 16, v2
	v_add3_u32 v32, v110, v32, s33
	v_and_or_b32 v32, v32, s86, v2
	s_waitcnt lgkmcnt(5)
	v_bfe_u32 v2, v112, 16, 1
	v_add3_u32 v2, v112, v2, s33
	s_waitcnt lgkmcnt(4)
	v_bfe_u32 v33, v114, 16, 1
	v_lshrrev_b32_e32 v2, 16, v2
	v_add3_u32 v33, v114, v33, s33
	v_and_or_b32 v33, v33, s86, v2
	s_waitcnt lgkmcnt(3)
	v_bfe_u32 v2, v116, 16, 1
	v_add3_u32 v2, v116, v2, s33
	s_waitcnt lgkmcnt(2)
	v_bfe_u32 v34, v118, 16, 1
	v_lshrrev_b32_e32 v2, 16, v2
	v_add3_u32 v34, v118, v34, s33
	v_and_or_b32 v34, v34, s86, v2
	s_waitcnt lgkmcnt(1)
	v_bfe_u32 v2, v120, 16, 1
	v_add3_u32 v2, v120, v2, s33
	s_waitcnt lgkmcnt(0)
	v_bfe_u32 v35, v122, 16, 1
	v_lshrrev_b32_e32 v2, 16, v2
	v_add3_u32 v35, v122, v35, s33
	v_and_or_b32 v35, v35, s86, v2
	v_xor_b32_e32 v2, 32, v124
	v_lshl_add_u64 v[124:125], s[2:3], 0, v[2:3]
	global_store_dwordx4 v[124:125], v[32:35], off offset:512
	v_bfe_u32 v2, v111, 16, 1
	v_add3_u32 v2, v111, v2, s33
	v_bfe_u32 v32, v109, 16, 1
	v_add3_u32 v32, v109, v32, s33
	v_lshrrev_b32_e32 v32, 16, v32
	v_bfe_u32 v33, v113, 16, 1
	v_and_or_b32 v32, v2, s86, v32
	v_bfe_u32 v2, v115, 16, 1
	v_add3_u32 v33, v113, v33, s33
	v_add3_u32 v2, v115, v2, s33
	v_lshrrev_b32_e32 v33, 16, v33
	v_bfe_u32 v34, v117, 16, 1
	v_and_or_b32 v33, v2, s86, v33
	v_bfe_u32 v2, v119, 16, 1
	v_add3_u32 v34, v117, v34, s33
	v_add3_u32 v2, v119, v2, s33
	v_lshrrev_b32_e32 v34, 16, v34
	v_bfe_u32 v35, v121, 16, 1
	v_and_or_b32 v34, v2, s86, v34
	v_bfe_u32 v2, v123, 16, 1
	v_add3_u32 v35, v121, v35, s33
	v_add3_u32 v2, v123, v2, s33
	v_lshrrev_b32_e32 v35, 16, v35
	v_and_or_b32 v35, v2, s86, v35
	global_store_dwordx4 v[124:125], v[32:35], off offset:768
	s_waitcnt lgkmcnt(0)

; #define TR(cnt, W, K_, N_, DST, MODE, GAIN) if (r < (cnt)) { transpose_item((W), (K_), (N_), (bf16*)(ws + (DST)), (MODE), (GAIN), scr, r, lane); continue; } r -= (cnt);
; __device__ __forceinline__ void transpose_item(const float* W, int K, int N, bf16* WT, int mode, const float* gain, LAS float* scr, int item, int lane) {
;     const int nblk = N / 32, kb = item / nblk, nb = item % nblk, k0 = 64 * kb, n0 = 32 * nb;
; #pragma unroll
;     for (int i = 0; i < 32; ++i) { const int kk = 2 * i + (lane >> 5); float w = W[(size_t)(k0 + kk) * N + n0 + (lane & 31)]; if (gain) w *= gain[k0 + kk]; scr[kk * 33 + (lane & 31)] = w; }
; __device__ __forceinline__ void p0_prologue(const Args& a, LAS unsigned char* lds, int vcu, int G, int wave, int lane) {
;     ...
;         TR(T_GU, a.in[I_FWG], D, DFF, WS_WGU0, 1, a.in[I_FNG])
;         TR(T_GU, a.in[I_FWU], D, DFF, WS_WGU0, 2, a.in[I_FNG])
;         TR(T_GU, a.in[I_FWG] + (size_t)D * DFF, D, DFF, WS_WGU1, 1, a.in[I_FNG] + D)
;         TR(T_GU, a.in[I_FWU] + (size_t)D * DFF, D, DFF, WS_WGU1, 2, a.in[I_FNG] + D)
.LBB0_123:
	s_andn2_b64 vcc, exec, s[2:3]
	s_cbranch_vccnz .LBB0_189
	s_add_i32 s2, s88, 0xec80
	s_and_b32 s3, s2, 0xffff
	s_mul_i32 s3, s3, 0xba2f
	s_lshr_b32 s18, s3, 22
	s_mul_i32 s19, s18, 0x58
	s_sub_i32 s2, s2, s19
	s_lshr_b32 s3, s3, 16
	s_and_b32 s19, s2, 0xffff
	s_and_b32 s21, s3, 0xffc0
	s_lshl_b32 s56, s19, 7
	v_lshl_add_u64 v[32:33], v[10:11], 0, s[56:57]
	v_or_b32_e32 v34, s21, v0
	v_mad_u64_u32 v[108:109], s[2:3], v34, s87, v[32:33]
	global_load_dword v2, v[108:109], off
	v_cndmask_b32_e64 v35, 0, 1, s[24:25]
	v_cmp_ne_u32_e64 s[2:3], 1, v35
	s_andn2_b64 vcc, exec, s[24:25]
	s_cbranch_vccnz .LBB0_126
	v_readlane_b32 s40, v255, 43
	v_lshlrev_b32_e32 v34, 2, v34
	v_readlane_b32 s52, v255, 55
	v_readlane_b32 s53, v255, 56
	v_readlane_b32 s41, v255, 44
	v_readlane_b32 s42, v255, 45
	v_readlane_b32 s43, v255, 46
	v_readlane_b32 s44, v255, 47
	v_readlane_b32 s45, v255, 48
	global_load_dword v34, v34, s[52:53]
	v_readlane_b32 s46, v255, 49
	v_readlane_b32 s47, v255, 50
	v_readlane_b32 s48, v255, 51
	v_readlane_b32 s49, v255, 52
	v_readlane_b32 s50, v255, 53
	v_readlane_b32 s51, v255, 54
	v_readlane_b32 s54, v255, 57
	v_readlane_b32 s55, v255, 58
	s_waitcnt vmcnt(0)
	v_mul_f32_e32 v2, v2, v34
.LBB0_126:
	v_or_b32_e32 v34, s21, v38
	v_mad_u64_u32 v[34:35], s[22:23], v34, s87, v[32:33]
	global_load_dword v34, v[34:35], off
	v_add_u32_e32 v35, v36, v37
	s_waitcnt vmcnt(1)
	ds_write_b32 v35, v2
	s_and_b64 vcc, exec, s[2:3]
	v_add_lshl_u32 v2, v0, s21, 2
	s_cbranch_vccnz .LBB0_128
	v_readlane_b32 s40, v255, 43
	v_readlane_b32 s52, v255, 55
	v_readlane_b32 s53, v255, 56
	v_readlane_b32 s41, v255, 44
	v_readlane_b32 s42, v255, 45
	v_readlane_b32 s43, v255, 46
	v_readlane_b32 s44, v255, 47
	v_readlane_b32 s45, v255, 48
	global_load_dword v35, v2, s[52:53] offset:8
	v_readlane_b32 s46, v255, 49
	v_readlane_b32 s47, v255, 50
	v_readlane_b32 s48, v255, 51
	v_readlane_b32 s49, v255, 52
	v_readlane_b32 s50, v255, 53
	v_readlane_b32 s51, v255, 54
	v_readlane_b32 s54, v255, 57
	v_readlane_b32 s55, v255, 58
	s_waitcnt vmcnt(0)
	v_mul_f32_e32 v34, v34, v35
.LBB0_128:
	v_or_b32_e32 v35, s21, v70
	v_mad_u64_u32 v[108:109], s[22:23], v35, s87, v[32:33]
	global_load_dword v35, v[108:109], off
	v_add_u32_e32 v108, v36, v39
	s_and_b64 vcc, exec, s[2:3]
	s_waitcnt vmcnt(1)
	ds_write_b32 v108, v34
	s_cbranch_vccnz .LBB0_130
	v_readlane_b32 s40, v255, 43
	v_readlane_b32 s52, v255, 55
	v_readlane_b32 s53, v255, 56
	v_readlane_b32 s41, v255, 44
	v_readlane_b32 s42, v255, 45
	v_readlane_b32 s43, v255, 46
	v_readlane_b32 s44, v255, 47
	v_readlane_b32 s45, v255, 48
	global_load_dword v34, v2, s[52:53] offset:16
	v_readlane_b32 s46, v255, 49
	v_readlane_b32 s47, v255, 50
	v_readlane_b32 s48, v255, 51
	v_readlane_b32 s49, v255, 52
	v_readlane_b32 s50, v255, 53
	v_readlane_b32 s51, v255, 54
	v_readlane_b32 s54, v255, 57
	v_readlane_b32 s55, v255, 58
	s_waitcnt vmcnt(0)
	v_mul_f32_e32 v35, v35, v34
.LBB0_130:
	v_or_b32_e32 v34, s21, v71
	v_mad_u64_u32 v[108:109], s[22:23], v34, s87, v[32:33]
	global_load_dword v34, v[108:109], off
	v_add_u32_e32 v108, v36, v40
	s_and_b64 vcc, exec, s[2:3]
	s_waitcnt vmcnt(1)
	ds_write_b32 v108, v35
	s_cbranch_vccnz .LBB0_132
	v_readlane_b32 s40, v255, 43
	v_readlane_b32 s52, v255, 55
	v_readlane_b32 s53, v255, 56
	v_readlane_b32 s41, v255, 44
	v_readlane_b32 s42, v255, 45
	v_readlane_b32 s43, v255, 46
	v_readlane_b32 s44, v255, 47
	v_readlane_b32 s45, v255, 48
	global_load_dword v35, v2, s[52:53] offset:24
	v_readlane_b32 s46, v255, 49
	v_readlane_b32 s47, v255, 50
	v_readlane_b32 s48, v255, 51
	v_readlane_b32 s49, v255, 52
	v_readlane_b32 s50, v255, 53
	v_readlane_b32 s51, v255, 54
	v_readlane_b32 s54, v255, 57
	v_readlane_b32 s55, v255, 58
	s_waitcnt vmcnt(0)
	v_mul_f32_e32 v34, v34, v35
.LBB0_132:
	v_or_b32_e32 v35, s21, v72
	v_mad_u64_u32 v[108:109], s[22:23], v35, s87, v[32:33]
	global_load_dword v35, v[108:109], off
	v_add_u32_e32 v108, v36, v41
	s_and_b64 vcc, exec, s[2:3]
	s_waitcnt vmcnt(1)
	ds_write_b32 v108, v34
	s_cbranch_vccnz .LBB0_134
	v_readlane_b32 s40, v255, 43
	v_readlane_b32 s52, v255, 55
	v_readlane_b32 s53, v255, 56
	v_readlane_b32 s41, v255, 44
	v_readlane_b32 s42, v255, 45
	v_readlane_b32 s43, v255, 46
	v_readlane_b32 s44, v255, 47
	v_readlane_b32 s45, v255, 48
	global_load_dword v34, v2, s[52:53] offset:32
	v_readlane_b32 s46, v255, 49
	v_readlane_b32 s47, v255, 50
	v_readlane_b32 s48, v255, 51
	v_readlane_b32 s49, v255, 52
	v_readlane_b32 s50, v255, 53
	v_readlane_b32 s51, v255, 54
	v_readlane_b32 s54, v255, 57
	v_readlane_b32 s55, v255, 58
	s_waitcnt vmcnt(0)
	v_mul_f32_e32 v35, v35, v34
.LBB0_134:
	v_or_b32_e32 v34, s21, v73
	v_mad_u64_u32 v[108:109], s[22:23], v34, s87, v[32:33]
	global_load_dword v34, v[108:109], off
	v_add_u32_e32 v108, v36, v42
	s_and_b64 vcc, exec, s[2:3]
	s_waitcnt vmcnt(1)
	ds_write_b32 v108, v35
	s_cbranch_vccnz .LBB0_136
	v_readlane_b32 s40, v255, 43
	v_readlane_b32 s52, v255, 55
	v_readlane_b32 s53, v255, 56
	v_readlane_b32 s41, v255, 44
	v_readlane_b32 s42, v255, 45
	v_readlane_b32 s43, v255, 46
	v_readlane_b32 s44, v255, 47
	v_readlane_b32 s45, v255, 48
	global_load_dword v35, v2, s[52:53] offset:40
	v_readlane_b32 s46, v255, 49
	v_readlane_b32 s47, v255, 50
	v_readlane_b32 s48, v255, 51
	v_readlane_b32 s49, v255, 52
	v_readlane_b32 s50, v255, 53
	v_readlane_b32 s51, v255, 54
	v_readlane_b32 s54, v255, 57
	v_readlane_b32 s55, v255, 58
	s_waitcnt vmcnt(0)
	v_mul_f32_e32 v34, v34, v35
; __device__ __forceinline__ void transpose_item(const float* W, int K, int N, bf16* WT, int mode, const float* gain, LAS float* scr, int item, int lane) {
;     const int nblk = N / 32, kb = item / nblk, nb = item % nblk, k0 = 64 * kb, n0 = 32 * nb;
; #pragma unroll
;     for (int i = 0; i < 32; ++i) { const int kk = 2 * i + (lane >> 5); float w = W[(size_t)(k0 + kk) * N + n0 + (lane & 31)]; if (gain) w *= gain[k0 + kk]; scr[kk * 33 + (lane & 31)] = w; }
.LBB0_136:
	v_or_b32_e32 v35, s21, v74
	v_mad_u64_u32 v[108:109], s[22:23], v35, s87, v[32:33]
	global_load_dword v35, v[108:109], off
	v_add_u32_e32 v108, v36, v43
	s_and_b64 vcc, exec, s[2:3]
	s_waitcnt vmcnt(1)
	ds_write_b32 v108, v34
	s_cbranch_vccnz .LBB0_138
	v_readlane_b32 s40, v255, 43
	v_readlane_b32 s52, v255, 55
	v_readlane_b32 s53, v255, 56
	v_readlane_b32 s41, v255, 44
	v_readlane_b32 s42, v255, 45
	v_readlane_b32 s43, v255, 46
	v_readlane_b32 s44, v255, 47
	v_readlane_b32 s45, v255, 48
	global_load_dword v34, v2, s[52:53] offset:48
	v_readlane_b32 s46, v255, 49
	v_readlane_b32 s47, v255, 50
	v_readlane_b32 s48, v255, 51
	v_readlane_b32 s49, v255, 52
	v_readlane_b32 s50, v255, 53
	v_readlane_b32 s51, v255, 54
	v_readlane_b32 s54, v255, 57
	v_readlane_b32 s55, v255, 58
	s_waitcnt vmcnt(0)
	v_mul_f32_e32 v35, v35, v34
.LBB0_138:
	v_or_b32_e32 v34, s21, v75
	v_mad_u64_u32 v[108:109], s[22:23], v34, s87, v[32:33]
	global_load_dword v34, v[108:109], off
	v_add_u32_e32 v108, v36, v44
	s_and_b64 vcc, exec, s[2:3]
	s_waitcnt vmcnt(1)
	ds_write_b32 v108, v35
	s_cbranch_vccnz .LBB0_140
	v_readlane_b32 s40, v255, 43
	v_readlane_b32 s52, v255, 55
	v_readlane_b32 s53, v255, 56
	v_readlane_b32 s41, v255, 44
	v_readlane_b32 s42, v255, 45
	v_readlane_b32 s43, v255, 46
	v_readlane_b32 s44, v255, 47
	v_readlane_b32 s45, v255, 48
	global_load_dword v35, v2, s[52:53] offset:56
	v_readlane_b32 s46, v255, 49
	v_readlane_b32 s47, v255, 50
	v_readlane_b32 s48, v255, 51
	v_readlane_b32 s49, v255, 52
	v_readlane_b32 s50, v255, 53
	v_readlane_b32 s51, v255, 54
	v_readlane_b32 s54, v255, 57
	v_readlane_b32 s55, v255, 58
	s_waitcnt vmcnt(0)
	v_mul_f32_e32 v34, v34, v35
.LBB0_140:
	v_or_b32_e32 v35, s21, v76
	v_mad_u64_u32 v[108:109], s[22:23], v35, s87, v[32:33]
	global_load_dword v35, v[108:109], off
	v_add_u32_e32 v108, v36, v45
	s_and_b64 vcc, exec, s[2:3]
	s_waitcnt vmcnt(1)
	ds_write_b32 v108, v34
	s_cbranch_vccnz .LBB0_142
	v_readlane_b32 s40, v255, 43
	v_readlane_b32 s52, v255, 55
	v_readlane_b32 s53, v255, 56
	v_readlane_b32 s41, v255, 44
	v_readlane_b32 s42, v255, 45
	v_readlane_b32 s43, v255, 46
	v_readlane_b32 s44, v255, 47
	v_readlane_b32 s45, v255, 48
	global_load_dword v34, v2, s[52:53] offset:64
	v_readlane_b32 s46, v255, 49
	v_readlane_b32 s47, v255, 50
	v_readlane_b32 s48, v255, 51
	v_readlane_b32 s49, v255, 52
	v_readlane_b32 s50, v255, 53
	v_readlane_b32 s51, v255, 54
	v_readlane_b32 s54, v255, 57
	v_readlane_b32 s55, v255, 58
	s_waitcnt vmcnt(0)
	v_mul_f32_e32 v35, v35, v34
.LBB0_142:
	v_or_b32_e32 v34, s21, v77
	v_mad_u64_u32 v[108:109], s[22:23], v34, s87, v[32:33]
	global_load_dword v34, v[108:109], off
	v_add_u32_e32 v108, v36, v46
	s_and_b64 vcc, exec, s[2:3]
	s_waitcnt vmcnt(1)
	ds_write_b32 v108, v35
	s_cbranch_vccnz .LBB0_144
	v_readlane_b32 s40, v255, 43
	v_readlane_b32 s52, v255, 55
	v_readlane_b32 s53, v255, 56
	v_readlane_b32 s41, v255, 44
	v_readlane_b32 s42, v255, 45
	v_readlane_b32 s43, v255, 46
	v_readlane_b32 s44, v255, 47
	v_readlane_b32 s45, v255, 48
	global_load_dword v35, v2, s[52:53] offset:72
	v_readlane_b32 s46, v255, 49
	v_readlane_b32 s47, v255, 50
	v_readlane_b32 s48, v255, 51
	v_readlane_b32 s49, v255, 52
	v_readlane_b32 s50, v255, 53
	v_readlane_b32 s51, v255, 54
	v_readlane_b32 s54, v255, 57
	v_readlane_b32 s55, v255, 58
	s_waitcnt vmcnt(0)
	v_mul_f32_e32 v34, v34, v35
.LBB0_144:
	v_or_b32_e32 v35, s21, v78
	v_mad_u64_u32 v[108:109], s[22:23], v35, s87, v[32:33]
	global_load_dword v35, v[108:109], off
	v_add_u32_e32 v108, v36, v47
	s_and_b64 vcc, exec, s[2:3]
	s_waitcnt vmcnt(1)
	ds_write_b32 v108, v34
	s_cbranch_vccnz .LBB0_146
	v_readlane_b32 s40, v255, 43
	v_readlane_b32 s52, v255, 55
	v_readlane_b32 s53, v255, 56
	v_readlane_b32 s41, v255, 44
	v_readlane_b32 s42, v255, 45
	v_readlane_b32 s43, v255, 46
	v_readlane_b32 s44, v255, 47
	v_readlane_b32 s45, v255, 48
	global_load_dword v34, v2, s[52:53] offset:80
	v_readlane_b32 s46, v255, 49
	v_readlane_b32 s47, v255, 50
	v_readlane_b32 s48, v255, 51
	v_readlane_b32 s49, v255, 52
	v_readlane_b32 s50, v255, 53
	v_readlane_b32 s51, v255, 54
	v_readlane_b32 s54, v255, 57
	v_readlane_b32 s55, v255, 58
	s_waitcnt vmcnt(0)
	v_mul_f32_e32 v35, v35, v34
.LBB0_146:
	v_or_b32_e32 v34, s21, v79
	v_mad_u64_u32 v[108:109], s[22:23], v34, s87, v[32:33]
	global_load_dword v34, v[108:109], off
	v_add_u32_e32 v108, v36, v48
	s_and_b64 vcc, exec, s[2:3]
	s_waitcnt vmcnt(1)
	ds_write_b32 v108, v35
	s_cbranch_vccnz .LBB0_148
	v_readlane_b32 s40, v255, 43
	v_readlane_b32 s52, v255, 55
	v_readlane_b32 s53, v255, 56
	v_readlane_b32 s41, v255, 44
	v_readlane_b32 s42, v255, 45
	v_readlane_b32 s43, v255, 46
	v_readlane_b32 s44, v255, 47
	v_readlane_b32 s45, v255, 48
	global_load_dword v35, v2, s[52:53] offset:88
	v_readlane_b32 s46, v255, 49
	v_readlane_b32 s47, v255, 50
	v_readlane_b32 s48, v255, 51
	v_readlane_b32 s49, v255, 52
	v_readlane_b32 s50, v255, 53
	v_readlane_b32 s51, v255, 54
	v_readlane_b32 s54, v255, 57
	v_readlane_b32 s55, v255, 58
	s_waitcnt vmcnt(0)
	v_mul_f32_e32 v34, v34, v35
.LBB0_148:
	v_or_b32_e32 v35, s21, v80
	v_mad_u64_u32 v[108:109], s[22:23], v35, s87, v[32:33]
	global_load_dword v35, v[108:109], off
	v_add_u32_e32 v108, v36, v49
	s_and_b64 vcc, exec, s[2:3]
	s_waitcnt vmcnt(1)
	ds_write_b32 v108, v34
	s_cbranch_vccnz .LBB0_150
	v_readlane_b32 s40, v255, 43
	v_readlane_b32 s52, v255, 55
	v_readlane_b32 s53, v255, 56
	v_readlane_b32 s41, v255, 44
	v_readlane_b32 s42, v255, 45
	v_readlane_b32 s43, v255, 46
	v_readlane_b32 s44, v255, 47
	v_readlane_b32 s45, v255, 48
	global_load_dword v34, v2, s[52:53] offset:96
	v_readlane_b32 s46, v255, 49
	v_readlane_b32 s47, v255, 50
	v_readlane_b32 s48, v255, 51
	v_readlane_b32 s49, v255, 52
	v_readlane_b32 s50, v255, 53
	v_readlane_b32 s51, v255, 54
	v_readlane_b32 s54, v255, 57
	v_readlane_b32 s55, v255, 58
	s_waitcnt vmcnt(0)
	v_mul_f32_e32 v35, v35, v34
; __device__ __forceinline__ void transpose_item(const float* W, int K, int N, bf16* WT, int mode, const float* gain, LAS float* scr, int item, int lane) {
;     const int nblk = N / 32, kb = item / nblk, nb = item % nblk, k0 = 64 * kb, n0 = 32 * nb;
; #pragma unroll
;     for (int i = 0; i < 32; ++i) { const int kk = 2 * i + (lane >> 5); float w = W[(size_t)(k0 + kk) * N + n0 + (lane & 31)]; if (gain) w *= gain[k0 + kk]; scr[kk * 33 + (lane & 31)] = w; }
.LBB0_150:
	v_or_b32_e32 v34, s21, v81
	v_mad_u64_u32 v[108:109], s[22:23], v34, s87, v[32:33]
	global_load_dword v34, v[108:109], off
	v_add_u32_e32 v108, v36, v50
	s_and_b64 vcc, exec, s[2:3]
	s_waitcnt vmcnt(1)
	ds_write_b32 v108, v35
	s_cbranch_vccnz .LBB0_152
	v_readlane_b32 s40, v255, 43
	v_readlane_b32 s52, v255, 55
	v_readlane_b32 s53, v255, 56
	v_readlane_b32 s41, v255, 44
	v_readlane_b32 s42, v255, 45
	v_readlane_b32 s43, v255, 46
	v_readlane_b32 s44, v255, 47
	v_readlane_b32 s45, v255, 48
	global_load_dword v35, v2, s[52:53] offset:104
	v_readlane_b32 s46, v255, 49
	v_readlane_b32 s47, v255, 50
	v_readlane_b32 s48, v255, 51
	v_readlane_b32 s49, v255, 52
	v_readlane_b32 s50, v255, 53
	v_readlane_b32 s51, v255, 54
	v_readlane_b32 s54, v255, 57
	v_readlane_b32 s55, v255, 58
	s_waitcnt vmcnt(0)
	v_mul_f32_e32 v34, v34, v35
.LBB0_152:
	v_or_b32_e32 v35, s21, v82
	v_mad_u64_u32 v[108:109], s[22:23], v35, s87, v[32:33]
	global_load_dword v35, v[108:109], off
	v_add_u32_e32 v108, v36, v51
	s_and_b64 vcc, exec, s[2:3]
	s_waitcnt vmcnt(1)
	ds_write_b32 v108, v34
	s_cbranch_vccnz .LBB0_154
	v_readlane_b32 s40, v255, 43
	v_readlane_b32 s52, v255, 55
	v_readlane_b32 s53, v255, 56
	v_readlane_b32 s41, v255, 44
	v_readlane_b32 s42, v255, 45
	v_readlane_b32 s43, v255, 46
	v_readlane_b32 s44, v255, 47
	v_readlane_b32 s45, v255, 48
	global_load_dword v34, v2, s[52:53] offset:112
	v_readlane_b32 s46, v255, 49
	v_readlane_b32 s47, v255, 50
	v_readlane_b32 s48, v255, 51
	v_readlane_b32 s49, v255, 52
	v_readlane_b32 s50, v255, 53
	v_readlane_b32 s51, v255, 54
	v_readlane_b32 s54, v255, 57
	v_readlane_b32 s55, v255, 58
	s_waitcnt vmcnt(0)
	v_mul_f32_e32 v35, v35, v34
.LBB0_154:
	v_or_b32_e32 v34, s21, v83
	v_mad_u64_u32 v[108:109], s[22:23], v34, s87, v[32:33]
	global_load_dword v34, v[108:109], off
	v_add_u32_e32 v108, v36, v52
	s_and_b64 vcc, exec, s[2:3]
	s_waitcnt vmcnt(1)
	ds_write_b32 v108, v35
	s_cbranch_vccnz .LBB0_156
	v_readlane_b32 s40, v255, 43
	v_readlane_b32 s52, v255, 55
	v_readlane_b32 s53, v255, 56
	v_readlane_b32 s41, v255, 44
	v_readlane_b32 s42, v255, 45
	v_readlane_b32 s43, v255, 46
	v_readlane_b32 s44, v255, 47
	v_readlane_b32 s45, v255, 48
	global_load_dword v35, v2, s[52:53] offset:120
	v_readlane_b32 s46, v255, 49
	v_readlane_b32 s47, v255, 50
	v_readlane_b32 s48, v255, 51
	v_readlane_b32 s49, v255, 52
	v_readlane_b32 s50, v255, 53
	v_readlane_b32 s51, v255, 54
	v_readlane_b32 s54, v255, 57
	v_readlane_b32 s55, v255, 58
	s_waitcnt vmcnt(0)
	v_mul_f32_e32 v34, v34, v35
.LBB0_156:
	v_or_b32_e32 v35, s21, v84
	v_mad_u64_u32 v[108:109], s[22:23], v35, s87, v[32:33]
	global_load_dword v35, v[108:109], off
	v_add_u32_e32 v108, v36, v53
	s_and_b64 vcc, exec, s[2:3]
	s_waitcnt vmcnt(1)
	ds_write_b32 v108, v34
	s_cbranch_vccnz .LBB0_158
	v_readlane_b32 s40, v255, 43
	v_readlane_b32 s52, v255, 55
	v_readlane_b32 s53, v255, 56
	v_readlane_b32 s41, v255, 44
	v_readlane_b32 s42, v255, 45
	v_readlane_b32 s43, v255, 46
	v_readlane_b32 s44, v255, 47
	v_readlane_b32 s45, v255, 48
	global_load_dword v34, v2, s[52:53] offset:128
	v_readlane_b32 s46, v255, 49
	v_readlane_b32 s47, v255, 50
	v_readlane_b32 s48, v255, 51
	v_readlane_b32 s49, v255, 52
	v_readlane_b32 s50, v255, 53
	v_readlane_b32 s51, v255, 54
	v_readlane_b32 s54, v255, 57
	v_readlane_b32 s55, v255, 58
	s_waitcnt vmcnt(0)
	v_mul_f32_e32 v35, v35, v34
.LBB0_158:
	v_or_b32_e32 v34, s21, v85
	v_mad_u64_u32 v[108:109], s[22:23], v34, s87, v[32:33]
	global_load_dword v34, v[108:109], off
	v_add_u32_e32 v108, v36, v54
	s_and_b64 vcc, exec, s[2:3]
	s_waitcnt vmcnt(1)
	ds_write_b32 v108, v35
	s_cbranch_vccnz .LBB0_160
	v_readlane_b32 s40, v255, 43
	v_readlane_b32 s52, v255, 55
	v_readlane_b32 s53, v255, 56
	v_readlane_b32 s41, v255, 44
	v_readlane_b32 s42, v255, 45
	v_readlane_b32 s43, v255, 46
	v_readlane_b32 s44, v255, 47
	v_readlane_b32 s45, v255, 48
	global_load_dword v35, v2, s[52:53] offset:136
	v_readlane_b32 s46, v255, 49
	v_readlane_b32 s47, v255, 50
	v_readlane_b32 s48, v255, 51
	v_readlane_b32 s49, v255, 52
	v_readlane_b32 s50, v255, 53
	v_readlane_b32 s51, v255, 54
	v_readlane_b32 s54, v255, 57
	v_readlane_b32 s55, v255, 58
	s_waitcnt vmcnt(0)
	v_mul_f32_e32 v34, v34, v35
.LBB0_160:
	v_or_b32_e32 v35, s21, v86
	v_mad_u64_u32 v[108:109], s[22:23], v35, s87, v[32:33]
	global_load_dword v35, v[108:109], off
	v_add_u32_e32 v108, v36, v55
	s_and_b64 vcc, exec, s[2:3]
	s_waitcnt vmcnt(1)
	ds_write_b32 v108, v34
	s_cbranch_vccnz .LBB0_162
	v_readlane_b32 s40, v255, 43
	v_readlane_b32 s52, v255, 55
	v_readlane_b32 s53, v255, 56
	v_readlane_b32 s41, v255, 44
	v_readlane_b32 s42, v255, 45
	v_readlane_b32 s43, v255, 46
	v_readlane_b32 s44, v255, 47
	v_readlane_b32 s45, v255, 48
	global_load_dword v34, v2, s[52:53] offset:144
	v_readlane_b32 s46, v255, 49
	v_readlane_b32 s47, v255, 50
	v_readlane_b32 s48, v255, 51
	v_readlane_b32 s49, v255, 52
	v_readlane_b32 s50, v255, 53
	v_readlane_b32 s51, v255, 54
	v_readlane_b32 s54, v255, 57
	v_readlane_b32 s55, v255, 58
	s_waitcnt vmcnt(0)
	v_mul_f32_e32 v35, v35, v34
.LBB0_162:
	v_or_b32_e32 v34, s21, v87
	v_mad_u64_u32 v[108:109], s[22:23], v34, s87, v[32:33]
	global_load_dword v34, v[108:109], off
	v_add_u32_e32 v108, v36, v56
	s_and_b64 vcc, exec, s[2:3]
	s_waitcnt vmcnt(1)
	ds_write_b32 v108, v35
	s_cbranch_vccnz .LBB0_164
	v_readlane_b32 s40, v255, 43
	v_readlane_b32 s52, v255, 55
	v_readlane_b32 s53, v255, 56
	v_readlane_b32 s41, v255, 44
	v_readlane_b32 s42, v255, 45
	v_readlane_b32 s43, v255, 46
	v_readlane_b32 s44, v255, 47
	v_readlane_b32 s45, v255, 48
	global_load_dword v35, v2, s[52:53] offset:152
	v_readlane_b32 s46, v255, 49
	v_readlane_b32 s47, v255, 50
	v_readlane_b32 s48, v255, 51
	v_readlane_b32 s49, v255, 52
	v_readlane_b32 s50, v255, 53
	v_readlane_b32 s51, v255, 54
	v_readlane_b32 s54, v255, 57
	v_readlane_b32 s55, v255, 58
	s_waitcnt vmcnt(0)
	v_mul_f32_e32 v34, v34, v35
; __device__ __forceinline__ void transpose_item(const float* W, int K, int N, bf16* WT, int mode, const float* gain, LAS float* scr, int item, int lane) {
;     const int nblk = N / 32, kb = item / nblk, nb = item % nblk, k0 = 64 * kb, n0 = 32 * nb;
; #pragma unroll
;     for (int i = 0; i < 32; ++i) { const int kk = 2 * i + (lane >> 5); float w = W[(size_t)(k0 + kk) * N + n0 + (lane & 31)]; if (gain) w *= gain[k0 + kk]; scr[kk * 33 + (lane & 31)] = w; }
.LBB0_164:
	v_or_b32_e32 v35, s21, v88
	v_mad_u64_u32 v[108:109], s[22:23], v35, s87, v[32:33]
	global_load_dword v35, v[108:109], off
	v_add_u32_e32 v108, v36, v57
	s_and_b64 vcc, exec, s[2:3]
	s_waitcnt vmcnt(1)
	ds_write_b32 v108, v34
	s_cbranch_vccnz .LBB0_166
	v_readlane_b32 s40, v255, 43
	v_readlane_b32 s52, v255, 55
	v_readlane_b32 s53, v255, 56
	v_readlane_b32 s41, v255, 44
	v_readlane_b32 s42, v255, 45
	v_readlane_b32 s43, v255, 46
	v_readlane_b32 s44, v255, 47
	v_readlane_b32 s45, v255, 48
	global_load_dword v34, v2, s[52:53] offset:160
	v_readlane_b32 s46, v255, 49
	v_readlane_b32 s47, v255, 50
	v_readlane_b32 s48, v255, 51
	v_readlane_b32 s49, v255, 52
	v_readlane_b32 s50, v255, 53
	v_readlane_b32 s51, v255, 54
	v_readlane_b32 s54, v255, 57
	v_readlane_b32 s55, v255, 58
	s_waitcnt vmcnt(0)
	v_mul_f32_e32 v35, v35, v34
.LBB0_166:
	v_or_b32_e32 v34, s21, v89
	v_mad_u64_u32 v[108:109], s[22:23], v34, s87, v[32:33]
	global_load_dword v34, v[108:109], off
	v_add_u32_e32 v108, v36, v58
	s_and_b64 vcc, exec, s[2:3]
	s_waitcnt vmcnt(1)
	ds_write_b32 v108, v35
	s_cbranch_vccnz .LBB0_168
	v_readlane_b32 s40, v255, 43
	v_readlane_b32 s52, v255, 55
	v_readlane_b32 s53, v255, 56
	v_readlane_b32 s41, v255, 44
	v_readlane_b32 s42, v255, 45
	v_readlane_b32 s43, v255, 46
	v_readlane_b32 s44, v255, 47
	v_readlane_b32 s45, v255, 48
	global_load_dword v35, v2, s[52:53] offset:168
	v_readlane_b32 s46, v255, 49
	v_readlane_b32 s47, v255, 50
	v_readlane_b32 s48, v255, 51
	v_readlane_b32 s49, v255, 52
	v_readlane_b32 s50, v255, 53
	v_readlane_b32 s51, v255, 54
	v_readlane_b32 s54, v255, 57
	v_readlane_b32 s55, v255, 58
	s_waitcnt vmcnt(0)
	v_mul_f32_e32 v34, v34, v35
.LBB0_168:
	v_or_b32_e32 v35, s21, v90
	v_mad_u64_u32 v[108:109], s[22:23], v35, s87, v[32:33]
	global_load_dword v35, v[108:109], off
	v_add_u32_e32 v108, v36, v59
	s_and_b64 vcc, exec, s[2:3]
	s_waitcnt vmcnt(1)
	ds_write_b32 v108, v34
	s_cbranch_vccnz .LBB0_170
	v_readlane_b32 s40, v255, 43
	v_readlane_b32 s52, v255, 55
	v_readlane_b32 s53, v255, 56
	v_readlane_b32 s41, v255, 44
	v_readlane_b32 s42, v255, 45
	v_readlane_b32 s43, v255, 46
	v_readlane_b32 s44, v255, 47
	v_readlane_b32 s45, v255, 48
	global_load_dword v34, v2, s[52:53] offset:176
	v_readlane_b32 s46, v255, 49
	v_readlane_b32 s47, v255, 50
	v_readlane_b32 s48, v255, 51
	v_readlane_b32 s49, v255, 52
	v_readlane_b32 s50, v255, 53
	v_readlane_b32 s51, v255, 54
	v_readlane_b32 s54, v255, 57
	v_readlane_b32 s55, v255, 58
	s_waitcnt vmcnt(0)
	v_mul_f32_e32 v35, v35, v34
.LBB0_170:
	v_or_b32_e32 v34, s21, v91
	v_mad_u64_u32 v[108:109], s[22:23], v34, s87, v[32:33]
	global_load_dword v34, v[108:109], off
	v_add_u32_e32 v108, v36, v60
	s_and_b64 vcc, exec, s[2:3]
	s_waitcnt vmcnt(1)
	ds_write_b32 v108, v35
	s_cbranch_vccnz .LBB0_172
	v_readlane_b32 s40, v255, 43
	v_readlane_b32 s52, v255, 55
	v_readlane_b32 s53, v255, 56
	v_readlane_b32 s41, v255, 44
	v_readlane_b32 s42, v255, 45
	v_readlane_b32 s43, v255, 46
	v_readlane_b32 s44, v255, 47
	v_readlane_b32 s45, v255, 48
	global_load_dword v35, v2, s[52:53] offset:184
	v_readlane_b32 s46, v255, 49
	v_readlane_b32 s47, v255, 50
	v_readlane_b32 s48, v255, 51
	v_readlane_b32 s49, v255, 52
	v_readlane_b32 s50, v255, 53
	v_readlane_b32 s51, v255, 54
	v_readlane_b32 s54, v255, 57
	v_readlane_b32 s55, v255, 58
	s_waitcnt vmcnt(0)
	v_mul_f32_e32 v34, v34, v35
.LBB0_172:
	v_or_b32_e32 v35, s21, v92
	v_mad_u64_u32 v[108:109], s[22:23], v35, s87, v[32:33]
	global_load_dword v35, v[108:109], off
	v_add_u32_e32 v108, v36, v61
	s_and_b64 vcc, exec, s[2:3]
	s_waitcnt vmcnt(1)
	ds_write_b32 v108, v34
	s_cbranch_vccnz .LBB0_174
	v_readlane_b32 s40, v255, 43
	v_readlane_b32 s52, v255, 55
	v_readlane_b32 s53, v255, 56
	v_readlane_b32 s41, v255, 44
	v_readlane_b32 s42, v255, 45
	v_readlane_b32 s43, v255, 46
	v_readlane_b32 s44, v255, 47
	v_readlane_b32 s45, v255, 48
	global_load_dword v34, v2, s[52:53] offset:192
	v_readlane_b32 s46, v255, 49
	v_readlane_b32 s47, v255, 50
	v_readlane_b32 s48, v255, 51
	v_readlane_b32 s49, v255, 52
	v_readlane_b32 s50, v255, 53
	v_readlane_b32 s51, v255, 54
	v_readlane_b32 s54, v255, 57
	v_readlane_b32 s55, v255, 58
	s_waitcnt vmcnt(0)
	v_mul_f32_e32 v35, v35, v34
.LBB0_174:
	v_or_b32_e32 v34, s21, v93
	v_mad_u64_u32 v[108:109], s[22:23], v34, s87, v[32:33]
	global_load_dword v108, v[108:109], off
	v_add_u32_e32 v34, v36, v62
	s_and_b64 vcc, exec, s[2:3]
	s_waitcnt vmcnt(1)
	ds_write_b32 v34, v35
	s_cbranch_vccnz .LBB0_176
	v_readlane_b32 s40, v255, 43
	v_readlane_b32 s52, v255, 55
	v_readlane_b32 s53, v255, 56
	v_readlane_b32 s41, v255, 44
	v_readlane_b32 s42, v255, 45
	v_readlane_b32 s43, v255, 46
	v_readlane_b32 s44, v255, 47
	v_readlane_b32 s45, v255, 48
	global_load_dword v35, v2, s[52:53] offset:200
	v_readlane_b32 s46, v255, 49
	v_readlane_b32 s47, v255, 50
	v_readlane_b32 s48, v255, 51
	v_readlane_b32 s49, v255, 52
	v_readlane_b32 s50, v255, 53
	v_readlane_b32 s51, v255, 54
	v_readlane_b32 s54, v255, 57
	v_readlane_b32 s55, v255, 58
	s_waitcnt vmcnt(0)
	v_mul_f32_e32 v108, v108, v35
; __device__ __forceinline__ void transpose_item(const float* W, int K, int N, bf16* WT, int mode, const float* gain, LAS float* scr, int item, int lane) {
;     const int nblk = N / 32, kb = item / nblk, nb = item % nblk, k0 = 64 * kb, n0 = 32 * nb;
; #pragma unroll
;     for (int i = 0; i < 32; ++i) { const int kk = 2 * i + (lane >> 5); float w = W[(size_t)(k0 + kk) * N + n0 + (lane & 31)]; if (gain) w *= gain[k0 + kk]; scr[kk * 33 + (lane & 31)] = w; }
.LBB0_176:
	v_or_b32_e32 v35, s21, v94
	v_mad_u64_u32 v[110:111], s[22:23], v35, s87, v[32:33]
	global_load_dword v35, v[110:111], off
	s_and_b64 vcc, exec, s[2:3]
	s_waitcnt vmcnt(1)
	ds_write_b32 v34, v108 offset:264
	s_cbranch_vccnz .LBB0_178
	v_readlane_b32 s40, v255, 43
	v_readlane_b32 s52, v255, 55
	v_readlane_b32 s53, v255, 56
	v_readlane_b32 s41, v255, 44
	v_readlane_b32 s42, v255, 45
	v_readlane_b32 s43, v255, 46
	v_readlane_b32 s44, v255, 47
	v_readlane_b32 s45, v255, 48
	global_load_dword v108, v2, s[52:53] offset:208
	v_readlane_b32 s46, v255, 49
	v_readlane_b32 s47, v255, 50
	v_readlane_b32 s48, v255, 51
	v_readlane_b32 s49, v255, 52
	v_readlane_b32 s50, v255, 53
	v_readlane_b32 s51, v255, 54
	v_readlane_b32 s54, v255, 57
	v_readlane_b32 s55, v255, 58
	s_waitcnt vmcnt(0)
	v_mul_f32_e32 v35, v35, v108
.LBB0_178:
	v_or_b32_e32 v108, s21, v95
	v_mad_u64_u32 v[108:109], s[22:23], v108, s87, v[32:33]
	global_load_dword v108, v[108:109], off
	s_and_b64 vcc, exec, s[2:3]
	s_waitcnt vmcnt(1)
	ds_write_b32 v34, v35 offset:528
	s_cbranch_vccnz .LBB0_180
	v_readlane_b32 s40, v255, 43
	v_readlane_b32 s52, v255, 55
	v_readlane_b32 s53, v255, 56
	v_readlane_b32 s41, v255, 44
	v_readlane_b32 s42, v255, 45
	v_readlane_b32 s43, v255, 46
	v_readlane_b32 s44, v255, 47
	v_readlane_b32 s45, v255, 48
	global_load_dword v35, v2, s[52:53] offset:216
	v_readlane_b32 s46, v255, 49
	v_readlane_b32 s47, v255, 50
	v_readlane_b32 s48, v255, 51
	v_readlane_b32 s49, v255, 52
	v_readlane_b32 s50, v255, 53
	v_readlane_b32 s51, v255, 54
	v_readlane_b32 s54, v255, 57
	v_readlane_b32 s55, v255, 58
	s_waitcnt vmcnt(0)
	v_mul_f32_e32 v108, v108, v35
.LBB0_180:
	v_or_b32_e32 v35, s21, v96
	v_mad_u64_u32 v[110:111], s[22:23], v35, s87, v[32:33]
	global_load_dword v35, v[110:111], off
	s_and_b64 vcc, exec, s[2:3]
	s_waitcnt vmcnt(1)
	ds_write_b32 v34, v108 offset:792
	s_cbranch_vccnz .LBB0_182
	v_readlane_b32 s40, v255, 43
	v_readlane_b32 s52, v255, 55
	v_readlane_b32 s53, v255, 56
	v_readlane_b32 s41, v255, 44
	v_readlane_b32 s42, v255, 45
	v_readlane_b32 s43, v255, 46
	v_readlane_b32 s44, v255, 47
	v_readlane_b32 s45, v255, 48
	global_load_dword v108, v2, s[52:53] offset:224
	v_readlane_b32 s46, v255, 49
	v_readlane_b32 s47, v255, 50
	v_readlane_b32 s48, v255, 51
	v_readlane_b32 s49, v255, 52
	v_readlane_b32 s50, v255, 53
	v_readlane_b32 s51, v255, 54
	v_readlane_b32 s54, v255, 57
	v_readlane_b32 s55, v255, 58
	s_waitcnt vmcnt(0)
	v_mul_f32_e32 v35, v35, v108
.LBB0_182:
	v_or_b32_e32 v108, s21, v97
	v_mad_u64_u32 v[108:109], s[22:23], v108, s87, v[32:33]
	global_load_dword v108, v[108:109], off
	s_and_b64 vcc, exec, s[2:3]
	s_waitcnt vmcnt(1)
	ds_write_b32 v34, v35 offset:1056
	s_cbranch_vccnz .LBB0_184
	v_readlane_b32 s40, v255, 43
	v_readlane_b32 s52, v255, 55
	v_readlane_b32 s53, v255, 56
	v_readlane_b32 s41, v255, 44
	v_readlane_b32 s42, v255, 45
	v_readlane_b32 s43, v255, 46
	v_readlane_b32 s44, v255, 47
	v_readlane_b32 s45, v255, 48
	global_load_dword v35, v2, s[52:53] offset:232
	v_readlane_b32 s46, v255, 49
	v_readlane_b32 s47, v255, 50
	v_readlane_b32 s48, v255, 51
	v_readlane_b32 s49, v255, 52
	v_readlane_b32 s50, v255, 53
	v_readlane_b32 s51, v255, 54
	v_readlane_b32 s54, v255, 57
	v_readlane_b32 s55, v255, 58
	s_waitcnt vmcnt(0)
	v_mul_f32_e32 v108, v108, v35
.LBB0_184:
	v_or_b32_e32 v35, s21, v98
	v_mad_u64_u32 v[110:111], s[22:23], v35, s87, v[32:33]
	global_load_dword v35, v[110:111], off
	s_and_b64 vcc, exec, s[2:3]
	s_waitcnt vmcnt(1)
	ds_write_b32 v34, v108 offset:1320
	s_cbranch_vccnz .LBB0_186
	v_readlane_b32 s40, v255, 43
	v_readlane_b32 s52, v255, 55
	v_readlane_b32 s53, v255, 56
	v_readlane_b32 s41, v255, 44
	v_readlane_b32 s42, v255, 45
	v_readlane_b32 s43, v255, 46
	v_readlane_b32 s44, v255, 47
	v_readlane_b32 s45, v255, 48
	global_load_dword v108, v2, s[52:53] offset:240
	v_readlane_b32 s46, v255, 49
	v_readlane_b32 s47, v255, 50
	v_readlane_b32 s48, v255, 51
	v_readlane_b32 s49, v255, 52
	v_readlane_b32 s50, v255, 53
	v_readlane_b32 s51, v255, 54
	v_readlane_b32 s54, v255, 57
	v_readlane_b32 s55, v255, 58
	s_waitcnt vmcnt(0)
	v_mul_f32_e32 v35, v35, v108
.LBB0_186:
	v_or_b32_e32 v108, s21, v99
	v_mad_u64_u32 v[32:33], s[22:23], v108, s87, v[32:33]
	global_load_dword v32, v[32:33], off
	s_and_b64 vcc, exec, s[2:3]
	s_waitcnt vmcnt(1)
	ds_write_b32 v34, v35 offset:1584
	s_cbranch_vccnz .LBB0_188
	v_readlane_b32 s40, v255, 43
	v_readlane_b32 s52, v255, 55
	v_readlane_b32 s53, v255, 56
	v_readlane_b32 s41, v255, 44
	v_readlane_b32 s42, v255, 45
	v_readlane_b32 s43, v255, 46
	v_readlane_b32 s44, v255, 47
	v_readlane_b32 s45, v255, 48
	global_load_dword v2, v2, s[52:53] offset:248
	v_readlane_b32 s46, v255, 49
	v_readlane_b32 s47, v255, 50
	v_readlane_b32 s48, v255, 51
	v_readlane_b32 s49, v255, 52
	v_readlane_b32 s50, v255, 53
	v_readlane_b32 s51, v255, 54
	v_readlane_b32 s54, v255, 57
	v_readlane_b32 s55, v255, 58
	s_waitcnt vmcnt(0)
	v_mul_f32_e32 v32, v32, v2

; #define TR(cnt, W, K_, N_, DST, MODE, GAIN) if (r < (cnt)) { transpose_item((W), (K_), (N_), (bf16*)(ws + (DST)), (MODE), (GAIN), scr, r, lane); continue; } r -= (cnt);
; __device__ __forceinline__ void transpose_item(const float* W, int K, int N, bf16* WT, int mode, const float* gain, LAS float* scr, int item, int lane) {
;     const int nblk = N / 32, kb = item / nblk, nb = item % nblk, k0 = 64 * kb, n0 = 32 * nb;
; #pragma unroll
;     for (int i = 0; i < 32; ++i) { const int kk = 2 * i + (lane >> 5); float w = W[(size_t)(k0 + kk) * N + n0 + (lane & 31)]; if (gain) w *= gain[k0 + kk]; scr[kk * 33 + (lane & 31)] = w; }
; __device__ __forceinline__ void p0_prologue(const Args& a, LAS unsigned char* lds, int vcu, int G, int wave, int lane) {
;     ...
;         TR(T_GU, a.in[I_FWG] + (size_t)D * DFF, D, DFF, WS_WGU1, 1, a.in[I_FNG] + D)
;         TR(T_GU, a.in[I_FWU] + (size_t)D * DFF, D, DFF, WS_WGU1, 2, a.in[I_FNG] + D)
.LBB0_190:
	s_andn2_b64 vcc, exec, s[2:3]
	s_cbranch_vccnz .LBB0_256
	s_add_i32 s2, s88, 0xf200
	s_and_b32 s3, s2, 0xffff
	s_mul_i32 s3, s3, 0xba2f
	s_lshr_b32 s18, s3, 22
	s_mul_i32 s19, s18, 0x58
	s_sub_i32 s2, s2, s19
	s_lshr_b32 s3, s3, 16
	s_and_b32 s19, s2, 0xffff
	s_and_b32 s21, s3, 0xffc0
	s_lshl_b32 s56, s19, 7
	v_lshl_add_u64 v[32:33], v[12:13], 0, s[56:57]
	v_or_b32_e32 v34, s21, v0
	v_mad_u64_u32 v[108:109], s[2:3], v34, s87, v[32:33]
	global_load_dword v2, v[108:109], off
	v_cndmask_b32_e64 v35, 0, 1, s[24:25]
	v_cmp_ne_u32_e64 s[2:3], 1, v35
	s_andn2_b64 vcc, exec, s[24:25]
	s_cbranch_vccnz .LBB0_193
	v_readlane_b32 s40, v255, 43
	v_lshlrev_b32_e32 v34, 2, v34
	v_readlane_b32 s52, v255, 55
	v_readlane_b32 s53, v255, 56
	v_readlane_b32 s41, v255, 44
	v_readlane_b32 s42, v255, 45
	v_readlane_b32 s43, v255, 46
	v_readlane_b32 s44, v255, 47
	v_readlane_b32 s45, v255, 48
	global_load_dword v34, v34, s[52:53]
	v_readlane_b32 s46, v255, 49
	v_readlane_b32 s47, v255, 50
	v_readlane_b32 s48, v255, 51
	v_readlane_b32 s49, v255, 52
	v_readlane_b32 s50, v255, 53
	v_readlane_b32 s51, v255, 54
	v_readlane_b32 s54, v255, 57
	v_readlane_b32 s55, v255, 58
	s_waitcnt vmcnt(0)
	v_mul_f32_e32 v2, v2, v34

; #define TR(cnt, W, K_, N_, DST, MODE, GAIN) if (r < (cnt)) { transpose_item((W), (K_), (N_), (bf16*)(ws + (DST)), (MODE), (GAIN), scr, r, lane); continue; } r -= (cnt);
; __device__ __forceinline__ void transpose_item(const float* W, int K, int N, bf16* WT, int mode, const float* gain, LAS float* scr, int item, int lane) {
;     const int nblk = N / 32, kb = item / nblk, nb = item % nblk, k0 = 64 * kb, n0 = 32 * nb;
; #pragma unroll
;     for (int i = 0; i < 32; ++i) { const int kk = 2 * i + (lane >> 5); float w = W[(size_t)(k0 + kk) * N + n0 + (lane & 31)]; if (gain) w *= gain[k0 + kk]; scr[kk * 33 + (lane & 31)] = w; }
; __device__ __forceinline__ void p0_prologue(const Args& a, LAS unsigned char* lds, int vcu, int G, int wave, int lane) {
;     ...
;         TR(T_QKV, a.in[I_AWQKV], D, 3 * D, WS_WQKV, 4, a.in[I_ANG])
.LBB0_260:
	s_andn2_b64 vcc, exec, s[2:3]
	s_cbranch_vccnz .LBB0_326
	s_add_i32 s2, s88, 0xfa00
	s_and_b32 s3, s2, 0xffff
	s_mul_i32 s3, s3, 0xaaab
	s_lshr_b32 s18, s3, 22
	s_mul_i32 s19, s18, 0x60
	s_sub_i32 s2, s2, s19
	s_lshr_b32 s3, s3, 16
	s_and_b32 s19, s2, 0xffff
	s_and_b32 s21, s3, 0xffc0
	s_lshl_b32 s56, s19, 7
	v_lshl_add_u64 v[32:33], v[26:27], 0, s[56:57]
	v_or_b32_e32 v34, s21, v0
	v_mad_u64_u32 v[108:109], s[2:3], v34, s93, v[32:33]
	global_load_dword v2, v[108:109], off
	v_cndmask_b32_e64 v35, 0, 1, s[30:31]
	v_cmp_ne_u32_e64 s[2:3], 1, v35
	s_andn2_b64 vcc, exec, s[30:31]
	s_cbranch_vccnz .LBB0_263
	v_readlane_b32 s40, v255, 27
	v_lshlrev_b32_e32 v34, 2, v34
	v_readlane_b32 s46, v255, 33
	v_readlane_b32 s47, v255, 34
	v_readlane_b32 s41, v255, 28
	v_readlane_b32 s42, v255, 29
	v_readlane_b32 s43, v255, 30
	v_readlane_b32 s44, v255, 31
	v_readlane_b32 s45, v255, 32
	global_load_dword v34, v34, s[46:47]
	v_readlane_b32 s48, v255, 35
	v_readlane_b32 s49, v255, 36
	v_readlane_b32 s50, v255, 37
	v_readlane_b32 s51, v255, 38
	v_readlane_b32 s52, v255, 39
	v_readlane_b32 s53, v255, 40
	v_readlane_b32 s54, v255, 41
	v_readlane_b32 s55, v255, 42
	s_waitcnt vmcnt(0)
	v_mul_f32_e32 v2, v2, v34
.LBB0_263:
	v_or_b32_e32 v34, s21, v38
	v_mad_u64_u32 v[34:35], s[22:23], v34, s93, v[32:33]
	global_load_dword v34, v[34:35], off
	v_add_u32_e32 v35, v36, v37
	s_waitcnt vmcnt(1)
	ds_write_b32 v35, v2
	s_and_b64 vcc, exec, s[2:3]
	v_add_lshl_u32 v2, v0, s21, 2
	s_cbranch_vccnz .LBB0_265
	v_readlane_b32 s40, v255, 27
	v_readlane_b32 s46, v255, 33
	v_readlane_b32 s47, v255, 34
	v_readlane_b32 s41, v255, 28
	v_readlane_b32 s42, v255, 29
	v_readlane_b32 s43, v255, 30
	v_readlane_b32 s44, v255, 31
	v_readlane_b32 s45, v255, 32
	global_load_dword v35, v2, s[46:47] offset:8
	v_readlane_b32 s48, v255, 35
	v_readlane_b32 s49, v255, 36
	v_readlane_b32 s50, v255, 37
	v_readlane_b32 s51, v255, 38
	v_readlane_b32 s52, v255, 39
	v_readlane_b32 s53, v255, 40
	v_readlane_b32 s54, v255, 41
	v_readlane_b32 s55, v255, 42
	s_waitcnt vmcnt(0)
	v_mul_f32_e32 v34, v34, v35
.LBB0_265:
	v_or_b32_e32 v35, s21, v70
	v_mad_u64_u32 v[108:109], s[22:23], v35, s93, v[32:33]
	global_load_dword v35, v[108:109], off
	v_add_u32_e32 v108, v36, v39
	s_and_b64 vcc, exec, s[2:3]
	s_waitcnt vmcnt(1)
	ds_write_b32 v108, v34
	s_cbranch_vccnz .LBB0_267
	v_readlane_b32 s40, v255, 27
	v_readlane_b32 s46, v255, 33
	v_readlane_b32 s47, v255, 34
	v_readlane_b32 s41, v255, 28
	v_readlane_b32 s42, v255, 29
	v_readlane_b32 s43, v255, 30
	v_readlane_b32 s44, v255, 31
	v_readlane_b32 s45, v255, 32
	global_load_dword v34, v2, s[46:47] offset:16
	v_readlane_b32 s48, v255, 35
	v_readlane_b32 s49, v255, 36
	v_readlane_b32 s50, v255, 37
	v_readlane_b32 s51, v255, 38
	v_readlane_b32 s52, v255, 39
	v_readlane_b32 s53, v255, 40
	v_readlane_b32 s54, v255, 41
	v_readlane_b32 s55, v255, 42
	s_waitcnt vmcnt(0)
	v_mul_f32_e32 v35, v35, v34
.LBB0_267:
	v_or_b32_e32 v34, s21, v71
	v_mad_u64_u32 v[108:109], s[22:23], v34, s93, v[32:33]
	global_load_dword v34, v[108:109], off
	v_add_u32_e32 v108, v36, v40
	s_and_b64 vcc, exec, s[2:3]
	s_waitcnt vmcnt(1)
	ds_write_b32 v108, v35
	s_cbranch_vccnz .LBB0_269
	v_readlane_b32 s40, v255, 27
	v_readlane_b32 s46, v255, 33
	v_readlane_b32 s47, v255, 34
	v_readlane_b32 s41, v255, 28
	v_readlane_b32 s42, v255, 29
	v_readlane_b32 s43, v255, 30
	v_readlane_b32 s44, v255, 31
	v_readlane_b32 s45, v255, 32
	global_load_dword v35, v2, s[46:47] offset:24
	v_readlane_b32 s48, v255, 35
	v_readlane_b32 s49, v255, 36
	v_readlane_b32 s50, v255, 37
	v_readlane_b32 s51, v255, 38
	v_readlane_b32 s52, v255, 39
	v_readlane_b32 s53, v255, 40
	v_readlane_b32 s54, v255, 41
	v_readlane_b32 s55, v255, 42
	s_waitcnt vmcnt(0)
	v_mul_f32_e32 v34, v34, v35
.LBB0_269:
	v_or_b32_e32 v35, s21, v72
	v_mad_u64_u32 v[108:109], s[22:23], v35, s93, v[32:33]
	global_load_dword v35, v[108:109], off
	v_add_u32_e32 v108, v36, v41
	s_and_b64 vcc, exec, s[2:3]
	s_waitcnt vmcnt(1)
	ds_write_b32 v108, v34
	s_cbranch_vccnz .LBB0_271
	v_readlane_b32 s40, v255, 27
	v_readlane_b32 s46, v255, 33
	v_readlane_b32 s47, v255, 34
	v_readlane_b32 s41, v255, 28
	v_readlane_b32 s42, v255, 29
	v_readlane_b32 s43, v255, 30
	v_readlane_b32 s44, v255, 31
	v_readlane_b32 s45, v255, 32
	global_load_dword v34, v2, s[46:47] offset:32
	v_readlane_b32 s48, v255, 35
	v_readlane_b32 s49, v255, 36
	v_readlane_b32 s50, v255, 37
	v_readlane_b32 s51, v255, 38
	v_readlane_b32 s52, v255, 39
	v_readlane_b32 s53, v255, 40
	v_readlane_b32 s54, v255, 41
	v_readlane_b32 s55, v255, 42
	s_waitcnt vmcnt(0)
	v_mul_f32_e32 v35, v35, v34
.LBB0_271:
	v_or_b32_e32 v34, s21, v73
	v_mad_u64_u32 v[108:109], s[22:23], v34, s93, v[32:33]
	global_load_dword v34, v[108:109], off
	v_add_u32_e32 v108, v36, v42
	s_and_b64 vcc, exec, s[2:3]
	s_waitcnt vmcnt(1)
	ds_write_b32 v108, v35
	s_cbranch_vccnz .LBB0_273
	v_readlane_b32 s40, v255, 27
	v_readlane_b32 s46, v255, 33
	v_readlane_b32 s47, v255, 34
	v_readlane_b32 s41, v255, 28
	v_readlane_b32 s42, v255, 29
	v_readlane_b32 s43, v255, 30
	v_readlane_b32 s44, v255, 31
	v_readlane_b32 s45, v255, 32
	global_load_dword v35, v2, s[46:47] offset:40
	v_readlane_b32 s48, v255, 35
	v_readlane_b32 s49, v255, 36
	v_readlane_b32 s50, v255, 37
	v_readlane_b32 s51, v255, 38
	v_readlane_b32 s52, v255, 39
	v_readlane_b32 s53, v255, 40
	v_readlane_b32 s54, v255, 41
	v_readlane_b32 s55, v255, 42
	s_waitcnt vmcnt(0)
	v_mul_f32_e32 v34, v34, v35
; __device__ __forceinline__ void transpose_item(const float* W, int K, int N, bf16* WT, int mode, const float* gain, LAS float* scr, int item, int lane) {
;     const int nblk = N / 32, kb = item / nblk, nb = item % nblk, k0 = 64 * kb, n0 = 32 * nb;
; #pragma unroll
;     for (int i = 0; i < 32; ++i) { const int kk = 2 * i + (lane >> 5); float w = W[(size_t)(k0 + kk) * N + n0 + (lane & 31)]; if (gain) w *= gain[k0 + kk]; scr[kk * 33 + (lane & 31)] = w; }
.LBB0_273:
	v_or_b32_e32 v35, s21, v74
	v_mad_u64_u32 v[108:109], s[22:23], v35, s93, v[32:33]
	global_load_dword v35, v[108:109], off
	v_add_u32_e32 v108, v36, v43
	s_and_b64 vcc, exec, s[2:3]
	s_waitcnt vmcnt(1)
	ds_write_b32 v108, v34
	s_cbranch_vccnz .LBB0_275
	v_readlane_b32 s40, v255, 27
	v_readlane_b32 s46, v255, 33
	v_readlane_b32 s47, v255, 34
	v_readlane_b32 s41, v255, 28
	v_readlane_b32 s42, v255, 29
	v_readlane_b32 s43, v255, 30
	v_readlane_b32 s44, v255, 31
	v_readlane_b32 s45, v255, 32
	global_load_dword v34, v2, s[46:47] offset:48
	v_readlane_b32 s48, v255, 35
	v_readlane_b32 s49, v255, 36
	v_readlane_b32 s50, v255, 37
	v_readlane_b32 s51, v255, 38
	v_readlane_b32 s52, v255, 39
	v_readlane_b32 s53, v255, 40
	v_readlane_b32 s54, v255, 41
	v_readlane_b32 s55, v255, 42
	s_waitcnt vmcnt(0)
	v_mul_f32_e32 v35, v35, v34
.LBB0_275:
	v_or_b32_e32 v34, s21, v75
	v_mad_u64_u32 v[108:109], s[22:23], v34, s93, v[32:33]
	global_load_dword v34, v[108:109], off
	v_add_u32_e32 v108, v36, v44
	s_and_b64 vcc, exec, s[2:3]
	s_waitcnt vmcnt(1)
	ds_write_b32 v108, v35
	s_cbranch_vccnz .LBB0_277
	v_readlane_b32 s40, v255, 27
	v_readlane_b32 s46, v255, 33
	v_readlane_b32 s47, v255, 34
	v_readlane_b32 s41, v255, 28
	v_readlane_b32 s42, v255, 29
	v_readlane_b32 s43, v255, 30
	v_readlane_b32 s44, v255, 31
	v_readlane_b32 s45, v255, 32
	global_load_dword v35, v2, s[46:47] offset:56
	v_readlane_b32 s48, v255, 35
	v_readlane_b32 s49, v255, 36
	v_readlane_b32 s50, v255, 37
	v_readlane_b32 s51, v255, 38
	v_readlane_b32 s52, v255, 39
	v_readlane_b32 s53, v255, 40
	v_readlane_b32 s54, v255, 41
	v_readlane_b32 s55, v255, 42
	s_waitcnt vmcnt(0)
	v_mul_f32_e32 v34, v34, v35
.LBB0_277:
	v_or_b32_e32 v35, s21, v76
	v_mad_u64_u32 v[108:109], s[22:23], v35, s93, v[32:33]
	global_load_dword v35, v[108:109], off
	v_add_u32_e32 v108, v36, v45
	s_and_b64 vcc, exec, s[2:3]
	s_waitcnt vmcnt(1)
	ds_write_b32 v108, v34
	s_cbranch_vccnz .LBB0_279
	v_readlane_b32 s40, v255, 27
	v_readlane_b32 s46, v255, 33
	v_readlane_b32 s47, v255, 34
	v_readlane_b32 s41, v255, 28
	v_readlane_b32 s42, v255, 29
	v_readlane_b32 s43, v255, 30
	v_readlane_b32 s44, v255, 31
	v_readlane_b32 s45, v255, 32
	global_load_dword v34, v2, s[46:47] offset:64
	v_readlane_b32 s48, v255, 35
	v_readlane_b32 s49, v255, 36
	v_readlane_b32 s50, v255, 37
	v_readlane_b32 s51, v255, 38
	v_readlane_b32 s52, v255, 39
	v_readlane_b32 s53, v255, 40
	v_readlane_b32 s54, v255, 41
	v_readlane_b32 s55, v255, 42
	s_waitcnt vmcnt(0)
	v_mul_f32_e32 v35, v35, v34
.LBB0_279:
	v_or_b32_e32 v34, s21, v77
	v_mad_u64_u32 v[108:109], s[22:23], v34, s93, v[32:33]
	global_load_dword v34, v[108:109], off
	v_add_u32_e32 v108, v36, v46
	s_and_b64 vcc, exec, s[2:3]
	s_waitcnt vmcnt(1)
	ds_write_b32 v108, v35
	s_cbranch_vccnz .LBB0_281
	v_readlane_b32 s40, v255, 27
	v_readlane_b32 s46, v255, 33
	v_readlane_b32 s47, v255, 34
	v_readlane_b32 s41, v255, 28
	v_readlane_b32 s42, v255, 29
	v_readlane_b32 s43, v255, 30
	v_readlane_b32 s44, v255, 31
	v_readlane_b32 s45, v255, 32
	global_load_dword v35, v2, s[46:47] offset:72
	v_readlane_b32 s48, v255, 35
	v_readlane_b32 s49, v255, 36
	v_readlane_b32 s50, v255, 37
	v_readlane_b32 s51, v255, 38
	v_readlane_b32 s52, v255, 39
	v_readlane_b32 s53, v255, 40
	v_readlane_b32 s54, v255, 41
	v_readlane_b32 s55, v255, 42
	s_waitcnt vmcnt(0)
	v_mul_f32_e32 v34, v34, v35
.LBB0_281:
	v_or_b32_e32 v35, s21, v78
	v_mad_u64_u32 v[108:109], s[22:23], v35, s93, v[32:33]
	global_load_dword v35, v[108:109], off
	v_add_u32_e32 v108, v36, v47
	s_and_b64 vcc, exec, s[2:3]
	s_waitcnt vmcnt(1)
	ds_write_b32 v108, v34
	s_cbranch_vccnz .LBB0_283
	v_readlane_b32 s40, v255, 27
	v_readlane_b32 s46, v255, 33
	v_readlane_b32 s47, v255, 34
	v_readlane_b32 s41, v255, 28
	v_readlane_b32 s42, v255, 29
	v_readlane_b32 s43, v255, 30
	v_readlane_b32 s44, v255, 31
	v_readlane_b32 s45, v255, 32
	global_load_dword v34, v2, s[46:47] offset:80
	v_readlane_b32 s48, v255, 35
	v_readlane_b32 s49, v255, 36
	v_readlane_b32 s50, v255, 37
	v_readlane_b32 s51, v255, 38
	v_readlane_b32 s52, v255, 39
	v_readlane_b32 s53, v255, 40
	v_readlane_b32 s54, v255, 41
	v_readlane_b32 s55, v255, 42
	s_waitcnt vmcnt(0)
	v_mul_f32_e32 v35, v35, v34
.LBB0_283:
	v_or_b32_e32 v34, s21, v79
	v_mad_u64_u32 v[108:109], s[22:23], v34, s93, v[32:33]
	global_load_dword v34, v[108:109], off
	v_add_u32_e32 v108, v36, v48
	s_and_b64 vcc, exec, s[2:3]
	s_waitcnt vmcnt(1)
	ds_write_b32 v108, v35
	s_cbranch_vccnz .LBB0_285
	v_readlane_b32 s40, v255, 27
	v_readlane_b32 s46, v255, 33
	v_readlane_b32 s47, v255, 34
	v_readlane_b32 s41, v255, 28
	v_readlane_b32 s42, v255, 29
	v_readlane_b32 s43, v255, 30
	v_readlane_b32 s44, v255, 31
	v_readlane_b32 s45, v255, 32
	global_load_dword v35, v2, s[46:47] offset:88
	v_readlane_b32 s48, v255, 35
	v_readlane_b32 s49, v255, 36
	v_readlane_b32 s50, v255, 37
	v_readlane_b32 s51, v255, 38
	v_readlane_b32 s52, v255, 39
	v_readlane_b32 s53, v255, 40
	v_readlane_b32 s54, v255, 41
	v_readlane_b32 s55, v255, 42
	s_waitcnt vmcnt(0)
	v_mul_f32_e32 v34, v34, v35
.LBB0_285:
	v_or_b32_e32 v35, s21, v80
	v_mad_u64_u32 v[108:109], s[22:23], v35, s93, v[32:33]
	global_load_dword v35, v[108:109], off
	v_add_u32_e32 v108, v36, v49
	s_and_b64 vcc, exec, s[2:3]
	s_waitcnt vmcnt(1)
	ds_write_b32 v108, v34
	s_cbranch_vccnz .LBB0_287
	v_readlane_b32 s40, v255, 27
	v_readlane_b32 s46, v255, 33
	v_readlane_b32 s47, v255, 34
	v_readlane_b32 s41, v255, 28
	v_readlane_b32 s42, v255, 29
	v_readlane_b32 s43, v255, 30
	v_readlane_b32 s44, v255, 31
	v_readlane_b32 s45, v255, 32
	global_load_dword v34, v2, s[46:47] offset:96
	v_readlane_b32 s48, v255, 35
	v_readlane_b32 s49, v255, 36
	v_readlane_b32 s50, v255, 37
	v_readlane_b32 s51, v255, 38
	v_readlane_b32 s52, v255, 39
	v_readlane_b32 s53, v255, 40
	v_readlane_b32 s54, v255, 41
	v_readlane_b32 s55, v255, 42
	s_waitcnt vmcnt(0)
	v_mul_f32_e32 v35, v35, v34
; __device__ __forceinline__ void transpose_item(const float* W, int K, int N, bf16* WT, int mode, const float* gain, LAS float* scr, int item, int lane) {
;     const int nblk = N / 32, kb = item / nblk, nb = item % nblk, k0 = 64 * kb, n0 = 32 * nb;
; #pragma unroll
;     for (int i = 0; i < 32; ++i) { const int kk = 2 * i + (lane >> 5); float w = W[(size_t)(k0 + kk) * N + n0 + (lane & 31)]; if (gain) w *= gain[k0 + kk]; scr[kk * 33 + (lane & 31)] = w; }
.LBB0_287:
	v_or_b32_e32 v34, s21, v81
	v_mad_u64_u32 v[108:109], s[22:23], v34, s93, v[32:33]
	global_load_dword v34, v[108:109], off
	v_add_u32_e32 v108, v36, v50
	s_and_b64 vcc, exec, s[2:3]
	s_waitcnt vmcnt(1)
	ds_write_b32 v108, v35
	s_cbranch_vccnz .LBB0_289
	v_readlane_b32 s40, v255, 27
	v_readlane_b32 s46, v255, 33
	v_readlane_b32 s47, v255, 34
	v_readlane_b32 s41, v255, 28
	v_readlane_b32 s42, v255, 29
	v_readlane_b32 s43, v255, 30
	v_readlane_b32 s44, v255, 31
	v_readlane_b32 s45, v255, 32
	global_load_dword v35, v2, s[46:47] offset:104
	v_readlane_b32 s48, v255, 35
	v_readlane_b32 s49, v255, 36
	v_readlane_b32 s50, v255, 37
	v_readlane_b32 s51, v255, 38
	v_readlane_b32 s52, v255, 39
	v_readlane_b32 s53, v255, 40
	v_readlane_b32 s54, v255, 41
	v_readlane_b32 s55, v255, 42
	s_waitcnt vmcnt(0)
	v_mul_f32_e32 v34, v34, v35
.LBB0_289:
	v_or_b32_e32 v35, s21, v82
	v_mad_u64_u32 v[108:109], s[22:23], v35, s93, v[32:33]
	global_load_dword v35, v[108:109], off
	v_add_u32_e32 v108, v36, v51
	s_and_b64 vcc, exec, s[2:3]
	s_waitcnt vmcnt(1)
	ds_write_b32 v108, v34
	s_cbranch_vccnz .LBB0_291
	v_readlane_b32 s40, v255, 27
	v_readlane_b32 s46, v255, 33
	v_readlane_b32 s47, v255, 34
	v_readlane_b32 s41, v255, 28
	v_readlane_b32 s42, v255, 29
	v_readlane_b32 s43, v255, 30
	v_readlane_b32 s44, v255, 31
	v_readlane_b32 s45, v255, 32
	global_load_dword v34, v2, s[46:47] offset:112
	v_readlane_b32 s48, v255, 35
	v_readlane_b32 s49, v255, 36
	v_readlane_b32 s50, v255, 37
	v_readlane_b32 s51, v255, 38
	v_readlane_b32 s52, v255, 39
	v_readlane_b32 s53, v255, 40
	v_readlane_b32 s54, v255, 41
	v_readlane_b32 s55, v255, 42
	s_waitcnt vmcnt(0)
	v_mul_f32_e32 v35, v35, v34
.LBB0_291:
	v_or_b32_e32 v34, s21, v83
	v_mad_u64_u32 v[108:109], s[22:23], v34, s93, v[32:33]
	global_load_dword v34, v[108:109], off
	v_add_u32_e32 v108, v36, v52
	s_and_b64 vcc, exec, s[2:3]
	s_waitcnt vmcnt(1)
	ds_write_b32 v108, v35
	s_cbranch_vccnz .LBB0_293
	v_readlane_b32 s40, v255, 27
	v_readlane_b32 s46, v255, 33
	v_readlane_b32 s47, v255, 34
	v_readlane_b32 s41, v255, 28
	v_readlane_b32 s42, v255, 29
	v_readlane_b32 s43, v255, 30
	v_readlane_b32 s44, v255, 31
	v_readlane_b32 s45, v255, 32
	global_load_dword v35, v2, s[46:47] offset:120
	v_readlane_b32 s48, v255, 35
	v_readlane_b32 s49, v255, 36
	v_readlane_b32 s50, v255, 37
	v_readlane_b32 s51, v255, 38
	v_readlane_b32 s52, v255, 39
	v_readlane_b32 s53, v255, 40
	v_readlane_b32 s54, v255, 41
	v_readlane_b32 s55, v255, 42
	s_waitcnt vmcnt(0)
	v_mul_f32_e32 v34, v34, v35
.LBB0_293:
	v_or_b32_e32 v35, s21, v84
	v_mad_u64_u32 v[108:109], s[22:23], v35, s93, v[32:33]
	global_load_dword v35, v[108:109], off
	v_add_u32_e32 v108, v36, v53
	s_and_b64 vcc, exec, s[2:3]
	s_waitcnt vmcnt(1)
	ds_write_b32 v108, v34
	s_cbranch_vccnz .LBB0_295
	v_readlane_b32 s40, v255, 27
	v_readlane_b32 s46, v255, 33
	v_readlane_b32 s47, v255, 34
	v_readlane_b32 s41, v255, 28
	v_readlane_b32 s42, v255, 29
	v_readlane_b32 s43, v255, 30
	v_readlane_b32 s44, v255, 31
	v_readlane_b32 s45, v255, 32
	global_load_dword v34, v2, s[46:47] offset:128
	v_readlane_b32 s48, v255, 35
	v_readlane_b32 s49, v255, 36
	v_readlane_b32 s50, v255, 37
	v_readlane_b32 s51, v255, 38
	v_readlane_b32 s52, v255, 39
	v_readlane_b32 s53, v255, 40
	v_readlane_b32 s54, v255, 41
	v_readlane_b32 s55, v255, 42
	s_waitcnt vmcnt(0)
	v_mul_f32_e32 v35, v35, v34
.LBB0_295:
	v_or_b32_e32 v34, s21, v85
	v_mad_u64_u32 v[108:109], s[22:23], v34, s93, v[32:33]
	global_load_dword v34, v[108:109], off
	v_add_u32_e32 v108, v36, v54
	s_and_b64 vcc, exec, s[2:3]
	s_waitcnt vmcnt(1)
	ds_write_b32 v108, v35
	s_cbranch_vccnz .LBB0_297
	v_readlane_b32 s40, v255, 27
	v_readlane_b32 s46, v255, 33
	v_readlane_b32 s47, v255, 34
	v_readlane_b32 s41, v255, 28
	v_readlane_b32 s42, v255, 29
	v_readlane_b32 s43, v255, 30
	v_readlane_b32 s44, v255, 31
	v_readlane_b32 s45, v255, 32
	global_load_dword v35, v2, s[46:47] offset:136
	v_readlane_b32 s48, v255, 35
	v_readlane_b32 s49, v255, 36
	v_readlane_b32 s50, v255, 37
	v_readlane_b32 s51, v255, 38
	v_readlane_b32 s52, v255, 39
	v_readlane_b32 s53, v255, 40
	v_readlane_b32 s54, v255, 41
	v_readlane_b32 s55, v255, 42
	s_waitcnt vmcnt(0)
	v_mul_f32_e32 v34, v34, v35
.LBB0_297:
	v_or_b32_e32 v35, s21, v86
	v_mad_u64_u32 v[108:109], s[22:23], v35, s93, v[32:33]
	global_load_dword v35, v[108:109], off
	v_add_u32_e32 v108, v36, v55
	s_and_b64 vcc, exec, s[2:3]
	s_waitcnt vmcnt(1)
	ds_write_b32 v108, v34
	s_cbranch_vccnz .LBB0_299
	v_readlane_b32 s40, v255, 27
	v_readlane_b32 s46, v255, 33
	v_readlane_b32 s47, v255, 34
	v_readlane_b32 s41, v255, 28
	v_readlane_b32 s42, v255, 29
	v_readlane_b32 s43, v255, 30
	v_readlane_b32 s44, v255, 31
	v_readlane_b32 s45, v255, 32
	global_load_dword v34, v2, s[46:47] offset:144
	v_readlane_b32 s48, v255, 35
	v_readlane_b32 s49, v255, 36
	v_readlane_b32 s50, v255, 37
	v_readlane_b32 s51, v255, 38
	v_readlane_b32 s52, v255, 39
	v_readlane_b32 s53, v255, 40
	v_readlane_b32 s54, v255, 41
	v_readlane_b32 s55, v255, 42
	s_waitcnt vmcnt(0)
	v_mul_f32_e32 v35, v35, v34
.LBB0_299:
	v_or_b32_e32 v34, s21, v87
	v_mad_u64_u32 v[108:109], s[22:23], v34, s93, v[32:33]
	global_load_dword v34, v[108:109], off
	v_add_u32_e32 v108, v36, v56
	s_and_b64 vcc, exec, s[2:3]
	s_waitcnt vmcnt(1)
	ds_write_b32 v108, v35
	s_cbranch_vccnz .LBB0_301
	v_readlane_b32 s40, v255, 27
	v_readlane_b32 s46, v255, 33
	v_readlane_b32 s47, v255, 34
	v_readlane_b32 s41, v255, 28
	v_readlane_b32 s42, v255, 29
	v_readlane_b32 s43, v255, 30
	v_readlane_b32 s44, v255, 31
	v_readlane_b32 s45, v255, 32
	global_load_dword v35, v2, s[46:47] offset:152
	v_readlane_b32 s48, v255, 35
	v_readlane_b32 s49, v255, 36
	v_readlane_b32 s50, v255, 37
	v_readlane_b32 s51, v255, 38
	v_readlane_b32 s52, v255, 39
	v_readlane_b32 s53, v255, 40
	v_readlane_b32 s54, v255, 41
	v_readlane_b32 s55, v255, 42
	s_waitcnt vmcnt(0)
	v_mul_f32_e32 v34, v34, v35
; __device__ __forceinline__ void transpose_item(const float* W, int K, int N, bf16* WT, int mode, const float* gain, LAS float* scr, int item, int lane) {
;     const int nblk = N / 32, kb = item / nblk, nb = item % nblk, k0 = 64 * kb, n0 = 32 * nb;
; #pragma unroll
;     for (int i = 0; i < 32; ++i) { const int kk = 2 * i + (lane >> 5); float w = W[(size_t)(k0 + kk) * N + n0 + (lane & 31)]; if (gain) w *= gain[k0 + kk]; scr[kk * 33 + (lane & 31)] = w; }
.LBB0_301:
	v_or_b32_e32 v35, s21, v88
	v_mad_u64_u32 v[108:109], s[22:23], v35, s93, v[32:33]
	global_load_dword v35, v[108:109], off
	v_add_u32_e32 v108, v36, v57
	s_and_b64 vcc, exec, s[2:3]
	s_waitcnt vmcnt(1)
	ds_write_b32 v108, v34
	s_cbranch_vccnz .LBB0_303
	v_readlane_b32 s40, v255, 27
	v_readlane_b32 s46, v255, 33
	v_readlane_b32 s47, v255, 34
	v_readlane_b32 s41, v255, 28
	v_readlane_b32 s42, v255, 29
	v_readlane_b32 s43, v255, 30
	v_readlane_b32 s44, v255, 31
	v_readlane_b32 s45, v255, 32
	global_load_dword v34, v2, s[46:47] offset:160
	v_readlane_b32 s48, v255, 35
	v_readlane_b32 s49, v255, 36
	v_readlane_b32 s50, v255, 37
	v_readlane_b32 s51, v255, 38
	v_readlane_b32 s52, v255, 39
	v_readlane_b32 s53, v255, 40
	v_readlane_b32 s54, v255, 41
	v_readlane_b32 s55, v255, 42
	s_waitcnt vmcnt(0)
	v_mul_f32_e32 v35, v35, v34
.LBB0_303:
	v_or_b32_e32 v34, s21, v89
	v_mad_u64_u32 v[108:109], s[22:23], v34, s93, v[32:33]
	global_load_dword v34, v[108:109], off
	v_add_u32_e32 v108, v36, v58
	s_and_b64 vcc, exec, s[2:3]
	s_waitcnt vmcnt(1)
	ds_write_b32 v108, v35
	s_cbranch_vccnz .LBB0_305
	v_readlane_b32 s40, v255, 27
	v_readlane_b32 s46, v255, 33
	v_readlane_b32 s47, v255, 34
	v_readlane_b32 s41, v255, 28
	v_readlane_b32 s42, v255, 29
	v_readlane_b32 s43, v255, 30
	v_readlane_b32 s44, v255, 31
	v_readlane_b32 s45, v255, 32
	global_load_dword v35, v2, s[46:47] offset:168
	v_readlane_b32 s48, v255, 35
	v_readlane_b32 s49, v255, 36
	v_readlane_b32 s50, v255, 37
	v_readlane_b32 s51, v255, 38
	v_readlane_b32 s52, v255, 39
	v_readlane_b32 s53, v255, 40
	v_readlane_b32 s54, v255, 41
	v_readlane_b32 s55, v255, 42
	s_waitcnt vmcnt(0)
	v_mul_f32_e32 v34, v34, v35
.LBB0_305:
	v_or_b32_e32 v35, s21, v90
	v_mad_u64_u32 v[108:109], s[22:23], v35, s93, v[32:33]
	global_load_dword v35, v[108:109], off
	v_add_u32_e32 v108, v36, v59
	s_and_b64 vcc, exec, s[2:3]
	s_waitcnt vmcnt(1)
	ds_write_b32 v108, v34
	s_cbranch_vccnz .LBB0_307
	v_readlane_b32 s40, v255, 27
	v_readlane_b32 s46, v255, 33
	v_readlane_b32 s47, v255, 34
	v_readlane_b32 s41, v255, 28
	v_readlane_b32 s42, v255, 29
	v_readlane_b32 s43, v255, 30
	v_readlane_b32 s44, v255, 31
	v_readlane_b32 s45, v255, 32
	global_load_dword v34, v2, s[46:47] offset:176
	v_readlane_b32 s48, v255, 35
	v_readlane_b32 s49, v255, 36
	v_readlane_b32 s50, v255, 37
	v_readlane_b32 s51, v255, 38
	v_readlane_b32 s52, v255, 39
	v_readlane_b32 s53, v255, 40
	v_readlane_b32 s54, v255, 41
	v_readlane_b32 s55, v255, 42
	s_waitcnt vmcnt(0)
	v_mul_f32_e32 v35, v35, v34
.LBB0_307:
	v_or_b32_e32 v34, s21, v91
	v_mad_u64_u32 v[108:109], s[22:23], v34, s93, v[32:33]
	global_load_dword v34, v[108:109], off
	v_add_u32_e32 v108, v36, v60
	s_and_b64 vcc, exec, s[2:3]
	s_waitcnt vmcnt(1)
	ds_write_b32 v108, v35
	s_cbranch_vccnz .LBB0_309
	v_readlane_b32 s40, v255, 27
	v_readlane_b32 s46, v255, 33
	v_readlane_b32 s47, v255, 34
	v_readlane_b32 s41, v255, 28
	v_readlane_b32 s42, v255, 29
	v_readlane_b32 s43, v255, 30
	v_readlane_b32 s44, v255, 31
	v_readlane_b32 s45, v255, 32
	global_load_dword v35, v2, s[46:47] offset:184
	v_readlane_b32 s48, v255, 35
	v_readlane_b32 s49, v255, 36
	v_readlane_b32 s50, v255, 37
	v_readlane_b32 s51, v255, 38
	v_readlane_b32 s52, v255, 39
	v_readlane_b32 s53, v255, 40
	v_readlane_b32 s54, v255, 41
	v_readlane_b32 s55, v255, 42
	s_waitcnt vmcnt(0)
	v_mul_f32_e32 v34, v34, v35
.LBB0_309:
	v_or_b32_e32 v35, s21, v92
	v_mad_u64_u32 v[108:109], s[22:23], v35, s93, v[32:33]
	global_load_dword v35, v[108:109], off
	v_add_u32_e32 v108, v36, v61
	s_and_b64 vcc, exec, s[2:3]
	s_waitcnt vmcnt(1)
	ds_write_b32 v108, v34
	s_cbranch_vccnz .LBB0_311
	v_readlane_b32 s40, v255, 27
	v_readlane_b32 s46, v255, 33
	v_readlane_b32 s47, v255, 34
	v_readlane_b32 s41, v255, 28
	v_readlane_b32 s42, v255, 29
	v_readlane_b32 s43, v255, 30
	v_readlane_b32 s44, v255, 31
	v_readlane_b32 s45, v255, 32
	global_load_dword v34, v2, s[46:47] offset:192
	v_readlane_b32 s48, v255, 35
	v_readlane_b32 s49, v255, 36
	v_readlane_b32 s50, v255, 37
	v_readlane_b32 s51, v255, 38
	v_readlane_b32 s52, v255, 39
	v_readlane_b32 s53, v255, 40
	v_readlane_b32 s54, v255, 41
	v_readlane_b32 s55, v255, 42
	s_waitcnt vmcnt(0)
	v_mul_f32_e32 v35, v35, v34
.LBB0_311:
	v_or_b32_e32 v34, s21, v93
	v_mad_u64_u32 v[108:109], s[22:23], v34, s93, v[32:33]
	global_load_dword v108, v[108:109], off
	v_add_u32_e32 v34, v36, v62
	s_and_b64 vcc, exec, s[2:3]
	s_waitcnt vmcnt(1)
	ds_write_b32 v34, v35
	s_cbranch_vccnz .LBB0_313
	v_readlane_b32 s40, v255, 27
	v_readlane_b32 s46, v255, 33
	v_readlane_b32 s47, v255, 34
	v_readlane_b32 s41, v255, 28
	v_readlane_b32 s42, v255, 29
	v_readlane_b32 s43, v255, 30
	v_readlane_b32 s44, v255, 31
	v_readlane_b32 s45, v255, 32
	global_load_dword v35, v2, s[46:47] offset:200
	v_readlane_b32 s48, v255, 35
	v_readlane_b32 s49, v255, 36
	v_readlane_b32 s50, v255, 37
	v_readlane_b32 s51, v255, 38
	v_readlane_b32 s52, v255, 39
	v_readlane_b32 s53, v255, 40
	v_readlane_b32 s54, v255, 41
	v_readlane_b32 s55, v255, 42
	s_waitcnt vmcnt(0)
	v_mul_f32_e32 v108, v108, v35
; __device__ __forceinline__ void transpose_item(const float* W, int K, int N, bf16* WT, int mode, const float* gain, LAS float* scr, int item, int lane) {
;     const int nblk = N / 32, kb = item / nblk, nb = item % nblk, k0 = 64 * kb, n0 = 32 * nb;
; #pragma unroll
;     for (int i = 0; i < 32; ++i) { const int kk = 2 * i + (lane >> 5); float w = W[(size_t)(k0 + kk) * N + n0 + (lane & 31)]; if (gain) w *= gain[k0 + kk]; scr[kk * 33 + (lane & 31)] = w; }
.LBB0_313:
	v_or_b32_e32 v35, s21, v94
	v_mad_u64_u32 v[110:111], s[22:23], v35, s93, v[32:33]
	global_load_dword v35, v[110:111], off
	s_and_b64 vcc, exec, s[2:3]
	s_waitcnt vmcnt(1)
	ds_write_b32 v34, v108 offset:264
	s_cbranch_vccnz .LBB0_315
	v_readlane_b32 s40, v255, 27
	v_readlane_b32 s46, v255, 33
	v_readlane_b32 s47, v255, 34
	v_readlane_b32 s41, v255, 28
	v_readlane_b32 s42, v255, 29
	v_readlane_b32 s43, v255, 30
	v_readlane_b32 s44, v255, 31
	v_readlane_b32 s45, v255, 32
	global_load_dword v108, v2, s[46:47] offset:208
	v_readlane_b32 s48, v255, 35
	v_readlane_b32 s49, v255, 36
	v_readlane_b32 s50, v255, 37
	v_readlane_b32 s51, v255, 38
	v_readlane_b32 s52, v255, 39
	v_readlane_b32 s53, v255, 40
	v_readlane_b32 s54, v255, 41
	v_readlane_b32 s55, v255, 42
	s_waitcnt vmcnt(0)
	v_mul_f32_e32 v35, v35, v108
.LBB0_315:
	v_or_b32_e32 v108, s21, v95
	v_mad_u64_u32 v[108:109], s[22:23], v108, s93, v[32:33]
	global_load_dword v108, v[108:109], off
	s_and_b64 vcc, exec, s[2:3]
	s_waitcnt vmcnt(1)
	ds_write_b32 v34, v35 offset:528
	s_cbranch_vccnz .LBB0_317
	v_readlane_b32 s40, v255, 27
	v_readlane_b32 s46, v255, 33
	v_readlane_b32 s47, v255, 34
	v_readlane_b32 s41, v255, 28
	v_readlane_b32 s42, v255, 29
	v_readlane_b32 s43, v255, 30
	v_readlane_b32 s44, v255, 31
	v_readlane_b32 s45, v255, 32
	global_load_dword v35, v2, s[46:47] offset:216
	v_readlane_b32 s48, v255, 35
	v_readlane_b32 s49, v255, 36
	v_readlane_b32 s50, v255, 37
	v_readlane_b32 s51, v255, 38
	v_readlane_b32 s52, v255, 39
	v_readlane_b32 s53, v255, 40
	v_readlane_b32 s54, v255, 41
	v_readlane_b32 s55, v255, 42
	s_waitcnt vmcnt(0)
	v_mul_f32_e32 v108, v108, v35
.LBB0_317:
	v_or_b32_e32 v35, s21, v96
	v_mad_u64_u32 v[110:111], s[22:23], v35, s93, v[32:33]
	global_load_dword v35, v[110:111], off
	s_and_b64 vcc, exec, s[2:3]
	s_waitcnt vmcnt(1)
	ds_write_b32 v34, v108 offset:792
	s_cbranch_vccnz .LBB0_319
	v_readlane_b32 s40, v255, 27
	v_readlane_b32 s46, v255, 33
	v_readlane_b32 s47, v255, 34
	v_readlane_b32 s41, v255, 28
	v_readlane_b32 s42, v255, 29
	v_readlane_b32 s43, v255, 30
	v_readlane_b32 s44, v255, 31
	v_readlane_b32 s45, v255, 32
	global_load_dword v108, v2, s[46:47] offset:224
	v_readlane_b32 s48, v255, 35
	v_readlane_b32 s49, v255, 36
	v_readlane_b32 s50, v255, 37
	v_readlane_b32 s51, v255, 38
	v_readlane_b32 s52, v255, 39
	v_readlane_b32 s53, v255, 40
	v_readlane_b32 s54, v255, 41
	v_readlane_b32 s55, v255, 42
	s_waitcnt vmcnt(0)
	v_mul_f32_e32 v35, v35, v108
.LBB0_319:
	v_or_b32_e32 v108, s21, v97
	v_mad_u64_u32 v[108:109], s[22:23], v108, s93, v[32:33]
	global_load_dword v108, v[108:109], off
	s_and_b64 vcc, exec, s[2:3]
	s_waitcnt vmcnt(1)
	ds_write_b32 v34, v35 offset:1056
	s_cbranch_vccnz .LBB0_321
	v_readlane_b32 s40, v255, 27
	v_readlane_b32 s46, v255, 33
	v_readlane_b32 s47, v255, 34
	v_readlane_b32 s41, v255, 28
	v_readlane_b32 s42, v255, 29
	v_readlane_b32 s43, v255, 30
	v_readlane_b32 s44, v255, 31
	v_readlane_b32 s45, v255, 32
	global_load_dword v35, v2, s[46:47] offset:232
	v_readlane_b32 s48, v255, 35
	v_readlane_b32 s49, v255, 36
	v_readlane_b32 s50, v255, 37
	v_readlane_b32 s51, v255, 38
	v_readlane_b32 s52, v255, 39
	v_readlane_b32 s53, v255, 40
	v_readlane_b32 s54, v255, 41
	v_readlane_b32 s55, v255, 42
	s_waitcnt vmcnt(0)
	v_mul_f32_e32 v108, v108, v35
.LBB0_321:
	v_or_b32_e32 v35, s21, v98
	v_mad_u64_u32 v[110:111], s[22:23], v35, s93, v[32:33]
	global_load_dword v35, v[110:111], off
	s_and_b64 vcc, exec, s[2:3]
	s_waitcnt vmcnt(1)
	ds_write_b32 v34, v108 offset:1320
	s_cbranch_vccnz .LBB0_323
	v_readlane_b32 s40, v255, 27
	v_readlane_b32 s46, v255, 33
	v_readlane_b32 s47, v255, 34
	v_readlane_b32 s41, v255, 28
	v_readlane_b32 s42, v255, 29
	v_readlane_b32 s43, v255, 30
	v_readlane_b32 s44, v255, 31
	v_readlane_b32 s45, v255, 32
	global_load_dword v108, v2, s[46:47] offset:240
	v_readlane_b32 s48, v255, 35
	v_readlane_b32 s49, v255, 36
	v_readlane_b32 s50, v255, 37
	v_readlane_b32 s51, v255, 38
	v_readlane_b32 s52, v255, 39
	v_readlane_b32 s53, v255, 40
	v_readlane_b32 s54, v255, 41
	v_readlane_b32 s55, v255, 42
	s_waitcnt vmcnt(0)
	v_mul_f32_e32 v35, v35, v108
.LBB0_323:
	v_or_b32_e32 v108, s21, v99
	v_mad_u64_u32 v[32:33], s[22:23], v108, s93, v[32:33]
	global_load_dword v32, v[32:33], off
	s_and_b64 vcc, exec, s[2:3]
	s_waitcnt vmcnt(1)
	ds_write_b32 v34, v35 offset:1584
	s_cbranch_vccnz .LBB0_325
	v_readlane_b32 s40, v255, 27
	v_readlane_b32 s46, v255, 33
	v_readlane_b32 s47, v255, 34
	v_readlane_b32 s41, v255, 28
	v_readlane_b32 s42, v255, 29
	v_readlane_b32 s43, v255, 30
	v_readlane_b32 s44, v255, 31
	v_readlane_b32 s45, v255, 32
	global_load_dword v2, v2, s[46:47] offset:248
	v_readlane_b32 s48, v255, 35
	v_readlane_b32 s49, v255, 36
	v_readlane_b32 s50, v255, 37
	v_readlane_b32 s51, v255, 38
	v_readlane_b32 s52, v255, 39
	v_readlane_b32 s53, v255, 40
	v_readlane_b32 s54, v255, 41
	v_readlane_b32 s55, v255, 42
	s_waitcnt vmcnt(0)
	v_mul_f32_e32 v32, v32, v2

; #define TR(cnt, W, K_, N_, DST, MODE, GAIN) if (r < (cnt)) { transpose_item((W), (K_), (N_), (bf16*)(ws + (DST)), (MODE), (GAIN), scr, r, lane); continue; } r -= (cnt);
; __device__ __forceinline__ void transpose_item(const float* W, int K, int N, bf16* WT, int mode, const float* gain, LAS float* scr, int item, int lane) {
;     const int nblk = N / 32, kb = item / nblk, nb = item % nblk, k0 = 64 * kb, n0 = 32 * nb;
; #pragma unroll
;     for (int i = 0; i < 32; ++i) { const int kk = 2 * i + (lane >> 5); float w = W[(size_t)(k0 + kk) * N + n0 + (lane & 31)]; if (gain) w *= gain[k0 + kk]; scr[kk * 33 + (lane & 31)] = w; }
; __device__ __forceinline__ void p0_prologue(const Args& a, LAS unsigned char* lds, int vcu, int G, int wave, int lane) {
;     ...
;         TR(T_PW1, a.in[I_CW1], D, 2 * D, WS_WPW1, 3, a.in[I_CNG])
.LBB0_330:
	s_andn2_b64 vcc, exec, s[2:3]
	s_cbranch_vccnz .LBB0_23
	s_ashr_i32 s2, s88, 31
	s_lshr_b32 s2, s2, 26
	s_add_i32 s2, s88, s2
	s_ashr_i32 s60, s2, 6
	s_and_b32 s84, s2, 0xffffffc0
	s_lshl_b32 s2, s60, 11
	s_sub_i32 s74, s10, s2
	v_or_b32_e32 v34, s84, v0
	s_ashr_i32 s75, s74, 31
	v_ashrrev_i32_e32 v35, 31, v34
	v_lshl_add_u64 v[32:33], s[74:75], 2, v[30:31]
	v_lshlrev_b64 v[108:109], 13, v[34:35]
	v_lshl_add_u64 v[108:109], v[32:33], 0, v[108:109]
	global_load_dword v108, v[108:109], off
	v_cndmask_b32_e64 v2, 0, 1, s[38:39]
	v_cmp_ne_u32_e64 s[2:3], 1, v2
	s_andn2_b64 vcc, exec, s[38:39]
	s_cbranch_vccnz .LBB0_333
	v_readlane_b32 s40, v255, 11
	v_readlane_b32 s44, v255, 15
	v_readlane_b32 s45, v255, 16
	v_readlane_b32 s41, v255, 12
	v_readlane_b32 s42, v255, 13
	v_lshl_add_u64 v[34:35], v[34:35], 2, s[44:45]
	global_load_dword v2, v[34:35], off
	v_readlane_b32 s43, v255, 14
	v_readlane_b32 s46, v255, 17
	v_readlane_b32 s47, v255, 18
	v_readlane_b32 s48, v255, 19
	v_readlane_b32 s49, v255, 20
	v_readlane_b32 s50, v255, 21
	v_readlane_b32 s51, v255, 22
	v_readlane_b32 s52, v255, 23
	v_readlane_b32 s53, v255, 24
	v_readlane_b32 s54, v255, 25
	v_readlane_b32 s55, v255, 26
	s_waitcnt vmcnt(0)
	v_mul_f32_e32 v108, v108, v2
.LBB0_333:
	v_or_b32_e32 v34, s84, v38
	v_ashrrev_i32_e32 v35, 31, v34
	v_lshlrev_b64 v[34:35], 13, v[34:35]
	v_lshl_add_u64 v[34:35], v[32:33], 0, v[34:35]
	global_load_dword v2, v[34:35], off
	v_add_u32_e32 v34, v36, v37
	s_and_b64 vcc, exec, s[2:3]
	s_waitcnt vmcnt(1)
	ds_write_b32 v34, v108
	s_cbranch_vccnz .LBB0_335
	s_ashr_i32 s85, s84, 31
	v_readlane_b32 s40, v255, 11
	v_lshl_add_u64 v[34:35], s[84:85], 0, v[0:1]
	v_readlane_b32 s44, v255, 15
	v_readlane_b32 s45, v255, 16
	v_readlane_b32 s41, v255, 12
	v_readlane_b32 s42, v255, 13
	v_lshl_add_u64 v[34:35], v[34:35], 2, s[44:45]
	global_load_dword v34, v[34:35], off offset:8
	v_readlane_b32 s43, v255, 14
	v_readlane_b32 s46, v255, 17
	v_readlane_b32 s47, v255, 18
	v_readlane_b32 s48, v255, 19
	v_readlane_b32 s49, v255, 20
	v_readlane_b32 s50, v255, 21
	v_readlane_b32 s51, v255, 22
	v_readlane_b32 s52, v255, 23
	v_readlane_b32 s53, v255, 24
	v_readlane_b32 s54, v255, 25
	v_readlane_b32 s55, v255, 26
	s_waitcnt vmcnt(0)
	v_mul_f32_e32 v2, v2, v34
.LBB0_335:
	v_or_b32_e32 v34, s84, v70
	v_ashrrev_i32_e32 v35, 31, v34
	v_lshlrev_b64 v[34:35], 13, v[34:35]
	v_lshl_add_u64 v[34:35], v[32:33], 0, v[34:35]
	global_load_dword v34, v[34:35], off
	v_add_u32_e32 v35, v36, v39
	s_and_b64 vcc, exec, s[2:3]
	s_waitcnt vmcnt(1)
	ds_write_b32 v35, v2
	s_cbranch_vccnz .LBB0_337
	s_ashr_i32 s85, s84, 31
	v_readlane_b32 s40, v255, 11
	v_lshl_add_u64 v[108:109], s[84:85], 0, v[0:1]
	v_readlane_b32 s44, v255, 15
	v_readlane_b32 s45, v255, 16
	v_readlane_b32 s41, v255, 12
	v_readlane_b32 s42, v255, 13
	v_lshl_add_u64 v[108:109], v[108:109], 2, s[44:45]
	global_load_dword v2, v[108:109], off offset:16
	v_readlane_b32 s43, v255, 14
	v_readlane_b32 s46, v255, 17
	v_readlane_b32 s47, v255, 18
	v_readlane_b32 s48, v255, 19
	v_readlane_b32 s49, v255, 20
	v_readlane_b32 s50, v255, 21
	v_readlane_b32 s51, v255, 22
	v_readlane_b32 s52, v255, 23
	v_readlane_b32 s53, v255, 24
	v_readlane_b32 s54, v255, 25
	v_readlane_b32 s55, v255, 26
	s_waitcnt vmcnt(0)
	v_mul_f32_e32 v34, v34, v2
.LBB0_337:
	v_or_b32_e32 v108, s84, v71
	v_ashrrev_i32_e32 v109, 31, v108
	v_lshlrev_b64 v[108:109], 13, v[108:109]
	v_lshl_add_u64 v[108:109], v[32:33], 0, v[108:109]
	global_load_dword v2, v[108:109], off
	v_add_u32_e32 v35, v36, v40
	s_and_b64 vcc, exec, s[2:3]
	s_waitcnt vmcnt(1)
	ds_write_b32 v35, v34
	s_cbranch_vccnz .LBB0_339
	s_ashr_i32 s85, s84, 31
	v_readlane_b32 s40, v255, 11
	v_lshl_add_u64 v[34:35], s[84:85], 0, v[0:1]
	v_readlane_b32 s44, v255, 15
	v_readlane_b32 s45, v255, 16
	v_readlane_b32 s41, v255, 12
	v_readlane_b32 s42, v255, 13
	v_lshl_add_u64 v[34:35], v[34:35], 2, s[44:45]
	global_load_dword v34, v[34:35], off offset:24
	v_readlane_b32 s43, v255, 14
	v_readlane_b32 s46, v255, 17
	v_readlane_b32 s47, v255, 18
	v_readlane_b32 s48, v255, 19
	v_readlane_b32 s49, v255, 20
	v_readlane_b32 s50, v255, 21
	v_readlane_b32 s51, v255, 22
	v_readlane_b32 s52, v255, 23
	v_readlane_b32 s53, v255, 24
	v_readlane_b32 s54, v255, 25
	v_readlane_b32 s55, v255, 26
	s_waitcnt vmcnt(0)
	v_mul_f32_e32 v2, v2, v34
.LBB0_339:
	v_or_b32_e32 v34, s84, v72
	v_ashrrev_i32_e32 v35, 31, v34
	v_lshlrev_b64 v[34:35], 13, v[34:35]
	v_lshl_add_u64 v[34:35], v[32:33], 0, v[34:35]
	global_load_dword v34, v[34:35], off
	v_add_u32_e32 v35, v36, v41
	s_and_b64 vcc, exec, s[2:3]
	s_waitcnt vmcnt(1)
	ds_write_b32 v35, v2
	s_cbranch_vccnz .LBB0_341
	s_ashr_i32 s85, s84, 31
	v_readlane_b32 s40, v255, 11
	v_lshl_add_u64 v[108:109], s[84:85], 0, v[0:1]
	v_readlane_b32 s44, v255, 15
	v_readlane_b32 s45, v255, 16
	v_readlane_b32 s41, v255, 12
	v_readlane_b32 s42, v255, 13
	v_lshl_add_u64 v[108:109], v[108:109], 2, s[44:45]
	global_load_dword v2, v[108:109], off offset:32
	v_readlane_b32 s43, v255, 14
	v_readlane_b32 s46, v255, 17
	v_readlane_b32 s47, v255, 18
	v_readlane_b32 s48, v255, 19
	v_readlane_b32 s49, v255, 20
	v_readlane_b32 s50, v255, 21
	v_readlane_b32 s51, v255, 22
	v_readlane_b32 s52, v255, 23
	v_readlane_b32 s53, v255, 24
	v_readlane_b32 s54, v255, 25
	v_readlane_b32 s55, v255, 26
	s_waitcnt vmcnt(0)
	v_mul_f32_e32 v34, v34, v2
; __device__ __forceinline__ void transpose_item(const float* W, int K, int N, bf16* WT, int mode, const float* gain, LAS float* scr, int item, int lane) {
;     const int nblk = N / 32, kb = item / nblk, nb = item % nblk, k0 = 64 * kb, n0 = 32 * nb;
; #pragma unroll
;     for (int i = 0; i < 32; ++i) { const int kk = 2 * i + (lane >> 5); float w = W[(size_t)(k0 + kk) * N + n0 + (lane & 31)]; if (gain) w *= gain[k0 + kk]; scr[kk * 33 + (lane & 31)] = w; }
.LBB0_341:
	v_or_b32_e32 v108, s84, v73
	v_ashrrev_i32_e32 v109, 31, v108
	v_lshlrev_b64 v[108:109], 13, v[108:109]
	v_lshl_add_u64 v[108:109], v[32:33], 0, v[108:109]
	global_load_dword v2, v[108:109], off
	v_add_u32_e32 v35, v36, v42
	s_and_b64 vcc, exec, s[2:3]
	s_waitcnt vmcnt(1)
	ds_write_b32 v35, v34
	s_cbranch_vccnz .LBB0_343
	s_ashr_i32 s85, s84, 31
	v_readlane_b32 s40, v255, 11
	v_lshl_add_u64 v[34:35], s[84:85], 0, v[0:1]
	v_readlane_b32 s44, v255, 15
	v_readlane_b32 s45, v255, 16
	v_readlane_b32 s41, v255, 12
	v_readlane_b32 s42, v255, 13
	v_lshl_add_u64 v[34:35], v[34:35], 2, s[44:45]
	global_load_dword v34, v[34:35], off offset:40
	v_readlane_b32 s43, v255, 14
	v_readlane_b32 s46, v255, 17
	v_readlane_b32 s47, v255, 18
	v_readlane_b32 s48, v255, 19
	v_readlane_b32 s49, v255, 20
	v_readlane_b32 s50, v255, 21
	v_readlane_b32 s51, v255, 22
	v_readlane_b32 s52, v255, 23
	v_readlane_b32 s53, v255, 24
	v_readlane_b32 s54, v255, 25
	v_readlane_b32 s55, v255, 26
	s_waitcnt vmcnt(0)
	v_mul_f32_e32 v2, v2, v34
.LBB0_343:
	v_or_b32_e32 v34, s84, v74
	v_ashrrev_i32_e32 v35, 31, v34
	v_lshlrev_b64 v[34:35], 13, v[34:35]
	v_lshl_add_u64 v[34:35], v[32:33], 0, v[34:35]
	global_load_dword v34, v[34:35], off
	v_add_u32_e32 v35, v36, v43
	s_and_b64 vcc, exec, s[2:3]
	s_waitcnt vmcnt(1)
	ds_write_b32 v35, v2
	s_cbranch_vccnz .LBB0_345
	s_ashr_i32 s85, s84, 31
	v_readlane_b32 s40, v255, 11
	v_lshl_add_u64 v[108:109], s[84:85], 0, v[0:1]
	v_readlane_b32 s44, v255, 15
	v_readlane_b32 s45, v255, 16
	v_readlane_b32 s41, v255, 12
	v_readlane_b32 s42, v255, 13
	v_lshl_add_u64 v[108:109], v[108:109], 2, s[44:45]
	global_load_dword v2, v[108:109], off offset:48
	v_readlane_b32 s43, v255, 14
	v_readlane_b32 s46, v255, 17
	v_readlane_b32 s47, v255, 18
	v_readlane_b32 s48, v255, 19
	v_readlane_b32 s49, v255, 20
	v_readlane_b32 s50, v255, 21
	v_readlane_b32 s51, v255, 22
	v_readlane_b32 s52, v255, 23
	v_readlane_b32 s53, v255, 24
	v_readlane_b32 s54, v255, 25
	v_readlane_b32 s55, v255, 26
	s_waitcnt vmcnt(0)
	v_mul_f32_e32 v34, v34, v2
.LBB0_345:
	v_or_b32_e32 v108, s84, v75
	v_ashrrev_i32_e32 v109, 31, v108
	v_lshlrev_b64 v[108:109], 13, v[108:109]
	v_lshl_add_u64 v[108:109], v[32:33], 0, v[108:109]
	global_load_dword v2, v[108:109], off
	v_add_u32_e32 v35, v36, v44
	s_and_b64 vcc, exec, s[2:3]
	s_waitcnt vmcnt(1)
	ds_write_b32 v35, v34
	s_cbranch_vccnz .LBB0_347
	s_ashr_i32 s85, s84, 31
	v_readlane_b32 s40, v255, 11
	v_lshl_add_u64 v[34:35], s[84:85], 0, v[0:1]
	v_readlane_b32 s44, v255, 15
	v_readlane_b32 s45, v255, 16
	v_readlane_b32 s41, v255, 12
	v_readlane_b32 s42, v255, 13
	v_lshl_add_u64 v[34:35], v[34:35], 2, s[44:45]
	global_load_dword v34, v[34:35], off offset:56
	v_readlane_b32 s43, v255, 14
	v_readlane_b32 s46, v255, 17
	v_readlane_b32 s47, v255, 18
	v_readlane_b32 s48, v255, 19
	v_readlane_b32 s49, v255, 20
	v_readlane_b32 s50, v255, 21
	v_readlane_b32 s51, v255, 22
	v_readlane_b32 s52, v255, 23
	v_readlane_b32 s53, v255, 24
	v_readlane_b32 s54, v255, 25
	v_readlane_b32 s55, v255, 26
	s_waitcnt vmcnt(0)
	v_mul_f32_e32 v2, v2, v34
.LBB0_347:
	v_or_b32_e32 v34, s84, v76
	v_ashrrev_i32_e32 v35, 31, v34
	v_lshlrev_b64 v[34:35], 13, v[34:35]
	v_lshl_add_u64 v[34:35], v[32:33], 0, v[34:35]
	global_load_dword v34, v[34:35], off
	v_add_u32_e32 v35, v36, v45
	s_and_b64 vcc, exec, s[2:3]
	s_waitcnt vmcnt(1)
	ds_write_b32 v35, v2
	s_cbranch_vccnz .LBB0_349
	s_ashr_i32 s85, s84, 31
	v_readlane_b32 s40, v255, 11
	v_lshl_add_u64 v[108:109], s[84:85], 0, v[0:1]
	v_readlane_b32 s44, v255, 15
	v_readlane_b32 s45, v255, 16
	v_readlane_b32 s41, v255, 12
	v_readlane_b32 s42, v255, 13
	v_lshl_add_u64 v[108:109], v[108:109], 2, s[44:45]
	global_load_dword v2, v[108:109], off offset:64
	v_readlane_b32 s43, v255, 14
	v_readlane_b32 s46, v255, 17
	v_readlane_b32 s47, v255, 18
	v_readlane_b32 s48, v255, 19
	v_readlane_b32 s49, v255, 20
	v_readlane_b32 s50, v255, 21
	v_readlane_b32 s51, v255, 22
	v_readlane_b32 s52, v255, 23
	v_readlane_b32 s53, v255, 24
	v_readlane_b32 s54, v255, 25
	v_readlane_b32 s55, v255, 26
	s_waitcnt vmcnt(0)
	v_mul_f32_e32 v34, v34, v2
.LBB0_349:
	v_or_b32_e32 v108, s84, v77
	v_ashrrev_i32_e32 v109, 31, v108
	v_lshlrev_b64 v[108:109], 13, v[108:109]
	v_lshl_add_u64 v[108:109], v[32:33], 0, v[108:109]
	global_load_dword v2, v[108:109], off
	v_add_u32_e32 v35, v36, v46
	s_and_b64 vcc, exec, s[2:3]
	s_waitcnt vmcnt(1)
	ds_write_b32 v35, v34
	s_cbranch_vccnz .LBB0_351
	s_ashr_i32 s85, s84, 31
	v_readlane_b32 s40, v255, 11
	v_lshl_add_u64 v[34:35], s[84:85], 0, v[0:1]
	v_readlane_b32 s44, v255, 15
	v_readlane_b32 s45, v255, 16
	v_readlane_b32 s41, v255, 12
	v_readlane_b32 s42, v255, 13
	v_lshl_add_u64 v[34:35], v[34:35], 2, s[44:45]
	global_load_dword v34, v[34:35], off offset:72
	v_readlane_b32 s43, v255, 14
	v_readlane_b32 s46, v255, 17
	v_readlane_b32 s47, v255, 18
	v_readlane_b32 s48, v255, 19
	v_readlane_b32 s49, v255, 20
	v_readlane_b32 s50, v255, 21
	v_readlane_b32 s51, v255, 22
	v_readlane_b32 s52, v255, 23
	v_readlane_b32 s53, v255, 24
	v_readlane_b32 s54, v255, 25
	v_readlane_b32 s55, v255, 26
	s_waitcnt vmcnt(0)
	v_mul_f32_e32 v2, v2, v34
; __device__ __forceinline__ void transpose_item(const float* W, int K, int N, bf16* WT, int mode, const float* gain, LAS float* scr, int item, int lane) {
;     const int nblk = N / 32, kb = item / nblk, nb = item % nblk, k0 = 64 * kb, n0 = 32 * nb;
; #pragma unroll
;     for (int i = 0; i < 32; ++i) { const int kk = 2 * i + (lane >> 5); float w = W[(size_t)(k0 + kk) * N + n0 + (lane & 31)]; if (gain) w *= gain[k0 + kk]; scr[kk * 33 + (lane & 31)] = w; }
.LBB0_351:
	v_or_b32_e32 v34, s84, v78
	v_ashrrev_i32_e32 v35, 31, v34
	v_lshlrev_b64 v[34:35], 13, v[34:35]
	v_lshl_add_u64 v[34:35], v[32:33], 0, v[34:35]
	global_load_dword v34, v[34:35], off
	v_add_u32_e32 v35, v36, v47
	s_and_b64 vcc, exec, s[2:3]
	s_waitcnt vmcnt(1)
	ds_write_b32 v35, v2
	s_cbranch_vccnz .LBB0_353
	s_ashr_i32 s85, s84, 31
	v_readlane_b32 s40, v255, 11
	v_lshl_add_u64 v[108:109], s[84:85], 0, v[0:1]
	v_readlane_b32 s44, v255, 15
	v_readlane_b32 s45, v255, 16
	v_readlane_b32 s41, v255, 12
	v_readlane_b32 s42, v255, 13
	v_lshl_add_u64 v[108:109], v[108:109], 2, s[44:45]
	global_load_dword v2, v[108:109], off offset:80
	v_readlane_b32 s43, v255, 14
	v_readlane_b32 s46, v255, 17
	v_readlane_b32 s47, v255, 18
	v_readlane_b32 s48, v255, 19
	v_readlane_b32 s49, v255, 20
	v_readlane_b32 s50, v255, 21
	v_readlane_b32 s51, v255, 22
	v_readlane_b32 s52, v255, 23
	v_readlane_b32 s53, v255, 24
	v_readlane_b32 s54, v255, 25
	v_readlane_b32 s55, v255, 26
	s_waitcnt vmcnt(0)
	v_mul_f32_e32 v34, v34, v2
.LBB0_353:
	v_or_b32_e32 v108, s84, v79
	v_ashrrev_i32_e32 v109, 31, v108
	v_lshlrev_b64 v[108:109], 13, v[108:109]
	v_lshl_add_u64 v[108:109], v[32:33], 0, v[108:109]
	global_load_dword v2, v[108:109], off
	v_add_u32_e32 v35, v36, v48
	s_and_b64 vcc, exec, s[2:3]
	s_waitcnt vmcnt(1)
	ds_write_b32 v35, v34
	s_cbranch_vccnz .LBB0_355
	s_ashr_i32 s85, s84, 31
	v_readlane_b32 s40, v255, 11
	v_lshl_add_u64 v[34:35], s[84:85], 0, v[0:1]
	v_readlane_b32 s44, v255, 15
	v_readlane_b32 s45, v255, 16
	v_readlane_b32 s41, v255, 12
	v_readlane_b32 s42, v255, 13
	v_lshl_add_u64 v[34:35], v[34:35], 2, s[44:45]
	global_load_dword v34, v[34:35], off offset:88
	v_readlane_b32 s43, v255, 14
	v_readlane_b32 s46, v255, 17
	v_readlane_b32 s47, v255, 18
	v_readlane_b32 s48, v255, 19
	v_readlane_b32 s49, v255, 20
	v_readlane_b32 s50, v255, 21
	v_readlane_b32 s51, v255, 22
	v_readlane_b32 s52, v255, 23
	v_readlane_b32 s53, v255, 24
	v_readlane_b32 s54, v255, 25
	v_readlane_b32 s55, v255, 26
	s_waitcnt vmcnt(0)
	v_mul_f32_e32 v2, v2, v34
.LBB0_355:
	v_or_b32_e32 v34, s84, v80
	v_ashrrev_i32_e32 v35, 31, v34
	v_lshlrev_b64 v[34:35], 13, v[34:35]
	v_lshl_add_u64 v[34:35], v[32:33], 0, v[34:35]
	global_load_dword v34, v[34:35], off
	v_add_u32_e32 v35, v36, v49
	s_and_b64 vcc, exec, s[2:3]
	s_waitcnt vmcnt(1)
	ds_write_b32 v35, v2
	s_cbranch_vccnz .LBB0_357
	s_ashr_i32 s85, s84, 31
	v_readlane_b32 s40, v255, 11
	v_lshl_add_u64 v[108:109], s[84:85], 0, v[0:1]
	v_readlane_b32 s44, v255, 15
	v_readlane_b32 s45, v255, 16
	v_readlane_b32 s41, v255, 12
	v_readlane_b32 s42, v255, 13
	v_lshl_add_u64 v[108:109], v[108:109], 2, s[44:45]
	global_load_dword v2, v[108:109], off offset:96
	v_readlane_b32 s43, v255, 14
	v_readlane_b32 s46, v255, 17
	v_readlane_b32 s47, v255, 18
	v_readlane_b32 s48, v255, 19
	v_readlane_b32 s49, v255, 20
	v_readlane_b32 s50, v255, 21
	v_readlane_b32 s51, v255, 22
	v_readlane_b32 s52, v255, 23
	v_readlane_b32 s53, v255, 24
	v_readlane_b32 s54, v255, 25
	v_readlane_b32 s55, v255, 26
	s_waitcnt vmcnt(0)
	v_mul_f32_e32 v34, v34, v2
.LBB0_357:
	v_or_b32_e32 v108, s84, v81
	v_ashrrev_i32_e32 v109, 31, v108
	v_lshlrev_b64 v[108:109], 13, v[108:109]
	v_lshl_add_u64 v[108:109], v[32:33], 0, v[108:109]
	global_load_dword v2, v[108:109], off
	v_add_u32_e32 v35, v36, v50
	s_and_b64 vcc, exec, s[2:3]
	s_waitcnt vmcnt(1)
	ds_write_b32 v35, v34
	s_cbranch_vccnz .LBB0_359
	s_ashr_i32 s85, s84, 31
	v_readlane_b32 s40, v255, 11
	v_lshl_add_u64 v[34:35], s[84:85], 0, v[0:1]
	v_readlane_b32 s44, v255, 15
	v_readlane_b32 s45, v255, 16
	v_readlane_b32 s41, v255, 12
	v_readlane_b32 s42, v255, 13
	v_lshl_add_u64 v[34:35], v[34:35], 2, s[44:45]
	global_load_dword v34, v[34:35], off offset:104
	v_readlane_b32 s43, v255, 14
	v_readlane_b32 s46, v255, 17
	v_readlane_b32 s47, v255, 18
	v_readlane_b32 s48, v255, 19
	v_readlane_b32 s49, v255, 20
	v_readlane_b32 s50, v255, 21
	v_readlane_b32 s51, v255, 22
	v_readlane_b32 s52, v255, 23
	v_readlane_b32 s53, v255, 24
	v_readlane_b32 s54, v255, 25
	v_readlane_b32 s55, v255, 26
	s_waitcnt vmcnt(0)
	v_mul_f32_e32 v2, v2, v34
.LBB0_359:
	v_or_b32_e32 v34, s84, v82
	v_ashrrev_i32_e32 v35, 31, v34
	v_lshlrev_b64 v[34:35], 13, v[34:35]
	v_lshl_add_u64 v[34:35], v[32:33], 0, v[34:35]
	global_load_dword v34, v[34:35], off
	v_add_u32_e32 v35, v36, v51
	s_and_b64 vcc, exec, s[2:3]
	s_waitcnt vmcnt(1)
	ds_write_b32 v35, v2
	s_cbranch_vccnz .LBB0_361
	s_ashr_i32 s85, s84, 31
	v_readlane_b32 s40, v255, 11
	v_lshl_add_u64 v[108:109], s[84:85], 0, v[0:1]
	v_readlane_b32 s44, v255, 15
	v_readlane_b32 s45, v255, 16
	v_readlane_b32 s41, v255, 12
	v_readlane_b32 s42, v255, 13
	v_lshl_add_u64 v[108:109], v[108:109], 2, s[44:45]
	global_load_dword v2, v[108:109], off offset:112
	v_readlane_b32 s43, v255, 14
	v_readlane_b32 s46, v255, 17
	v_readlane_b32 s47, v255, 18
	v_readlane_b32 s48, v255, 19
	v_readlane_b32 s49, v255, 20
	v_readlane_b32 s50, v255, 21
	v_readlane_b32 s51, v255, 22
	v_readlane_b32 s52, v255, 23
	v_readlane_b32 s53, v255, 24
	v_readlane_b32 s54, v255, 25
	v_readlane_b32 s55, v255, 26
	s_waitcnt vmcnt(0)
	v_mul_f32_e32 v34, v34, v2
; __device__ __forceinline__ void transpose_item(const float* W, int K, int N, bf16* WT, int mode, const float* gain, LAS float* scr, int item, int lane) {
;     const int nblk = N / 32, kb = item / nblk, nb = item % nblk, k0 = 64 * kb, n0 = 32 * nb;
; #pragma unroll
;     for (int i = 0; i < 32; ++i) { const int kk = 2 * i + (lane >> 5); float w = W[(size_t)(k0 + kk) * N + n0 + (lane & 31)]; if (gain) w *= gain[k0 + kk]; scr[kk * 33 + (lane & 31)] = w; }
.LBB0_361:
	v_or_b32_e32 v108, s84, v83
	v_ashrrev_i32_e32 v109, 31, v108
	v_lshlrev_b64 v[108:109], 13, v[108:109]
	v_lshl_add_u64 v[108:109], v[32:33], 0, v[108:109]
	global_load_dword v2, v[108:109], off
	v_add_u32_e32 v35, v36, v52
	s_and_b64 vcc, exec, s[2:3]
	s_waitcnt vmcnt(1)
	ds_write_b32 v35, v34
	s_cbranch_vccnz .LBB0_363
	s_ashr_i32 s85, s84, 31
	v_readlane_b32 s40, v255, 11
	v_lshl_add_u64 v[34:35], s[84:85], 0, v[0:1]
	v_readlane_b32 s44, v255, 15
	v_readlane_b32 s45, v255, 16
	v_readlane_b32 s41, v255, 12
	v_readlane_b32 s42, v255, 13
	v_lshl_add_u64 v[34:35], v[34:35], 2, s[44:45]
	global_load_dword v34, v[34:35], off offset:120
	v_readlane_b32 s43, v255, 14
	v_readlane_b32 s46, v255, 17
	v_readlane_b32 s47, v255, 18
	v_readlane_b32 s48, v255, 19
	v_readlane_b32 s49, v255, 20
	v_readlane_b32 s50, v255, 21
	v_readlane_b32 s51, v255, 22
	v_readlane_b32 s52, v255, 23
	v_readlane_b32 s53, v255, 24
	v_readlane_b32 s54, v255, 25
	v_readlane_b32 s55, v255, 26
	s_waitcnt vmcnt(0)
	v_mul_f32_e32 v2, v2, v34
.LBB0_363:
	v_or_b32_e32 v34, s84, v84
	v_ashrrev_i32_e32 v35, 31, v34
	v_lshlrev_b64 v[34:35], 13, v[34:35]
	v_lshl_add_u64 v[34:35], v[32:33], 0, v[34:35]
	global_load_dword v34, v[34:35], off
	v_add_u32_e32 v35, v36, v53
	s_and_b64 vcc, exec, s[2:3]
	s_waitcnt vmcnt(1)
	ds_write_b32 v35, v2
	s_cbranch_vccnz .LBB0_365
	s_ashr_i32 s85, s84, 31
	v_readlane_b32 s40, v255, 11
	v_lshl_add_u64 v[108:109], s[84:85], 0, v[0:1]
	v_readlane_b32 s44, v255, 15
	v_readlane_b32 s45, v255, 16
	v_readlane_b32 s41, v255, 12
	v_readlane_b32 s42, v255, 13
	v_lshl_add_u64 v[108:109], v[108:109], 2, s[44:45]
	global_load_dword v2, v[108:109], off offset:128
	v_readlane_b32 s43, v255, 14
	v_readlane_b32 s46, v255, 17
	v_readlane_b32 s47, v255, 18
	v_readlane_b32 s48, v255, 19
	v_readlane_b32 s49, v255, 20
	v_readlane_b32 s50, v255, 21
	v_readlane_b32 s51, v255, 22
	v_readlane_b32 s52, v255, 23
	v_readlane_b32 s53, v255, 24
	v_readlane_b32 s54, v255, 25
	v_readlane_b32 s55, v255, 26
	s_waitcnt vmcnt(0)
	v_mul_f32_e32 v34, v34, v2
.LBB0_365:
	v_or_b32_e32 v108, s84, v85
	v_ashrrev_i32_e32 v109, 31, v108
	v_lshlrev_b64 v[108:109], 13, v[108:109]
	v_lshl_add_u64 v[108:109], v[32:33], 0, v[108:109]
	global_load_dword v2, v[108:109], off
	v_add_u32_e32 v35, v36, v54
	s_and_b64 vcc, exec, s[2:3]
	s_waitcnt vmcnt(1)
	ds_write_b32 v35, v34
	s_cbranch_vccnz .LBB0_367
	s_ashr_i32 s85, s84, 31
	v_readlane_b32 s40, v255, 11
	v_lshl_add_u64 v[34:35], s[84:85], 0, v[0:1]
	v_readlane_b32 s44, v255, 15
	v_readlane_b32 s45, v255, 16
	v_readlane_b32 s41, v255, 12
	v_readlane_b32 s42, v255, 13
	v_lshl_add_u64 v[34:35], v[34:35], 2, s[44:45]
	global_load_dword v34, v[34:35], off offset:136
	v_readlane_b32 s43, v255, 14
	v_readlane_b32 s46, v255, 17
	v_readlane_b32 s47, v255, 18
	v_readlane_b32 s48, v255, 19
	v_readlane_b32 s49, v255, 20
	v_readlane_b32 s50, v255, 21
	v_readlane_b32 s51, v255, 22
	v_readlane_b32 s52, v255, 23
	v_readlane_b32 s53, v255, 24
	v_readlane_b32 s54, v255, 25
	v_readlane_b32 s55, v255, 26
	s_waitcnt vmcnt(0)
	v_mul_f32_e32 v2, v2, v34
.LBB0_367:
	v_or_b32_e32 v34, s84, v86
	v_ashrrev_i32_e32 v35, 31, v34
	v_lshlrev_b64 v[34:35], 13, v[34:35]
	v_lshl_add_u64 v[34:35], v[32:33], 0, v[34:35]
	global_load_dword v34, v[34:35], off
	v_add_u32_e32 v35, v36, v55
	s_and_b64 vcc, exec, s[2:3]
	s_waitcnt vmcnt(1)
	ds_write_b32 v35, v2
	s_cbranch_vccnz .LBB0_369
	s_ashr_i32 s85, s84, 31
	v_readlane_b32 s40, v255, 11
	v_lshl_add_u64 v[108:109], s[84:85], 0, v[0:1]
	v_readlane_b32 s44, v255, 15
	v_readlane_b32 s45, v255, 16
	v_readlane_b32 s41, v255, 12
	v_readlane_b32 s42, v255, 13
	v_lshl_add_u64 v[108:109], v[108:109], 2, s[44:45]
	global_load_dword v2, v[108:109], off offset:144
	v_readlane_b32 s43, v255, 14
	v_readlane_b32 s46, v255, 17
	v_readlane_b32 s47, v255, 18
	v_readlane_b32 s48, v255, 19
	v_readlane_b32 s49, v255, 20
	v_readlane_b32 s50, v255, 21
	v_readlane_b32 s51, v255, 22
	v_readlane_b32 s52, v255, 23
	v_readlane_b32 s53, v255, 24
	v_readlane_b32 s54, v255, 25
	v_readlane_b32 s55, v255, 26
	s_waitcnt vmcnt(0)
	v_mul_f32_e32 v34, v34, v2
.LBB0_369:
	v_or_b32_e32 v108, s84, v87
	v_ashrrev_i32_e32 v109, 31, v108
	v_lshlrev_b64 v[108:109], 13, v[108:109]
	v_lshl_add_u64 v[108:109], v[32:33], 0, v[108:109]
	global_load_dword v2, v[108:109], off
	v_add_u32_e32 v35, v36, v56
	s_and_b64 vcc, exec, s[2:3]
	s_waitcnt vmcnt(1)
	ds_write_b32 v35, v34
	s_cbranch_vccnz .LBB0_371
	s_ashr_i32 s85, s84, 31
	v_readlane_b32 s40, v255, 11
	v_lshl_add_u64 v[34:35], s[84:85], 0, v[0:1]
	v_readlane_b32 s44, v255, 15
	v_readlane_b32 s45, v255, 16
	v_readlane_b32 s41, v255, 12
	v_readlane_b32 s42, v255, 13
	v_lshl_add_u64 v[34:35], v[34:35], 2, s[44:45]
	global_load_dword v34, v[34:35], off offset:152
	v_readlane_b32 s43, v255, 14
	v_readlane_b32 s46, v255, 17
	v_readlane_b32 s47, v255, 18
	v_readlane_b32 s48, v255, 19
	v_readlane_b32 s49, v255, 20
	v_readlane_b32 s50, v255, 21
	v_readlane_b32 s51, v255, 22
	v_readlane_b32 s52, v255, 23
	v_readlane_b32 s53, v255, 24
	v_readlane_b32 s54, v255, 25
	v_readlane_b32 s55, v255, 26
	s_waitcnt vmcnt(0)
	v_mul_f32_e32 v2, v2, v34
; #define LAS __attribute__((address_space(3)))
; #define LDS_WAIT() asm volatile("s_waitcnt lgkmcnt(0)" ::: "memory")
; __device__ __forceinline__ void transpose_item(const float* W, int K, int N, bf16* WT, int mode, const float* gain, LAS float* scr, int item, int lane) {
;     const int nblk = N / 32, kb = item / nblk, nb = item % nblk, k0 = 64 * kb, n0 = 32 * nb;
; #pragma unroll
;     for (int i = 0; i < 32; ++i) { const int kk = 2 * i + (lane >> 5); float w = W[(size_t)(k0 + kk) * N + n0 + (lane & 31)]; if (gain) w *= gain[k0 + kk]; scr[kk * 33 + (lane & 31)] = w; }
;     LDS_WAIT(); asm volatile("" ::: "memory");
.LBB0_371:
	v_or_b32_e32 v34, s84, v88
	v_ashrrev_i32_e32 v35, 31, v34
	v_lshlrev_b64 v[34:35], 13, v[34:35]
	v_lshl_add_u64 v[34:35], v[32:33], 0, v[34:35]
	global_load_dword v34, v[34:35], off
	v_add_u32_e32 v35, v36, v57
	s_and_b64 vcc, exec, s[2:3]
	s_waitcnt vmcnt(1)
	ds_write_b32 v35, v2
	s_cbranch_vccnz .LBB0_373
	s_ashr_i32 s85, s84, 31
	v_readlane_b32 s40, v255, 11
	v_lshl_add_u64 v[108:109], s[84:85], 0, v[0:1]
	v_readlane_b32 s44, v255, 15
	v_readlane_b32 s45, v255, 16
	v_readlane_b32 s41, v255, 12
	v_readlane_b32 s42, v255, 13
	v_lshl_add_u64 v[108:109], v[108:109], 2, s[44:45]
	global_load_dword v2, v[108:109], off offset:160
	v_readlane_b32 s43, v255, 14
	v_readlane_b32 s46, v255, 17
	v_readlane_b32 s47, v255, 18
	v_readlane_b32 s48, v255, 19
	v_readlane_b32 s49, v255, 20
	v_readlane_b32 s50, v255, 21
	v_readlane_b32 s51, v255, 22
	v_readlane_b32 s52, v255, 23
	v_readlane_b32 s53, v255, 24
	v_readlane_b32 s54, v255, 25
	v_readlane_b32 s55, v255, 26
	s_waitcnt vmcnt(0)
	v_mul_f32_e32 v34, v34, v2
.LBB0_373:
	v_or_b32_e32 v108, s84, v89
	v_ashrrev_i32_e32 v109, 31, v108
	v_lshlrev_b64 v[108:109], 13, v[108:109]
	v_lshl_add_u64 v[108:109], v[32:33], 0, v[108:109]
	global_load_dword v2, v[108:109], off
	v_add_u32_e32 v35, v36, v58
	s_and_b64 vcc, exec, s[2:3]
	s_waitcnt vmcnt(1)
	ds_write_b32 v35, v34
	s_cbranch_vccnz .LBB0_375
	s_ashr_i32 s85, s84, 31
	v_readlane_b32 s40, v255, 11
	v_lshl_add_u64 v[34:35], s[84:85], 0, v[0:1]
	v_readlane_b32 s44, v255, 15
	v_readlane_b32 s45, v255, 16
	v_readlane_b32 s41, v255, 12
	v_readlane_b32 s42, v255, 13
	v_lshl_add_u64 v[34:35], v[34:35], 2, s[44:45]
	global_load_dword v34, v[34:35], off offset:168
	v_readlane_b32 s43, v255, 14
	v_readlane_b32 s46, v255, 17
	v_readlane_b32 s47, v255, 18
	v_readlane_b32 s48, v255, 19
	v_readlane_b32 s49, v255, 20
	v_readlane_b32 s50, v255, 21
	v_readlane_b32 s51, v255, 22
	v_readlane_b32 s52, v255, 23
	v_readlane_b32 s53, v255, 24
	v_readlane_b32 s54, v255, 25
	v_readlane_b32 s55, v255, 26
	s_waitcnt vmcnt(0)
	v_mul_f32_e32 v2, v2, v34
.LBB0_375:
	v_or_b32_e32 v34, s84, v90
	v_ashrrev_i32_e32 v35, 31, v34
	v_lshlrev_b64 v[34:35], 13, v[34:35]
	v_lshl_add_u64 v[34:35], v[32:33], 0, v[34:35]
	global_load_dword v34, v[34:35], off
	v_add_u32_e32 v35, v36, v59
	s_and_b64 vcc, exec, s[2:3]
	s_waitcnt vmcnt(1)
	ds_write_b32 v35, v2
	s_cbranch_vccnz .LBB0_377
	s_ashr_i32 s85, s84, 31
	v_readlane_b32 s40, v255, 11
	v_lshl_add_u64 v[108:109], s[84:85], 0, v[0:1]
	v_readlane_b32 s44, v255, 15
	v_readlane_b32 s45, v255, 16
	v_readlane_b32 s41, v255, 12
	v_readlane_b32 s42, v255, 13
	v_lshl_add_u64 v[108:109], v[108:109], 2, s[44:45]
	global_load_dword v2, v[108:109], off offset:176
	v_readlane_b32 s43, v255, 14
	v_readlane_b32 s46, v255, 17
	v_readlane_b32 s47, v255, 18
	v_readlane_b32 s48, v255, 19
	v_readlane_b32 s49, v255, 20
	v_readlane_b32 s50, v255, 21
	v_readlane_b32 s51, v255, 22
	v_readlane_b32 s52, v255, 23
	v_readlane_b32 s53, v255, 24
	v_readlane_b32 s54, v255, 25
	v_readlane_b32 s55, v255, 26
	s_waitcnt vmcnt(0)
	v_mul_f32_e32 v34, v34, v2
.LBB0_377:
	v_or_b32_e32 v108, s84, v91
	v_ashrrev_i32_e32 v109, 31, v108
	v_lshlrev_b64 v[108:109], 13, v[108:109]
	v_lshl_add_u64 v[108:109], v[32:33], 0, v[108:109]
	global_load_dword v2, v[108:109], off
	v_add_u32_e32 v35, v36, v60
	s_and_b64 vcc, exec, s[2:3]
	s_waitcnt vmcnt(1)
	ds_write_b32 v35, v34
	s_cbranch_vccnz .LBB0_379
	s_ashr_i32 s85, s84, 31
	v_readlane_b32 s40, v255, 11
	v_lshl_add_u64 v[34:35], s[84:85], 0, v[0:1]
	v_readlane_b32 s44, v255, 15
	v_readlane_b32 s45, v255, 16
	v_readlane_b32 s41, v255, 12
	v_readlane_b32 s42, v255, 13
	v_lshl_add_u64 v[34:35], v[34:35], 2, s[44:45]
	global_load_dword v34, v[34:35], off offset:184
	v_readlane_b32 s43, v255, 14
	v_readlane_b32 s46, v255, 17
	v_readlane_b32 s47, v255, 18
	v_readlane_b32 s48, v255, 19
	v_readlane_b32 s49, v255, 20
	v_readlane_b32 s50, v255, 21
	v_readlane_b32 s51, v255, 22
	v_readlane_b32 s52, v255, 23
	v_readlane_b32 s53, v255, 24
	v_readlane_b32 s54, v255, 25
	v_readlane_b32 s55, v255, 26
	s_waitcnt vmcnt(0)
	v_mul_f32_e32 v2, v2, v34
.LBB0_379:
	v_or_b32_e32 v34, s84, v92
	v_ashrrev_i32_e32 v35, 31, v34
	v_lshlrev_b64 v[34:35], 13, v[34:35]
	v_lshl_add_u64 v[34:35], v[32:33], 0, v[34:35]
	global_load_dword v34, v[34:35], off
	v_add_u32_e32 v35, v36, v61
	s_and_b64 vcc, exec, s[2:3]
	s_waitcnt vmcnt(1)
	ds_write_b32 v35, v2
	s_cbranch_vccnz .LBB0_381
	s_ashr_i32 s85, s84, 31
	v_readlane_b32 s40, v255, 11
	v_lshl_add_u64 v[108:109], s[84:85], 0, v[0:1]
	v_readlane_b32 s44, v255, 15
	v_readlane_b32 s45, v255, 16
	v_readlane_b32 s41, v255, 12
	v_readlane_b32 s42, v255, 13
	v_lshl_add_u64 v[108:109], v[108:109], 2, s[44:45]
	global_load_dword v2, v[108:109], off offset:192
	v_readlane_b32 s43, v255, 14
	v_readlane_b32 s46, v255, 17
	v_readlane_b32 s47, v255, 18
	v_readlane_b32 s48, v255, 19
	v_readlane_b32 s49, v255, 20
	v_readlane_b32 s50, v255, 21
	v_readlane_b32 s51, v255, 22
	v_readlane_b32 s52, v255, 23
	v_readlane_b32 s53, v255, 24
	v_readlane_b32 s54, v255, 25
	v_readlane_b32 s55, v255, 26
	s_waitcnt vmcnt(0)
	v_mul_f32_e32 v34, v34, v2
; #define LAS __attribute__((address_space(3)))
; #define LDS_WAIT() asm volatile("s_waitcnt lgkmcnt(0)" ::: "memory")
; __device__ __forceinline__ void transpose_item(const float* W, int K, int N, bf16* WT, int mode, const float* gain, LAS float* scr, int item, int lane) {
;     const int nblk = N / 32, kb = item / nblk, nb = item % nblk, k0 = 64 * kb, n0 = 32 * nb;
; #pragma unroll
;     for (int i = 0; i < 32; ++i) { const int kk = 2 * i + (lane >> 5); float w = W[(size_t)(k0 + kk) * N + n0 + (lane & 31)]; if (gain) w *= gain[k0 + kk]; scr[kk * 33 + (lane & 31)] = w; }
;     LDS_WAIT(); asm volatile("" ::: "memory");
.LBB0_381:
	v_or_b32_e32 v108, s84, v93
	v_ashrrev_i32_e32 v109, 31, v108
	v_lshlrev_b64 v[108:109], 13, v[108:109]
	v_lshl_add_u64 v[108:109], v[32:33], 0, v[108:109]
	global_load_dword v35, v[108:109], off
	v_add_u32_e32 v2, v36, v62
	s_and_b64 vcc, exec, s[2:3]
	s_waitcnt vmcnt(1)
	ds_write_b32 v2, v34
	s_cbranch_vccnz .LBB0_383
	s_ashr_i32 s85, s84, 31
	v_readlane_b32 s40, v255, 11
	v_lshl_add_u64 v[108:109], s[84:85], 0, v[0:1]
	v_readlane_b32 s44, v255, 15
	v_readlane_b32 s45, v255, 16
	v_readlane_b32 s41, v255, 12
	v_readlane_b32 s42, v255, 13
	v_lshl_add_u64 v[108:109], v[108:109], 2, s[44:45]
	global_load_dword v34, v[108:109], off offset:200
	v_readlane_b32 s43, v255, 14
	v_readlane_b32 s46, v255, 17
	v_readlane_b32 s47, v255, 18
	v_readlane_b32 s48, v255, 19
	v_readlane_b32 s49, v255, 20
	v_readlane_b32 s50, v255, 21
	v_readlane_b32 s51, v255, 22
	v_readlane_b32 s52, v255, 23
	v_readlane_b32 s53, v255, 24
	v_readlane_b32 s54, v255, 25
	v_readlane_b32 s55, v255, 26
	s_waitcnt vmcnt(0)
	v_mul_f32_e32 v35, v35, v34
.LBB0_383:
	v_or_b32_e32 v108, s84, v94
	v_ashrrev_i32_e32 v109, 31, v108
	v_lshlrev_b64 v[108:109], 13, v[108:109]
	v_lshl_add_u64 v[108:109], v[32:33], 0, v[108:109]
	global_load_dword v34, v[108:109], off
	s_and_b64 vcc, exec, s[2:3]
	s_waitcnt vmcnt(1)
	ds_write_b32 v2, v35 offset:264
	s_cbranch_vccnz .LBB0_385
	s_ashr_i32 s85, s84, 31
	v_readlane_b32 s40, v255, 11
	v_lshl_add_u64 v[108:109], s[84:85], 0, v[0:1]
	v_readlane_b32 s44, v255, 15
	v_readlane_b32 s45, v255, 16
	v_readlane_b32 s41, v255, 12
	v_readlane_b32 s42, v255, 13
	v_lshl_add_u64 v[108:109], v[108:109], 2, s[44:45]
	global_load_dword v35, v[108:109], off offset:208
	v_readlane_b32 s43, v255, 14
	v_readlane_b32 s46, v255, 17
	v_readlane_b32 s47, v255, 18
	v_readlane_b32 s48, v255, 19
	v_readlane_b32 s49, v255, 20
	v_readlane_b32 s50, v255, 21
	v_readlane_b32 s51, v255, 22
	v_readlane_b32 s52, v255, 23
	v_readlane_b32 s53, v255, 24
	v_readlane_b32 s54, v255, 25
	v_readlane_b32 s55, v255, 26
	s_waitcnt vmcnt(0)
	v_mul_f32_e32 v34, v34, v35
.LBB0_385:
	v_or_b32_e32 v108, s84, v95
	v_ashrrev_i32_e32 v109, 31, v108
	v_lshlrev_b64 v[108:109], 13, v[108:109]
	v_lshl_add_u64 v[108:109], v[32:33], 0, v[108:109]
	global_load_dword v35, v[108:109], off
	s_and_b64 vcc, exec, s[2:3]
	s_waitcnt vmcnt(1)
	ds_write_b32 v2, v34 offset:528
	s_cbranch_vccnz .LBB0_387
	s_ashr_i32 s85, s84, 31
	v_readlane_b32 s40, v255, 11
	v_lshl_add_u64 v[108:109], s[84:85], 0, v[0:1]
	v_readlane_b32 s44, v255, 15
	v_readlane_b32 s45, v255, 16
	v_readlane_b32 s41, v255, 12
	v_readlane_b32 s42, v255, 13
	v_lshl_add_u64 v[108:109], v[108:109], 2, s[44:45]
	global_load_dword v34, v[108:109], off offset:216
	v_readlane_b32 s43, v255, 14
	v_readlane_b32 s46, v255, 17
	v_readlane_b32 s47, v255, 18
	v_readlane_b32 s48, v255, 19
	v_readlane_b32 s49, v255, 20
	v_readlane_b32 s50, v255, 21
	v_readlane_b32 s51, v255, 22
	v_readlane_b32 s52, v255, 23
	v_readlane_b32 s53, v255, 24
	v_readlane_b32 s54, v255, 25
	v_readlane_b32 s55, v255, 26
	s_waitcnt vmcnt(0)
	v_mul_f32_e32 v35, v35, v34
.LBB0_387:
	v_or_b32_e32 v108, s84, v96
	v_ashrrev_i32_e32 v109, 31, v108
	v_lshlrev_b64 v[108:109], 13, v[108:109]
	v_lshl_add_u64 v[108:109], v[32:33], 0, v[108:109]
	global_load_dword v34, v[108:109], off
	s_and_b64 vcc, exec, s[2:3]
	s_waitcnt vmcnt(1)
	ds_write_b32 v2, v35 offset:792
	s_cbranch_vccnz .LBB0_389
	s_ashr_i32 s85, s84, 31
	v_readlane_b32 s40, v255, 11
	v_lshl_add_u64 v[108:109], s[84:85], 0, v[0:1]
	v_readlane_b32 s44, v255, 15
	v_readlane_b32 s45, v255, 16
	v_readlane_b32 s41, v255, 12
	v_readlane_b32 s42, v255, 13
	v_lshl_add_u64 v[108:109], v[108:109], 2, s[44:45]
	global_load_dword v35, v[108:109], off offset:224
	v_readlane_b32 s43, v255, 14
	v_readlane_b32 s46, v255, 17
	v_readlane_b32 s47, v255, 18
	v_readlane_b32 s48, v255, 19
	v_readlane_b32 s49, v255, 20
	v_readlane_b32 s50, v255, 21
	v_readlane_b32 s51, v255, 22
	v_readlane_b32 s52, v255, 23
	v_readlane_b32 s53, v255, 24
	v_readlane_b32 s54, v255, 25
	v_readlane_b32 s55, v255, 26
	s_waitcnt vmcnt(0)
	v_mul_f32_e32 v34, v34, v35
.LBB0_389:
	v_or_b32_e32 v108, s84, v97
	v_ashrrev_i32_e32 v109, 31, v108
	v_lshlrev_b64 v[108:109], 13, v[108:109]
	v_lshl_add_u64 v[108:109], v[32:33], 0, v[108:109]
	global_load_dword v35, v[108:109], off
	s_and_b64 vcc, exec, s[2:3]
	s_waitcnt vmcnt(1)
	ds_write_b32 v2, v34 offset:1056
	s_cbranch_vccnz .LBB0_391
	s_ashr_i32 s85, s84, 31
	v_readlane_b32 s40, v255, 11
	v_lshl_add_u64 v[108:109], s[84:85], 0, v[0:1]
	v_readlane_b32 s44, v255, 15
	v_readlane_b32 s45, v255, 16
	v_readlane_b32 s41, v255, 12
	v_readlane_b32 s42, v255, 13
	v_lshl_add_u64 v[108:109], v[108:109], 2, s[44:45]
	global_load_dword v34, v[108:109], off offset:232
	v_readlane_b32 s43, v255, 14
	v_readlane_b32 s46, v255, 17
	v_readlane_b32 s47, v255, 18
	v_readlane_b32 s48, v255, 19
	v_readlane_b32 s49, v255, 20
	v_readlane_b32 s50, v255, 21
	v_readlane_b32 s51, v255, 22
	v_readlane_b32 s52, v255, 23
	v_readlane_b32 s53, v255, 24
	v_readlane_b32 s54, v255, 25
	v_readlane_b32 s55, v255, 26
	s_waitcnt vmcnt(0)
	v_mul_f32_e32 v35, v35, v34
; __host__ __device__ __forceinline__ size_t tiled_off(int row, int col, int K) { return ((size_t)(row >> 7) * (K >> 6) + (col >> 6)) * 8192 + (lds_byte(row & 127, col & 63) >> 1); }
; #define GAS __attribute__((address_space(1)))
; #define LDS_WAIT() asm volatile("s_waitcnt lgkmcnt(0)" ::: "memory")
; __device__ __forceinline__ unsigned pk2(float lo, float hi) { return f2bf(lo) | (f2bf(hi) << 16); }
; __device__ __forceinline__ void transpose_item(const float* W, int K, int N, bf16* WT, int mode, const float* gain, LAS float* scr, int item, int lane) {
;     ...
;     for (int i = 0; i < 32; ++i) { const int kk = 2 * i + (lane >> 5); float w = W[(size_t)(k0 + kk) * N + n0 + (lane & 31)]; if (gain) w *= gain[k0 + kk]; scr[kk * 33 + (lane & 31)] = w; }
;     LDS_WAIT(); asm volatile("" ::: "memory");
; __device__ __forceinline__ void p0_prologue(const Args& a, LAS unsigned char* lds, int vcu, int G, int wave, int lane) {
;     ...
;     { const float* x = a.in[I_X]; bf16* hb = (bf16*)(ws + WS_HBA); float* ss = (float*)(ws + WS_SSA);
;       for (int m0 = gw * 4; m0 < M; m0 += NGW * 4) {
;           f32x4 v[4][4]; float s[4];
; #pragma unroll
;           for (int r = 0; r < 4; ++r) { const GAS f32x4* xr = (const GAS f32x4*)(x + (size_t)(m0 + r) * D) + lane;
; #pragma unroll
;               for (int j = 0; j < 4; ++j) v[r][j] = xr[64 * j]; }
; #pragma unroll
;           for (int r = 0; r < 4; ++r) { float t = 0.f;
; #pragma unroll
;               for (int j = 0; j < 4; ++j) t += (v[r][j].x * v[r][j].x + v[r][j].y * v[r][j].y) + (v[r][j].z * v[r][j].z + v[r][j].w * v[r][j].w);
;               s[r] = wave_sum(t); }
; #pragma unroll
;           for (int r = 0; r < 4; ++r) {
; #pragma unroll
;               for (int j = 0; j < 4; ++j) *(GAS unsigned long long*)(hb + pg8::tiled_off(m0 + r, 4 * lane + 256 * j, D)) = (unsigned long long)pk2(v[r][j].x, v[r][j].y) | ((unsigned long long)pk2(v[r][j].z, v[r][j].w) << 32);
;               if (lane < 16) ss[(size_t)(m0 + r) * 16 + lane] = lane == 0 ? s[r] : 0.f; } } }
.LBB0_391:
	v_or_b32_e32 v108, s84, v98
	v_ashrrev_i32_e32 v109, 31, v108
	v_lshlrev_b64 v[108:109], 13, v[108:109]
	v_lshl_add_u64 v[108:109], v[32:33], 0, v[108:109]
	global_load_dword v34, v[108:109], off
	s_and_b64 vcc, exec, s[2:3]
	s_waitcnt vmcnt(1)
	ds_write_b32 v2, v35 offset:1320
	s_cbranch_vccnz .LBB0_393
	s_ashr_i32 s85, s84, 31
	v_readlane_b32 s40, v255, 11
	v_lshl_add_u64 v[108:109], s[84:85], 0, v[0:1]
	v_readlane_b32 s44, v255, 15
	v_readlane_b32 s45, v255, 16
	v_readlane_b32 s41, v255, 12
	v_readlane_b32 s42, v255, 13
	v_lshl_add_u64 v[108:109], v[108:109], 2, s[44:45]
	global_load_dword v35, v[108:109], off offset:240
	v_readlane_b32 s43, v255, 14
	v_readlane_b32 s46, v255, 17
	v_readlane_b32 s47, v255, 18
	v_readlane_b32 s48, v255, 19
	v_readlane_b32 s49, v255, 20
	v_readlane_b32 s50, v255, 21
	v_readlane_b32 s51, v255, 22
	v_readlane_b32 s52, v255, 23
	v_readlane_b32 s53, v255, 24
	v_readlane_b32 s54, v255, 25
	v_readlane_b32 s55, v255, 26
	s_waitcnt vmcnt(0)
	v_mul_f32_e32 v34, v34, v35
.LBB0_393:
	v_or_b32_e32 v108, s84, v99
	v_ashrrev_i32_e32 v109, 31, v108
	v_lshlrev_b64 v[108:109], 13, v[108:109]
	v_lshl_add_u64 v[32:33], v[32:33], 0, v[108:109]
	global_load_dword v32, v[32:33], off
	s_and_b64 vcc, exec, s[2:3]
	s_waitcnt vmcnt(1)
	ds_write_b32 v2, v34 offset:1584
	s_cbranch_vccnz .LBB0_22
	s_ashr_i32 s85, s84, 31
	v_readlane_b32 s40, v255, 11
	v_lshl_add_u64 v[34:35], s[84:85], 0, v[0:1]
	v_readlane_b32 s44, v255, 15
	v_readlane_b32 s45, v255, 16
	v_readlane_b32 s41, v255, 12
	v_readlane_b32 s42, v255, 13
	v_lshl_add_u64 v[34:35], v[34:35], 2, s[44:45]
	global_load_dword v33, v[34:35], off offset:248
	v_readlane_b32 s43, v255, 14
	v_readlane_b32 s46, v255, 17
	v_readlane_b32 s47, v255, 18
	v_readlane_b32 s48, v255, 19
	v_readlane_b32 s49, v255, 20
	v_readlane_b32 s50, v255, 21
	v_readlane_b32 s51, v255, 22
	v_readlane_b32 s52, v255, 23
	v_readlane_b32 s53, v255, 24
	v_readlane_b32 s54, v255, 25
	v_readlane_b32 s55, v255, 26
	s_waitcnt vmcnt(0)
	v_mul_f32_e32 v32, v32, v33
	s_branch .LBB0_22
.LBB0_395:
	s_cmpk_gt_i32 s12, 0x1fff
	v_lshlrev_b32_e32 v64, 4, v209
	s_cbranch_scc1 .LBB0_406
	v_mbcnt_lo_u32_b32 v0, -1, 0
	v_mbcnt_hi_u32_b32 v0, -1, v0
	v_and_b32_e32 v1, 64, v0
	v_add_u32_e32 v1, 64, v1
	v_xor_b32_e32 v2, 1, v0
	v_cmp_lt_i32_e32 vcc, v2, v1
	v_readlane_b32 s7, v255, 6
	v_readlane_b32 s9, v255, 59
	v_cndmask_b32_e32 v2, v0, v2, vcc
	v_lshlrev_b32_e32 v84, 2, v2
	v_xor_b32_e32 v2, 2, v0
	v_cmp_lt_i32_e32 vcc, v2, v1
	s_lshl_b32 s6, s12, 2
	v_readlane_b32 s10, v255, 4
	v_cndmask_b32_e32 v2, v0, v2, vcc
	v_lshlrev_b32_e32 v85, 2, v2
	v_xor_b32_e32 v2, 4, v0
	v_cmp_lt_i32_e32 vcc, v2, v1
	s_lshl_b32 s7, s7, 11
	s_lshl_b32 s9, s9, 8
	v_cndmask_b32_e32 v2, v0, v2, vcc
	v_lshlrev_b32_e32 v86, 2, v2
	v_xor_b32_e32 v2, 8, v0
	v_cmp_lt_i32_e32 vcc, v2, v1
	v_readlane_b32 s11, v255, 5
	s_add_i32 s13, s7, s9
	v_cndmask_b32_e32 v2, v0, v2, vcc
	v_lshlrev_b32_e32 v87, 2, v2
	v_xor_b32_e32 v2, 16, v0
	v_cmp_lt_i32_e32 vcc, v2, v1
	s_ashr_i32 s7, s6, 31
	s_lshl_b32 s8, s10, 5
	v_cndmask_b32_e32 v2, v0, v2, vcc
	s_lshl_b32 s15, s10, 11
	s_lshl_b64 s[10:11], s[6:7], 6
	v_lshlrev_b32_e32 v88, 2, v2
	v_xor_b32_e32 v2, 32, v0
	s_add_u32 s10, s28, s10
	v_cmp_lt_i32_e32 vcc, v2, v1
	v_mov_b32_e32 v67, 0
	v_lshlrev_b32_e32 v66, 2, v209
	s_addc_u32 s11, s29, s11
	v_cndmask_b32_e32 v0, v0, v2, vcc
	v_lshl_add_u64 v[8:9], s[10:11], 0, v[66:67]
	s_mov_b64 s[10:11], 0x2000c0
	s_ashr_i32 s9, s8, 31
	v_lshlrev_b32_e32 v89, 2, v0
	v_lshlrev_b32_e32 v0, 9, v208
	v_lshl_add_u64 v[68:69], v[8:9], 0, s[10:11]
	s_lshl_b64 s[10:11], s[8:9], 6
	s_lshl_b64 s[16:17], s[6:7], 12
	v_readlane_b32 s40, v255, 11
	v_and_b32_e32 v0, 0x6000, v0
	v_readlane_b32 s41, v255, 12
	s_add_u32 s16, s40, s16
	v_or_b32_e32 v2, 0x8000, v0
	v_or_b32_e32 v4, 0x10000, v0
	v_or_b32_e32 v6, 0x18000, v0
	v_mov_b32_e32 v65, v67
	s_addc_u32 s17, s41, s17
	v_lshlrev_b32_e32 v1, 3, v208
	v_lshl_add_u64 v[8:9], s[16:17], 0, v[64:65]
	s_mov_b64 s[16:17], 0x3c00
	v_lshlrev_b32_e32 v72, 1, v2
	v_lshlrev_b32_e32 v76, 1, v4
	v_lshlrev_b32_e32 v80, 1, v6
	v_bfe_u32 v90, v208, 3, 1
	v_and_b32_e32 v91, 56, v1
	v_cmp_gt_u32_e64 s[2:3], 16, v209
	v_cmp_eq_u32_e64 s[4:5], 0, v209
	v_lshl_add_u64 v[70:71], v[8:9], 0, s[16:17]
	s_lshl_b64 s[16:17], s[8:9], 12
	s_movk_i32 s7, 0x7fff
	s_mov_b32 s9, 0xffff0000
	v_lshlrev_b32_e32 v66, 1, v0
	v_mov_b32_e32 v74, v72
	v_mov_b32_e32 v75, v67
	v_mov_b32_e32 v78, v76
	v_mov_b32_e32 v79, v67
	v_mov_b32_e32 v82, v80
	v_mov_b32_e32 v83, v67
	v_readlane_b32 s42, v255, 13
	v_readlane_b32 s43, v255, 14
	v_readlane_b32 s44, v255, 15
	v_readlane_b32 s45, v255, 16
	v_readlane_b32 s46, v255, 17
	v_readlane_b32 s47, v255, 18
	v_readlane_b32 s48, v255, 19
	v_readlane_b32 s49, v255, 20
	v_readlane_b32 s50, v255, 21
	v_readlane_b32 s51, v255, 22
	v_readlane_b32 s52, v255, 23
	v_readlane_b32 s53, v255, 24
	v_readlane_b32 s54, v255, 25
	v_readlane_b32 s55, v255, 26
	s_branch .LBB0_398

; __host__ __device__ __forceinline__ size_t tiled_off(int row, int col, int K) { return ((size_t)(row >> 7) * (K >> 6) + (col >> 6)) * 8192 + (lds_byte(row & 127, col & 63) >> 1); }
; #define GAS __attribute__((address_space(1)))
; __device__ __forceinline__ unsigned pk2(float lo, float hi) { return f2bf(lo) | (f2bf(hi) << 16); }
; __device__ __forceinline__ void p0_prologue(const Args& a, LAS unsigned char* lds, int vcu, int G, int wave, int lane) {
;     ...
;     { const GAS f32x4* p = (const GAS f32x4*)a.in[I_P]; GAS unsigned long long* o = (GAS unsigned long long*)(ws + WS_PB); const size_t n4 = (size_t)2 * M * PLE / 4;
;       const size_t stride = (size_t)NGW * 64;
;       for (size_t i = (size_t)gw * 64 + lane; i < n4; i += 8 * stride) { f32x4 v[8];
; #pragma unroll
;           for (int k = 0; k < 8; ++k) v[k] = p[i + k * stride];
; #pragma unroll
;           for (int k = 0; k < 8; ++k) { const size_t e = (i + k * stride) * 4, lay = e / ((size_t)M * PLE), rem = e % ((size_t)M * PLE);
;               *(GAS unsigned long long*)((bf16*)(ws + WS_PB) + lay * ((size_t)M * PLE) + pg8::tiled_off((int)(rem / PLE), (int)(rem % PLE), PLE)) = (unsigned long long)pk2(v[k].x, v[k].y) | ((unsigned long long)pk2(v[k].z, v[k].w) << 32); } } }
.LBB0_406:
	s_ashr_i32 s13, s12, 31
	s_lshl_b64 s[8:9], s[12:13], 6
	v_mov_b64_e32 v[0:1], 0x3fffff
	v_cmp_gt_u64_e32 vcc, s[8:9], v[0:1]
	s_mov_b64 s[2:3], 0x3fffff
	s_cbranch_vccnz .LBB0_410
	s_add_u32 s4, s28, 0x4000000
	s_addc_u32 s5, s29, 0
	s_ashr_i32 s15, s14, 31
	s_lshl_b64 s[16:17], s[12:13], 8
	s_lshl_b64 s[18:19], s[12:13], 15
	v_readlane_b32 s60, v255, 11
	s_lshl_b64 s[6:7], s[14:15], 6
	v_or_b32_e32 v4, s8, v209
	v_mov_b32_e32 v5, s9
	s_lshl_b64 s[8:9], s[14:15], 10
	s_lshl_b64 s[10:11], s[14:15], 9
	v_lshl_or_b32 v6, v209, 2, s16
	v_mov_b32_e32 v7, s17
	s_lshl_b64 s[16:17], s[14:15], 11
	s_lshl_b64 s[54:55], s[14:15], 8
	v_lshl_or_b32 v8, v209, 9, s18
	v_mov_b32_e32 v9, s19
	s_lshl_b64 s[58:59], s[14:15], 18
	s_lshl_b64 s[18:19], s[12:13], 10
	v_readlane_b32 s62, v255, 13
	v_readlane_b32 s63, v255, 14
	s_add_u32 s18, s62, s18
	v_mov_b32_e32 v65, 0
	v_readlane_b32 s61, v255, 12
	s_addc_u32 s19, s63, s19
	s_mul_hi_i32 s25, s14, 0x300
	s_mul_i32 s24, s14, 0x300
	s_mul_hi_i32 s45, s14, 0x500
	s_mul_i32 s44, s14, 0x500
	s_mul_hi_i32 s49, s14, 0x600
	s_mul_i32 s48, s14, 0x600
	s_mul_hi_i32 s51, s14, 0x700
	s_mul_i32 s50, s14, 0x700
	v_lshl_add_u64 v[10:11], s[18:19], 0, v[64:65]
	s_lshl_b64 s[60:61], s[14:15], 13
	s_mov_b64 s[14:15], 0
	s_movk_i32 s13, 0x7fff
	s_mov_b32 s18, 0xffff0000
	v_readlane_b32 s64, v255, 15
	v_readlane_b32 s65, v255, 16
	v_readlane_b32 s66, v255, 17
	v_readlane_b32 s67, v255, 18
	v_readlane_b32 s68, v255, 19
	v_readlane_b32 s69, v255, 20
	v_readlane_b32 s70, v255, 21
	v_readlane_b32 s71, v255, 22
	v_readlane_b32 s72, v255, 23
	v_readlane_b32 s73, v255, 24
	v_readlane_b32 s74, v255, 25
	v_readlane_b32 s75, v255, 26

; __device__ __forceinline__ void p0_prologue(const Args& a, LAS unsigned char* lds, int vcu, int G, int wave, int lane) {
;     ...
;     if (gw == 0) { const float* rb = a.in[I_RB]; float* bt = (float*)(ws + WS_BT);
;         for (int i = lane; i < 8 * 128; i += 64) { const int h = i >> 7, d = i & 127; bt[i] = (rb[T5_BUCKET[d] * 8 + h] - rb[31 * 8 + h]) * 1.4426950408889634f; } }
.LBB0_410:
	s_cmp_eq_u32 s12, 0
	s_cbranch_scc0 .LBB0_414
	v_and_b32_e32 v0, 63, v208
	v_lshlrev_b32_e32 v0, 2, v0
	v_mov_b32_e32 v1, 0
	v_readlane_b32 s40, v255, 43
	v_lshl_add_u64 v[0:1], s[28:29], 0, v[0:1]
	s_mov_b64 s[2:3], 0x100000
	v_readlane_b32 s50, v255, 53
	v_readlane_b32 s51, v255, 54
	v_lshl_add_u64 v[0:1], v[0:1], 0, s[2:3]
	s_mov_b64 s[2:3], 0
	s_mov_b64 s[4:5], 0x100
	s_movk_i32 s6, 0x3bf
	v_mov_b32_e32 v2, v209
	s_mov_b64 s[18:19], s[50:51]
	v_readlane_b32 s41, v255, 44
	v_readlane_b32 s42, v255, 45
	v_readlane_b32 s43, v255, 46
	v_readlane_b32 s44, v255, 47
	v_readlane_b32 s45, v255, 48
	v_readlane_b32 s46, v255, 49
	v_readlane_b32 s47, v255, 50
	v_readlane_b32 s48, v255, 51
	v_readlane_b32 s49, v255, 52
	v_readlane_b32 s52, v255, 55
	v_readlane_b32 s53, v255, 56
	v_readlane_b32 s54, v255, 57
	v_readlane_b32 s55, v255, 58

; __device__ __forceinline__ unsigned xb_ld(unsigned* p)              { return __hip_atomic_load(p, __ATOMIC_RELAXED, __HIP_MEMORY_SCOPE_AGENT); }
; __device__ __forceinline__ void xcd_barrier_complete(unsigned* bar, unsigned x, unsigned& nloc, unsigned& nx) {
;     const unsigned G = gridDim.x * gridDim.y * gridDim.z;
;     unsigned sum, cnt, mine, sp = 0u;
;     for (;;) {
;         sum = 0u; cnt = 0u; mine = 0u;
; #pragma unroll
;         for (unsigned j = 0; j < 16; ++j) { const unsigned c = xb_ld(&bar[XB_XCNT(j)]); sum += c; cnt += (c > 0u) ? 1u : 0u; mine = (j == x) ? c : mine; }
; __device__ __forceinline__ void xcd_barrier(const XcdBarrier& b) {
;     asm volatile("s_waitcnt vmcnt(0)" ::: "memory");
;     __syncthreads();
;     if (threadIdx.x == 0) {
;         unsigned* bar = b.bar;
;         __builtin_amdgcn_s_waitcnt(0);
;         unsigned nloc = b.st[0], nx = b.st[1];
;         if (nloc == 0u) { xcd_barrier_complete(bar, b.x, nloc, nx); b.st[0] = nloc; b.st[1] = nx; }
.LBB0_414:
	s_cmp_gt_i32 s37, 1
	s_cselect_b64 s[2:3], -1, 0
	s_and_b64 s[0:1], s[0:1], s[2:3]
	s_andn2_b64 vcc, exec, s[0:1]
	s_cbranch_vccnz .LBB0_468
	s_waitcnt vmcnt(0)
	s_waitcnt lgkmcnt(0)
	s_barrier
	s_mov_b64 s[0:1], exec
	v_readlane_b32 s4, v255, 9
	v_readlane_b32 s5, v255, 10
	s_and_b64 s[4:5], s[0:1], s[4:5]
	s_mov_b64 exec, s[4:5]
	s_cbranch_execz .LBB0_467
	s_add_i32 s4, 0, 0x20040
	v_mov_b32_e32 v0, s4
	s_waitcnt vmcnt(0) expcnt(0) lgkmcnt(0)
	ds_read_b32 v2, v0
	s_add_i32 s4, 0, 0x20044
	v_mov_b32_e32 v0, s4
	ds_read_b32 v0, v0
	s_waitcnt lgkmcnt(1)
	v_cmp_ne_u32_e32 vcc, 0, v2
	s_cbranch_vccnz .LBB0_431
	v_readlane_b32 s4, v255, 4
	v_readlane_b32 s5, v255, 5
	v_readlane_b32 s6, v255, 7
	s_mul_i32 s18, s5, s6
	s_mul_i32 s18, s18, s4
	s_add_u32 s4, s28, 0x1000
	s_addc_u32 s5, s29, 0
	s_add_u32 s6, s28, 0x1100
	s_addc_u32 s7, s29, 0
	s_add_u32 s8, s28, 0x1200
	s_addc_u32 s9, s29, 0
	s_add_u32 s10, s28, 0x1300
	s_addc_u32 s11, s29, 0
	s_mov_b32 s19, 1
	v_mov_b32_e32 v16, 0
	s_branch .LBB0_419

; __device__ __forceinline__ unsigned xb_ld(unsigned* p)              { return __hip_atomic_load(p, __ATOMIC_RELAXED, __HIP_MEMORY_SCOPE_AGENT); }
; __device__ __forceinline__ unsigned xb_add(unsigned* p, unsigned v) { return __hip_atomic_fetch_add(p, v, __ATOMIC_RELAXED, __HIP_MEMORY_SCOPE_AGENT); }
; __device__ __forceinline__ void xcd_barrier_complete(unsigned* bar, unsigned x, unsigned& nloc, unsigned& nx) {
;     ...
;         for (unsigned j = 0; j < 16; ++j) { const unsigned c = xb_ld(&bar[XB_XCNT(j)]); sum += c; cnt += (c > 0u) ? 1u : 0u; mine = (j == x) ? c : mine; }
;         if (sum == G) break;
;         __builtin_amdgcn_s_sleep(1);
;         if ((++sp & 255u) == 0u) { if (xb_ld(&bar[XB_TMO])) break; if (sp > XB_SPIN_CAP) { atomicAdd(&bar[XB_TMO], 1u); break; } }
;     }
;     nloc = mine > 0u ? mine : 1u; nx = cnt > 0u ? cnt : 1u;
; }
; __device__ __forceinline__ void xcd_barrier(const XcdBarrier& b) {
;     ...
;         const unsigned old = xb_add(&bar[XB_XSUB(b.x)], 1u);
;         const unsigned gen = old / nloc;
;         if (old + 1u == (gen + 1u) * nloc) {
.LBB0_430:
	v_readlane_b32 s4, v255, 8
	s_cmp_eq_u32 s4, 0
	s_cselect_b64 vcc, -1, 0
	s_cmp_eq_u32 s4, 1
	v_cndmask_b32_e32 v16, 0, v15, vcc
	s_cselect_b64 vcc, -1, 0
	s_cmp_eq_u32 s4, 2
	v_cndmask_b32_e32 v16, v16, v0, vcc
	s_cselect_b64 vcc, -1, 0
	s_cmp_eq_u32 s4, 3
	v_cndmask_b32_e32 v16, v16, v1, vcc
	s_cselect_b64 vcc, -1, 0
	s_cmp_eq_u32 s4, 4
	v_cndmask_b32_e32 v16, v16, v2, vcc
	s_cselect_b64 vcc, -1, 0
	s_cmp_eq_u32 s4, 5
	v_cndmask_b32_e32 v16, v16, v3, vcc
	s_cselect_b64 vcc, -1, 0
	s_cmp_eq_u32 s4, 6
	v_cndmask_b32_e32 v16, v16, v4, vcc
	s_cselect_b64 vcc, -1, 0
	s_cmp_eq_u32 s4, 7
	v_cndmask_b32_e32 v16, v16, v5, vcc
	s_cselect_b64 vcc, -1, 0
	s_cmp_eq_u32 s4, 8
	v_cndmask_b32_e32 v16, v16, v6, vcc
	s_cselect_b64 vcc, -1, 0
	s_cmp_eq_u32 s4, 9
	v_cndmask_b32_e32 v16, v16, v7, vcc
	s_cselect_b64 vcc, -1, 0
	s_cmp_eq_u32 s4, 10
	v_cndmask_b32_e32 v16, v16, v8, vcc
	s_cselect_b64 vcc, -1, 0
	s_cmp_eq_u32 s4, 11
	v_cndmask_b32_e32 v16, v16, v9, vcc
	s_cselect_b64 vcc, -1, 0
	s_cmp_eq_u32 s4, 12
	v_cndmask_b32_e32 v16, v16, v10, vcc
	s_cselect_b64 vcc, -1, 0
	s_cmp_eq_u32 s4, 13
	v_cndmask_b32_e32 v16, v16, v11, vcc
	s_cselect_b64 vcc, -1, 0
	s_cmp_eq_u32 s4, 14
	v_cndmask_b32_e32 v16, v16, v12, vcc
	s_cselect_b64 vcc, -1, 0
	s_cmp_eq_u32 s4, 15
	v_cndmask_b32_e32 v16, v16, v13, vcc
	s_cselect_b64 vcc, -1, 0
	v_cndmask_b32_e32 v16, v16, v14, vcc
	v_cmp_ne_u32_e32 vcc, 0, v15
	s_add_i32 s4, 0, 0x20040
	s_nop 0
	v_cndmask_b32_e64 v15, 0, 1, vcc
	v_cmp_ne_u32_e32 vcc, 0, v0
	s_nop 1
	v_addc_co_u32_e32 v0, vcc, 0, v15, vcc
	v_cmp_ne_u32_e32 vcc, 0, v1
	s_nop 1
	v_cndmask_b32_e64 v1, 0, 1, vcc
	v_cmp_ne_u32_e32 vcc, 0, v2
	v_max_u32_e32 v2, 1, v16
	s_nop 0
	v_addc_co_u32_e32 v0, vcc, v0, v1, vcc
	v_cmp_ne_u32_e32 vcc, 0, v3
	s_nop 1
	v_cndmask_b32_e64 v1, 0, 1, vcc
	v_cmp_ne_u32_e32 vcc, 0, v4
	s_nop 1
	v_addc_co_u32_e32 v0, vcc, v0, v1, vcc
	v_cmp_ne_u32_e32 vcc, 0, v5
	s_nop 1
	v_cndmask_b32_e64 v1, 0, 1, vcc
	v_cmp_ne_u32_e32 vcc, 0, v6
	s_nop 1
	v_addc_co_u32_e32 v0, vcc, v0, v1, vcc
	v_cmp_ne_u32_e32 vcc, 0, v7
	s_nop 1
	v_cndmask_b32_e64 v1, 0, 1, vcc
	v_cmp_ne_u32_e32 vcc, 0, v8
	s_nop 1
	v_addc_co_u32_e32 v0, vcc, v0, v1, vcc
	v_cmp_ne_u32_e32 vcc, 0, v9
	s_nop 1
	v_cndmask_b32_e64 v1, 0, 1, vcc
	v_cmp_ne_u32_e32 vcc, 0, v10
	s_nop 1
	v_addc_co_u32_e32 v0, vcc, v0, v1, vcc
	v_cmp_ne_u32_e32 vcc, 0, v11
	s_nop 1
	v_cndmask_b32_e64 v1, 0, 1, vcc
	v_cmp_ne_u32_e32 vcc, 0, v12
	s_nop 1
	v_addc_co_u32_e32 v0, vcc, v0, v1, vcc
	v_cmp_ne_u32_e32 vcc, 0, v13
	s_nop 1
	v_cndmask_b32_e64 v1, 0, 1, vcc
	v_cmp_ne_u32_e32 vcc, 0, v14
	s_nop 1
	v_addc_co_u32_e32 v0, vcc, v0, v1, vcc
	v_mov_b32_e32 v1, s4
	s_add_i32 s4, 0, 0x20044
	v_max_u32_e32 v0, 1, v0
	ds_write_b32 v1, v2
	v_mov_b32_e32 v1, s4
	ds_write_b32 v1, v0
.LBB0_431:
	s_mov_b64 s[6:7], exec
	v_readlane_b32 s4, v255, 8
	s_lshl_b32 s4, s4, 8
	v_mbcnt_lo_u32_b32 v1, s6, 0
	s_add_u32 s4, s28, s4
	v_mbcnt_hi_u32_b32 v1, s7, v1
	s_addc_u32 s5, s29, 0
	v_cmp_eq_u32_e32 vcc, 0, v1
	s_and_saveexec_b64 s[8:9], vcc
	s_cbranch_execz .LBB0_433
	s_bcnt1_i32_b64 s6, s[6:7]
	v_mov_b32_e32 v3, 0x1000
	v_mov_b32_e32 v4, s6
	global_atomic_add v3, v3, v4, s[4:5] offset:1024 sc0

;   __device__ __forceinline__ bool next(int i,AttnUnit&u)const{ if(i>=8)return false; const int s=vcu&7,k=i&3; { const int p_=vcu>>3; u.bh=(p_>>3)*16+(p_&7)*2+(i>>2); } u.qb=(k==0)?s:(k==1)?15-s:(k==2)?16+s:31-s; return true; }
; #define RUN_GEMM(EPI, A_, B_, N_, K_, E_) do { pg8::Gemm g_{(const bf16*)(A_), (const bf16*)(ws + (B_)), M, (N_), (K_)}; SO S_; S_.init(M, (N_), G, bx); \
;         pg8::gemm_phase<EPI, SO, PG8_ALIGN, PG8_SP2>(lds, g_, S_, (E_)); } while (0)
;     __host__ __device__ bool next(int i, Unit& u) const {
;         const long L = (long)i * G + c; if (L >= nwg) return false;
;         int wgid = (int)L; { const int q = nwg / NXCD, r = nwg % NXCD, xcd = wgid % NXCD, off = wgid / NXCD; wgid = (xcd < r ? xcd * (q + 1) : r * (q + 1) + (xcd - r) * q) + off; }
;         const int nig = WGM * nN, gid = wgid / nig, fm = gid * WGM, gsz = (nM - fm) < WGM ? (nM - fm) : WGM;
;         u.pm = fm + ((wgid % nig) % gsz); u.pn = (wgid % nig) / gsz; return true;
; __global__ void __launch_bounds__(NWAVES * 64, 2) mega_fwd(Args args) {
;     ...
;     if (IN(1)) {
;         pg8::EpiGated<0> E{(bf16*)(ws + WS_U), D, SSA, args.in[I_CB1], args.in[I_CB1] + D};
;         RUN_GEMM(pg8::EpiGated<0>, HBA, WS_WPW1, 2 * D, D, E);
.LBB0_468:
	s_cmp_lt_i32 s36, 2
	s_cselect_b64 s[0:1], -1, 0
	s_add_u32 s24, s28, 0x200000
	s_addc_u32 s25, s29, 0
	s_and_b64 s[0:1], s[0:1], s[2:3]
	s_andn2_b64 vcc, exec, s[0:1]
	v_writelane_b32 v254, s36, 4
	s_nop 1
	v_writelane_b32 v254, s37, 5
	s_cbranch_vccnz .LBB0_497
	s_cmpk_gt_i32 s20, 0x3ff
	v_readfirstlane_b32 s22, v208
	s_cbranch_scc1 .LBB0_497
	s_ashr_i32 s33, s20, 31
	s_lshr_b32 s2, s33, 29
	s_add_i32 s4, s20, s2
	s_and_b32 s2, s4, -8
	s_sub_i32 s5, s20, s2
	s_cmp_gt_i32 s5, -1
	s_cbranch_scc0 .LBB0_472
	s_lshl_b32 s6, s5, 7
	s_cbranch_execz .LBB0_473
	s_branch .LBB0_474

; #define PG8_STAGE(bufoff, gbase, voff) do { _Pragma("unroll") for (int _i = 0; _i < 2; ++_i) \
;         __builtin_amdgcn_global_load_lds((const unsigned*)((const char*)(gbase) + (voff)[_i]), (PG8_LAS unsigned*)(lds + (bufoff) + ldsw + _i * 8192), 16, 0, 0); } while (0)
; #define PG8_WAIT_V(n) asm volatile("s_waitcnt vmcnt(" #n ")" ::: "memory")
; #define PG8_BAR __builtin_amdgcn_s_barrier()
; template <class Epi, class Sched, bool ALIGN_EPI = false, bool SP2 = false, bool TA = true>
; __device__ __forceinline__ void gemm_phase(PG8_LAS unsigned char* lds, const Gemm g, const Sched& S, const Epi& E) {
;     const int tid = threadIdx.x, wid = __builtin_amdgcn_readfirstlane(tid >> 6), lane = tid & 63, wr = wid >> 2, wc = wid & 3, fr = lane & 15, fq = lane >> 4;
;     const int K = g.K, nt = K / BK;
;     unsigned voffA[2], voffB[2];
; #pragma unroll
;     for (int i = 0; i < 2; ++i) { int R, C; stage_rc(tid * 16 + i * 8192, R, C); const int Rb = Epi::PERM ? ((R & ~31) + perm32(R & 31)) : R;
;         voffA[i] = TA ? (unsigned)(tid * 16 + i * 8192) : (unsigned)(R * K + C) * 2u; voffB[i] = (unsigned)(tid * 16 + i * 8192); (void)Rb; }
;     const size_t kstep = TA ? (size_t)HTB : (size_t)(BK * 2);
;     const size_t kstepB = (size_t)HTB;
;     const size_t hstep = (size_t)HALF * K * 2;
;     const size_t tstep = 2 * hstep;
;     const unsigned ldsw = (unsigned)wid * 1024u;
;     const int aoff = lds_byte(wr * 64 + fr, fq * 8), boff = lds_byte(wc * 32 + fr, fq * 8);
;     ...
;         PG8_STAGE(PG8_SB(0, 0), cB, voffB); PG8_STAGE(PG8_SA(0, 0), cA, voffA); PG8_STAGE(PG8_SB(0, 1), cB + hstep, voffB); PG8_STAGE(PG8_SA(0, 1), cA + hstep, voffA);
;         if (wr == 1) PG8_BAR;
;         PG8_WAIT_V(4); PG8_BAR;
;         PG8_STAGE(PG8_SB(1, 0), cB + kstepB, voffB); PG8_STAGE(PG8_SA(1, 0), cA + kstep, voffA); PG8_STAGE(PG8_SB(1, 1), cB + hstep + kstepB, voffB);
;         PG8_WAIT_V(6); PG8_BAR;
;     }
.LBB0_478:
	s_add_u32 s14, s28, 0xe000000
	v_readlane_b32 s36, v255, 11
	s_addc_u32 s15, s29, 0
	v_readlane_b32 s44, v255, 19
	v_readlane_b32 s45, v255, 20
	s_add_u32 s16, s44, 0x1000
	v_readlane_b32 s46, v255, 21
	v_readlane_b32 s47, v255, 22
	s_addc_u32 s17, s45, 0
	s_mov_b64 s[44:45], 0x4000
	s_add_i32 m0, s84, 0x18000
	v_lshl_add_u64 v[4:5], v[0:1], 0, s[44:45]
	s_mov_b64 s[46:47], 0x6000
	s_waitcnt vmcnt(2)
	s_barrier
	global_load_lds_dwordx4 v[4:5], off
	v_lshl_add_u64 v[4:5], v[0:1], 0, s[46:47]
	s_add_i32 m0, s84, 0x1a000
	s_add_i32 s19, s84, 0x8000
	v_readlane_b32 s48, v255, 23
	v_readlane_b32 s49, v255, 24
	global_load_lds_dwordx4 v[4:5], off
	v_lshl_add_u64 v[4:5], v[2:3], 0, s[44:45]
	s_mov_b32 m0, s19
	s_add_i32 s21, s84, 0xa000
	v_readlane_b32 s50, v255, 25
	v_readlane_b32 s51, v255, 26
	global_load_lds_dwordx4 v[4:5], off
	v_lshl_add_u64 v[2:3], v[2:3], 0, s[46:47]
	s_mov_b32 m0, s21
	s_mov_b64 s[48:49], 0x44000
	global_load_lds_dwordx4 v[2:3], off
	s_add_i32 m0, s84, 0x1c000
	v_lshl_add_u64 v[2:3], v[0:1], 0, s[48:49]
	s_mov_b64 s[50:51], 0x46000
	global_load_lds_dwordx4 v[2:3], off
	v_lshl_add_u64 v[0:1], v[0:1], 0, s[50:51]
	s_add_i32 m0, s84, 0x1e000
	s_lshl_b32 s4, s4, 5
	global_load_lds_dwordx4 v[0:1], off
	v_lshrrev_b32_e32 v1, 1, v208
	v_and_b32_e32 v1, 24, v1
	v_and_b32_e32 v0, 15, v208
	v_lshlrev_b32_e32 v2, 1, v1
	v_lshl_or_b32 v162, s5, 6, v0
	v_lshl_or_b32 v3, v0, 6, v2
	v_lshlrev_b32_e32 v0, 2, v0
	s_lshl_b32 s5, s5, 13
	v_and_b32_e32 v4, 32, v0
	v_bitop3_b32 v3, v3, s5, v4 bitop3:0xde
	v_lshlrev_b32_e32 v4, 6, v208
	s_movk_i32 s5, 0x3c0
	s_and_b32 s4, s4, 0x60
	v_and_or_b32 v2, v4, s5, v2
	v_lshlrev_b32_e32 v4, 2, v208
	s_lshl_b32 s5, s4, 7
	v_and_b32_e32 v5, 32, v4
	v_bitop3_b32 v163, s5, v2, v5 bitop3:0xf6
	s_add_i32 s5, 0, 0x20400
	s_cmpk_lt_u32 s22, 0x100
	v_readlane_b32 s30, v255, 4
	v_readlane_b32 s37, v255, 12
	s_waitcnt vmcnt(6)
	s_cselect_b64 s[68:69], -1, 0
	s_and_b32 s22, s22, 0xffffff00
	v_readlane_b32 s31, v255, 5
	s_sext_i32_i8 s37, s23
	v_add_u32_e32 v164, s5, v4
	s_add_i32 s5, s5, s22
	s_ashr_i32 s22, s30, 31
	s_mov_b32 s23, s30
	s_add_i32 s30, 0, 0x10000
	s_add_i32 s31, 0, 0x14000
	v_add_u32_e32 v165, s5, v0
	v_or_b32_e32 v166, s4, v1
	v_mov_b64_e32 v[146:147], 0x400
	v_mov_b64_e32 v[148:149], 0x3ff
	v_add_u32_e32 v167, s30, v163
	v_add_u32_e32 v168, s31, v163
	v_add_u32_e32 v169, 0, v3
	v_mov_b32_e32 v170, 0x358637bd
	v_readlane_b32 s38, v255, 13
	v_readlane_b32 s39, v255, 14
	v_readlane_b32 s40, v255, 15
	v_readlane_b32 s41, v255, 16
	v_readlane_b32 s42, v255, 17
	v_readlane_b32 s43, v255, 18
	s_barrier
	s_branch .LBB0_481

; #define PG8_LAS __attribute__((address_space(3)))
; __host__ __device__ __forceinline__ size_t tiled_off(int row, int col, int K) { return ((size_t)(row >> 7) * (K >> 6) + (col >> 6)) * 8192 + (lds_byte(row & 127, col & 63) >> 1); }
; __device__ __forceinline__ unsigned cvt_pk_bf16(float lo, float hi) { unsigned r; asm volatile("v_cvt_pk_bf16_f32 %0, %1, %2" : "=v"(r) : "v"(lo), "v"(hi)); return r; }
; __device__ __forceinline__ float fast_sigmoid(float x) { return __builtin_amdgcn_rcpf(1.0f + __builtin_amdgcn_exp2f(x * -1.4426950408889634f)); }
;     __device__ __forceinline__ void operator()(const f32x4 (&acc)[2][2][4][2], const Unit& u, int wr, int wc, int fr, int fq, const PG8_LAS float* rtab) const {
;         const int row0 = u.pm * BM + wr * 64 + fr, lcol = u.pn * HALF + wc * 32 + 8 * fq;
;         float rs[2][4]; load_rstd(rtab, wr, fr, rs);
;         f32x4 bv[2], bg[2];
; #pragma unroll
;         for (int n = 0; n < 2; ++n) { bv[n] = (MODE == 0) ? *(const f32x4*)(b0 + lcol + 4 * n) : (f32x4){0.f, 0.f, 0.f, 0.f}; bg[n] = (MODE == 0) ? *(const f32x4*)(b1 + lcol + 4 * n) : (f32x4){0.f, 0.f, 0.f, 0.f}; }
; #pragma unroll
;         for (int ai = 0; ai < 2; ++ai)
; #pragma unroll
;             for (int m = 0; m < 4; ++m) { const float r = rs[ai][m]; float o[8];
; #pragma unroll
;                 for (int n = 0; n < 2; ++n) { const f32x4 a = acc[ai][0][m][n] * r + bv[n], g = acc[ai][1][m][n] * r + bg[n];
; #pragma unroll
;                     for (int e = 0; e < 4; ++e) o[4 * n + e] = (MODE == 0) ? a[e] * fast_sigmoid(g[e]) : a[e] * fast_sigmoid(a[e]) * g[e]; }
;                 u32x4 w; w.x = cvt_pk_bf16(o[0], o[1]); w.y = cvt_pk_bf16(o[2], o[3]); w.z = cvt_pk_bf16(o[4], o[5]); w.w = cvt_pk_bf16(o[6], o[7]);
;                 if (MODE == 1) *(u32x4*)(O + tiled_off(row0 + ai * HALF + m * 16, lcol, ldc)) = w;
;                 else *(u32x4*)(O + (size_t)(row0 + ai * HALF + m * 16) * ldc + lcol) = w; }
.LBB0_491:
	s_lshl_b32 s38, s85, 10
	s_and_b32 s38, s38, 0x400
	v_lshl_or_b32 v160, s37, 7, v166
	v_add_u32_e32 v56, s38, v165
	v_ashrrev_i32_e32 v161, 31, v160
	v_readlane_b32 s52, v255, 11
	ds_read2_b32 v[158:159], v56 offset1:16
	ds_read2_b32 v[154:155], v56 offset0:32 offset1:48
	ds_read2_b32 v[152:153], v56 offset0:128 offset1:144
	ds_read2_b32 v[150:151], v56 offset0:160 offset1:176
	v_lshlrev_b64 v[56:57], 2, v[160:161]
	v_readlane_b32 s60, v255, 19
	v_readlane_b32 s61, v255, 20
	v_lshl_add_u64 v[76:77], s[16:17], 0, v[56:57]
	v_lshl_add_u32 v156, s74, 8, v162
	v_lshl_add_u64 v[64:65], s[60:61], 0, v[56:57]
	global_load_dwordx4 v[56:59], v[64:65], off offset:16
	global_load_dwordx4 v[72:75], v[64:65], off
	s_nop 0
	global_load_dwordx4 v[64:67], v[76:77], off offset:16
	s_nop 0
	global_load_dwordx4 v[76:79], v[76:77], off
	v_ashrrev_i32_e32 v157, 31, v156
	s_mov_b32 s37, 0x40000
	s_mov_b64 s[74:75], -1
	v_readlane_b32 s53, v255, 12
	v_readlane_b32 s54, v255, 13
	v_readlane_b32 s55, v255, 14
	v_readlane_b32 s56, v255, 15
	v_readlane_b32 s57, v255, 16
	v_readlane_b32 s58, v255, 17
	v_readlane_b32 s59, v255, 18
	v_readlane_b32 s62, v255, 21
	v_readlane_b32 s63, v255, 22
	v_readlane_b32 s64, v255, 23
	v_readlane_b32 s65, v255, 24
	v_readlane_b32 s66, v255, 25
	v_readlane_b32 s67, v255, 26
	s_waitcnt vmcnt(0) lgkmcnt(0)
	v_fma_f32 v136, v136, v158, v56
	v_fma_f32 v116, v116, v159, v56
	v_fma_f32 v128, v128, v158, v64
	v_mul_f32_e32 v128, 0xbfb8aa3b, v128
	v_fma_f32 v129, v129, v158, v65
	v_exp_f32_e32 v128, v128
	v_mul_f32_e32 v129, 0xbfb8aa3b, v129
	v_exp_f32_e32 v129, v129
	v_fma_f32 v112, v112, v159, v64
	v_mul_f32_e32 v112, 0xbfb8aa3b, v112
	v_fma_f32 v113, v113, v159, v65
	v_exp_f32_e32 v112, v112
	v_mul_f32_e32 v113, 0xbfb8aa3b, v113
	v_add_f32_e32 v128, 1.0, v128
	v_exp_f32_e32 v113, v113
	v_rcp_f32_e32 v128, v128
	v_add_f32_e32 v129, 1.0, v129
	v_rcp_f32_e32 v129, v129
	v_fma_f32 v96, v96, v154, v64
	v_add_f32_e32 v112, 1.0, v112
	v_mul_f32_e32 v96, 0xbfb8aa3b, v96
	v_fma_f32 v97, v97, v154, v65
	v_rcp_f32_e32 v112, v112
	v_add_f32_e32 v113, 1.0, v113
	v_exp_f32_e32 v96, v96
	v_mul_f32_e32 v97, 0xbfb8aa3b, v97
	v_mul_f32_e32 v136, v136, v128
	v_fma_f32 v128, v137, v158, v57
	v_rcp_f32_e32 v113, v113
	v_exp_f32_e32 v97, v97
	v_mul_f32_e32 v137, v128, v129
	v_fma_f32 v129, v130, v158, v66
	v_mul_f32_e32 v129, 0xbfb8aa3b, v129
	v_fma_f32 v80, v80, v155, v64
	v_exp_f32_e32 v129, v129
	v_mul_f32_e32 v116, v116, v112
	v_fma_f32 v112, v117, v159, v57
	v_add_f32_e32 v96, 1.0, v96
	v_mul_f32_e32 v80, 0xbfb8aa3b, v80
	v_fma_f32 v81, v81, v155, v65
	v_mul_f32_e32 v117, v112, v113
	v_fma_f32 v113, v114, v159, v66
	v_rcp_f32_e32 v96, v96
	v_add_f32_e32 v97, 1.0, v97
	v_exp_f32_e32 v80, v80
	v_mul_f32_e32 v81, 0xbfb8aa3b, v81
	v_mul_f32_e32 v113, 0xbfb8aa3b, v113
	v_rcp_f32_e32 v97, v97
	v_exp_f32_e32 v81, v81
	v_exp_f32_e32 v113, v113
	v_add_f32_e32 v129, 1.0, v129
	v_fma_f32 v100, v100, v154, v56
	v_fma_f32 v48, v48, v152, v64
	v_rcp_f32_e32 v129, v129
	v_mul_f32_e32 v100, v100, v96
	v_fma_f32 v96, v101, v154, v57
	v_add_f32_e32 v80, 1.0, v80
	v_mul_f32_e32 v48, 0xbfb8aa3b, v48
	v_fma_f32 v49, v49, v152, v65
	v_fma_f32 v132, v132, v158, v76
	v_mul_f32_e32 v101, v96, v97
	v_fma_f32 v97, v98, v154, v66
	v_rcp_f32_e32 v80, v80
	v_add_f32_e32 v81, 1.0, v81
	v_exp_f32_e32 v48, v48
	v_mul_f32_e32 v49, 0xbfb8aa3b, v49
	v_fma_f32 v32, v32, v153, v64
	v_mul_f32_e32 v132, 0xbfb8aa3b, v132
	v_fma_f32 v133, v133, v158, v77
	v_add_f32_e32 v113, 1.0, v113
	v_mul_f32_e32 v97, 0xbfb8aa3b, v97
	v_rcp_f32_e32 v81, v81
	v_exp_f32_e32 v49, v49
	v_mul_f32_e32 v32, 0xbfb8aa3b, v32
	v_fma_f32 v33, v33, v153, v65
	v_exp_f32_e32 v132, v132
	v_mul_f32_e32 v133, 0xbfb8aa3b, v133
	v_fma_f32 v134, v134, v158, v78
	v_fma_f32 v128, v138, v158, v58
	v_rcp_f32_e32 v113, v113
	v_exp_f32_e32 v97, v97
	v_exp_f32_e32 v32, v32
	v_mul_f32_e32 v33, 0xbfb8aa3b, v33
	v_fma_f32 v16, v16, v150, v64
	v_exp_f32_e32 v133, v133
	v_mul_f32_e32 v134, 0xbfb8aa3b, v134
	v_fma_f32 v135, v135, v158, v79
	v_mul_f32_e32 v138, v128, v129
	v_fma_f32 v129, v131, v158, v67
	v_fma_f32 v120, v120, v159, v76
	v_fma_f32 v84, v84, v155, v56
	v_exp_f32_e32 v33, v33
	v_mul_f32_e32 v16, 0xbfb8aa3b, v16
	v_fma_f32 v17, v17, v150, v65
	v_exp_f32_e32 v134, v134
	v_mul_f32_e32 v135, 0xbfb8aa3b, v135
	v_mul_f32_e32 v129, 0xbfb8aa3b, v129
	v_mul_f32_e32 v120, 0xbfb8aa3b, v120
	v_fma_f32 v121, v121, v159, v77
	v_mul_f32_e32 v84, v84, v80
	v_fma_f32 v80, v85, v155, v57
	v_add_f32_e32 v48, 1.0, v48
	v_exp_f32_e32 v16, v16
	v_mul_f32_e32 v17, 0xbfb8aa3b, v17
	v_exp_f32_e32 v135, v135
	v_exp_f32_e32 v129, v129
	v_exp_f32_e32 v120, v120
	v_mul_f32_e32 v121, 0xbfb8aa3b, v121
	v_fma_f32 v122, v122, v159, v78
	v_fma_f32 v112, v118, v159, v58
	v_mul_f32_e32 v85, v80, v81
	v_fma_f32 v81, v82, v155, v66
	v_rcp_f32_e32 v48, v48
	v_add_f32_e32 v49, 1.0, v49
	v_exp_f32_e32 v17, v17
	v_fma_f32 v0, v0, v151, v64
	v_add_f32_e32 v132, 1.0, v132
	v_exp_f32_e32 v121, v121
	v_mul_f32_e32 v122, 0xbfb8aa3b, v122
	v_fma_f32 v123, v123, v159, v79
	v_mul_f32_e32 v118, v112, v113
	v_fma_f32 v113, v115, v159, v67
	v_add_f32_e32 v97, 1.0, v97
	v_mul_f32_e32 v81, 0xbfb8aa3b, v81
	v_rcp_f32_e32 v49, v49
	v_add_f32_e32 v32, 1.0, v32
	v_mul_f32_e32 v0, 0xbfb8aa3b, v0
	v_fma_f32 v1, v1, v151, v65
	v_rcp_f32_e32 v132, v132
	v_add_f32_e32 v133, 1.0, v133
	v_exp_f32_e32 v122, v122
	v_mul_f32_e32 v123, 0xbfb8aa3b, v123
	v_mul_f32_e32 v113, 0xbfb8aa3b, v113
	v_rcp_f32_e32 v97, v97
	v_exp_f32_e32 v81, v81
	v_rcp_f32_e32 v32, v32
	v_add_f32_e32 v33, 1.0, v33
	v_exp_f32_e32 v0, v0
	v_mul_f32_e32 v1, 0xbfb8aa3b, v1
	v_rcp_f32_e32 v133, v133
; __host__ __device__ __forceinline__ size_t tiled_off(int row, int col, int K) { return ((size_t)(row >> 7) * (K >> 6) + (col >> 6)) * 8192 + (lds_byte(row & 127, col & 63) >> 1); }
; __device__ __forceinline__ unsigned cvt_pk_bf16(float lo, float hi) { unsigned r; asm volatile("v_cvt_pk_bf16_f32 %0, %1, %2" : "=v"(r) : "v"(lo), "v"(hi)); return r; }
; __device__ __forceinline__ float fast_sigmoid(float x) { return __builtin_amdgcn_rcpf(1.0f + __builtin_amdgcn_exp2f(x * -1.4426950408889634f)); }
;     __device__ __forceinline__ void operator()(const f32x4 (&acc)[2][2][4][2], const Unit& u, int wr, int wc, int fr, int fq, const PG8_LAS float* rtab) const {
;     ...
;             for (int m = 0; m < 4; ++m) { const float r = rs[ai][m]; float o[8];
; #pragma unroll
;                 for (int n = 0; n < 2; ++n) { const f32x4 a = acc[ai][0][m][n] * r + bv[n], g = acc[ai][1][m][n] * r + bg[n];
; #pragma unroll
;                     for (int e = 0; e < 4; ++e) o[4 * n + e] = (MODE == 0) ? a[e] * fast_sigmoid(g[e]) : a[e] * fast_sigmoid(a[e]) * g[e]; }
;                 u32x4 w; w.x = cvt_pk_bf16(o[0], o[1]); w.y = cvt_pk_bf16(o[2], o[3]); w.z = cvt_pk_bf16(o[4], o[5]); w.w = cvt_pk_bf16(o[6], o[7]);
;                 if (MODE == 1) *(u32x4*)(O + tiled_off(row0 + ai * HALF + m * 16, lcol, ldc)) = w;
;                 else *(u32x4*)(O + (size_t)(row0 + ai * HALF + m * 16) * ldc + lcol) = w; }
	v_add_f32_e32 v134, 1.0, v134
	v_exp_f32_e32 v123, v123
	v_exp_f32_e32 v113, v113
	v_fma_f32 v104, v104, v154, v76
	v_fma_f32 v52, v52, v152, v56
	v_rcp_f32_e32 v33, v33
	v_add_f32_e32 v16, 1.0, v16
	v_exp_f32_e32 v1, v1
	v_rcp_f32_e32 v134, v134
	v_add_f32_e32 v135, 1.0, v135
	v_add_f32_e32 v129, 1.0, v129
	v_add_f32_e32 v120, 1.0, v120
	v_mul_f32_e32 v104, 0xbfb8aa3b, v104
	v_fma_f32 v105, v105, v154, v77
	v_mul_f32_e32 v52, v52, v48
	v_fma_f32 v48, v53, v152, v57
	v_rcp_f32_e32 v16, v16
	v_add_f32_e32 v17, 1.0, v17
	v_fma_f32 v140, v140, v158, v72
	v_rcp_f32_e32 v135, v135
	v_rcp_f32_e32 v129, v129
	v_rcp_f32_e32 v120, v120
	v_add_f32_e32 v121, 1.0, v121
	v_exp_f32_e32 v104, v104
	v_mul_f32_e32 v105, 0xbfb8aa3b, v105
	v_fma_f32 v106, v106, v154, v78
	v_fma_f32 v96, v102, v154, v58
	v_mul_f32_e32 v53, v48, v49
	v_fma_f32 v49, v50, v152, v66
	v_fma_f32 v36, v36, v153, v56
	v_rcp_f32_e32 v17, v17
	v_mul_f32_e32 v132, v140, v132
	v_fma_f32 v140, v141, v158, v73
	v_rcp_f32_e32 v121, v121
	v_add_f32_e32 v122, 1.0, v122
	v_exp_f32_e32 v105, v105
	v_mul_f32_e32 v106, 0xbfb8aa3b, v106
	v_fma_f32 v107, v107, v154, v79
	v_mul_f32_e32 v102, v96, v97
	v_fma_f32 v97, v99, v154, v67
	v_add_f32_e32 v81, 1.0, v81
	v_mul_f32_e32 v49, 0xbfb8aa3b, v49
	v_mul_f32_e32 v36, v36, v32
	v_fma_f32 v32, v37, v153, v57
	v_add_f32_e32 v0, 1.0, v0
	v_mul_f32_e32 v133, v140, v133
	v_fma_f32 v140, v142, v158, v74
	v_rcp_f32_e32 v122, v122
	v_add_f32_e32 v123, 1.0, v123
	v_add_f32_e32 v113, 1.0, v113
	v_exp_f32_e32 v106, v106
	v_mul_f32_e32 v107, 0xbfb8aa3b, v107
	v_mul_f32_e32 v97, 0xbfb8aa3b, v97
	v_rcp_f32_e32 v81, v81
	v_exp_f32_e32 v49, v49
	v_mul_f32_e32 v37, v32, v33
	v_fma_f32 v33, v34, v153, v66
	v_fma_f32 v20, v20, v150, v56
	v_rcp_f32_e32 v0, v0
	v_add_f32_e32 v1, 1.0, v1
	v_mul_f32_e32 v134, v140, v134
	v_fma_f32 v140, v143, v158, v75
	v_fma_f32 v128, v139, v158, v59
	v_fma_f32 v124, v124, v159, v72
	v_rcp_f32_e32 v123, v123
	v_rcp_f32_e32 v113, v113
	v_exp_f32_e32 v107, v107
	v_exp_f32_e32 v97, v97
	v_fma_f32 v88, v88, v155, v76
	v_mul_f32_e32 v33, 0xbfb8aa3b, v33
	v_mul_f32_e32 v20, v20, v16
	v_fma_f32 v16, v21, v150, v57
	v_rcp_f32_e32 v1, v1
	v_mul_f32_e32 v135, v140, v135
	v_mul_f32_e32 v131, v128, v129
	v_cvt_pk_bf16_f32 v128, v132, v133
	v_lshlrev_b64 v[132:133], 11, v[156:157]
	v_mul_f32_e32 v120, v124, v120
	v_fma_f32 v124, v125, v159, v73
	v_add_f32_e32 v104, 1.0, v104
	v_mul_f32_e32 v88, 0xbfb8aa3b, v88
	v_fma_f32 v89, v89, v155, v77
	v_exp_f32_e32 v33, v33
	v_mul_f32_e32 v21, v16, v17
	v_fma_f32 v17, v18, v150, v66
	v_cvt_pk_bf16_f32 v129, v134, v135
	v_lshl_add_u64 v[132:133], s[14:15], 0, v[132:133]
	v_lshlrev_b64 v[134:135], 1, v[160:161]
	v_mul_f32_e32 v121, v124, v121
	v_fma_f32 v124, v126, v159, v74
	v_rcp_f32_e32 v104, v104
	v_add_f32_e32 v105, 1.0, v105
	v_exp_f32_e32 v88, v88
	v_mul_f32_e32 v89, 0xbfb8aa3b, v89
	v_fma_f32 v90, v90, v155, v78
	v_fma_f32 v80, v86, v155, v58
	v_mul_f32_e32 v17, 0xbfb8aa3b, v17
	v_fma_f32 v4, v4, v151, v56
	v_lshl_add_u64 v[132:133], v[132:133], 0, v[134:135]
	v_mul_f32_e32 v122, v124, v122
	v_fma_f32 v124, v127, v159, v75
	v_fma_f32 v112, v119, v159, v59
	v_rcp_f32_e32 v105, v105
	v_add_f32_e32 v106, 1.0, v106
	v_exp_f32_e32 v89, v89
	v_mul_f32_e32 v90, 0xbfb8aa3b, v90
	v_fma_f32 v91, v91, v155, v79
	v_mul_f32_e32 v86, v80, v81
	v_fma_f32 v81, v83, v155, v67
	v_add_f32_e32 v49, 1.0, v49
	v_exp_f32_e32 v17, v17
	v_mul_f32_e32 v4, v4, v0
	v_fma_f32 v0, v5, v151, v57
	v_cvt_pk_bf16_f32 v130, v136, v137
	v_cvt_pk_bf16_f32 v131, v138, v131
	global_store_dwordx4 v[132:133], v[128:131], off
	v_mul_f32_e32 v123, v124, v123
	v_mul_f32_e32 v115, v112, v113
	v_cvt_pk_bf16_f32 v112, v120, v121
	v_cvt_pk_bf16_f32 v113, v122, v123
	v_cvt_pk_bf16_f32 v114, v116, v117
	v_or_b32_e32 v116, 16, v156
	v_rcp_f32_e32 v106, v106
	v_add_f32_e32 v107, 1.0, v107
	v_add_f32_e32 v97, 1.0, v97
	v_exp_f32_e32 v90, v90
	v_mul_f32_e32 v91, 0xbfb8aa3b, v91
	v_mul_f32_e32 v81, 0xbfb8aa3b, v81
	v_rcp_f32_e32 v49, v49
	v_mul_f32_e32 v5, v0, v1
	v_fma_f32 v1, v2, v151, v66
	v_ashrrev_i32_e32 v117, 31, v116
	v_fma_f32 v108, v108, v154, v72
	v_rcp_f32_e32 v107, v107
	v_rcp_f32_e32 v97, v97
	v_exp_f32_e32 v91, v91
	v_exp_f32_e32 v81, v81
	v_fma_f32 v60, v60, v152, v76
	v_add_f32_e32 v33, 1.0, v33
	v_mul_f32_e32 v1, 0xbfb8aa3b, v1
	v_lshlrev_b64 v[116:117], 11, v[116:117]
	v_mul_f32_e32 v104, v108, v104
	v_fma_f32 v108, v109, v154, v73
	v_add_f32_e32 v88, 1.0, v88
	v_mul_f32_e32 v60, 0xbfb8aa3b, v60
	v_fma_f32 v61, v61, v152, v77
	v_rcp_f32_e32 v33, v33
	v_exp_f32_e32 v1, v1
	v_lshl_add_u64 v[116:117], s[14:15], 0, v[116:117]
	v_mul_f32_e32 v105, v108, v105
	v_fma_f32 v108, v110, v154, v74
	v_rcp_f32_e32 v88, v88
	v_add_f32_e32 v89, 1.0, v89
	v_exp_f32_e32 v60, v60
	v_mul_f32_e32 v61, 0xbfb8aa3b, v61
	v_fma_f32 v62, v62, v152, v78
	v_fma_f32 v48, v54, v152, v58
	v_fma_f32 v40, v40, v153, v76
	v_add_f32_e32 v17, 1.0, v17
	v_lshl_add_u64 v[116:117], v[116:117], 0, v[134:135]
	v_mul_f32_e32 v106, v108, v106
	v_fma_f32 v108, v111, v154, v75
	v_fma_f32 v96, v103, v154, v59
	v_rcp_f32_e32 v89, v89
	v_add_f32_e32 v90, 1.0, v90
	v_exp_f32_e32 v61, v61
	v_mul_f32_e32 v62, 0xbfb8aa3b, v62
	v_fma_f32 v63, v63, v152, v79
	v_mul_f32_e32 v54, v48, v49
	v_fma_f32 v49, v51, v152, v67
	v_mul_f32_e32 v40, 0xbfb8aa3b, v40
	v_fma_f32 v41, v41, v153, v77
	v_rcp_f32_e32 v17, v17
	v_cvt_pk_bf16_f32 v115, v118, v115
	global_store_dwordx4 v[116:117], v[112:115], off
	v_mul_f32_e32 v107, v108, v107
	v_mul_f32_e32 v99, v96, v97
	v_cvt_pk_bf16_f32 v96, v104, v105
	v_cvt_pk_bf16_f32 v97, v106, v107
	v_cvt_pk_bf16_f32 v98, v100, v101
	v_or_b32_e32 v100, 32, v156
; __host__ __device__ __forceinline__ size_t tiled_off(int row, int col, int K) { return ((size_t)(row >> 7) * (K >> 6) + (col >> 6)) * 8192 + (lds_byte(row & 127, col & 63) >> 1); }
; __device__ __forceinline__ unsigned cvt_pk_bf16(float lo, float hi) { unsigned r; asm volatile("v_cvt_pk_bf16_f32 %0, %1, %2" : "=v"(r) : "v"(lo), "v"(hi)); return r; }
; __device__ __forceinline__ float fast_sigmoid(float x) { return __builtin_amdgcn_rcpf(1.0f + __builtin_amdgcn_exp2f(x * -1.4426950408889634f)); }
;     __device__ __forceinline__ void operator()(const f32x4 (&acc)[2][2][4][2], const Unit& u, int wr, int wc, int fr, int fq, const PG8_LAS float* rtab) const {
;     ...
;             for (int m = 0; m < 4; ++m) { const float r = rs[ai][m]; float o[8];
; #pragma unroll
;                 for (int n = 0; n < 2; ++n) { const f32x4 a = acc[ai][0][m][n] * r + bv[n], g = acc[ai][1][m][n] * r + bg[n];
; #pragma unroll
;                     for (int e = 0; e < 4; ++e) o[4 * n + e] = (MODE == 0) ? a[e] * fast_sigmoid(g[e]) : a[e] * fast_sigmoid(a[e]) * g[e]; }
;                 u32x4 w; w.x = cvt_pk_bf16(o[0], o[1]); w.y = cvt_pk_bf16(o[2], o[3]); w.z = cvt_pk_bf16(o[4], o[5]); w.w = cvt_pk_bf16(o[6], o[7]);
;                 if (MODE == 1) *(u32x4*)(O + tiled_off(row0 + ai * HALF + m * 16, lcol, ldc)) = w;
;                 else *(u32x4*)(O + (size_t)(row0 + ai * HALF + m * 16) * ldc + lcol) = w; }
	v_rcp_f32_e32 v90, v90
	v_add_f32_e32 v91, 1.0, v91
	v_add_f32_e32 v81, 1.0, v81
	v_exp_f32_e32 v62, v62
	v_mul_f32_e32 v63, 0xbfb8aa3b, v63
	v_mul_f32_e32 v49, 0xbfb8aa3b, v49
	v_exp_f32_e32 v40, v40
	v_mul_f32_e32 v41, 0xbfb8aa3b, v41
	v_fma_f32 v42, v42, v153, v78
	v_fma_f32 v32, v38, v153, v58
	v_fma_f32 v24, v24, v150, v76
	v_ashrrev_i32_e32 v101, 31, v100
	v_fma_f32 v92, v92, v155, v72
	v_rcp_f32_e32 v91, v91
	v_rcp_f32_e32 v81, v81
	v_exp_f32_e32 v63, v63
	v_exp_f32_e32 v49, v49
	v_exp_f32_e32 v41, v41
	v_mul_f32_e32 v42, 0xbfb8aa3b, v42
	v_fma_f32 v43, v43, v153, v79
	v_mul_f32_e32 v38, v32, v33
	v_fma_f32 v33, v35, v153, v67
	v_mul_f32_e32 v24, 0xbfb8aa3b, v24
	v_fma_f32 v25, v25, v150, v77
	v_add_f32_e32 v1, 1.0, v1
	v_lshlrev_b64 v[100:101], 11, v[100:101]
	v_mul_f32_e32 v88, v92, v88
	v_fma_f32 v92, v93, v155, v73
	v_add_f32_e32 v60, 1.0, v60
	v_exp_f32_e32 v42, v42
	v_mul_f32_e32 v43, 0xbfb8aa3b, v43
	v_mul_f32_e32 v33, 0xbfb8aa3b, v33
	v_exp_f32_e32 v24, v24
	v_mul_f32_e32 v25, 0xbfb8aa3b, v25
	v_fma_f32 v26, v26, v150, v78
	v_fma_f32 v16, v22, v150, v58
	v_rcp_f32_e32 v1, v1
	v_lshl_add_u64 v[100:101], s[14:15], 0, v[100:101]
	v_mul_f32_e32 v89, v92, v89
	v_fma_f32 v92, v94, v155, v74
	v_rcp_f32_e32 v60, v60
	v_add_f32_e32 v61, 1.0, v61
	v_exp_f32_e32 v43, v43
	v_exp_f32_e32 v33, v33
	v_exp_f32_e32 v25, v25
	v_mul_f32_e32 v26, 0xbfb8aa3b, v26
	v_fma_f32 v27, v27, v150, v79
	v_mul_f32_e32 v22, v16, v17
	v_fma_f32 v17, v19, v150, v67
	v_fma_f32 v8, v8, v151, v76
	v_lshl_add_u64 v[100:101], v[100:101], 0, v[134:135]
	v_mul_f32_e32 v90, v92, v90
	v_fma_f32 v92, v95, v155, v75
	v_fma_f32 v80, v87, v155, v59
	v_rcp_f32_e32 v61, v61
	v_add_f32_e32 v62, 1.0, v62
	v_add_f32_e32 v40, 1.0, v40
	v_exp_f32_e32 v26, v26
	v_mul_f32_e32 v27, 0xbfb8aa3b, v27
	v_mul_f32_e32 v17, 0xbfb8aa3b, v17
	v_mul_f32_e32 v8, 0xbfb8aa3b, v8
	v_fma_f32 v9, v9, v151, v77
	v_cvt_pk_bf16_f32 v99, v102, v99
	global_store_dwordx4 v[100:101], v[96:99], off
	v_mul_f32_e32 v91, v92, v91
	v_mul_f32_e32 v83, v80, v81
	v_cvt_pk_bf16_f32 v80, v88, v89
	v_cvt_pk_bf16_f32 v81, v90, v91
	v_cvt_pk_bf16_f32 v82, v84, v85
	v_or_b32_e32 v84, 48, v156
	v_rcp_f32_e32 v62, v62
	v_add_f32_e32 v63, 1.0, v63
	v_add_f32_e32 v49, 1.0, v49
	v_rcp_f32_e32 v40, v40
	v_add_f32_e32 v41, 1.0, v41
	v_exp_f32_e32 v27, v27
	v_exp_f32_e32 v17, v17
	v_exp_f32_e32 v8, v8
	v_mul_f32_e32 v9, 0xbfb8aa3b, v9
	v_fma_f32 v10, v10, v151, v78
	v_fmac_f32_e32 v79, v11, v151
	v_fma_f32 v0, v6, v151, v58
	v_fmac_f32_e32 v67, v3, v151
	v_ashrrev_i32_e32 v85, 31, v84
	v_fma_f32 v68, v68, v152, v72
	v_rcp_f32_e32 v63, v63
	v_rcp_f32_e32 v49, v49
	v_rcp_f32_e32 v41, v41
	v_add_f32_e32 v42, 1.0, v42
	v_add_f32_e32 v24, 1.0, v24
	v_exp_f32_e32 v9, v9
	v_mul_f32_e32 v10, 0xbfb8aa3b, v10
	v_mul_f32_e32 v11, 0xbfb8aa3b, v79
	v_mul_f32_e32 v6, v0, v1
	v_mul_f32_e32 v0, 0xbfb8aa3b, v67
	v_lshlrev_b64 v[84:85], 11, v[84:85]
	v_mul_f32_e32 v60, v68, v60
	v_fma_f32 v68, v69, v152, v73
	v_rcp_f32_e32 v42, v42
	v_add_f32_e32 v43, 1.0, v43
	v_add_f32_e32 v33, 1.0, v33
	v_rcp_f32_e32 v24, v24
	v_add_f32_e32 v25, 1.0, v25
	v_exp_f32_e32 v10, v10
	v_exp_f32_e32 v11, v11
	v_exp_f32_e32 v0, v0
	v_lshl_add_u64 v[84:85], s[14:15], 0, v[84:85]
	v_mul_f32_e32 v61, v68, v61
	v_fma_f32 v68, v70, v152, v74
	v_fma_f32 v44, v44, v153, v72
	v_rcp_f32_e32 v43, v43
	v_rcp_f32_e32 v33, v33
	v_rcp_f32_e32 v25, v25
	v_add_f32_e32 v26, 1.0, v26
	v_lshl_add_u64 v[84:85], v[84:85], 0, v[134:135]
	v_mul_f32_e32 v62, v68, v62
	v_fma_f32 v68, v71, v152, v75
	v_fma_f32 v48, v55, v152, v59
	v_mul_f32_e32 v40, v44, v40
	v_fma_f32 v44, v45, v153, v73
	v_rcp_f32_e32 v26, v26
	v_add_f32_e32 v27, 1.0, v27
	v_add_f32_e32 v17, 1.0, v17
	v_add_f32_e32 v8, 1.0, v8
	v_cvt_pk_bf16_f32 v83, v86, v83
	global_store_dwordx4 v[84:85], v[80:83], off
	v_mul_f32_e32 v63, v68, v63
	v_mul_f32_e32 v51, v48, v49
	v_cvt_pk_bf16_f32 v48, v60, v61
	v_cvt_pk_bf16_f32 v49, v62, v63
	v_cvt_pk_bf16_f32 v50, v52, v53
	v_add_co_u32_e32 v52, vcc, s37, v132
	v_mul_f32_e32 v41, v44, v41
	v_fma_f32 v44, v46, v153, v74
	v_fma_f32 v28, v28, v150, v72
	v_rcp_f32_e32 v27, v27
	v_rcp_f32_e32 v17, v17
	v_rcp_f32_e32 v8, v8
	v_add_f32_e32 v9, 1.0, v9
	v_addc_co_u32_e32 v53, vcc, 0, v133, vcc
	v_mul_f32_e32 v42, v44, v42
	v_fma_f32 v44, v47, v153, v75
	v_fma_f32 v32, v39, v153, v59
	s_mov_b32 s37, 0x48000
	v_mul_f32_e32 v24, v28, v24
	v_fma_f32 v28, v29, v150, v73
	v_rcp_f32_e32 v9, v9
	v_add_f32_e32 v10, 1.0, v10
	v_add_f32_e32 v11, 1.0, v11
	v_add_f32_e32 v0, 1.0, v0
	v_cvt_pk_bf16_f32 v51, v54, v51
	global_store_dwordx4 v[52:53], v[48:51], off
	v_mul_f32_e32 v43, v44, v43
	v_mul_f32_e32 v35, v32, v33
	v_cvt_pk_bf16_f32 v32, v40, v41
	v_cvt_pk_bf16_f32 v33, v42, v43
	v_cvt_pk_bf16_f32 v34, v36, v37
	v_add_co_u32_e32 v36, vcc, s37, v132
	v_mul_f32_e32 v25, v28, v25
	v_fma_f32 v28, v30, v150, v74
	v_rcp_f32_e32 v10, v10
	v_rcp_f32_e32 v11, v11
	v_rcp_f32_e32 v0, v0
	v_addc_co_u32_e32 v37, vcc, 0, v133, vcc
	v_mul_f32_e32 v26, v28, v26
	v_fma_f32 v28, v31, v150, v75
	v_fma_f32 v16, v23, v150, v59
	s_mov_b32 s37, 0x50000
	v_fma_f32 v12, v12, v151, v72
	v_cvt_pk_bf16_f32 v35, v38, v35
	global_store_dwordx4 v[36:37], v[32:35], off
	v_mul_f32_e32 v27, v28, v27
	v_mul_f32_e32 v19, v16, v17
	v_cvt_pk_bf16_f32 v16, v24, v25
	v_cvt_pk_bf16_f32 v17, v26, v27
	v_cvt_pk_bf16_f32 v18, v20, v21
	v_add_co_u32_e32 v20, vcc, s37, v132
	v_mul_f32_e32 v8, v12, v8
	v_fma_f32 v12, v13, v151, v73
	v_addc_co_u32_e32 v21, vcc, 0, v133, vcc
	v_mul_f32_e32 v9, v12, v9
	v_fma_f32 v12, v14, v151, v74
	v_fmac_f32_e32 v75, v15, v151
	v_fmac_f32_e32 v59, v7, v151
	v_cvt_pk_bf16_f32 v19, v22, v19
	global_store_dwordx4 v[20:21], v[16:19], off
	v_mul_f32_e32 v10, v12, v10
	v_mul_f32_e32 v11, v75, v11
	v_mul_f32_e32 v3, v59, v0
	v_cvt_pk_bf16_f32 v0, v8, v9
	v_cvt_pk_bf16_f32 v1, v10, v11
	v_cvt_pk_bf16_f32 v2, v4, v5
	v_add_co_u32_e32 v4, vcc, 0x58000, v132
	v_cvt_pk_bf16_f32 v3, v6, v3
	s_nop 1
	v_addc_co_u32_e32 v5, vcc, 0, v133, vcc
	s_andn2_b64 vcc, exec, s[4:5]
	global_store_dwordx4 v[4:5], v[0:3], off
	s_cbranch_vccnz .LBB0_480
; template <class Epi, class Sched, bool ALIGN_EPI = false, bool SP2 = false, bool TA = true>
; __device__ __forceinline__ void gemm_phase(PG8_LAS unsigned char* lds, const Gemm g, const Sched& S, const Epi& E) {
;     ...
;         PG8_RTAB(cur, ui);
	s_and_saveexec_b64 s[4:5], s[2:3]
	s_cbranch_execz .LBB0_494
	v_lshl_or_b32 v0, s26, 8, v208
	v_ashrrev_i32_e32 v1, 31, v0
	v_lshlrev_b64 v[0:1], 6, v[0:1]
	v_lshl_add_u64 v[12:13], s[24:25], 0, v[0:1]
	global_load_dwordx4 v[0:3], v[12:13], off
	global_load_dwordx4 v[4:7], v[12:13], off offset:16
	global_load_dwordx4 v[8:11], v[12:13], off offset:32
	s_nop 0
	global_load_dwordx4 v[12:15], v[12:13], off offset:48
	s_lshl_b32 s37, s36, 10
	s_and_b32 s37, s37, 0x400
	s_waitcnt vmcnt(2)
	v_pk_add_f32 v[2:3], v[2:3], v[6:7]
	v_pk_add_f32 v[0:1], v[0:1], v[4:5]
	s_waitcnt vmcnt(0)
	v_pk_add_f32 v[4:5], v[10:11], v[14:15]
	v_pk_add_f32 v[6:7], v[8:9], v[12:13]
	v_pk_add_f32 v[2:3], v[2:3], v[4:5]
	v_pk_add_f32 v[0:1], v[0:1], v[6:7]
	s_nop 0
	v_pk_mov_b32 v[4:5], v[0:1], v[2:3] op_sel:[1,0]
	v_mov_b32_e32 v1, v3
	v_pk_add_f32 v[0:1], v[4:5], v[0:1]
	s_nop 0
	v_add_f32_e32 v0, v0, v1
	v_fmamk_f32 v0, v0, 0x3a800000, v170
	v_rsq_f32_e32 v0, v0
	v_add_u32_e32 v1, s37, v164
	ds_write_b32 v1, v0

; #define PG8_WAIT_V(n) asm volatile("s_waitcnt vmcnt(" #n ")" ::: "memory")
; #define PG8_BAR __builtin_amdgcn_s_barrier()
; template <class Epi, class Sched, bool ALIGN_EPI = false, bool SP2 = false, bool TA = true>
; __device__ __forceinline__ void gemm_phase(PG8_LAS unsigned char* lds, const Gemm g, const Sched& S, const Epi& E) {
;     ...
;     PG8_WAIT_V(0);
;     if constexpr (!ALIGN_EPI) { if (wr == 0) PG8_BAR; }
;     PG8_BAR;
; __device__ __forceinline__ void xcd_barrier(const XcdBarrier& b) {
;     asm volatile("s_waitcnt vmcnt(0)" ::: "memory");
;     __syncthreads();
;     if (threadIdx.x == 0) {
;         unsigned* bar = b.bar;
;         __builtin_amdgcn_s_waitcnt(0);
;         unsigned nloc = b.st[0], nx = b.st[1];
;         if (nloc == 0u) { xcd_barrier_complete(bar, b.x, nloc, nx); b.st[0] = nloc; b.st[1] = nx; }
.LBB0_496:
	s_waitcnt vmcnt(0)
	v_readlane_b32 s36, v254, 4
	v_readlane_b32 s37, v254, 5
	s_barrier
.LBB0_497:
	s_cmp_gt_i32 s37, 2
	s_cselect_b64 s[2:3], -1, 0
	s_and_b64 s[0:1], s[0:1], s[2:3]
	s_andn2_b64 vcc, exec, s[0:1]
	s_cbranch_vccnz .LBB0_551
	s_waitcnt vmcnt(0)
	s_waitcnt lgkmcnt(0)
	s_barrier
	s_mov_b64 s[0:1], exec
	v_readlane_b32 s4, v255, 9
	v_readlane_b32 s5, v255, 10
	s_and_b64 s[4:5], s[0:1], s[4:5]
	s_mov_b64 exec, s[4:5]
	s_cbranch_execz .LBB0_550
	s_add_i32 s4, 0, 0x20040
	v_mov_b32_e32 v0, s4
	s_waitcnt vmcnt(0) expcnt(0) lgkmcnt(0)
	ds_read_b32 v2, v0
	s_add_i32 s4, 0, 0x20044
	v_mov_b32_e32 v0, s4
	ds_read_b32 v0, v0
	s_waitcnt lgkmcnt(1)
	v_cmp_ne_u32_e32 vcc, 0, v2
	s_cbranch_vccnz .LBB0_514
	v_readlane_b32 s4, v255, 4
	v_readlane_b32 s5, v255, 5
	v_readlane_b32 s6, v255, 7
	s_mul_i32 s18, s5, s6
	s_mul_i32 s18, s18, s4
	s_add_u32 s4, s28, 0x1000
	s_addc_u32 s5, s29, 0
	s_add_u32 s6, s28, 0x1100
	s_addc_u32 s7, s29, 0
	s_add_u32 s8, s28, 0x1200
	s_addc_u32 s9, s29, 0
	s_add_u32 s10, s28, 0x1300
	s_addc_u32 s11, s29, 0
	s_mov_b32 s19, 1
	v_mov_b32_e32 v16, 0
	s_branch .LBB0_502

; #define LAS __attribute__((address_space(3)))
; __device__ __forceinline__ void conv_phase(const Args& a, LAS unsigned char* lds, int vcu, int G, int tid, int wave, int lane) {
;     const bf16* U = (const bf16*)(a.ws + WS_U); bf16* V2 = (bf16*)(a.ws + WS_V2);
;     const float* dw = a.in[I_CDW]; const float* db = a.in[I_CDB]; const float* lg = a.in[I_CLG]; const float* lb = a.in[I_CLB];
;     typedef float f32x2 __attribute__((ext_vector_type(2)));
;     LAS f32x2* red = (LAS f32x2*)lds;
;     LAS f32x2* stat = (LAS f32x2*)(lds + 4096);
;     const int c0 = 2 * tid;
;     f32x2 w[CW];
; #pragma unroll
;     for (int j = 0; j < CW; ++j) w[j] = *(const f32x2*)(dw + j * D + c0);
;     const f32x2 bias = *(const f32x2*)(db + c0), g2 = *(const f32x2*)(lg + c0), b2 = *(const f32x2*)(lb + c0);
.LBB0_551:
	s_cmp_lt_i32 s36, 3
	s_cselect_b64 s[0:1], -1, 0
	s_and_b64 s[0:1], s[0:1], s[2:3]
	s_andn2_b64 vcc, exec, s[0:1]
	s_cbranch_vccnz .LBB0_619
	v_readlane_b32 s2, v255, 6
	s_cmpk_gt_i32 s2, 0x3ff
	s_waitcnt lgkmcnt(0)
	s_barrier
	s_cbranch_scc1 .LBB0_619
	v_readlane_b32 s40, v255, 11
	v_lshlrev_b32_e32 v0, 3, v208
	v_mov_b32_e32 v1, 0
	v_readlane_b32 s50, v255, 21
	v_readlane_b32 s51, v255, 22
	v_readlane_b32 s52, v255, 23
	v_readlane_b32 s53, v255, 24
	v_lshl_add_u64 v[58:59], s[50:51], 0, v[0:1]
	v_add_co_u32_e32 v10, vcc, 0x1000, v58
	v_readlane_b32 s54, v255, 25
	s_nop 0
	v_addc_co_u32_e32 v11, vcc, 0, v59, vcc
	v_add_co_u32_e32 v12, vcc, 0x2000, v58
	v_readlane_b32 s55, v255, 26
	s_nop 0
	v_addc_co_u32_e32 v13, vcc, 0, v59, vcc
	v_add_co_u32_e32 v14, vcc, 0x3000, v58
	v_readlane_b32 s4, v255, 27
	s_nop 0
	v_addc_co_u32_e32 v15, vcc, 0, v59, vcc
	v_add_co_u32_e32 v16, vcc, 0x4000, v58
	v_readlane_b32 s5, v255, 28
	s_nop 0
	v_addc_co_u32_e32 v17, vcc, 0, v59, vcc
	global_load_dwordx2 v[2:3], v[10:11], off
	global_load_dwordx2 v[4:5], v[12:13], off
	global_load_dwordx2 v[6:7], v[14:15], off
	global_load_dwordx2 v[8:9], v[16:17], off
	v_add_co_u32_e32 v10, vcc, 0x5000, v58
	v_readlane_b32 s6, v255, 29
	s_nop 0
	v_addc_co_u32_e32 v11, vcc, 0, v59, vcc
	v_add_co_u32_e32 v18, vcc, 0x6000, v58
	v_readlane_b32 s7, v255, 30
	s_nop 0
	v_addc_co_u32_e32 v19, vcc, 0, v59, vcc
	v_add_co_u32_e32 v20, vcc, 0x7000, v58
	v_readlane_b32 s8, v255, 31
	s_nop 0
	v_addc_co_u32_e32 v21, vcc, 0, v59, vcc
	v_add_co_u32_e32 v22, vcc, 0x8000, v58
	v_readlane_b32 s9, v255, 32
	s_nop 0
	v_addc_co_u32_e32 v23, vcc, 0, v59, vcc
	global_load_dwordx2 v[10:11], v[10:11], off
	s_nop 0
	global_load_dwordx2 v[12:13], v[18:19], off
	global_load_dwordx2 v[14:15], v[20:21], off
	global_load_dwordx2 v[16:17], v[22:23], off
	v_add_co_u32_e32 v18, vcc, 0x9000, v58
	v_readlane_b32 s10, v255, 33
	s_nop 0
	v_addc_co_u32_e32 v19, vcc, 0, v59, vcc
	v_add_co_u32_e32 v26, vcc, 0xa000, v58
	v_readlane_b32 s11, v255, 34
	s_nop 0
	v_addc_co_u32_e32 v27, vcc, 0, v59, vcc
	v_add_co_u32_e32 v28, vcc, 0xb000, v58
	v_readlane_b32 s12, v255, 35
	s_nop 0
	v_addc_co_u32_e32 v29, vcc, 0, v59, vcc
	v_add_co_u32_e32 v30, vcc, 0xc000, v58
	v_readlane_b32 s13, v255, 36
	s_nop 0
	v_addc_co_u32_e32 v31, vcc, 0, v59, vcc
	global_load_dwordx2 v[18:19], v[18:19], off
	s_nop 0
	global_load_dwordx2 v[20:21], v[26:27], off
	global_load_dwordx2 v[22:23], v[28:29], off
	global_load_dwordx2 v[24:25], v[30:31], off
	v_add_co_u32_e32 v26, vcc, 0xd000, v58
	v_add_u32_e32 v188, 0, v0
	s_nop 0
	v_addc_co_u32_e32 v27, vcc, 0, v59, vcc
	v_add_co_u32_e32 v34, vcc, 0xe000, v58
	v_readlane_b32 s14, v255, 37
	s_nop 0
	v_addc_co_u32_e32 v35, vcc, 0, v59, vcc
	v_add_co_u32_e32 v36, vcc, 0xf000, v58
	v_readlane_b32 s16, v255, 39
	s_nop 0
	v_addc_co_u32_e32 v37, vcc, 0, v59, vcc
	v_add_co_u32_e32 v38, vcc, 0x10000, v58
	v_readlane_b32 s17, v255, 40
	s_nop 0
	v_addc_co_u32_e32 v39, vcc, 0, v59, vcc
	global_load_dwordx2 v[26:27], v[26:27], off
	s_nop 0
	global_load_dwordx2 v[28:29], v[34:35], off
	global_load_dwordx2 v[30:31], v[36:37], off
	global_load_dwordx2 v[32:33], v[38:39], off
	v_add_co_u32_e32 v34, vcc, 0x11000, v58
	v_readlane_b32 s14, v255, 59
	s_nop 0
	v_addc_co_u32_e32 v35, vcc, 0, v59, vcc
	v_add_co_u32_e32 v42, vcc, 0x12000, v58
	s_mov_b64 s[16:17], 0x12000000
	s_nop 0
	v_addc_co_u32_e32 v43, vcc, 0, v59, vcc
	v_add_co_u32_e32 v44, vcc, 0x13000, v58
	v_readlane_b32 s44, v255, 15
	s_nop 0
	v_addc_co_u32_e32 v45, vcc, 0, v59, vcc
	v_add_co_u32_e32 v46, vcc, 0x14000, v58
	v_readlane_b32 s46, v255, 17
	s_nop 0
	v_addc_co_u32_e32 v47, vcc, 0, v59, vcc
	global_load_dwordx2 v[34:35], v[34:35], off
	s_nop 0
	global_load_dwordx2 v[36:37], v[42:43], off
	global_load_dwordx2 v[38:39], v[44:45], off
	global_load_dwordx2 v[40:41], v[46:47], off
	v_add_co_u32_e32 v42, vcc, 0x15000, v58
	v_readlane_b32 s15, v255, 38
	s_nop 0
	v_addc_co_u32_e32 v43, vcc, 0, v59, vcc
	v_add_co_u32_e32 v50, vcc, 0x16000, v58
	v_readlane_b32 s18, v255, 41
	s_nop 0
	v_addc_co_u32_e32 v51, vcc, 0, v59, vcc
	v_add_co_u32_e32 v52, vcc, 0x17000, v58
	v_readlane_b32 s19, v255, 42
	s_nop 0
	v_addc_co_u32_e32 v53, vcc, 0, v59, vcc
	v_add_co_u32_e32 v54, vcc, 0x18000, v58
	v_lshl_add_u32 v74, v209, 2, 0
	s_nop 0
	v_addc_co_u32_e32 v55, vcc, 0, v59, vcc
	global_load_dwordx2 v[42:43], v[42:43], off
	s_nop 0
	global_load_dwordx2 v[44:45], v[50:51], off
	global_load_dwordx2 v[46:47], v[52:53], off
	global_load_dwordx2 v[48:49], v[54:55], off
	v_add_co_u32_e32 v50, vcc, 0x19000, v58
	s_mov_b64 s[2:3], 0xe000000
	s_nop 0
	v_addc_co_u32_e32 v51, vcc, 0, v59, vcc
	v_add_co_u32_e32 v60, vcc, 0x1a000, v58
	s_lshl_b32 s21, s14, 8
	s_nop 0
	v_addc_co_u32_e32 v61, vcc, 0, v59, vcc
	v_add_co_u32_e32 v62, vcc, 0x1b000, v58
	v_readlane_b32 s22, v255, 6
	s_nop 0
	v_addc_co_u32_e32 v63, vcc, 0, v59, vcc
	v_add_co_u32_e32 v64, vcc, 0x1c000, v58
	v_cmp_gt_u32_e64 s[14:15], 32, v208
	s_nop 0
	v_addc_co_u32_e32 v65, vcc, 0, v59, vcc
	v_add_co_u32_e32 v70, vcc, 0x1d000, v58
	global_load_dwordx2 v[50:51], v[50:51], off
	s_nop 0
	global_load_dwordx2 v[52:53], v[60:61], off
	global_load_dwordx2 v[54:55], v[62:63], off
	global_load_dwordx2 v[56:57], v[64:65], off
	v_addc_co_u32_e32 v71, vcc, 0, v59, vcc
	v_add_co_u32_e32 v72, vcc, 0x1e000, v58
	v_bfe_u32 v189, v208, 4, 1
	s_nop 0
	v_addc_co_u32_e32 v73, vcc, 0, v59, vcc
	global_load_dwordx2 v[58:59], v0, s[50:51]
	global_load_dwordx2 v[60:61], v[70:71], off
	global_load_dwordx2 v[62:63], v0, s[52:53]
	global_load_dwordx2 v[64:65], v[72:73], off
	global_load_dwordx2 v[66:67], v0, s[54:55]
	global_load_dwordx2 v[68:69], v0, s[4:5]
; __host__ __device__ __forceinline__ size_t tiled_off(int row, int col, int K) { return ((size_t)(row >> 7) * (K >> 6) + (col >> 6)) * 8192 + (lds_byte(row & 127, col & 63) >> 1); }
; __device__ __forceinline__ float fast_sigmoid(float x) { return __builtin_amdgcn_rcpf(1.0f + __builtin_amdgcn_exp2f(x * -1.4426950408889634f)); }
; __device__ __forceinline__ unsigned pk2(float lo, float hi) { return f2bf(lo) | (f2bf(hi) << 16); }
; #define RS_STEP(m_, n_) { const bool up_ = (lane & (m_)) != 0; _Pragma("unroll") for (int j = 0; j < (n_); ++j) { const float a_ = v[j], b_ = v[j + (n_)]; const float send_ = up_ ? a_ : b_, keep_ = up_ ? b_ : a_; v[j] = keep_ + __shfl_xor(send_, (m_)); } }
; __device__ __forceinline__ void conv_phase(const Args& a, LAS unsigned char* lds, int vcu, int G, int tid, int wave, int lane) {
;     ...
;             RS_STEP(32, 32) RS_STEP(16, 16) RS_STEP(8, 8) RS_STEP(4, 4) RS_STEP(2, 2) RS_STEP(1, 1)
;     ...
;         __syncthreads();
;         if (tid < 32) { float s = 0.f, q = 0.f;
; #pragma unroll
;             for (int wv = 0; wv < 8; ++wv) { const f32x2 r = red[wv * 32 + tid]; s += r.x; q += r.y; }
;             const float mean = s * (1.0f / D), var = fmaxf(q * (1.0f / D) - mean * mean, 0.f);
;             stat[tid] = (f32x2){mean, __builtin_amdgcn_rsqf(var + 1e-6f)}; }
;         __syncthreads();
; #pragma unroll
;         for (int i = 0; i < 32; ++i) { const f32x2 st = stat[i]; f32x2 y = (o[i] - st.x) * st.y * g2 + b2;
;             y.x = y.x * pg8::fast_sigmoid(y.x); y.y = y.y * pg8::fast_sigmoid(y.y);
;             *(unsigned*)(V2 + pg8::tiled_off(t0 + i, c0, D)) = pk2(y.x, y.y); }
	v_mbcnt_lo_u32_b32 v73, -1, 0
	v_mbcnt_hi_u32_b32 v73, -1, v73
	v_and_b32_e32 v76, 64, v73
	v_xor_b32_e32 v75, 32, v73
	v_add_u32_e32 v76, 64, v76
	v_cmp_lt_i32_e32 vcc, v75, v76
	v_lshlrev_b32_e32 v0, 9, v208
	v_lshlrev_b32_e32 v72, 1, v208
	v_cndmask_b32_e32 v75, v73, v75, vcc
	v_lshlrev_b32_e32 v182, 2, v75
	v_and_b32_e32 v75, 16, v208
	v_cmp_eq_u32_e64 s[4:5], 0, v75
	v_xor_b32_e32 v75, 16, v73
	v_cmp_lt_i32_e32 vcc, v75, v76
	v_and_b32_e32 v0, 0x7c000, v0
	v_lshlrev_b32_e32 v70, 2, v208
	v_cndmask_b32_e32 v75, v73, v75, vcc
	v_lshlrev_b32_e32 v183, 2, v75
	v_and_b32_e32 v75, 8, v208
	v_cmp_eq_u32_e64 s[6:7], 0, v75
	v_xor_b32_e32 v75, 8, v73
	v_cmp_lt_i32_e32 vcc, v75, v76
	v_mov_b32_e32 v71, v1
	v_and_b32_e32 v190, 30, v72
	v_cndmask_b32_e32 v75, v73, v75, vcc
	v_lshlrev_b32_e32 v184, 2, v75
	v_and_b32_e32 v75, 4, v208
	v_cmp_eq_u32_e64 s[8:9], 0, v75
	v_xor_b32_e32 v75, 4, v73
	v_cmp_lt_i32_e32 vcc, v75, v76
	v_lshl_add_u64 v[70:71], s[28:29], 0, v[70:71]
	v_lshl_add_u64 v[70:71], v[70:71], 0, s[2:3]
	v_cndmask_b32_e32 v75, v73, v75, vcc
	v_lshlrev_b32_e32 v185, 2, v75
	v_and_b32_e32 v75, 2, v208
	v_cmp_eq_u32_e64 s[10:11], 0, v75
	v_xor_b32_e32 v75, 2, v73
	v_cmp_lt_i32_e32 vcc, v75, v76
	v_cmp_gt_u32_e64 s[2:3], 32, v209
	s_lshl_b32 s44, s22, 5
	v_cndmask_b32_e32 v75, v73, v75, vcc
	v_lshlrev_b32_e32 v186, 2, v75
	v_and_b32_e32 v75, 1, v208
	v_cmp_eq_u32_e64 s[12:13], 0, v75
	v_xor_b32_e32 v75, 1, v73
	v_cmp_lt_i32_e32 vcc, v75, v76
	s_mov_b32 s19, 0xffff0000
	v_add_u32_e32 v191, s21, v74
	v_cndmask_b32_e32 v73, v73, v75, vcc
	v_lshlrev_b32_e32 v187, 2, v73
	v_lshl_add_u64 v[72:73], s[28:29], 0, v[0:1]
	v_lshl_add_u64 v[72:73], v[72:73], 0, s[16:17]
	v_readlane_b32 s16, v255, 4
	s_lshl_b32 s18, s16, 5
	s_mov_b32 s46, 0x3a800000
	s_movk_i32 s21, 0x7fff
	v_readlane_b32 s41, v255, 12
	v_readlane_b32 s42, v255, 13
	v_readlane_b32 s43, v255, 14
	v_readlane_b32 s45, v255, 16
	v_readlane_b32 s47, v255, 18
	v_readlane_b32 s48, v255, 19
	v_readlane_b32 s49, v255, 20
	v_readlane_b32 s17, v255, 5
	s_branch .LBB0_555
.LBB0_554:
	s_or_b64 exec, exec, s[16:17]
	s_waitcnt lgkmcnt(0)
	s_barrier
	ds_read_b128 v[138:141], v1 offset:4096
	ds_read_b128 v[142:145], v1 offset:4112
	s_ashr_i32 s16, s22, 2
	s_ashr_i32 s17, s16, 31
	s_lshl_b64 s[16:17], s[16:17], 18
	s_waitcnt lgkmcnt(1)
	v_pk_add_f32 v[88:89], v[88:89], v[138:139] op_sel_hi:[1,0] neg_lo:[0,1] neg_hi:[0,1]
	s_nop 0
	v_pk_mul_f32 v[88:89], v[138:139], v[88:89] op_sel:[1,0]
	s_nop 0
	v_pk_fma_f32 v[88:89], v[66:67], v[88:89], v[68:69]
	s_nop 0
	v_mul_f32_e32 v0, 0xbfb8aa3b, v88
	v_exp_f32_e32 v0, v0
	v_mul_f32_e32 v138, 0xbfb8aa3b, v89
	v_exp_f32_e32 v146, v138
	v_lshl_add_u64 v[138:139], v[72:73], 0, s[16:17]
	v_add_f32_e32 v0, 1.0, v0
	v_rcp_f32_e32 v0, v0
	v_add_f32_e32 v146, 1.0, v146
	v_rcp_f32_e32 v154, v146
	s_lshr_b32 s16, s44, 3
	v_mul_f32_e32 v0, v88, v0
	ds_read_b128 v[146:149], v1 offset:4128
	ds_read_b128 v[150:153], v1 offset:4144
	v_mul_f32_e32 v88, v89, v154
	v_bfe_u32 v89, v0, 16, 1
	v_add3_u32 v0, v0, v89, s21
	v_bfe_u32 v89, v88, 16, 1
	v_lshrrev_b32_e32 v0, 16, v0
	v_add3_u32 v88, v88, v89, s21
	v_and_or_b32 v154, v88, s19, v0
	v_and_or_b32 v0, s16, 12, v189
	v_lshl_or_b32 v155, v0, 9, v190
	v_pk_add_f32 v[88:89], v[90:91], v[140:141] op_sel_hi:[1,0] neg_lo:[0,1] neg_hi:[0,1]
	v_mov_b32_e32 v0, v141
	v_pk_mul_f32 v[88:89], v[0:1], v[88:89] op_sel_hi:[0,1]
	v_pk_fma_f32 v[90:91], v[66:67], v[88:89], v[68:69]
	v_readlane_b32 s16, v255, 4
	v_mul_f32_e32 v0, 0xbfb8aa3b, v90
	v_exp_f32_e32 v88, v0
	v_mul_f32_e32 v0, 0xbfb8aa3b, v91
	v_exp_f32_e32 v89, v0
	v_lshlrev_b32_e32 v0, 1, v155
	v_add_f32_e32 v88, 1.0, v88
	v_rcp_f32_e32 v140, v88
	v_add_f32_e32 v88, 1.0, v89
	v_rcp_f32_e32 v141, v88
	v_lshl_add_u64 v[88:89], v[138:139], 0, v[0:1]
	v_mul_f32_e32 v0, v90, v140
	v_bfe_u32 v90, v0, 16, 1
	v_mul_f32_e32 v140, v91, v141
	v_add3_u32 v0, v0, v90, s21
	s_waitcnt lgkmcnt(2)
	v_pk_add_f32 v[90:91], v[98:99], v[142:143] op_sel_hi:[1,0] neg_lo:[0,1] neg_hi:[0,1]
	v_bfe_u32 v141, v140, 16, 1
	v_pk_mul_f32 v[90:91], v[142:143], v[90:91] op_sel:[1,0]
	v_lshrrev_b32_e32 v0, 16, v0
	v_pk_fma_f32 v[90:91], v[66:67], v[90:91], v[68:69]
	v_add3_u32 v140, v140, v141, s21
	v_mul_f32_e32 v98, 0xbfb8aa3b, v90
	v_exp_f32_e32 v98, v98
	v_mul_f32_e32 v99, 0xbfb8aa3b, v91
	v_exp_f32_e32 v99, v99
	v_and_or_b32 v0, v140, s19, v0
	v_add_f32_e32 v98, 1.0, v98
	v_rcp_f32_e32 v98, v98
	v_add_f32_e32 v99, 1.0, v99
	v_rcp_f32_e32 v99, v99
	global_store_dword v[88:89], v0, off offset:64
	v_mul_f32_e32 v0, v90, v98
	v_bfe_u32 v90, v0, 16, 1
	v_add3_u32 v0, v0, v90, s21
	v_mul_f32_e32 v98, v91, v99
	v_lshrrev_b32_e32 v99, 16, v0
	v_pk_add_f32 v[90:91], v[108:109], v[144:145] op_sel_hi:[1,0] neg_lo:[0,1] neg_hi:[0,1]
	v_mov_b32_e32 v0, v145
	v_pk_mul_f32 v[90:91], v[0:1], v[90:91] op_sel_hi:[0,1]
	v_pk_fma_f32 v[90:91], v[66:67], v[90:91], v[68:69]
	v_bfe_u32 v140, v98, 16, 1
	v_mul_f32_e32 v0, 0xbfb8aa3b, v90
	v_exp_f32_e32 v0, v0
	v_mul_f32_e32 v108, 0xbfb8aa3b, v91
	v_exp_f32_e32 v108, v108
	v_add3_u32 v98, v98, v140, s21
	v_add_f32_e32 v0, 1.0, v0
	v_rcp_f32_e32 v0, v0
	v_add_f32_e32 v108, 1.0, v108
	v_rcp_f32_e32 v108, v108
	v_and_or_b32 v98, v98, s19, v99
	v_mul_f32_e32 v0, v90, v0
	v_bfe_u32 v90, v0, 16, 1
	global_store_dword v[88:89], v98, off offset:128
	v_mul_f32_e32 v98, v91, v108
	v_add3_u32 v0, v0, v90, s21
	s_waitcnt lgkmcnt(1)
; __host__ __device__ __forceinline__ size_t tiled_off(int row, int col, int K) { return ((size_t)(row >> 7) * (K >> 6) + (col >> 6)) * 8192 + (lds_byte(row & 127, col & 63) >> 1); }
; __device__ __forceinline__ float fast_sigmoid(float x) { return __builtin_amdgcn_rcpf(1.0f + __builtin_amdgcn_exp2f(x * -1.4426950408889634f)); }
; __device__ __forceinline__ unsigned pk2(float lo, float hi) { return f2bf(lo) | (f2bf(hi) << 16); }
; __device__ __forceinline__ void conv_phase(const Args& a, LAS unsigned char* lds, int vcu, int G, int tid, int wave, int lane) {
;     ...
;         for (int i = 0; i < 32; ++i) { const f32x2 st = stat[i]; f32x2 y = (o[i] - st.x) * st.y * g2 + b2;
;             y.x = y.x * pg8::fast_sigmoid(y.x); y.y = y.y * pg8::fast_sigmoid(y.y);
;             *(unsigned*)(V2 + pg8::tiled_off(t0 + i, c0, D)) = pk2(y.x, y.y); }
	v_pk_add_f32 v[90:91], v[118:119], v[146:147] op_sel_hi:[1,0] neg_lo:[0,1] neg_hi:[0,1]
	v_bfe_u32 v99, v98, 16, 1
	v_pk_mul_f32 v[90:91], v[146:147], v[90:91] op_sel:[1,0]
	v_add3_u32 v98, v98, v99, s21
	v_pk_fma_f32 v[90:91], v[66:67], v[90:91], v[68:69]
	v_lshrrev_b32_e32 v0, 16, v0
	v_mul_f32_e32 v108, 0xbfb8aa3b, v90
	v_exp_f32_e32 v108, v108
	v_mul_f32_e32 v109, 0xbfb8aa3b, v91
	v_exp_f32_e32 v109, v109
	v_and_or_b32 v0, v98, s19, v0
	v_add_f32_e32 v99, 1.0, v108
	v_rcp_f32_e32 v99, v99
	v_add_f32_e32 v108, 1.0, v109
	v_rcp_f32_e32 v108, v108
	global_store_dword v[88:89], v0, off offset:192
	v_mul_f32_e32 v0, v90, v99
	v_bfe_u32 v90, v0, 16, 1
	v_add3_u32 v0, v0, v90, s21
	v_mul_f32_e32 v98, v91, v108
	v_lshrrev_b32_e32 v99, 16, v0
	v_pk_add_f32 v[90:91], v[128:129], v[148:149] op_sel_hi:[1,0] neg_lo:[0,1] neg_hi:[0,1]
	v_mov_b32_e32 v0, v149
	v_pk_mul_f32 v[90:91], v[0:1], v[90:91] op_sel_hi:[0,1]
	v_pk_fma_f32 v[90:91], v[66:67], v[90:91], v[68:69]
	v_bfe_u32 v108, v98, 16, 1
	v_mul_f32_e32 v0, 0xbfb8aa3b, v90
	v_exp_f32_e32 v0, v0
	v_mul_f32_e32 v109, 0xbfb8aa3b, v91
	v_exp_f32_e32 v109, v109
	v_add3_u32 v98, v98, v108, s21
	v_add_f32_e32 v0, 1.0, v0
	v_rcp_f32_e32 v0, v0
	v_add_f32_e32 v108, 1.0, v109
	v_rcp_f32_e32 v108, v108
	v_and_or_b32 v98, v98, s19, v99
	v_mul_f32_e32 v0, v90, v0
	v_bfe_u32 v90, v0, 16, 1
	global_store_dword v[88:89], v98, off offset:256
	v_mul_f32_e32 v98, v91, v108
	v_add3_u32 v0, v0, v90, s21
	s_waitcnt lgkmcnt(0)
	v_pk_add_f32 v[90:91], v[134:135], v[150:151] op_sel_hi:[1,0] neg_lo:[0,1] neg_hi:[0,1]
	v_bfe_u32 v99, v98, 16, 1
	v_pk_mul_f32 v[90:91], v[150:151], v[90:91] op_sel:[1,0]
	v_add3_u32 v98, v98, v99, s21
	v_pk_fma_f32 v[90:91], v[66:67], v[90:91], v[68:69]
	v_lshrrev_b32_e32 v0, 16, v0
	v_mul_f32_e32 v108, 0xbfb8aa3b, v90
	v_exp_f32_e32 v108, v108
	v_mul_f32_e32 v109, 0xbfb8aa3b, v91
	v_exp_f32_e32 v109, v109
	v_and_or_b32 v0, v98, s19, v0
	v_add_f32_e32 v99, 1.0, v108
	v_rcp_f32_e32 v99, v99
	v_add_f32_e32 v108, 1.0, v109
	v_rcp_f32_e32 v108, v108
	global_store_dword v[88:89], v0, off offset:320
	v_mul_f32_e32 v0, v90, v99
	v_bfe_u32 v90, v0, 16, 1
	v_add3_u32 v0, v0, v90, s21
	v_mul_f32_e32 v98, v91, v108
	v_lshrrev_b32_e32 v99, 16, v0
	v_pk_add_f32 v[90:91], v[136:137], v[152:153] op_sel_hi:[1,0] neg_lo:[0,1] neg_hi:[0,1]
	v_mov_b32_e32 v0, v153
	v_pk_mul_f32 v[90:91], v[0:1], v[90:91] op_sel_hi:[0,1]
	v_pk_fma_f32 v[90:91], v[66:67], v[90:91], v[68:69]
	v_bfe_u32 v108, v98, 16, 1
	v_mul_f32_e32 v0, 0xbfb8aa3b, v90
	v_exp_f32_e32 v0, v0
	v_mul_f32_e32 v109, 0xbfb8aa3b, v91
	v_exp_f32_e32 v109, v109
	v_add3_u32 v98, v98, v108, s21
	v_add_f32_e32 v0, 1.0, v0
	v_rcp_f32_e32 v0, v0
	v_add_f32_e32 v108, 1.0, v109
	ds_read_b128 v[134:137], v1 offset:4160
	ds_read_b128 v[140:143], v1 offset:4176
	v_rcp_f32_e32 v108, v108
	v_mul_f32_e32 v0, v90, v0
	v_and_or_b32 v98, v98, s19, v99
	v_bfe_u32 v90, v0, 16, 1
	global_store_dword v[88:89], v98, off offset:384
	v_mul_f32_e32 v98, v91, v108
	v_add3_u32 v0, v0, v90, s21
	s_waitcnt lgkmcnt(1)
	v_pk_add_f32 v[90:91], v[92:93], v[134:135] op_sel_hi:[1,0] neg_lo:[0,1] neg_hi:[0,1]
	v_bfe_u32 v99, v98, 16, 1
	v_pk_mul_f32 v[90:91], v[134:135], v[90:91] op_sel:[1,0]
	v_lshrrev_b32_e32 v0, 16, v0
	v_pk_fma_f32 v[90:91], v[66:67], v[90:91], v[68:69]
	v_add3_u32 v98, v98, v99, s21
	v_mul_f32_e32 v92, 0xbfb8aa3b, v90
	v_exp_f32_e32 v92, v92
	v_mul_f32_e32 v93, 0xbfb8aa3b, v91
	v_exp_f32_e32 v93, v93
	v_and_or_b32 v0, v98, s19, v0
	v_add_f32_e32 v92, 1.0, v92
	v_rcp_f32_e32 v92, v92
	v_add_f32_e32 v93, 1.0, v93
	v_rcp_f32_e32 v93, v93
	global_store_dword v[88:89], v0, off offset:448
	v_mul_f32_e32 v0, v90, v92
	global_store_dword v[88:89], v154, off
	v_mul_f32_e32 v90, v91, v93
	v_bfe_u32 v91, v0, 16, 1
	v_add3_u32 v0, v0, v91, s21
	v_bfe_u32 v91, v90, 16, 1
	v_lshrrev_b32_e32 v0, 16, v0
	v_add3_u32 v90, v90, v91, s21
	v_and_or_b32 v98, v90, s19, v0
	v_pk_add_f32 v[90:91], v[106:107], v[136:137] op_sel_hi:[1,0] neg_lo:[0,1] neg_hi:[0,1]
	v_mov_b32_e32 v0, v137
	v_pk_mul_f32 v[90:91], v[0:1], v[90:91] op_sel_hi:[0,1]
	v_pk_fma_f32 v[92:93], v[66:67], v[90:91], v[68:69]
	s_add_i32 s22, s22, s16
	v_mul_f32_e32 v0, 0xbfb8aa3b, v92
	v_exp_f32_e32 v90, v0
	v_mul_f32_e32 v0, 0xbfb8aa3b, v93
	v_exp_f32_e32 v91, v0
	v_xor_b32_e32 v0, 16, v155
	v_add_f32_e32 v90, 1.0, v90
	v_rcp_f32_e32 v99, v90
	v_add_f32_e32 v90, 1.0, v91
	v_rcp_f32_e32 v106, v90
	v_lshl_add_u64 v[90:91], v[0:1], 1, v[138:139]
	v_mul_f32_e32 v0, v92, v99
	v_bfe_u32 v92, v0, 16, 1
	global_store_dword v[90:91], v98, off offset:512
	v_mul_f32_e32 v98, v93, v106
	v_add3_u32 v0, v0, v92, s21
	s_waitcnt lgkmcnt(0)
	v_pk_add_f32 v[92:93], v[124:125], v[140:141] op_sel_hi:[1,0] neg_lo:[0,1] neg_hi:[0,1]
	v_bfe_u32 v99, v98, 16, 1
	v_pk_mul_f32 v[92:93], v[140:141], v[92:93] op_sel:[1,0]
	v_add3_u32 v98, v98, v99, s21
	v_pk_fma_f32 v[92:93], v[66:67], v[92:93], v[68:69]
	v_lshrrev_b32_e32 v0, 16, v0
	v_mul_f32_e32 v106, 0xbfb8aa3b, v92
	v_exp_f32_e32 v106, v106
	v_mul_f32_e32 v107, 0xbfb8aa3b, v93
	v_exp_f32_e32 v107, v107
	v_and_or_b32 v0, v98, s19, v0
	v_add_f32_e32 v99, 1.0, v106
	v_rcp_f32_e32 v99, v99
	v_add_f32_e32 v106, 1.0, v107
	v_rcp_f32_e32 v106, v106
	global_store_dword v[90:91], v0, off offset:576
	v_mul_f32_e32 v0, v92, v99
	v_bfe_u32 v92, v0, 16, 1
	v_add3_u32 v0, v0, v92, s21
	v_mul_f32_e32 v98, v93, v106
	v_lshrrev_b32_e32 v99, 16, v0
	v_pk_add_f32 v[92:93], v[132:133], v[142:143] op_sel_hi:[1,0] neg_lo:[0,1] neg_hi:[0,1]
	v_mov_b32_e32 v0, v143
	v_pk_mul_f32 v[92:93], v[0:1], v[92:93] op_sel_hi:[0,1]
	v_pk_fma_f32 v[92:93], v[66:67], v[92:93], v[68:69]
	v_bfe_u32 v106, v98, 16, 1
	v_mul_f32_e32 v0, 0xbfb8aa3b, v92
	v_mul_f32_e32 v107, 0xbfb8aa3b, v93
	v_exp_f32_e32 v0, v0
	v_exp_f32_e32 v107, v107
	v_add3_u32 v98, v98, v106, s21
	ds_read_b128 v[132:135], v1 offset:4208
	v_add_f32_e32 v0, 1.0, v0
	v_add_f32_e32 v106, 1.0, v107
	v_rcp_f32_e32 v0, v0
	v_rcp_f32_e32 v106, v106
	v_and_or_b32 v98, v98, s19, v99
	global_store_dword v[90:91], v98, off offset:640
	v_mul_f32_e32 v0, v92, v0
	v_mul_f32_e32 v92, v93, v106
	ds_read_b128 v[106:109], v1 offset:4192
	v_bfe_u32 v93, v0, 16, 1
	v_add3_u32 v0, v0, v93, s21
	v_bfe_u32 v93, v92, 16, 1
	v_add3_u32 v92, v92, v93, s21
	s_waitcnt lgkmcnt(0)
; __host__ __device__ __forceinline__ size_t tiled_off(int row, int col, int K) { return ((size_t)(row >> 7) * (K >> 6) + (col >> 6)) * 8192 + (lds_byte(row & 127, col & 63) >> 1); }
; __device__ __forceinline__ float fast_sigmoid(float x) { return __builtin_amdgcn_rcpf(1.0f + __builtin_amdgcn_exp2f(x * -1.4426950408889634f)); }
; __device__ __forceinline__ unsigned pk2(float lo, float hi) { return f2bf(lo) | (f2bf(hi) << 16); }
; __device__ __forceinline__ void conv_phase(const Args& a, LAS unsigned char* lds, int vcu, int G, int tid, int wave, int lane) {
;     ...
;         for (int i = 0; i < 32; ++i) { const f32x2 st = stat[i]; f32x2 y = (o[i] - st.x) * st.y * g2 + b2;
;             y.x = y.x * pg8::fast_sigmoid(y.x); y.y = y.y * pg8::fast_sigmoid(y.y);
;             *(unsigned*)(V2 + pg8::tiled_off(t0 + i, c0, D)) = pk2(y.x, y.y); }
	v_pk_add_f32 v[84:85], v[84:85], v[106:107] op_sel_hi:[1,0] neg_lo:[0,1] neg_hi:[0,1]
	v_lshrrev_b32_e32 v0, 16, v0
	v_pk_mul_f32 v[84:85], v[106:107], v[84:85] op_sel:[1,0]
	v_and_or_b32 v0, v92, s19, v0
	v_pk_fma_f32 v[84:85], v[66:67], v[84:85], v[68:69]
	global_store_dword v[90:91], v0, off offset:704
	v_mul_f32_e32 v98, 0xbfb8aa3b, v84
	v_exp_f32_e32 v98, v98
	v_mul_f32_e32 v99, 0xbfb8aa3b, v85
	v_exp_f32_e32 v99, v99
	s_add_i32 s44, s44, s18
	v_add_f32_e32 v93, 1.0, v98
	v_rcp_f32_e32 v93, v93
	v_add_f32_e32 v98, 1.0, v99
	v_rcp_f32_e32 v98, v98
	s_cmpk_lt_i32 s22, 0x400
	v_mul_f32_e32 v0, v84, v93
	v_bfe_u32 v84, v0, 16, 1
	v_add3_u32 v0, v0, v84, s21
	v_mul_f32_e32 v92, v85, v98
	v_lshrrev_b32_e32 v93, 16, v0
	v_pk_add_f32 v[84:85], v[102:103], v[108:109] op_sel_hi:[1,0] neg_lo:[0,1] neg_hi:[0,1]
	v_mov_b32_e32 v0, v109
	v_pk_mul_f32 v[84:85], v[0:1], v[84:85] op_sel_hi:[0,1]
	v_pk_fma_f32 v[84:85], v[66:67], v[84:85], v[68:69]
	v_bfe_u32 v98, v92, 16, 1
	v_mul_f32_e32 v0, 0xbfb8aa3b, v84
	v_exp_f32_e32 v0, v0
	v_mul_f32_e32 v99, 0xbfb8aa3b, v85
	v_exp_f32_e32 v99, v99
	v_add3_u32 v92, v92, v98, s21
	v_add_f32_e32 v0, 1.0, v0
	v_rcp_f32_e32 v0, v0
	v_add_f32_e32 v98, 1.0, v99
	v_rcp_f32_e32 v98, v98
	v_and_or_b32 v92, v92, s19, v93
	v_mul_f32_e32 v0, v84, v0
	v_bfe_u32 v84, v0, 16, 1
	global_store_dword v[90:91], v92, off offset:768
	v_mul_f32_e32 v92, v85, v98
	v_add3_u32 v0, v0, v84, s21
	v_pk_add_f32 v[84:85], v[120:121], v[132:133] op_sel_hi:[1,0] neg_lo:[0,1] neg_hi:[0,1]
	v_bfe_u32 v93, v92, 16, 1
	v_pk_mul_f32 v[84:85], v[132:133], v[84:85] op_sel:[1,0]
	v_add3_u32 v92, v92, v93, s21
	v_pk_fma_f32 v[84:85], v[66:67], v[84:85], v[68:69]
	v_lshrrev_b32_e32 v0, 16, v0
	v_mul_f32_e32 v98, 0xbfb8aa3b, v84
	v_exp_f32_e32 v98, v98
	v_mul_f32_e32 v99, 0xbfb8aa3b, v85
	v_exp_f32_e32 v99, v99
	v_and_or_b32 v0, v92, s19, v0
	v_add_f32_e32 v93, 1.0, v98
	v_rcp_f32_e32 v93, v93
	v_add_f32_e32 v98, 1.0, v99
	v_rcp_f32_e32 v98, v98
	global_store_dword v[90:91], v0, off offset:832
	v_mul_f32_e32 v0, v84, v93
	v_bfe_u32 v84, v0, 16, 1
	v_add3_u32 v0, v0, v84, s21
	v_mul_f32_e32 v92, v85, v98
	v_lshrrev_b32_e32 v93, 16, v0
	v_pk_add_f32 v[84:85], v[130:131], v[134:135] op_sel_hi:[1,0] neg_lo:[0,1] neg_hi:[0,1]
	v_mov_b32_e32 v0, v135
	v_pk_mul_f32 v[84:85], v[0:1], v[84:85] op_sel_hi:[0,1]
	v_pk_fma_f32 v[84:85], v[66:67], v[84:85], v[68:69]
	ds_read_b128 v[106:109], v1 offset:4224
	ds_read_b128 v[118:121], v1 offset:4240
	v_mul_f32_e32 v0, 0xbfb8aa3b, v84
	v_exp_f32_e32 v0, v0
	v_mul_f32_e32 v99, 0xbfb8aa3b, v85
	v_exp_f32_e32 v99, v99
	v_bfe_u32 v98, v92, 16, 1
	v_add_f32_e32 v0, 1.0, v0
	s_waitcnt lgkmcnt(1)
	v_pk_add_f32 v[80:81], v[80:81], v[106:107] op_sel_hi:[1,0] neg_lo:[0,1] neg_hi:[0,1]
	v_add3_u32 v92, v92, v98, s21
	v_rcp_f32_e32 v0, v0
	v_add_f32_e32 v98, 1.0, v99
	v_pk_mul_f32 v[80:81], v[106:107], v[80:81] op_sel:[1,0]
	v_rcp_f32_e32 v98, v98
	v_and_or_b32 v92, v92, s19, v93
	v_pk_fma_f32 v[80:81], v[66:67], v[80:81], v[68:69]
	global_store_dword v[90:91], v92, off offset:896
	v_mul_f32_e32 v92, 0xbfb8aa3b, v80
	v_exp_f32_e32 v92, v92
	v_mul_f32_e32 v0, v84, v0
	v_mul_f32_e32 v84, v85, v98
	v_bfe_u32 v85, v0, 16, 1
	v_mul_f32_e32 v93, 0xbfb8aa3b, v81
	v_add3_u32 v0, v0, v85, s21
	v_bfe_u32 v85, v84, 16, 1
	v_exp_f32_e32 v93, v93
	v_add3_u32 v84, v84, v85, s21
	v_add_f32_e32 v85, 1.0, v92
	v_rcp_f32_e32 v85, v85
	v_lshrrev_b32_e32 v0, 16, v0
	v_add_f32_e32 v92, 1.0, v93
	v_rcp_f32_e32 v92, v92
	v_and_or_b32 v0, v84, s19, v0
	global_store_dword v[90:91], v0, off offset:960
	v_mul_f32_e32 v0, v80, v85
	v_bfe_u32 v80, v0, 16, 1
	v_add3_u32 v0, v0, v80, s21
	v_mul_f32_e32 v84, v81, v92
	v_lshrrev_b32_e32 v85, 16, v0
	v_pk_add_f32 v[80:81], v[96:97], v[108:109] op_sel_hi:[1,0] neg_lo:[0,1] neg_hi:[0,1]
	v_mov_b32_e32 v0, v109
	v_pk_mul_f32 v[80:81], v[0:1], v[80:81] op_sel_hi:[0,1]
	v_pk_fma_f32 v[80:81], v[66:67], v[80:81], v[68:69]
	v_bfe_u32 v92, v84, 16, 1
	v_mul_f32_e32 v0, 0xbfb8aa3b, v80
	v_exp_f32_e32 v0, v0
	v_mul_f32_e32 v93, 0xbfb8aa3b, v81
	v_exp_f32_e32 v93, v93
	v_add3_u32 v84, v84, v92, s21
	v_add_f32_e32 v0, 1.0, v0
	v_rcp_f32_e32 v0, v0
	v_add_f32_e32 v92, 1.0, v93
	v_rcp_f32_e32 v92, v92
	v_and_or_b32 v84, v84, s19, v85
	v_mul_f32_e32 v0, v80, v0
	v_bfe_u32 v80, v0, 16, 1
	global_store_dword v[88:89], v84, off offset:2048
	v_mul_f32_e32 v84, v81, v92
	v_add3_u32 v0, v0, v80, s21
	s_waitcnt lgkmcnt(0)
	v_pk_add_f32 v[80:81], v[114:115], v[118:119] op_sel_hi:[1,0] neg_lo:[0,1] neg_hi:[0,1]
	v_bfe_u32 v85, v84, 16, 1
	v_pk_mul_f32 v[80:81], v[118:119], v[80:81] op_sel:[1,0]
	v_add3_u32 v84, v84, v85, s21
	v_pk_fma_f32 v[80:81], v[66:67], v[80:81], v[68:69]
	v_lshrrev_b32_e32 v0, 16, v0
	v_mul_f32_e32 v92, 0xbfb8aa3b, v80
	v_exp_f32_e32 v92, v92
	v_mul_f32_e32 v93, 0xbfb8aa3b, v81
	v_exp_f32_e32 v93, v93
	v_and_or_b32 v0, v84, s19, v0
	v_add_f32_e32 v85, 1.0, v92
	v_rcp_f32_e32 v85, v85
	v_add_f32_e32 v92, 1.0, v93
	v_rcp_f32_e32 v92, v92
	global_store_dword v[88:89], v0, off offset:2112
	v_mul_f32_e32 v0, v80, v85
	v_bfe_u32 v80, v0, 16, 1
	v_add3_u32 v0, v0, v80, s21
	v_mul_f32_e32 v84, v81, v92
	v_lshrrev_b32_e32 v85, 16, v0
	v_pk_add_f32 v[80:81], v[126:127], v[120:121] op_sel_hi:[1,0] neg_lo:[0,1] neg_hi:[0,1]
	v_mov_b32_e32 v0, v121
	v_pk_mul_f32 v[80:81], v[0:1], v[80:81] op_sel_hi:[0,1]
	v_pk_fma_f32 v[80:81], v[66:67], v[80:81], v[68:69]
	ds_read_b128 v[96:99], v1 offset:4256
	ds_read_b128 v[106:109], v1 offset:4272
	v_mul_f32_e32 v0, 0xbfb8aa3b, v80
	v_exp_f32_e32 v0, v0
	v_mul_f32_e32 v93, 0xbfb8aa3b, v81
	v_exp_f32_e32 v93, v93
	v_bfe_u32 v92, v84, 16, 1
	v_add_f32_e32 v0, 1.0, v0
	s_waitcnt lgkmcnt(1)
; __host__ __device__ __forceinline__ size_t tiled_off(int row, int col, int K) { return ((size_t)(row >> 7) * (K >> 6) + (col >> 6)) * 8192 + (lds_byte(row & 127, col & 63) >> 1); }
; __device__ __forceinline__ float fast_sigmoid(float x) { return __builtin_amdgcn_rcpf(1.0f + __builtin_amdgcn_exp2f(x * -1.4426950408889634f)); }
; __device__ __forceinline__ unsigned pk2(float lo, float hi) { return f2bf(lo) | (f2bf(hi) << 16); }
; __device__ __forceinline__ void conv_phase(const Args& a, LAS unsigned char* lds, int vcu, int G, int tid, int wave, int lane) {
;     ...
;         for (int i = 0; i < 32; ++i) { const f32x2 st = stat[i]; f32x2 y = (o[i] - st.x) * st.y * g2 + b2;
;             y.x = y.x * pg8::fast_sigmoid(y.x); y.y = y.y * pg8::fast_sigmoid(y.y);
;             *(unsigned*)(V2 + pg8::tiled_off(t0 + i, c0, D)) = pk2(y.x, y.y); }
	v_pk_add_f32 v[78:79], v[78:79], v[96:97] op_sel_hi:[1,0] neg_lo:[0,1] neg_hi:[0,1]
	v_add3_u32 v84, v84, v92, s21
	v_rcp_f32_e32 v0, v0
	v_add_f32_e32 v92, 1.0, v93
	v_pk_mul_f32 v[78:79], v[96:97], v[78:79] op_sel:[1,0]
	v_rcp_f32_e32 v92, v92
	v_and_or_b32 v84, v84, s19, v85
	v_pk_fma_f32 v[78:79], v[66:67], v[78:79], v[68:69]
	global_store_dword v[88:89], v84, off offset:2176
	v_mul_f32_e32 v84, 0xbfb8aa3b, v78
	v_exp_f32_e32 v84, v84
	v_mul_f32_e32 v0, v80, v0
	v_mul_f32_e32 v80, v81, v92
	v_bfe_u32 v81, v0, 16, 1
	v_mul_f32_e32 v85, 0xbfb8aa3b, v79
	v_add3_u32 v0, v0, v81, s21
	v_bfe_u32 v81, v80, 16, 1
	v_exp_f32_e32 v85, v85
	v_add3_u32 v80, v80, v81, s21
	v_add_f32_e32 v81, 1.0, v84
	v_rcp_f32_e32 v81, v81
	v_lshrrev_b32_e32 v0, 16, v0
	v_add_f32_e32 v84, 1.0, v85
	v_rcp_f32_e32 v84, v84
	v_and_or_b32 v0, v80, s19, v0
	global_store_dword v[88:89], v0, off offset:2240
	v_mul_f32_e32 v0, v78, v81
	v_bfe_u32 v78, v0, 16, 1
	v_add3_u32 v0, v0, v78, s21
	v_mul_f32_e32 v80, v79, v84
	v_lshrrev_b32_e32 v81, 16, v0
	v_pk_add_f32 v[78:79], v[94:95], v[98:99] op_sel_hi:[1,0] neg_lo:[0,1] neg_hi:[0,1]
	v_mov_b32_e32 v0, v99
	v_pk_mul_f32 v[78:79], v[0:1], v[78:79] op_sel_hi:[0,1]
	v_pk_fma_f32 v[78:79], v[66:67], v[78:79], v[68:69]
	v_bfe_u32 v84, v80, 16, 1
	v_mul_f32_e32 v0, 0xbfb8aa3b, v78
	v_exp_f32_e32 v0, v0
	v_mul_f32_e32 v85, 0xbfb8aa3b, v79
	v_exp_f32_e32 v85, v85
	v_add3_u32 v80, v80, v84, s21
	v_add_f32_e32 v0, 1.0, v0
	v_rcp_f32_e32 v0, v0
	v_add_f32_e32 v84, 1.0, v85
	v_rcp_f32_e32 v84, v84
	v_and_or_b32 v80, v80, s19, v81
	v_mul_f32_e32 v0, v78, v0
	v_bfe_u32 v78, v0, 16, 1
	global_store_dword v[88:89], v80, off offset:2304
	v_mul_f32_e32 v80, v79, v84
	v_add3_u32 v0, v0, v78, s21
	s_waitcnt lgkmcnt(0)
	v_pk_add_f32 v[78:79], v[110:111], v[106:107] op_sel_hi:[1,0] neg_lo:[0,1] neg_hi:[0,1]
	v_bfe_u32 v81, v80, 16, 1
	v_pk_mul_f32 v[78:79], v[106:107], v[78:79] op_sel:[1,0]
	v_add3_u32 v80, v80, v81, s21
	v_pk_fma_f32 v[78:79], v[66:67], v[78:79], v[68:69]
	v_lshrrev_b32_e32 v0, 16, v0
	v_mul_f32_e32 v84, 0xbfb8aa3b, v78
	v_exp_f32_e32 v84, v84
	v_mul_f32_e32 v85, 0xbfb8aa3b, v79
	v_exp_f32_e32 v85, v85
	v_and_or_b32 v0, v80, s19, v0
	v_add_f32_e32 v81, 1.0, v84
	v_rcp_f32_e32 v81, v81
	v_add_f32_e32 v84, 1.0, v85
	v_rcp_f32_e32 v84, v84
	global_store_dword v[88:89], v0, off offset:2368
	v_mul_f32_e32 v0, v78, v81
	v_bfe_u32 v78, v0, 16, 1
	v_add3_u32 v0, v0, v78, s21
	v_mul_f32_e32 v80, v79, v84
	v_lshrrev_b32_e32 v81, 16, v0
	v_pk_add_f32 v[78:79], v[122:123], v[108:109] op_sel_hi:[1,0] neg_lo:[0,1] neg_hi:[0,1]
	v_mov_b32_e32 v0, v109
	v_pk_mul_f32 v[78:79], v[0:1], v[78:79] op_sel_hi:[0,1]
	v_pk_fma_f32 v[78:79], v[66:67], v[78:79], v[68:69]
	v_bfe_u32 v84, v80, 16, 1
	v_mul_f32_e32 v0, 0xbfb8aa3b, v78
	v_mul_f32_e32 v85, 0xbfb8aa3b, v79
	v_exp_f32_e32 v0, v0
	v_exp_f32_e32 v85, v85
	v_add3_u32 v80, v80, v84, s21
	v_and_or_b32 v80, v80, s19, v81
	v_add_f32_e32 v0, 1.0, v0
	v_add_f32_e32 v84, 1.0, v85
	v_rcp_f32_e32 v0, v0
	v_rcp_f32_e32 v84, v84
	global_store_dword v[88:89], v80, off offset:2432
	ds_read_b128 v[92:95], v1 offset:4304
	v_mul_f32_e32 v0, v78, v0
	v_mul_f32_e32 v84, v79, v84
	ds_read_b128 v[78:81], v1 offset:4288
	v_bfe_u32 v85, v0, 16, 1
	v_add3_u32 v0, v0, v85, s21
	v_bfe_u32 v85, v84, 16, 1
	v_lshrrev_b32_e32 v0, 16, v0
	s_waitcnt lgkmcnt(0)
; __host__ __device__ __forceinline__ size_t tiled_off(int row, int col, int K) { return ((size_t)(row >> 7) * (K >> 6) + (col >> 6)) * 8192 + (lds_byte(row & 127, col & 63) >> 1); }
; __device__ __forceinline__ float fast_sigmoid(float x) { return __builtin_amdgcn_rcpf(1.0f + __builtin_amdgcn_exp2f(x * -1.4426950408889634f)); }
; __device__ __forceinline__ unsigned pk2(float lo, float hi) { return f2bf(lo) | (f2bf(hi) << 16); }
; __device__ __forceinline__ void conv_phase(const Args& a, LAS unsigned char* lds, int vcu, int G, int tid, int wave, int lane) {
;     ...
;         for (int i = 0; i < 32; ++i) { const f32x2 st = stat[i]; f32x2 y = (o[i] - st.x) * st.y * g2 + b2;
;             y.x = y.x * pg8::fast_sigmoid(y.x); y.y = y.y * pg8::fast_sigmoid(y.y);
;             *(unsigned*)(V2 + pg8::tiled_off(t0 + i, c0, D)) = pk2(y.x, y.y); }
;         __syncthreads();
	v_pk_add_f32 v[76:77], v[76:77], v[78:79] op_sel_hi:[1,0] neg_lo:[0,1] neg_hi:[0,1]
	v_add3_u32 v84, v84, v85, s21
	v_pk_mul_f32 v[76:77], v[78:79], v[76:77] op_sel:[1,0]
	v_and_or_b32 v0, v84, s19, v0
	v_pk_fma_f32 v[76:77], v[66:67], v[76:77], v[68:69]
	global_store_dword v[88:89], v0, off offset:2496
	v_mul_f32_e32 v78, 0xbfb8aa3b, v76
	v_exp_f32_e32 v78, v78
	v_mul_f32_e32 v79, 0xbfb8aa3b, v77
	v_exp_f32_e32 v79, v79
	v_readlane_b32 s17, v255, 5
	v_add_f32_e32 v78, 1.0, v78
	v_rcp_f32_e32 v78, v78
	v_add_f32_e32 v79, 1.0, v79
	v_rcp_f32_e32 v79, v79
	v_mul_f32_e32 v0, v76, v78
	v_bfe_u32 v76, v0, 16, 1
	v_add3_u32 v0, v0, v76, s21
	v_mul_f32_e32 v78, v77, v79
	v_lshrrev_b32_e32 v79, 16, v0
	v_pk_add_f32 v[76:77], v[86:87], v[80:81] op_sel_hi:[1,0] neg_lo:[0,1] neg_hi:[0,1]
	v_mov_b32_e32 v0, v81
	v_pk_mul_f32 v[76:77], v[0:1], v[76:77] op_sel_hi:[0,1]
	v_pk_fma_f32 v[76:77], v[66:67], v[76:77], v[68:69]
	v_bfe_u32 v84, v78, 16, 1
	v_mul_f32_e32 v0, 0xbfb8aa3b, v76
	v_exp_f32_e32 v0, v0
	v_mul_f32_e32 v80, 0xbfb8aa3b, v77
	v_exp_f32_e32 v80, v80
	v_add3_u32 v78, v78, v84, s21
	v_add_f32_e32 v0, 1.0, v0
	v_rcp_f32_e32 v0, v0
	v_add_f32_e32 v80, 1.0, v80
	v_rcp_f32_e32 v80, v80
	v_and_or_b32 v78, v78, s19, v79
	v_mul_f32_e32 v0, v76, v0
	v_bfe_u32 v76, v0, 16, 1
	global_store_dword v[90:91], v78, off offset:2560
	v_mul_f32_e32 v78, v77, v80
	v_add3_u32 v0, v0, v76, s21
	v_pk_add_f32 v[76:77], v[104:105], v[92:93] op_sel_hi:[1,0] neg_lo:[0,1] neg_hi:[0,1]
	v_bfe_u32 v79, v78, 16, 1
	v_pk_mul_f32 v[76:77], v[92:93], v[76:77] op_sel:[1,0]
	v_add3_u32 v78, v78, v79, s21
	v_pk_fma_f32 v[76:77], v[66:67], v[76:77], v[68:69]
	v_lshrrev_b32_e32 v0, 16, v0
	v_mul_f32_e32 v80, 0xbfb8aa3b, v76
	v_exp_f32_e32 v80, v80
	v_mul_f32_e32 v81, 0xbfb8aa3b, v77
	v_exp_f32_e32 v81, v81
	v_and_or_b32 v0, v78, s19, v0
	v_add_f32_e32 v79, 1.0, v80
	v_rcp_f32_e32 v79, v79
	v_add_f32_e32 v80, 1.0, v81
	v_rcp_f32_e32 v80, v80
	global_store_dword v[90:91], v0, off offset:2624
	v_mul_f32_e32 v0, v76, v79
	v_bfe_u32 v76, v0, 16, 1
	v_add3_u32 v0, v0, v76, s21
	v_mul_f32_e32 v78, v77, v80
	v_lshrrev_b32_e32 v79, 16, v0
	v_pk_add_f32 v[76:77], v[116:117], v[94:95] op_sel_hi:[1,0] neg_lo:[0,1] neg_hi:[0,1]
	v_mov_b32_e32 v0, v95
	v_pk_mul_f32 v[76:77], v[0:1], v[76:77] op_sel_hi:[0,1]
	v_pk_fma_f32 v[76:77], v[66:67], v[76:77], v[68:69]
	v_bfe_u32 v80, v78, 16, 1
	v_mul_f32_e32 v0, 0xbfb8aa3b, v76
	v_mul_f32_e32 v81, 0xbfb8aa3b, v77
	v_exp_f32_e32 v0, v0
	v_exp_f32_e32 v81, v81
	v_add3_u32 v78, v78, v80, s21
	v_and_or_b32 v78, v78, s19, v79
	v_add_f32_e32 v0, 1.0, v0
	v_add_f32_e32 v80, 1.0, v81
	v_rcp_f32_e32 v0, v0
	v_rcp_f32_e32 v80, v80
	global_store_dword v[90:91], v78, off offset:2688
	ds_read_b128 v[84:87], v1 offset:4336
	v_mul_f32_e32 v0, v76, v0
	v_mul_f32_e32 v80, v77, v80
	ds_read_b128 v[76:79], v1 offset:4320
	v_bfe_u32 v81, v0, 16, 1
	v_add3_u32 v0, v0, v81, s21
	v_bfe_u32 v81, v80, 16, 1
	v_lshrrev_b32_e32 v0, 16, v0
	s_waitcnt lgkmcnt(0)
	v_pk_add_f32 v[74:75], v[74:75], v[76:77] op_sel_hi:[1,0] neg_lo:[0,1] neg_hi:[0,1]
	v_add3_u32 v80, v80, v81, s21
	v_pk_mul_f32 v[74:75], v[76:77], v[74:75] op_sel:[1,0]
	v_and_or_b32 v0, v80, s19, v0
	v_pk_fma_f32 v[74:75], v[66:67], v[74:75], v[68:69]
	global_store_dword v[90:91], v0, off offset:2752
	v_mul_f32_e32 v76, 0xbfb8aa3b, v74
	v_exp_f32_e32 v76, v76
	v_mul_f32_e32 v77, 0xbfb8aa3b, v75
	v_exp_f32_e32 v77, v77
	v_add_f32_e32 v76, 1.0, v76
	v_rcp_f32_e32 v76, v76
	v_add_f32_e32 v77, 1.0, v77
	v_rcp_f32_e32 v77, v77
	v_mul_f32_e32 v0, v74, v76
	v_bfe_u32 v74, v0, 16, 1
	v_add3_u32 v0, v0, v74, s21
	v_mul_f32_e32 v76, v75, v77
	v_lshrrev_b32_e32 v77, 16, v0
	v_pk_add_f32 v[74:75], v[82:83], v[78:79] op_sel_hi:[1,0] neg_lo:[0,1] neg_hi:[0,1]
	v_mov_b32_e32 v0, v79
	v_pk_mul_f32 v[74:75], v[0:1], v[74:75] op_sel_hi:[0,1]
	v_pk_fma_f32 v[74:75], v[66:67], v[74:75], v[68:69]
	v_bfe_u32 v80, v76, 16, 1
	v_mul_f32_e32 v0, 0xbfb8aa3b, v74
	v_exp_f32_e32 v0, v0
	v_mul_f32_e32 v78, 0xbfb8aa3b, v75
	v_exp_f32_e32 v78, v78
	v_add3_u32 v76, v76, v80, s21
	v_add_f32_e32 v0, 1.0, v0
	v_rcp_f32_e32 v0, v0
	v_add_f32_e32 v78, 1.0, v78
	v_rcp_f32_e32 v78, v78
	v_and_or_b32 v76, v76, s19, v77
	v_mul_f32_e32 v0, v74, v0
	v_bfe_u32 v74, v0, 16, 1
	global_store_dword v[90:91], v76, off offset:2816
	v_mul_f32_e32 v76, v75, v78
	v_add3_u32 v0, v0, v74, s21
	v_pk_add_f32 v[74:75], v[100:101], v[84:85] op_sel_hi:[1,0] neg_lo:[0,1] neg_hi:[0,1]
	v_bfe_u32 v77, v76, 16, 1
	v_pk_mul_f32 v[74:75], v[84:85], v[74:75] op_sel:[1,0]
	v_add3_u32 v76, v76, v77, s21
	v_pk_fma_f32 v[74:75], v[66:67], v[74:75], v[68:69]
	v_lshrrev_b32_e32 v0, 16, v0
	v_mul_f32_e32 v78, 0xbfb8aa3b, v74
	v_exp_f32_e32 v78, v78
	v_mul_f32_e32 v79, 0xbfb8aa3b, v75
	v_exp_f32_e32 v79, v79
	v_and_or_b32 v0, v76, s19, v0
	v_add_f32_e32 v77, 1.0, v78
	v_rcp_f32_e32 v77, v77
	v_add_f32_e32 v78, 1.0, v79
	v_rcp_f32_e32 v78, v78
	global_store_dword v[90:91], v0, off offset:2880
	v_mul_f32_e32 v0, v74, v77
	v_bfe_u32 v74, v0, 16, 1
	v_add3_u32 v0, v0, v74, s21
	v_mul_f32_e32 v76, v75, v78
	v_lshrrev_b32_e32 v77, 16, v0
	v_pk_add_f32 v[74:75], v[112:113], v[86:87] op_sel_hi:[1,0] neg_lo:[0,1] neg_hi:[0,1]
	v_mov_b32_e32 v0, v87
	v_pk_mul_f32 v[74:75], v[0:1], v[74:75] op_sel_hi:[0,1]
	v_pk_fma_f32 v[74:75], v[66:67], v[74:75], v[68:69]
	v_bfe_u32 v78, v76, 16, 1
	v_mul_f32_e32 v0, 0xbfb8aa3b, v74
	v_exp_f32_e32 v0, v0
	v_mul_f32_e32 v79, 0xbfb8aa3b, v75
	v_exp_f32_e32 v79, v79
	v_add3_u32 v76, v76, v78, s21
	v_add_f32_e32 v0, 1.0, v0
	v_rcp_f32_e32 v0, v0
	v_add_f32_e32 v78, 1.0, v79
	v_rcp_f32_e32 v78, v78
	v_and_or_b32 v76, v76, s19, v77
	v_mul_f32_e32 v0, v74, v0
	global_store_dword v[90:91], v76, off offset:2944
	v_mul_f32_e32 v74, v75, v78
	v_bfe_u32 v75, v0, 16, 1
	v_add3_u32 v0, v0, v75, s21
	v_bfe_u32 v75, v74, 16, 1
	v_lshrrev_b32_e32 v0, 16, v0
	v_add3_u32 v74, v74, v75, s21
	v_and_or_b32 v0, v74, s19, v0
	global_store_dword v[90:91], v0, off offset:3008
	s_barrier
	s_cbranch_scc0 .LBB0_619

; __device__ __forceinline__ unsigned xb_ld(unsigned* p)              { return __hip_atomic_load(p, __ATOMIC_RELAXED, __HIP_MEMORY_SCOPE_AGENT); }
; __device__ __forceinline__ void xcd_barrier_complete(unsigned* bar, unsigned x, unsigned& nloc, unsigned& nx) {
;     const unsigned G = gridDim.x * gridDim.y * gridDim.z;
;     unsigned sum, cnt, mine, sp = 0u;
;     for (;;) {
;         sum = 0u; cnt = 0u; mine = 0u;
; #pragma unroll
;         for (unsigned j = 0; j < 16; ++j) { const unsigned c = xb_ld(&bar[XB_XCNT(j)]); sum += c; cnt += (c > 0u) ? 1u : 0u; mine = (j == x) ? c : mine; }
; __device__ __forceinline__ void xcd_barrier(const XcdBarrier& b) {
;     asm volatile("s_waitcnt vmcnt(0)" ::: "memory");
;     __syncthreads();
;     if (threadIdx.x == 0) {
;         unsigned* bar = b.bar;
;         __builtin_amdgcn_s_waitcnt(0);
;         unsigned nloc = b.st[0], nx = b.st[1];
;         if (nloc == 0u) { xcd_barrier_complete(bar, b.x, nloc, nx); b.st[0] = nloc; b.st[1] = nx; }
.LBB0_619:
	s_cmp_gt_i32 s37, 3
	s_cselect_b64 s[2:3], -1, 0
	s_and_b64 s[0:1], s[0:1], s[2:3]
	s_andn2_b64 vcc, exec, s[0:1]
	s_cbranch_vccnz .LBB0_673
	s_waitcnt vmcnt(0)
	s_waitcnt lgkmcnt(0)
	s_barrier
	s_mov_b64 s[0:1], exec
	v_readlane_b32 s4, v255, 9
	v_readlane_b32 s5, v255, 10
	s_and_b64 s[4:5], s[0:1], s[4:5]
	s_mov_b64 exec, s[4:5]
	s_cbranch_execz .LBB0_672
	s_add_i32 s4, 0, 0x20040
	v_mov_b32_e32 v0, s4
	s_waitcnt vmcnt(0) expcnt(0) lgkmcnt(0)
	ds_read_b32 v2, v0
	s_add_i32 s4, 0, 0x20044
	v_mov_b32_e32 v0, s4
	ds_read_b32 v0, v0
	s_waitcnt lgkmcnt(1)
	v_cmp_ne_u32_e32 vcc, 0, v2
	s_cbranch_vccnz .LBB0_636
	v_readlane_b32 s4, v255, 4
	v_readlane_b32 s5, v255, 5
	v_readlane_b32 s6, v255, 7
	s_mul_i32 s18, s5, s6
	s_mul_i32 s18, s18, s4
	s_add_u32 s4, s28, 0x1000
	s_addc_u32 s5, s29, 0
	s_add_u32 s6, s28, 0x1100
	s_addc_u32 s7, s29, 0
	s_add_u32 s8, s28, 0x1200
	s_addc_u32 s9, s29, 0
	s_add_u32 s10, s28, 0x1300
	s_addc_u32 s11, s29, 0
	s_mov_b32 s19, 1
	v_mov_b32_e32 v16, 0
	s_branch .LBB0_624

; #define PG8_STAGE(bufoff, gbase, voff) do { _Pragma("unroll") for (int _i = 0; _i < 2; ++_i) \
;         __builtin_amdgcn_global_load_lds((const unsigned*)((const char*)(gbase) + (voff)[_i]), (PG8_LAS unsigned*)(lds + (bufoff) + ldsw + _i * 8192), 16, 0, 0); } while (0)
; #define PG8_WAIT_V(n) asm volatile("s_waitcnt vmcnt(" #n ")" ::: "memory")
; #define PG8_BAR __builtin_amdgcn_s_barrier()
; template <class Epi, class Sched, bool ALIGN_EPI = false, bool SP2 = false, bool TA = true>
; __device__ __forceinline__ void gemm_phase(PG8_LAS unsigned char* lds, const Gemm g, const Sched& S, const Epi& E) {
;     const int tid = threadIdx.x, wid = __builtin_amdgcn_readfirstlane(tid >> 6), lane = tid & 63, wr = wid >> 2, wc = wid & 3, fr = lane & 15, fq = lane >> 4;
;     const int K = g.K, nt = K / BK;
;     unsigned voffA[2], voffB[2];
; #pragma unroll
;     for (int i = 0; i < 2; ++i) { int R, C; stage_rc(tid * 16 + i * 8192, R, C); const int Rb = Epi::PERM ? ((R & ~31) + perm32(R & 31)) : R;
;         voffA[i] = TA ? (unsigned)(tid * 16 + i * 8192) : (unsigned)(R * K + C) * 2u; voffB[i] = (unsigned)(tid * 16 + i * 8192); (void)Rb; }
;     const size_t kstep = TA ? (size_t)HTB : (size_t)(BK * 2);
;     const size_t kstepB = (size_t)HTB;
;     const size_t hstep = (size_t)HALF * K * 2;
;     const size_t tstep = 2 * hstep;
;     const unsigned ldsw = (unsigned)wid * 1024u;
;     const int aoff = lds_byte(wr * 64 + fr, fq * 8), boff = lds_byte(wc * 32 + fr, fq * 8);
;     ...
;         PG8_STAGE(PG8_SB(0, 0), cB, voffB); PG8_STAGE(PG8_SA(0, 0), cA, voffA); PG8_STAGE(PG8_SB(0, 1), cB + hstep, voffB); PG8_STAGE(PG8_SA(0, 1), cA + hstep, voffA);
;         if (wr == 1) PG8_BAR;
;         PG8_WAIT_V(4); PG8_BAR;
;         PG8_STAGE(PG8_SB(1, 0), cB + kstepB, voffB); PG8_STAGE(PG8_SA(1, 0), cA + kstep, voffA); PG8_STAGE(PG8_SB(1, 1), cB + hstep + kstepB, voffB);
;         PG8_WAIT_V(6); PG8_BAR;
;     }
; __global__ void __launch_bounds__(NWAVES * 64, 2) mega_fwd(Args args) {
;     ...
;     if (IN(3)) {
;         typedef pg8::EpiRes<0, true, false> EP; EP E{args.in[I_X], nullptr, nullptr, HBA, SSA, args.in[I_CB2], nullptr, nullptr};
;         RUN_GEMM(EP, ws + WS_V2, WS_WPW2, D, D, E);
.LBB0_680:
	s_andn2_b64 vcc, exec, s[0:1]
	s_cbranch_vccnz .LBB0_724
	s_add_u32 s18, s28, 0x12000000
	s_addc_u32 s19, s29, 0
	s_add_u32 s21, s28, 0xc00000
	s_addc_u32 s22, s29, 0
	s_lshr_b32 s2, s4, 6
	s_ashr_i32 s91, s90, 31
	s_ashr_i32 s17, s16, 31
	s_lshr_b32 s5, s4, 8
	s_lshl_b32 s23, s2, 10
	s_lshl_b64 s[0:1], s[90:91], 19
	s_lshl_b64 s[8:9], s[16:17], 19
	s_add_u32 s76, s21, s8
	v_mov_b32_e32 v163, 0
	v_lshlrev_b32_e32 v160, 4, v208
	s_addc_u32 s77, s22, s9
	s_add_i32 s30, s23, 0
	v_mov_b32_e32 v161, v163
	s_add_i32 m0, s30, 0x10000
	v_lshl_add_u64 v[0:1], s[76:77], 0, v[160:161]
	s_mov_b64 s[8:9], 0x2000
	global_load_lds_dwordx4 v160, s[76:77]
	v_lshl_add_u64 v[2:3], v[0:1], 0, s[8:9]
	s_add_i32 m0, s30, 0x12000
	s_mov_b64 s[10:11], 0x40000
	global_load_lds_dwordx4 v[2:3], off
	s_add_i32 m0, s30, 0x14000
	v_lshl_add_u64 v[2:3], v[0:1], 0, s[10:11]
	global_load_lds_dwordx4 v[2:3], off
	s_add_i32 m0, s30, 0x16000
	s_mov_b64 s[12:13], 0x42000
	s_add_u32 s0, s18, s0
	v_lshl_add_u64 v[2:3], v[0:1], 0, s[12:13]
	s_addc_u32 s1, s19, s1
	global_load_lds_dwordx4 v[2:3], off
	v_lshl_add_u64 v[2:3], s[0:1], 0, v[160:161]
	s_mov_b32 m0, s30
	s_add_i32 s31, s30, 0x2000
	global_load_lds_dwordx4 v160, s[0:1]
	v_lshl_add_u64 v[4:5], v[2:3], 0, s[8:9]
	s_mov_b32 m0, s31
	s_add_i32 s33, s30, 0x4000
	global_load_lds_dwordx4 v[4:5], off
	v_lshl_add_u64 v[4:5], v[2:3], 0, s[10:11]
	s_mov_b32 m0, s33
	s_add_i32 s36, s30, 0x6000
	global_load_lds_dwordx4 v[4:5], off
	v_lshl_add_u64 v[4:5], v[2:3], 0, s[12:13]
	s_mov_b32 m0, s36
	v_writelane_b32 v254, s6, 1
	global_load_lds_dwordx4 v[4:5], off
	s_cmp_eq_u32 s5, 1
	v_writelane_b32 v254, s7, 2
	s_cselect_b64 s[6:7], -1, 0
	v_writelane_b32 v254, s6, 6
	s_cmp_lg_u32 s5, 1
	s_mov_b32 s17, 0
	v_writelane_b32 v254, s7, 7
	s_cbranch_scc1 .LBB0_683
	s_barrier
.LBB0_683:
	s_mov_b64 s[44:45], 0x4000
	s_add_i32 m0, s30, 0x18000
	v_lshl_add_u64 v[4:5], v[0:1], 0, s[44:45]
	s_mov_b64 s[46:47], 0x6000
	s_waitcnt vmcnt(2)
	s_barrier
	global_load_lds_dwordx4 v[4:5], off
	v_lshl_add_u64 v[4:5], v[0:1], 0, s[46:47]
	s_add_i32 m0, s30, 0x1a000
	s_add_i32 s37, s30, 0x8000
	global_load_lds_dwordx4 v[4:5], off
	v_lshl_add_u64 v[4:5], v[2:3], 0, s[44:45]
	s_mov_b32 m0, s37
	s_add_i32 s38, s30, 0xa000
	global_load_lds_dwordx4 v[4:5], off
	v_lshl_add_u64 v[2:3], v[2:3], 0, s[46:47]
	s_mov_b32 m0, s38
	s_mov_b64 s[48:49], 0x44000
	global_load_lds_dwordx4 v[2:3], off
	s_add_i32 m0, s30, 0x1c000
	v_lshl_add_u64 v[2:3], v[0:1], 0, s[48:49]
	s_mov_b64 s[50:51], 0x46000
	global_load_lds_dwordx4 v[2:3], off
	v_lshl_add_u64 v[0:1], v[0:1], 0, s[50:51]
	s_add_i32 m0, s30, 0x1e000
	v_and_b32_e32 v176, 15, v208
	global_load_lds_dwordx4 v[0:1], off
	v_and_b32_e32 v1, 48, v208
	v_lshlrev_b32_e32 v3, 2, v208
	s_and_b32 s39, s2, 3
	s_lshl_b32 s2, s5, 13
	v_lshl_or_b32 v2, v176, 6, v1
	v_and_b32_e32 v3, 32, v3
	s_lshl_b32 s40, s5, 6
	v_bitop3_b32 v2, v2, s2, v3 bitop3:0xde
	s_lshl_b32 s41, s39, 5
	s_lshl_b32 s2, s39, 12
	s_cmpk_lt_u32 s4, 0x100
	s_cselect_b64 s[6:7], -1, 0
	s_lshl_b32 s4, s5, 3
	s_and_b32 s43, s4, 8
	v_readlane_b32 s4, v255, 4
	v_readlane_b32 s56, v255, 27
	v_lshlrev_b32_e32 v4, 6, v208
	s_movk_i32 s42, 0x3c0
	s_ashr_i32 s84, s4, 31
	s_ashr_i32 s86, s20, 31
	v_readlane_b32 s60, v255, 31
	v_readlane_b32 s61, v255, 32
	v_bfe_u32 v0, v208, 4, 2
	v_and_or_b32 v1, v4, s42, v1
	s_waitcnt vmcnt(6)
	s_cmp_lg_u64 s[60:61], 0
	v_lshlrev_b32_e32 v177, 3, v0
	v_bitop3_b32 v178, s2, v1, v3 bitop3:0xf6
	v_cmp_eq_u32_e64 s[2:3], 0, v0
	s_cselect_b64 s[14:15], -1, 0
	s_add_i32 s87, 0, 0x10000
	s_add_i32 s88, 0, 0x14000
	v_mbcnt_lo_u32_b32 v0, -1, 0
	s_mov_b32 s85, s4
	v_mov_b64_e32 v[164:165], 0x200
	v_mov_b64_e32 v[166:167], 0x1ff
	v_add_u32_e32 v179, s87, v178
	v_add_u32_e32 v180, s88, v178
	v_add_u32_e32 v181, 0, v2
	v_mbcnt_hi_u32_b32 v182, -1, v0
	s_mov_b32 s89, 0
	s_barrier
	v_readlane_b32 s5, v255, 5
	v_readlane_b32 s57, v255, 28
	v_readlane_b32 s58, v255, 29
	v_readlane_b32 s59, v255, 30
	v_readlane_b32 s62, v255, 33
	v_readlane_b32 s63, v255, 34
	v_readlane_b32 s64, v255, 35
	v_readlane_b32 s65, v255, 36
	v_readlane_b32 s66, v255, 37
	v_readlane_b32 s67, v255, 38
	v_readlane_b32 s68, v255, 39
	v_readlane_b32 s69, v255, 40
	v_readlane_b32 s70, v255, 41
	v_readlane_b32 s71, v255, 42
	s_branch .LBB0_686

;     __device__ __forceinline__ void operator()(const f32x4 (&acc)[2][2][4][2], const Unit& u, int wr, int wc, int fr, int fq, const PG8_LAS float* rtab) const {
;         const int row0 = u.pm * BM + wr * 64 + fr, col0 = u.pn * BM + wc * 32 + 8 * fq;
;         f32x4 bv[2][2];
; #pragma unroll
;         for (int bj = 0; bj < 2; ++bj)
; #pragma unroll
;             for (int n = 0; n < 2; ++n) bv[bj][n] = (MODE == 0 && bias) ? *(const f32x4*)(bias + col0 + bj * HALF + 4 * n) : (f32x4){0.f, 0.f, 0.f, 0.f};
.LBB0_696:
	s_lshl_b32 s0, s16, 8
	s_or_b32 s59, s0, s41
	v_or_b32_e32 v168, s59, v177
	v_readlane_b32 s60, v255, 27
	v_ashrrev_i32_e32 v169, 31, v168
	v_readlane_b32 s64, v255, 31
	v_readlane_b32 s65, v255, 32
	v_cndmask_b32_e64 v80, 0, 1, s[14:15]
	v_mov_b32_e32 v84, 0
	v_lshl_add_u64 v[144:145], v[168:169], 2, s[64:65]
	v_cmp_ne_u32_e64 s[0:1], 1, v80
	s_andn2_b64 vcc, exec, s[14:15]
	v_mov_b32_e32 v92, 0
	v_mov_b32_e32 v93, 0
	v_mov_b32_e32 v94, 0
	v_mov_b32_e32 v95, 0
	v_readlane_b32 s61, v255, 28
	v_readlane_b32 s62, v255, 29
	v_readlane_b32 s63, v255, 30
	v_readlane_b32 s66, v255, 33
	v_readlane_b32 s67, v255, 34
	v_readlane_b32 s68, v255, 35
	v_readlane_b32 s69, v255, 36
	v_readlane_b32 s70, v255, 37
	v_readlane_b32 s71, v255, 38
	v_readlane_b32 s72, v255, 39
	v_readlane_b32 s73, v255, 40
	v_readlane_b32 s74, v255, 41
	v_readlane_b32 s75, v255, 42
	s_cbranch_vccnz .LBB0_698
	global_load_dwordx4 v[92:95], v[144:145], off

;     __device__ __forceinline__ void operator()(const f32x4 (&acc)[2][2][4][2], const Unit& u, int wr, int wc, int fr, int fq, const PG8_LAS float* rtab) const {
;     ...
;         Grp cur, nxt; load_grp(cur, row0, col0);
; #pragma unroll
;         for (int gi = 0; gi < 8; ++gi) { const int ai = gi >> 2, m = gi & 3; const int row = row0 + ai * HALF + m * 16; float ssq = 0.f;
;             if (gi < 7) load_grp(nxt, row0 + ((gi + 1) >> 2) * HALF + ((gi + 1) & 3) * 16, col0);
;             float rsr = 0.f;
;             if (MODE == 1) rsr = rtab[ai * HALF + wr * 64 + m * 16 + fr];
; #pragma unroll
;             for (int bj = 0; bj < 2; ++bj) { const size_t off = (size_t)row * 1024 + col0 + bj * HALF;
;                 f32x4 v0, v1;
;                 if (BASEF32) { v0 = cur.b[bj][0]; v1 = cur.b[bj][1]; }
;                 else { const u32x4 hw = cur.h[bj];
;                     v0 = (f32x4){__uint_as_float(hw.x << 16), __uint_as_float(hw.x & 0xffff0000u), __uint_as_float(hw.y << 16), __uint_as_float(hw.y & 0xffff0000u)};
;                     v1 = (f32x4){__uint_as_float(hw.z << 16), __uint_as_float(hw.z & 0xffff0000u), __uint_as_float(hw.w << 16), __uint_as_float(hw.w & 0xffff0000u)}; }
;                 if (MODE == 0) { v0 += acc[ai][bj][m][0] + bv[bj][0]; v1 += acc[ai][bj][m][1] + bv[bj][1]; }
;                 else { const u32x4 pw = cur.p[bj]; const f32x4 a0 = acc[ai][bj][m][0] * rsr, a1 = acc[ai][bj][m][1] * rsr;
;                     v0[0] += fast_sigmoid(a0[0]) * __uint_as_float(pw.x << 16); v0[1] += fast_sigmoid(a0[1]) * __uint_as_float(pw.x & 0xffff0000u);
;                     v0[2] += fast_sigmoid(a0[2]) * __uint_as_float(pw.y << 16); v0[3] += fast_sigmoid(a0[3]) * __uint_as_float(pw.y & 0xffff0000u);
;                     v1[0] += fast_sigmoid(a1[0]) * __uint_as_float(pw.z << 16); v1[1] += fast_sigmoid(a1[1]) * __uint_as_float(pw.z & 0xffff0000u);
;                     v1[2] += fast_sigmoid(a1[2]) * __uint_as_float(pw.w << 16); v1[3] += fast_sigmoid(a1[3]) * __uint_as_float(pw.w & 0xffff0000u); }
;                 if (OUTF32) { *(f32x4*)(out + off) = v0; *(f32x4*)(out + off + 4) = v1; }
;                 else { u32x4 w; w.x = cvt_pk_bf16(v0[0], v0[1]); w.y = cvt_pk_bf16(v0[2], v0[3]); w.z = cvt_pk_bf16(v1[0], v1[1]); w.w = cvt_pk_bf16(v1[2], v1[3]);
;                     *(u32x4*)(hb + tiled_off(row, col0 + bj * HALF, 1024)) = w;
.LBB0_704:
	s_lshl_b32 s0, s90, 8
	s_add_i32 s61, s0, s40
	v_or_b32_e32 v170, s61, v176
	v_ashrrev_i32_e32 v171, 31, v170
	v_readlane_b32 s64, v255, 11
	v_lshlrev_b64 v[144:145], 12, v[170:171]
	v_readlane_b32 s65, v255, 12
	v_lshlrev_b64 v[146:147], 2, v[168:169]
	v_or_b32_e32 v174, 16, v170
	v_lshl_add_u64 v[144:145], s[64:65], 0, v[144:145]
	v_lshl_add_u64 v[144:145], v[144:145], 0, v[146:147]
	global_load_dwordx4 v[152:155], v[144:145], off
	global_load_dwordx4 v[156:159], v[144:145], off offset:16
	global_load_dwordx4 v[188:191], v[144:145], off offset:512
	global_load_dwordx4 v[192:195], v[144:145], off offset:528
	v_ashrrev_i32_e32 v175, 31, v174
	s_waitcnt vmcnt(0)
	v_pk_add_f32 v[198:199], v[132:133], v[88:89]
	v_lshlrev_b64 v[132:133], 12, v[174:175]
	v_lshl_add_u64 v[132:133], s[64:65], 0, v[132:133]
	v_pk_add_f32 v[184:185], v[136:137], v[84:85]
	v_lshl_add_u64 v[136:137], v[132:133], 0, v[146:147]
	v_pk_add_f32 v[172:173], v[138:139], v[86:87]
	v_pk_add_f32 v[196:197], v[134:135], v[90:91]
	global_load_dwordx4 v[144:147], v[136:137], off offset:16
	global_load_dwordx4 v[148:151], v[136:137], off
	global_load_dwordx4 v[132:135], v[136:137], off offset:528
	s_nop 0
	global_load_dwordx4 v[136:139], v[136:137], off offset:512
	v_readlane_b32 s76, v255, 23
	v_readlane_b32 s74, v255, 21
	v_readlane_b32 s77, v255, 24
	s_ashr_i32 s76, s61, 7
	v_readlane_b32 s75, v255, 22
	s_lshl_b32 s0, s16, 2
	s_ashr_i32 s74, s59, 6
	s_ashr_i32 s77, s76, 31
	s_ashr_i32 s1, s0, 31
	s_ashr_i32 s75, s74, 31
	s_lshl_b64 s[76:77], s[76:77], 18
	v_bfe_u32 v183, v168, 5, 1
	v_lshlrev_b32_e32 v162, 1, v168
	v_pk_add_f32 v[142:143], v[142:143], v[94:95]
	v_pk_add_f32 v[140:141], v[140:141], v[92:93]
	s_add_u32 s16, s34, s76
	v_readlane_b32 s78, v255, 25
	v_pk_add_f32 v[128:129], v[128:129], v[80:81]
	v_and_b32_e32 v186, 48, v162
	v_or_b32_e32 v162, s43, v183
	v_lshlrev_b32_e32 v201, 6, v170
	v_lshlrev_b32_e32 v202, 2, v170
	s_addc_u32 s59, s35, s77
	s_lshl_b64 s[76:77], s[74:75], 14
	v_readlane_b32 s79, v255, 26
	v_pk_add_f32 v[130:131], v[130:131], v[82:83]
	v_lshlrev_b32_e32 v162, 10, v162
	v_and_or_b32 v201, v201, s42, v186
	v_and_b32_e32 v202, 32, v202
	s_add_u32 s78, s16, s76
	v_and_b32_e32 v200, 64, v182
	v_bitop3_b32 v201, v201, v162, v202 bitop3:0xde
	s_addc_u32 s79, s59, s77
	v_xor_b32_e32 v187, 16, v182
	v_add_u32_e32 v200, 64, v200
	v_cmp_lt_i32_e32 vcc, v187, v200
	s_or_b32 s74, s74, 2
	s_ashr_i32 s75, s74, 31
	v_cndmask_b32_e32 v187, v182, v187, vcc
	s_lshl_b64 s[74:75], s[74:75], 14
	s_add_u32 s80, s16, s74
	s_addc_u32 s81, s59, s75
	v_readlane_b32 s66, v255, 13
	v_readlane_b32 s67, v255, 14
	v_readlane_b32 s68, v255, 15
	v_readlane_b32 s69, v255, 16
	v_readlane_b32 s70, v255, 17
	v_readlane_b32 s71, v255, 18
	v_readlane_b32 s72, v255, 19
	v_readlane_b32 s73, v255, 20
	v_pk_add_f32 v[142:143], v[142:143], v[154:155]
	v_pk_add_f32 v[140:141], v[140:141], v[152:153]
	v_pk_add_f32 v[152:153], v[172:173], v[158:159]
	v_pk_add_f32 v[154:155], v[184:185], v[156:157]
	v_pk_add_f32 v[156:157], v[196:197], v[190:191]
	v_pk_add_f32 v[158:159], v[198:199], v[188:189]
	v_pk_add_f32 v[188:189], v[128:129], v[192:193]
	v_cvt_pk_bf16_f32 v128, v140, v141
	v_cvt_pk_bf16_f32 v129, v142, v143
	v_mul_f32_e32 v184, v141, v141
	v_mul_f32_e32 v143, v143, v143
	v_mul_f32_e32 v185, v159, v159
	v_mul_f32_e32 v190, v157, v157
	v_pk_add_f32 v[172:173], v[130:131], v[194:195]
	v_cvt_pk_bf16_f32 v130, v154, v155
	v_mul_f32_e32 v155, v155, v155
	v_mul_f32_e32 v191, v189, v189
	v_fmac_f32_e32 v184, v140, v140
	v_fmac_f32_e32 v143, v142, v142
	v_fmac_f32_e32 v185, v158, v158
	v_fmac_f32_e32 v190, v156, v156
	v_cvt_pk_bf16_f32 v131, v152, v153
	v_mul_f32_e32 v153, v153, v153
	v_mul_f32_e32 v192, v173, v173
	global_store_dwordx4 v201, v[128:131], s[78:79]
	v_fmac_f32_e32 v155, v154, v154
	v_fmac_f32_e32 v191, v188, v188
	v_add_f32_e32 v128, v184, v143
	v_add_f32_e32 v129, v185, v190
	v_fmac_f32_e32 v153, v152, v152
	v_fmac_f32_e32 v192, v172, v172
	v_add_f32_e32 v128, v128, v155
	v_add_f32_e32 v129, v129, v191
	v_add_f32_e32 v128, v153, v128
	v_add_f32_e32 v129, v192, v129
	v_add_f32_e32 v128, v128, v129
	v_lshlrev_b32_e32 v184, 2, v187
	ds_bpermute_b32 v129, v184, v128
	v_cvt_pk_bf16_f32 v140, v158, v159
	v_cvt_pk_bf16_f32 v141, v156, v157
	v_cvt_pk_bf16_f32 v142, v188, v189
	v_cvt_pk_bf16_f32 v143, v172, v173
	s_waitcnt lgkmcnt(0)
	v_add_f32_e32 v128, v128, v129
	v_xor_b32_e32 v129, 32, v182
	v_cmp_lt_i32_e32 vcc, v129, v200
	global_store_dwordx4 v201, v[140:143], s[80:81]
	s_nop 0
	v_cndmask_b32_e32 v129, v182, v129, vcc
	v_lshlrev_b32_e32 v185, 2, v129
	ds_bpermute_b32 v129, v185, v128
	s_and_saveexec_b64 s[82:83], s[2:3]
	s_cbranch_execz .LBB0_706
	v_lshlrev_b64 v[130:131], 6, v[170:171]
	v_lshl_add_u64 v[130:131], s[24:25], 0, v[130:131]
	v_lshl_add_u64 v[130:131], s[0:1], 2, v[130:131]
	s_lshl_b32 s16, s39, 2
	v_lshl_add_u64 v[130:131], v[130:131], 0, s[16:17]
	s_waitcnt lgkmcnt(0)
	v_add_f32_e32 v128, v128, v129
	global_store_dword v[130:131], v128, off
;     __device__ __forceinline__ void operator()(const f32x4 (&acc)[2][2][4][2], const Unit& u, int wr, int wc, int fr, int fq, const PG8_LAS float* rtab) const {
;     ...
;         for (int gi = 0; gi < 8; ++gi) { const int ai = gi >> 2, m = gi & 3; const int row = row0 + ai * HALF + m * 16; float ssq = 0.f;
;             if (gi < 7) load_grp(nxt, row0 + ((gi + 1) >> 2) * HALF + ((gi + 1) & 3) * 16, col0);
;             float rsr = 0.f;
;             if (MODE == 1) rsr = rtab[ai * HALF + wr * 64 + m * 16 + fr];
; #pragma unroll
;             for (int bj = 0; bj < 2; ++bj) { const size_t off = (size_t)row * 1024 + col0 + bj * HALF;
;                 f32x4 v0, v1;
;                 if (BASEF32) { v0 = cur.b[bj][0]; v1 = cur.b[bj][1]; }
;                 else { const u32x4 hw = cur.h[bj];
;                     v0 = (f32x4){__uint_as_float(hw.x << 16), __uint_as_float(hw.x & 0xffff0000u), __uint_as_float(hw.y << 16), __uint_as_float(hw.y & 0xffff0000u)};
;                     v1 = (f32x4){__uint_as_float(hw.z << 16), __uint_as_float(hw.z & 0xffff0000u), __uint_as_float(hw.w << 16), __uint_as_float(hw.w & 0xffff0000u)}; }
;                 if (MODE == 0) { v0 += acc[ai][bj][m][0] + bv[bj][0]; v1 += acc[ai][bj][m][1] + bv[bj][1]; }
;                 else { const u32x4 pw = cur.p[bj]; const f32x4 a0 = acc[ai][bj][m][0] * rsr, a1 = acc[ai][bj][m][1] * rsr;
;                     v0[0] += fast_sigmoid(a0[0]) * __uint_as_float(pw.x << 16); v0[1] += fast_sigmoid(a0[1]) * __uint_as_float(pw.x & 0xffff0000u);
;                     v0[2] += fast_sigmoid(a0[2]) * __uint_as_float(pw.y << 16); v0[3] += fast_sigmoid(a0[3]) * __uint_as_float(pw.y & 0xffff0000u);
;                     v1[0] += fast_sigmoid(a1[0]) * __uint_as_float(pw.z << 16); v1[1] += fast_sigmoid(a1[1]) * __uint_as_float(pw.z & 0xffff0000u);
;                     v1[2] += fast_sigmoid(a1[2]) * __uint_as_float(pw.w << 16); v1[3] += fast_sigmoid(a1[3]) * __uint_as_float(pw.w & 0xffff0000u); }
;                 if (OUTF32) { *(f32x4*)(out + off) = v0; *(f32x4*)(out + off + 4) = v1; }
;                 else { u32x4 w; w.x = cvt_pk_bf16(v0[0], v0[1]); w.y = cvt_pk_bf16(v0[2], v0[3]); w.z = cvt_pk_bf16(v1[0], v1[1]); w.w = cvt_pk_bf16(v1[2], v1[3]);
;                     *(u32x4*)(hb + tiled_off(row, col0 + bj * HALF, 1024)) = w;
.LBB0_706:
	s_or_b64 exec, exec, s[82:83]
	v_or_b32_e32 v172, 32, v170
	v_ashrrev_i32_e32 v173, 31, v172
	v_readlane_b32 s52, v255, 11
	s_waitcnt lgkmcnt(0)
	v_lshlrev_b64 v[128:129], 12, v[172:173]
	v_readlane_b32 s53, v255, 12
	v_pk_add_f32 v[124:125], v[124:125], v[92:93]
	v_pk_add_f32 v[126:127], v[126:127], v[94:95]
	v_lshl_add_u64 v[128:129], s[52:53], 0, v[128:129]
	v_lshl_add_u64 v[140:141], v[168:169], 2, v[128:129]
	global_load_dwordx4 v[152:155], v[140:141], off offset:16
	global_load_dwordx4 v[156:159], v[140:141], off
	global_load_dwordx4 v[128:131], v[140:141], off offset:528
	s_nop 0
	global_load_dwordx4 v[140:143], v[140:141], off offset:512
	s_waitcnt vmcnt(8)
	v_pk_add_f32 v[124:125], v[124:125], v[148:149]
	v_pk_add_f32 v[122:123], v[122:123], v[86:87]
	v_pk_add_f32 v[120:121], v[120:121], v[84:85]
	v_pk_add_f32 v[126:127], v[126:127], v[150:151]
	v_pk_add_f32 v[146:147], v[122:123], v[146:147]
	v_pk_add_f32 v[122:123], v[120:121], v[144:145]
	v_cvt_pk_bf16_f32 v120, v124, v125
	v_mul_f32_e32 v125, v125, v125
	v_fmac_f32_e32 v125, v124, v124
	v_mul_f32_e32 v124, v127, v127
	v_fmac_f32_e32 v124, v126, v126
	v_pk_add_f32 v[118:119], v[118:119], v[90:91]
	v_pk_add_f32 v[116:117], v[116:117], v[88:89]
	v_add_f32_e32 v124, v125, v124
	v_mul_f32_e32 v125, v123, v123
	s_waitcnt vmcnt(6)
	v_pk_add_f32 v[118:119], v[118:119], v[138:139]
	v_pk_add_f32 v[116:117], v[116:117], v[136:137]
	v_pk_add_f32 v[112:113], v[112:113], v[80:81]
	v_cvt_pk_bf16_f32 v121, v126, v127
	v_fmac_f32_e32 v125, v122, v122
	v_pk_add_f32 v[126:127], v[112:113], v[132:133]
	v_mul_f32_e32 v112, v117, v117
	v_mul_f32_e32 v113, v119, v119
	v_add_f32_e32 v124, v124, v125
	v_mul_f32_e32 v125, v147, v147
	v_fmac_f32_e32 v112, v116, v116
	v_fmac_f32_e32 v113, v118, v118
	v_fmac_f32_e32 v125, v146, v146
	v_pk_add_f32 v[114:115], v[114:115], v[82:83]
	v_add_f32_e32 v112, v112, v113
	v_mul_f32_e32 v113, v127, v127
	v_add_f32_e32 v144, v125, v124
	v_pk_add_f32 v[124:125], v[114:115], v[134:135]
	v_fmac_f32_e32 v113, v126, v126
	v_add_f32_e32 v112, v112, v113
	v_mul_f32_e32 v113, v125, v125
	v_fmac_f32_e32 v113, v124, v124
	v_add_f32_e32 v112, v113, v112
	v_add_f32_e32 v112, v144, v112
	ds_bpermute_b32 v113, v184, v112
	v_lshrrev_b32_e32 v171, 3, v174
	v_and_or_b32 v171, v171, 10, v183
	v_lshlrev_b32_e32 v187, 6, v174
	v_lshlrev_b32_e32 v188, 2, v174
	s_waitcnt lgkmcnt(0)
	v_add_f32_e32 v112, v112, v113
	ds_bpermute_b32 v113, v185, v112
	v_and_or_b32 v187, v187, s42, v186
	v_lshlrev_b32_e32 v171, 10, v171
	v_and_b32_e32 v188, 32, v188
	v_bitop3_b32 v171, v187, v171, v188 bitop3:0xde
	v_readlane_b32 s54, v255, 13
	v_readlane_b32 s55, v255, 14
	v_readlane_b32 s56, v255, 15
	v_readlane_b32 s57, v255, 16
	v_readlane_b32 s58, v255, 17
	v_readlane_b32 s59, v255, 18
	v_readlane_b32 s60, v255, 19
	v_readlane_b32 s61, v255, 20
	v_readlane_b32 s62, v255, 21
	v_readlane_b32 s63, v255, 22
	v_readlane_b32 s64, v255, 23
	v_readlane_b32 s65, v255, 24
	v_readlane_b32 s66, v255, 25
	v_readlane_b32 s67, v255, 26
	v_cvt_pk_bf16_f32 v122, v122, v123
	v_cvt_pk_bf16_f32 v123, v146, v147
	global_store_dwordx4 v171, v[120:123], s[78:79]
	v_cvt_pk_bf16_f32 v114, v116, v117
	v_cvt_pk_bf16_f32 v115, v118, v119
	v_cvt_pk_bf16_f32 v116, v126, v127
	v_cvt_pk_bf16_f32 v117, v124, v125
	global_store_dwordx4 v171, v[114:117], s[80:81]
	s_and_saveexec_b64 s[82:83], s[2:3]
	s_cbranch_execz .LBB0_708
	v_lshlrev_b64 v[114:115], 6, v[174:175]
	v_lshl_add_u64 v[114:115], s[24:25], 0, v[114:115]
	v_lshl_add_u64 v[114:115], s[0:1], 2, v[114:115]
	s_lshl_b32 s16, s39, 2
	v_lshl_add_u64 v[114:115], v[114:115], 0, s[16:17]
	s_waitcnt lgkmcnt(0)
	v_add_f32_e32 v112, v112, v113
	global_store_dword v[114:115], v112, off
.LBB0_708:
	s_or_b64 exec, exec, s[82:83]
	v_or_b32_e32 v132, 48, v170
	v_ashrrev_i32_e32 v133, 31, v132
	v_readlane_b32 s52, v255, 11
	s_waitcnt lgkmcnt(0)
	v_lshlrev_b64 v[112:113], 12, v[132:133]
	v_readlane_b32 s53, v255, 12
	v_lshrrev_b32_e32 v134, 3, v172
	v_and_or_b32 v134, v134, 12, v183
	v_lshl_add_u64 v[112:113], s[52:53], 0, v[112:113]
	v_lshl_add_u64 v[116:117], v[168:169], 2, v[112:113]
	global_load_dwordx4 v[120:123], v[116:117], off offset:16
	global_load_dwordx4 v[124:127], v[116:117], off
	global_load_dwordx4 v[112:115], v[116:117], off offset:528
	s_nop 0
	global_load_dwordx4 v[116:119], v[116:117], off offset:512
	v_lshlrev_b32_e32 v135, 6, v172
	v_lshlrev_b32_e32 v136, 2, v172
	v_pk_add_f32 v[108:109], v[108:109], v[92:93]
	v_and_or_b32 v135, v135, s42, v186
	v_lshlrev_b32_e32 v134, 10, v134
	v_and_b32_e32 v136, 32, v136
	v_pk_add_f32 v[110:111], v[110:111], v[94:95]
	s_waitcnt vmcnt(8)
	v_pk_add_f32 v[108:109], v[108:109], v[156:157]
	v_pk_add_f32 v[106:107], v[106:107], v[86:87]
	v_pk_add_f32 v[104:105], v[104:105], v[84:85]
	v_bitop3_b32 v136, v135, v134, v136 bitop3:0xde
	v_pk_add_f32 v[110:111], v[110:111], v[158:159]
	v_pk_add_f32 v[134:135], v[106:107], v[154:155]
	v_pk_add_f32 v[106:107], v[104:105], v[152:153]
	v_cvt_pk_bf16_f32 v104, v108, v109
	v_mul_f32_e32 v109, v109, v109
	v_fmac_f32_e32 v109, v108, v108
	v_mul_f32_e32 v108, v111, v111
	v_fmac_f32_e32 v108, v110, v110
	v_pk_add_f32 v[102:103], v[102:103], v[90:91]
	v_pk_add_f32 v[100:101], v[100:101], v[88:89]
	v_add_f32_e32 v108, v109, v108
	v_mul_f32_e32 v109, v107, v107
	s_waitcnt vmcnt(6)
;     __device__ __forceinline__ void operator()(const f32x4 (&acc)[2][2][4][2], const Unit& u, int wr, int wc, int fr, int fq, const PG8_LAS float* rtab) const {
;     ...
;         for (int gi = 0; gi < 8; ++gi) { const int ai = gi >> 2, m = gi & 3; const int row = row0 + ai * HALF + m * 16; float ssq = 0.f;
;             if (gi < 7) load_grp(nxt, row0 + ((gi + 1) >> 2) * HALF + ((gi + 1) & 3) * 16, col0);
;             float rsr = 0.f;
;             if (MODE == 1) rsr = rtab[ai * HALF + wr * 64 + m * 16 + fr];
; #pragma unroll
;             for (int bj = 0; bj < 2; ++bj) { const size_t off = (size_t)row * 1024 + col0 + bj * HALF;
;                 f32x4 v0, v1;
;                 if (BASEF32) { v0 = cur.b[bj][0]; v1 = cur.b[bj][1]; }
;                 else { const u32x4 hw = cur.h[bj];
;                     v0 = (f32x4){__uint_as_float(hw.x << 16), __uint_as_float(hw.x & 0xffff0000u), __uint_as_float(hw.y << 16), __uint_as_float(hw.y & 0xffff0000u)};
;                     v1 = (f32x4){__uint_as_float(hw.z << 16), __uint_as_float(hw.z & 0xffff0000u), __uint_as_float(hw.w << 16), __uint_as_float(hw.w & 0xffff0000u)}; }
;                 if (MODE == 0) { v0 += acc[ai][bj][m][0] + bv[bj][0]; v1 += acc[ai][bj][m][1] + bv[bj][1]; }
;                 else { const u32x4 pw = cur.p[bj]; const f32x4 a0 = acc[ai][bj][m][0] * rsr, a1 = acc[ai][bj][m][1] * rsr;
;                     v0[0] += fast_sigmoid(a0[0]) * __uint_as_float(pw.x << 16); v0[1] += fast_sigmoid(a0[1]) * __uint_as_float(pw.x & 0xffff0000u);
;                     v0[2] += fast_sigmoid(a0[2]) * __uint_as_float(pw.y << 16); v0[3] += fast_sigmoid(a0[3]) * __uint_as_float(pw.y & 0xffff0000u);
;                     v1[0] += fast_sigmoid(a1[0]) * __uint_as_float(pw.z << 16); v1[1] += fast_sigmoid(a1[1]) * __uint_as_float(pw.z & 0xffff0000u);
;                     v1[2] += fast_sigmoid(a1[2]) * __uint_as_float(pw.w << 16); v1[3] += fast_sigmoid(a1[3]) * __uint_as_float(pw.w & 0xffff0000u); }
;                 if (OUTF32) { *(f32x4*)(out + off) = v0; *(f32x4*)(out + off + 4) = v1; }
;                 else { u32x4 w; w.x = cvt_pk_bf16(v0[0], v0[1]); w.y = cvt_pk_bf16(v0[2], v0[3]); w.z = cvt_pk_bf16(v1[0], v1[1]); w.w = cvt_pk_bf16(v1[2], v1[3]);
;                     *(u32x4*)(hb + tiled_off(row, col0 + bj * HALF, 1024)) = w;
	v_pk_add_f32 v[102:103], v[102:103], v[142:143]
	v_pk_add_f32 v[100:101], v[100:101], v[140:141]
	v_pk_add_f32 v[96:97], v[96:97], v[80:81]
	v_cvt_pk_bf16_f32 v105, v110, v111
	v_fmac_f32_e32 v109, v106, v106
	v_pk_add_f32 v[110:111], v[96:97], v[128:129]
	v_mul_f32_e32 v96, v101, v101
	v_mul_f32_e32 v97, v103, v103
	v_add_f32_e32 v108, v108, v109
	v_mul_f32_e32 v109, v135, v135
	v_fmac_f32_e32 v96, v100, v100
	v_fmac_f32_e32 v97, v102, v102
	v_fmac_f32_e32 v109, v134, v134
	v_pk_add_f32 v[98:99], v[98:99], v[82:83]
	v_add_f32_e32 v96, v96, v97
	v_mul_f32_e32 v97, v111, v111
	v_add_f32_e32 v137, v109, v108
	v_pk_add_f32 v[108:109], v[98:99], v[130:131]
	v_fmac_f32_e32 v97, v110, v110
	v_add_f32_e32 v96, v96, v97
	v_mul_f32_e32 v97, v109, v109
	v_fmac_f32_e32 v97, v108, v108
	v_add_f32_e32 v96, v97, v96
	v_add_f32_e32 v96, v137, v96
	ds_bpermute_b32 v97, v184, v96
	v_readlane_b32 s54, v255, 13
	v_readlane_b32 s55, v255, 14
	v_readlane_b32 s56, v255, 15
	v_readlane_b32 s57, v255, 16
	s_waitcnt lgkmcnt(0)
	v_add_f32_e32 v96, v96, v97
	ds_bpermute_b32 v97, v185, v96
	v_readlane_b32 s58, v255, 17
	v_readlane_b32 s59, v255, 18
	v_readlane_b32 s60, v255, 19
	v_readlane_b32 s61, v255, 20
	v_readlane_b32 s62, v255, 21
	v_readlane_b32 s63, v255, 22
	v_readlane_b32 s64, v255, 23
	v_readlane_b32 s65, v255, 24
	v_readlane_b32 s66, v255, 25
	v_readlane_b32 s67, v255, 26
	v_cvt_pk_bf16_f32 v106, v106, v107
	v_cvt_pk_bf16_f32 v107, v134, v135
	global_store_dwordx4 v136, v[104:107], s[78:79]
	v_cvt_pk_bf16_f32 v98, v100, v101
	v_cvt_pk_bf16_f32 v99, v102, v103
	v_cvt_pk_bf16_f32 v100, v110, v111
	v_cvt_pk_bf16_f32 v101, v108, v109
	global_store_dwordx4 v136, v[98:101], s[80:81]
	s_and_saveexec_b64 s[82:83], s[2:3]
	s_cbranch_execz .LBB0_710
	v_lshlrev_b64 v[98:99], 6, v[172:173]
	v_lshl_add_u64 v[98:99], s[24:25], 0, v[98:99]
	v_lshl_add_u64 v[98:99], s[0:1], 2, v[98:99]
	s_lshl_b32 s16, s39, 2
	v_lshl_add_u64 v[98:99], v[98:99], 0, s[16:17]
	s_waitcnt lgkmcnt(0)
	v_add_f32_e32 v96, v96, v97
	global_store_dword v[98:99], v96, off
.LBB0_710:
	s_or_b64 exec, exec, s[82:83]
	v_add_u32_e32 v128, 0x80, v170
	v_ashrrev_i32_e32 v129, 31, v128
	v_readlane_b32 s52, v255, 11
	s_waitcnt lgkmcnt(0)
	v_lshlrev_b64 v[96:97], 12, v[128:129]
	v_readlane_b32 s53, v255, 12
	v_pk_add_f32 v[76:77], v[76:77], v[92:93]
	v_pk_add_f32 v[78:79], v[78:79], v[94:95]
	v_lshl_add_u64 v[96:97], s[52:53], 0, v[96:97]
	v_lshl_add_u64 v[100:101], v[168:169], 2, v[96:97]
	global_load_dwordx4 v[104:107], v[100:101], off offset:16
	global_load_dwordx4 v[108:111], v[100:101], off
	global_load_dwordx4 v[96:99], v[100:101], off offset:528
	s_nop 0
	global_load_dwordx4 v[100:103], v[100:101], off offset:512
	s_waitcnt vmcnt(8)
	v_pk_add_f32 v[76:77], v[76:77], v[124:125]
	v_pk_add_f32 v[74:75], v[74:75], v[86:87]
	v_pk_add_f32 v[72:73], v[72:73], v[84:85]
	v_pk_add_f32 v[78:79], v[78:79], v[126:127]
	v_pk_add_f32 v[122:123], v[74:75], v[122:123]
	v_pk_add_f32 v[74:75], v[72:73], v[120:121]
	v_cvt_pk_bf16_f32 v72, v76, v77
	v_mul_f32_e32 v77, v77, v77
	v_fmac_f32_e32 v77, v76, v76
	v_mul_f32_e32 v76, v79, v79
	v_fmac_f32_e32 v76, v78, v78
	v_pk_add_f32 v[70:71], v[70:71], v[90:91]
	v_pk_add_f32 v[68:69], v[68:69], v[88:89]
	v_add_f32_e32 v76, v77, v76
	v_mul_f32_e32 v77, v75, v75
	s_waitcnt vmcnt(6)
	v_pk_add_f32 v[70:71], v[70:71], v[118:119]
	v_pk_add_f32 v[68:69], v[68:69], v[116:117]
	v_pk_add_f32 v[64:65], v[64:65], v[80:81]
	v_cvt_pk_bf16_f32 v73, v78, v79
	v_fmac_f32_e32 v77, v74, v74
	v_pk_add_f32 v[78:79], v[64:65], v[112:113]
	v_mul_f32_e32 v64, v69, v69
	v_mul_f32_e32 v65, v71, v71
	v_add_f32_e32 v76, v76, v77
	v_mul_f32_e32 v77, v123, v123
	v_fmac_f32_e32 v64, v68, v68
	v_fmac_f32_e32 v65, v70, v70
	v_fmac_f32_e32 v77, v122, v122
	v_pk_add_f32 v[66:67], v[66:67], v[82:83]
	v_add_f32_e32 v64, v64, v65
	v_mul_f32_e32 v65, v79, v79
	v_add_f32_e32 v120, v77, v76
	v_pk_add_f32 v[76:77], v[66:67], v[114:115]
	v_fmac_f32_e32 v65, v78, v78
	v_add_f32_e32 v64, v64, v65
	v_mul_f32_e32 v65, v77, v77
	v_fmac_f32_e32 v65, v76, v76
	v_add_f32_e32 v64, v65, v64
	v_add_f32_e32 v64, v120, v64
	ds_bpermute_b32 v65, v184, v64
	v_lshrrev_b32_e32 v130, 3, v132
	v_and_or_b32 v130, v130, 14, v183
	v_lshlrev_b32_e32 v131, 6, v132
	v_lshlrev_b32_e32 v134, 2, v132
	s_waitcnt lgkmcnt(0)
	v_add_f32_e32 v64, v64, v65
	ds_bpermute_b32 v65, v185, v64
	v_and_or_b32 v131, v131, s42, v186
	v_lshlrev_b32_e32 v130, 10, v130
	v_and_b32_e32 v134, 32, v134
	v_bitop3_b32 v130, v131, v130, v134 bitop3:0xde
	v_readlane_b32 s54, v255, 13
	v_readlane_b32 s55, v255, 14
	v_readlane_b32 s56, v255, 15
	v_readlane_b32 s57, v255, 16
	v_readlane_b32 s58, v255, 17
	v_readlane_b32 s59, v255, 18
	v_readlane_b32 s60, v255, 19
	v_readlane_b32 s61, v255, 20
	v_readlane_b32 s62, v255, 21
	v_readlane_b32 s63, v255, 22
	v_readlane_b32 s64, v255, 23
	v_readlane_b32 s65, v255, 24
	v_readlane_b32 s66, v255, 25
	v_readlane_b32 s67, v255, 26
	v_cvt_pk_bf16_f32 v74, v74, v75
	v_cvt_pk_bf16_f32 v75, v122, v123
	global_store_dwordx4 v130, v[72:75], s[78:79]
	v_cvt_pk_bf16_f32 v66, v68, v69
	v_cvt_pk_bf16_f32 v67, v70, v71
	v_cvt_pk_bf16_f32 v68, v78, v79
	v_cvt_pk_bf16_f32 v69, v76, v77
	global_store_dwordx4 v130, v[66:69], s[80:81]
	s_and_saveexec_b64 s[78:79], s[2:3]
	s_cbranch_execz .LBB0_712
	v_lshlrev_b64 v[66:67], 6, v[132:133]
	v_lshl_add_u64 v[66:67], s[24:25], 0, v[66:67]
	v_lshl_add_u64 v[66:67], s[0:1], 2, v[66:67]
	s_lshl_b32 s16, s39, 2
	v_lshl_add_u64 v[66:67], v[66:67], 0, s[16:17]
	s_waitcnt lgkmcnt(0)
	v_add_f32_e32 v64, v64, v65
	global_store_dword v[66:67], v64, off
;     __device__ __forceinline__ void operator()(const f32x4 (&acc)[2][2][4][2], const Unit& u, int wr, int wc, int fr, int fq, const PG8_LAS float* rtab) const {
;     ...
;         for (int gi = 0; gi < 8; ++gi) { const int ai = gi >> 2, m = gi & 3; const int row = row0 + ai * HALF + m * 16; float ssq = 0.f;
;             if (gi < 7) load_grp(nxt, row0 + ((gi + 1) >> 2) * HALF + ((gi + 1) & 3) * 16, col0);
;             float rsr = 0.f;
;             if (MODE == 1) rsr = rtab[ai * HALF + wr * 64 + m * 16 + fr];
; #pragma unroll
;             for (int bj = 0; bj < 2; ++bj) { const size_t off = (size_t)row * 1024 + col0 + bj * HALF;
;                 f32x4 v0, v1;
;                 if (BASEF32) { v0 = cur.b[bj][0]; v1 = cur.b[bj][1]; }
;                 else { const u32x4 hw = cur.h[bj];
;                     v0 = (f32x4){__uint_as_float(hw.x << 16), __uint_as_float(hw.x & 0xffff0000u), __uint_as_float(hw.y << 16), __uint_as_float(hw.y & 0xffff0000u)};
;                     v1 = (f32x4){__uint_as_float(hw.z << 16), __uint_as_float(hw.z & 0xffff0000u), __uint_as_float(hw.w << 16), __uint_as_float(hw.w & 0xffff0000u)}; }
;                 if (MODE == 0) { v0 += acc[ai][bj][m][0] + bv[bj][0]; v1 += acc[ai][bj][m][1] + bv[bj][1]; }
;                 else { const u32x4 pw = cur.p[bj]; const f32x4 a0 = acc[ai][bj][m][0] * rsr, a1 = acc[ai][bj][m][1] * rsr;
;                     v0[0] += fast_sigmoid(a0[0]) * __uint_as_float(pw.x << 16); v0[1] += fast_sigmoid(a0[1]) * __uint_as_float(pw.x & 0xffff0000u);
;                     v0[2] += fast_sigmoid(a0[2]) * __uint_as_float(pw.y << 16); v0[3] += fast_sigmoid(a0[3]) * __uint_as_float(pw.y & 0xffff0000u);
;                     v1[0] += fast_sigmoid(a1[0]) * __uint_as_float(pw.z << 16); v1[1] += fast_sigmoid(a1[1]) * __uint_as_float(pw.z & 0xffff0000u);
;                     v1[2] += fast_sigmoid(a1[2]) * __uint_as_float(pw.w << 16); v1[3] += fast_sigmoid(a1[3]) * __uint_as_float(pw.w & 0xffff0000u); }
;                 if (OUTF32) { *(f32x4*)(out + off) = v0; *(f32x4*)(out + off + 4) = v1; }
;                 else { u32x4 w; w.x = cvt_pk_bf16(v0[0], v0[1]); w.y = cvt_pk_bf16(v0[2], v0[3]); w.z = cvt_pk_bf16(v1[0], v1[1]); w.w = cvt_pk_bf16(v1[2], v1[3]);
;                     *(u32x4*)(hb + tiled_off(row, col0 + bj * HALF, 1024)) = w;
.LBB0_712:
	s_or_b64 exec, exec, s[78:79]
	v_or_b32_e32 v112, 16, v128
	v_ashrrev_i32_e32 v113, 31, v112
	v_readlane_b32 s52, v255, 11
	s_waitcnt lgkmcnt(0)
	v_lshlrev_b64 v[64:65], 12, v[112:113]
	v_readlane_b32 s53, v255, 12
	v_pk_add_f32 v[60:61], v[60:61], v[92:93]
	v_pk_add_f32 v[62:63], v[62:63], v[94:95]
	v_lshl_add_u64 v[64:65], s[52:53], 0, v[64:65]
	v_lshl_add_u64 v[68:69], v[168:169], 2, v[64:65]
	global_load_dwordx4 v[72:75], v[68:69], off offset:16
	global_load_dwordx4 v[76:79], v[68:69], off
	global_load_dwordx4 v[64:67], v[68:69], off offset:528
	s_nop 0
	global_load_dwordx4 v[68:71], v[68:69], off offset:512
	s_waitcnt vmcnt(8)
	v_pk_add_f32 v[60:61], v[60:61], v[108:109]
	v_pk_add_f32 v[56:57], v[56:57], v[84:85]
	v_pk_add_f32 v[62:63], v[62:63], v[110:111]
	v_pk_add_f32 v[108:109], v[56:57], v[104:105]
	v_cvt_pk_bf16_f32 v56, v60, v61
	v_mul_f32_e32 v61, v61, v61
	v_fmac_f32_e32 v61, v60, v60
	v_mul_f32_e32 v60, v63, v63
	v_fmac_f32_e32 v60, v62, v62
	v_pk_add_f32 v[58:59], v[58:59], v[86:87]
	v_add_f32_e32 v60, v61, v60
	v_mul_f32_e32 v61, v109, v109
	v_pk_add_f32 v[106:107], v[58:59], v[106:107]
	v_fmac_f32_e32 v61, v108, v108
	v_add_f32_e32 v60, v60, v61
	v_mul_f32_e32 v61, v107, v107
	v_pk_add_f32 v[54:55], v[54:55], v[90:91]
	v_pk_add_f32 v[52:53], v[52:53], v[88:89]
	v_fmac_f32_e32 v61, v106, v106
	s_waitcnt vmcnt(6)
	v_pk_add_f32 v[54:55], v[54:55], v[102:103]
	v_pk_add_f32 v[52:53], v[52:53], v[100:101]
	v_pk_add_f32 v[50:51], v[50:51], v[82:83]
	v_cvt_pk_bf16_f32 v57, v62, v63
	v_add_f32_e32 v62, v61, v60
	v_pk_add_f32 v[48:49], v[48:49], v[80:81]
	v_pk_add_f32 v[60:61], v[50:51], v[98:99]
	v_mul_f32_e32 v50, v53, v53
	v_mul_f32_e32 v51, v55, v55
	v_pk_add_f32 v[48:49], v[48:49], v[96:97]
	v_fmac_f32_e32 v50, v52, v52
	v_fmac_f32_e32 v51, v54, v54
	v_add_f32_e32 v50, v50, v51
	v_mul_f32_e32 v51, v49, v49
	v_fmac_f32_e32 v51, v48, v48
	v_add_f32_e32 v50, v50, v51
	v_mul_f32_e32 v51, v61, v61
	v_fmac_f32_e32 v51, v60, v60
	v_add_f32_e32 v50, v51, v50
	v_ashrrev_i32_e32 v114, 7, v128
	v_add_f32_e32 v62, v62, v50
	v_ashrrev_i32_e32 v115, 31, v114
	ds_bpermute_b32 v63, v184, v62
	v_lshlrev_b32_e32 v116, 6, v128
	v_lshlrev_b32_e32 v117, 2, v128
	v_lshlrev_b64 v[114:115], 18, v[114:115]
	v_and_or_b32 v116, v116, s42, v186
	v_and_b32_e32 v117, 32, v117
	v_lshl_add_u64 v[110:111], s[34:35], 0, v[114:115]
	v_bitop3_b32 v162, v116, v162, v117 bitop3:0xde
	v_lshl_add_u64 v[104:105], v[110:111], 0, s[76:77]
	v_lshl_add_u64 v[114:115], v[104:105], 0, v[162:163]
	v_cvt_pk_bf16_f32 v58, v108, v109
	v_cvt_pk_bf16_f32 v59, v106, v107
	global_store_dwordx4 v[114:115], v[56:59], off
	v_cvt_pk_bf16_f32 v50, v52, v53
	v_cvt_pk_bf16_f32 v51, v54, v55
	v_cvt_pk_bf16_f32 v52, v48, v49
	s_waitcnt lgkmcnt(0)
	v_add_f32_e32 v48, v62, v63
	ds_bpermute_b32 v49, v185, v48
	v_lshl_add_u64 v[96:97], v[110:111], 0, s[74:75]
	v_lshl_add_u64 v[54:55], v[96:97], 0, v[162:163]
	v_readlane_b32 s54, v255, 13
	v_readlane_b32 s55, v255, 14
	v_readlane_b32 s56, v255, 15
	v_readlane_b32 s57, v255, 16
	v_readlane_b32 s58, v255, 17
	v_readlane_b32 s59, v255, 18
	v_readlane_b32 s60, v255, 19
	v_readlane_b32 s61, v255, 20
	v_readlane_b32 s62, v255, 21
	v_readlane_b32 s63, v255, 22
	v_readlane_b32 s64, v255, 23
	v_readlane_b32 s65, v255, 24
	v_readlane_b32 s66, v255, 25
	v_readlane_b32 s67, v255, 26
	v_cvt_pk_bf16_f32 v53, v60, v61
	global_store_dwordx4 v[54:55], v[50:53], off
	s_and_saveexec_b64 s[74:75], s[2:3]
	s_cbranch_execz .LBB0_714
	v_lshlrev_b64 v[50:51], 6, v[128:129]
	v_lshl_add_u64 v[50:51], s[24:25], 0, v[50:51]
	v_lshl_add_u64 v[50:51], s[0:1], 2, v[50:51]
	s_lshl_b32 s16, s39, 2
	v_lshl_add_u64 v[50:51], v[50:51], 0, s[16:17]
	s_waitcnt lgkmcnt(0)
	v_add_f32_e32 v48, v48, v49
	global_store_dword v[50:51], v48, off
.LBB0_714:
	s_or_b64 exec, exec, s[74:75]
	v_or_b32_e32 v98, 32, v128
	v_ashrrev_i32_e32 v99, 31, v98
	v_readlane_b32 s52, v255, 11
	s_waitcnt lgkmcnt(0)
	v_lshlrev_b64 v[48:49], 12, v[98:99]
	v_readlane_b32 s53, v255, 12
	v_pk_add_f32 v[44:45], v[44:45], v[92:93]
	v_pk_add_f32 v[46:47], v[46:47], v[94:95]
	v_lshl_add_u64 v[48:49], s[52:53], 0, v[48:49]
	v_lshl_add_u64 v[52:53], v[168:169], 2, v[48:49]
	global_load_dwordx4 v[56:59], v[52:53], off offset:16
	global_load_dwordx4 v[60:63], v[52:53], off
	global_load_dwordx4 v[48:51], v[52:53], off offset:528
	s_nop 0
	global_load_dwordx4 v[52:55], v[52:53], off offset:512
	s_waitcnt vmcnt(8)
	v_pk_add_f32 v[44:45], v[44:45], v[76:77]
	v_pk_add_f32 v[40:41], v[40:41], v[84:85]
	v_pk_add_f32 v[46:47], v[46:47], v[78:79]
	v_pk_add_f32 v[72:73], v[40:41], v[72:73]
	v_cvt_pk_bf16_f32 v40, v44, v45
	v_mul_f32_e32 v45, v45, v45
	v_fmac_f32_e32 v45, v44, v44
	v_mul_f32_e32 v44, v47, v47
	v_fmac_f32_e32 v44, v46, v46
	v_pk_add_f32 v[38:39], v[38:39], v[90:91]
	v_pk_add_f32 v[36:37], v[36:37], v[88:89]
	v_pk_add_f32 v[42:43], v[42:43], v[86:87]
	v_add_f32_e32 v44, v45, v44
	v_mul_f32_e32 v45, v73, v73
	s_waitcnt vmcnt(6)
;     __device__ __forceinline__ void operator()(const f32x4 (&acc)[2][2][4][2], const Unit& u, int wr, int wc, int fr, int fq, const PG8_LAS float* rtab) const {
;     ...
;         for (int gi = 0; gi < 8; ++gi) { const int ai = gi >> 2, m = gi & 3; const int row = row0 + ai * HALF + m * 16; float ssq = 0.f;
;             if (gi < 7) load_grp(nxt, row0 + ((gi + 1) >> 2) * HALF + ((gi + 1) & 3) * 16, col0);
;             float rsr = 0.f;
;             if (MODE == 1) rsr = rtab[ai * HALF + wr * 64 + m * 16 + fr];
; #pragma unroll
;             for (int bj = 0; bj < 2; ++bj) { const size_t off = (size_t)row * 1024 + col0 + bj * HALF;
;                 f32x4 v0, v1;
;                 if (BASEF32) { v0 = cur.b[bj][0]; v1 = cur.b[bj][1]; }
;                 else { const u32x4 hw = cur.h[bj];
;                     v0 = (f32x4){__uint_as_float(hw.x << 16), __uint_as_float(hw.x & 0xffff0000u), __uint_as_float(hw.y << 16), __uint_as_float(hw.y & 0xffff0000u)};
;                     v1 = (f32x4){__uint_as_float(hw.z << 16), __uint_as_float(hw.z & 0xffff0000u), __uint_as_float(hw.w << 16), __uint_as_float(hw.w & 0xffff0000u)}; }
;                 if (MODE == 0) { v0 += acc[ai][bj][m][0] + bv[bj][0]; v1 += acc[ai][bj][m][1] + bv[bj][1]; }
;                 else { const u32x4 pw = cur.p[bj]; const f32x4 a0 = acc[ai][bj][m][0] * rsr, a1 = acc[ai][bj][m][1] * rsr;
;                     v0[0] += fast_sigmoid(a0[0]) * __uint_as_float(pw.x << 16); v0[1] += fast_sigmoid(a0[1]) * __uint_as_float(pw.x & 0xffff0000u);
;                     v0[2] += fast_sigmoid(a0[2]) * __uint_as_float(pw.y << 16); v0[3] += fast_sigmoid(a0[3]) * __uint_as_float(pw.y & 0xffff0000u);
;                     v1[0] += fast_sigmoid(a1[0]) * __uint_as_float(pw.z << 16); v1[1] += fast_sigmoid(a1[1]) * __uint_as_float(pw.z & 0xffff0000u);
;                     v1[2] += fast_sigmoid(a1[2]) * __uint_as_float(pw.w << 16); v1[3] += fast_sigmoid(a1[3]) * __uint_as_float(pw.w & 0xffff0000u); }
;                 if (OUTF32) { *(f32x4*)(out + off) = v0; *(f32x4*)(out + off + 4) = v1; }
;                 else { u32x4 w; w.x = cvt_pk_bf16(v0[0], v0[1]); w.y = cvt_pk_bf16(v0[2], v0[3]); w.z = cvt_pk_bf16(v1[0], v1[1]); w.w = cvt_pk_bf16(v1[2], v1[3]);
;                     *(u32x4*)(hb + tiled_off(row, col0 + bj * HALF, 1024)) = w;
	v_pk_add_f32 v[38:39], v[38:39], v[70:71]
	v_pk_add_f32 v[36:37], v[36:37], v[68:69]
	v_pk_add_f32 v[32:33], v[32:33], v[80:81]
	v_pk_add_f32 v[74:75], v[42:43], v[74:75]
	v_cvt_pk_bf16_f32 v41, v46, v47
	v_fmac_f32_e32 v45, v72, v72
	v_pk_add_f32 v[46:47], v[32:33], v[64:65]
	v_mul_f32_e32 v32, v37, v37
	v_mul_f32_e32 v33, v39, v39
	v_add_f32_e32 v44, v44, v45
	v_mul_f32_e32 v45, v75, v75
	v_fmac_f32_e32 v32, v36, v36
	v_fmac_f32_e32 v33, v38, v38
	v_fmac_f32_e32 v45, v74, v74
	v_pk_add_f32 v[34:35], v[34:35], v[82:83]
	v_add_f32_e32 v32, v32, v33
	v_mul_f32_e32 v33, v47, v47
	v_cvt_pk_bf16_f32 v42, v72, v73
	v_add_f32_e32 v72, v45, v44
	v_pk_add_f32 v[44:45], v[34:35], v[66:67]
	v_fmac_f32_e32 v33, v46, v46
	v_add_f32_e32 v32, v32, v33
	v_mul_f32_e32 v33, v45, v45
	v_fmac_f32_e32 v33, v44, v44
	v_add_f32_e32 v32, v33, v32
	v_add_f32_e32 v64, v72, v32
	v_lshrrev_b32_e32 v100, 3, v112
	ds_bpermute_b32 v65, v184, v64
	v_and_or_b32 v100, v100, 14, v183
	v_lshlrev_b32_e32 v101, 6, v112
	v_lshlrev_b32_e32 v102, 2, v112
	v_and_or_b32 v101, v101, s42, v186
	v_lshlrev_b32_e32 v100, 10, v100
	v_and_b32_e32 v102, 32, v102
	v_bitop3_b32 v162, v101, v100, v102 bitop3:0xde
	v_lshl_add_u64 v[32:33], v[104:105], 0, v[162:163]
	v_cvt_pk_bf16_f32 v43, v74, v75
	global_store_dwordx4 v[32:33], v[40:43], off
	s_waitcnt lgkmcnt(0)
	v_add_f32_e32 v32, v64, v65
	ds_bpermute_b32 v33, v185, v32
	v_cvt_pk_bf16_f32 v34, v36, v37
	v_cvt_pk_bf16_f32 v35, v38, v39
	v_lshl_add_u64 v[38:39], v[96:97], 0, v[162:163]
	v_readlane_b32 s54, v255, 13
	v_readlane_b32 s55, v255, 14
	v_readlane_b32 s56, v255, 15
	v_readlane_b32 s57, v255, 16
	v_readlane_b32 s58, v255, 17
	v_readlane_b32 s59, v255, 18
	v_readlane_b32 s60, v255, 19
	v_readlane_b32 s61, v255, 20
	v_readlane_b32 s62, v255, 21
	v_readlane_b32 s63, v255, 22
	v_readlane_b32 s64, v255, 23
	v_readlane_b32 s65, v255, 24
	v_readlane_b32 s66, v255, 25
	v_readlane_b32 s67, v255, 26
	v_cvt_pk_bf16_f32 v36, v46, v47
	v_cvt_pk_bf16_f32 v37, v44, v45
	global_store_dwordx4 v[38:39], v[34:37], off
	s_and_saveexec_b64 s[74:75], s[2:3]
	s_cbranch_execz .LBB0_716
	v_lshlrev_b64 v[34:35], 6, v[112:113]
	v_lshl_add_u64 v[34:35], s[24:25], 0, v[34:35]
	v_lshl_add_u64 v[34:35], s[0:1], 2, v[34:35]
	s_lshl_b32 s16, s39, 2
	v_lshl_add_u64 v[34:35], v[34:35], 0, s[16:17]
	s_waitcnt lgkmcnt(0)
	v_add_f32_e32 v32, v32, v33
	global_store_dword v[34:35], v32, off
.LBB0_716:
	s_or_b64 exec, exec, s[74:75]
	v_or_b32_e32 v64, 48, v128
	v_ashrrev_i32_e32 v65, 31, v64
	v_readlane_b32 s52, v255, 11
	s_waitcnt lgkmcnt(0)
	v_lshlrev_b64 v[32:33], 12, v[64:65]
	v_readlane_b32 s53, v255, 12
	v_pk_add_f32 v[28:29], v[28:29], v[92:93]
	v_pk_add_f32 v[30:31], v[30:31], v[94:95]
	v_lshl_add_u64 v[32:33], s[52:53], 0, v[32:33]
	v_lshl_add_u64 v[36:37], v[168:169], 2, v[32:33]
	global_load_dwordx4 v[40:43], v[36:37], off offset:16
	global_load_dwordx4 v[44:47], v[36:37], off
	global_load_dwordx4 v[32:35], v[36:37], off offset:528
	s_nop 0
	global_load_dwordx4 v[36:39], v[36:37], off offset:512
	s_waitcnt vmcnt(8)
	v_pk_add_f32 v[28:29], v[28:29], v[60:61]
	v_pk_add_f32 v[24:25], v[24:25], v[84:85]
	v_pk_add_f32 v[30:31], v[30:31], v[62:63]
	v_pk_add_f32 v[56:57], v[24:25], v[56:57]
	v_cvt_pk_bf16_f32 v24, v28, v29
	v_mul_f32_e32 v29, v29, v29
	v_fmac_f32_e32 v29, v28, v28
	v_mul_f32_e32 v28, v31, v31
	v_fmac_f32_e32 v28, v30, v30
	v_pk_add_f32 v[22:23], v[22:23], v[90:91]
	v_pk_add_f32 v[20:21], v[20:21], v[88:89]
	v_pk_add_f32 v[26:27], v[26:27], v[86:87]
	v_add_f32_e32 v28, v29, v28
	v_mul_f32_e32 v29, v57, v57
	s_waitcnt vmcnt(6)
	v_pk_add_f32 v[22:23], v[22:23], v[54:55]
	v_pk_add_f32 v[20:21], v[20:21], v[52:53]
	v_pk_add_f32 v[16:17], v[16:17], v[80:81]
	v_pk_add_f32 v[58:59], v[26:27], v[58:59]
	v_cvt_pk_bf16_f32 v25, v30, v31
	v_fmac_f32_e32 v29, v56, v56
	v_pk_add_f32 v[30:31], v[16:17], v[48:49]
	v_mul_f32_e32 v16, v21, v21
	v_mul_f32_e32 v17, v23, v23
	v_add_f32_e32 v28, v28, v29
	v_mul_f32_e32 v29, v59, v59
	v_fmac_f32_e32 v16, v20, v20
	v_fmac_f32_e32 v17, v22, v22
	v_fmac_f32_e32 v29, v58, v58
	v_pk_add_f32 v[18:19], v[18:19], v[82:83]
	v_add_f32_e32 v16, v16, v17
	v_mul_f32_e32 v17, v31, v31
	v_cvt_pk_bf16_f32 v26, v56, v57
	v_add_f32_e32 v56, v29, v28
	v_pk_add_f32 v[28:29], v[18:19], v[50:51]
	v_fmac_f32_e32 v17, v30, v30
	v_add_f32_e32 v16, v16, v17
	v_mul_f32_e32 v17, v29, v29
	v_fmac_f32_e32 v17, v28, v28
	v_add_f32_e32 v16, v17, v16
	v_add_f32_e32 v48, v56, v16
	v_lshrrev_b32_e32 v66, 3, v98
	ds_bpermute_b32 v49, v184, v48
	v_and_or_b32 v66, v66, 14, v183
	v_lshlrev_b32_e32 v67, 6, v98
	v_lshlrev_b32_e32 v68, 2, v98
	v_and_or_b32 v67, v67, s42, v186
	v_lshlrev_b32_e32 v66, 10, v66
	v_and_b32_e32 v68, 32, v68
	v_bitop3_b32 v162, v67, v66, v68 bitop3:0xde
	v_lshl_add_u64 v[16:17], v[104:105], 0, v[162:163]
	v_cvt_pk_bf16_f32 v27, v58, v59
	global_store_dwordx4 v[16:17], v[24:27], off
	s_waitcnt lgkmcnt(0)
	v_add_f32_e32 v16, v48, v49
	ds_bpermute_b32 v17, v185, v16
	v_cvt_pk_bf16_f32 v18, v20, v21
	v_cvt_pk_bf16_f32 v19, v22, v23
	v_lshl_add_u64 v[22:23], v[96:97], 0, v[162:163]
	v_readlane_b32 s54, v255, 13
	v_readlane_b32 s55, v255, 14
	v_readlane_b32 s56, v255, 15
	v_readlane_b32 s57, v255, 16
	v_readlane_b32 s58, v255, 17
	v_readlane_b32 s59, v255, 18
	v_readlane_b32 s60, v255, 19
	v_readlane_b32 s61, v255, 20
	v_readlane_b32 s62, v255, 21
	v_readlane_b32 s63, v255, 22
	v_readlane_b32 s64, v255, 23
	v_readlane_b32 s65, v255, 24
	v_readlane_b32 s66, v255, 25
	v_readlane_b32 s67, v255, 26
	v_cvt_pk_bf16_f32 v20, v30, v31
	v_cvt_pk_bf16_f32 v21, v28, v29
	global_store_dwordx4 v[22:23], v[18:21], off
	s_and_saveexec_b64 s[74:75], s[2:3]
	s_cbranch_execz .LBB0_718
	v_lshlrev_b64 v[18:19], 6, v[98:99]
	v_lshl_add_u64 v[18:19], s[24:25], 0, v[18:19]
	v_lshl_add_u64 v[18:19], s[0:1], 2, v[18:19]
	s_lshl_b32 s16, s39, 2
	v_lshl_add_u64 v[18:19], v[18:19], 0, s[16:17]
	s_waitcnt lgkmcnt(0)
	v_add_f32_e32 v16, v16, v17
	global_store_dword v[18:19], v16, off

; #define PG8_LAS __attribute__((address_space(3)))
; #define PG8_WAIT_V(n) asm volatile("s_waitcnt vmcnt(" #n ")" ::: "memory")
; #define PG8_BAR __builtin_amdgcn_s_barrier()
; template <class Epi, class Sched, bool ALIGN_EPI = false, bool SP2 = false, bool TA = true>
; __device__ __forceinline__ void gemm_phase(PG8_LAS unsigned char* lds, const Gemm g, const Sched& S, const Epi& E) {
;     ...
;         if constexpr (!Epi::AFTER_DRAIN) { E(acc, cur, wr, wc, fr, fq, (const PG8_LAS float*)(lds + STAGE_BYTES + 1024 + (ui & 1) * 1024)); S.done(cur); }
;         if (!has_next) break;
; #pragma unroll
;         for (int a = 0; a < 2; ++a)
; #pragma unroll
;             for (int b = 0; b < 2; ++b)
; #pragma unroll
;                 for (int m = 0; m < 4; ++m)
; #pragma unroll
;                     for (int n = 0; n < 2; ++n) acc[a][b][m][n] = (f32x4){0.f, 0.f, 0.f, 0.f};
;         cur = nxt; cA = nA; cB = nB; ++ui;
;         PG8_RTAB(cur, ui);
;         if constexpr (ALIGN_EPI) { if (wr == 1) PG8_BAR; }
;     }
;     PG8_WAIT_V(0);
;     if constexpr (!ALIGN_EPI) { if (wr == 0) PG8_BAR; }
;     PG8_BAR;
; __device__ __forceinline__ void xcd_barrier(const XcdBarrier& b) {
;     asm volatile("s_waitcnt vmcnt(0)" ::: "memory");
;     __syncthreads();
;     if (threadIdx.x == 0) {
;         unsigned* bar = b.bar;
;         __builtin_amdgcn_s_waitcnt(0);
;         unsigned nloc = b.st[0], nx = b.st[1];
;         if (nloc == 0u) { xcd_barrier_complete(bar, b.x, nloc, nx); b.st[0] = nloc; b.st[1] = nx; }
.LBB0_720:
	s_or_b64 exec, exec, s[74:75]
	s_andn2_b64 vcc, exec, s[4:5]
	s_mov_b64 s[0:1], -1
	s_cbranch_vccnz .LBB0_685
	v_readlane_b32 s0, v254, 6
	v_readlane_b32 s1, v254, 7
	s_andn2_b64 vcc, exec, s[0:1]
	s_cbranch_vccnz .LBB0_684
	s_barrier
	s_branch .LBB0_684
.LBB0_723:
	s_waitcnt vmcnt(0)
	v_readlane_b32 s36, v254, 4
	v_readlane_b32 s6, v254, 1
	v_readlane_b32 s37, v254, 5
	v_readlane_b32 s7, v254, 2
	s_barrier
.LBB0_724:
	s_cmp_gt_i32 s37, 4
	s_cselect_b64 s[0:1], -1, 0
	s_and_b64 s[2:3], s[6:7], s[0:1]
	s_andn2_b64 vcc, exec, s[2:3]
	s_cbranch_vccnz .LBB0_778
	s_waitcnt vmcnt(0)
	s_waitcnt lgkmcnt(0)
	s_barrier
	s_mov_b64 s[2:3], exec
	v_readlane_b32 s4, v255, 9
	v_readlane_b32 s5, v255, 10
	s_and_b64 s[4:5], s[2:3], s[4:5]
	s_mov_b64 exec, s[4:5]
	s_cbranch_execz .LBB0_777
	s_add_i32 s4, 0, 0x20040
	v_mov_b32_e32 v0, s4
	s_waitcnt vmcnt(0) expcnt(0) lgkmcnt(0)
	ds_read_b32 v2, v0
	s_add_i32 s4, 0, 0x20044
	v_mov_b32_e32 v0, s4
	ds_read_b32 v0, v0
	s_waitcnt lgkmcnt(1)
	v_cmp_ne_u32_e32 vcc, 0, v2
	s_cbranch_vccnz .LBB0_741
	v_readlane_b32 s4, v255, 4
	v_readlane_b32 s5, v255, 5
	v_readlane_b32 s6, v255, 7
	s_mul_i32 s18, s5, s6
	s_mul_i32 s18, s18, s4
	s_add_u32 s4, s28, 0x1000
	s_addc_u32 s5, s29, 0
	s_add_u32 s6, s28, 0x1100
	s_addc_u32 s7, s29, 0
	s_add_u32 s8, s28, 0x1200
	s_addc_u32 s9, s29, 0
	s_add_u32 s10, s28, 0x1300
	s_addc_u32 s11, s29, 0
	s_mov_b32 s19, 1
	v_mov_b32_e32 v16, 0
	s_branch .LBB0_729

; #define PG8_STAGE(bufoff, gbase, voff) do { _Pragma("unroll") for (int _i = 0; _i < 2; ++_i) \
;         __builtin_amdgcn_global_load_lds((const unsigned*)((const char*)(gbase) + (voff)[_i]), (PG8_LAS unsigned*)(lds + (bufoff) + ldsw + _i * 8192), 16, 0, 0); } while (0)
; #define PG8_WAIT_V(n) asm volatile("s_waitcnt vmcnt(" #n ")" ::: "memory")
; #define PG8_BAR __builtin_amdgcn_s_barrier()
; template <class Epi, class Sched, bool ALIGN_EPI = false, bool SP2 = false, bool TA = true>
; __device__ __forceinline__ void gemm_phase(PG8_LAS unsigned char* lds, const Gemm g, const Sched& S, const Epi& E) {
;     ...
;     const unsigned ldsw = (unsigned)wid * 1024u;
;     const int aoff = lds_byte(wr * 64 + fr, fq * 8), boff = lds_byte(wc * 32 + fr, fq * 8);
;     ...
;         PG8_WAIT_V(2); PG8_BAR;
;         PG8_STAGE(PG8_SB(1, 0), cB + kstepB, voffB); PG8_STAGE(PG8_SA(1, 0), cA + kstep, voffA); PG8_STAGE(PG8_SB(1, 1), cB + hstep + kstepB, voffB);
;         PG8_WAIT_V(6); PG8_BAR;
.LBB0_784:
	s_add_u32 s14, s28, 0xe000000
	s_mov_b64 s[16:17], 0x4000
	s_addc_u32 s15, s29, 0
	s_add_i32 m0, s23, 0x18000
	v_lshl_add_u64 v[4:5], v[0:1], 0, s[16:17]
	s_mov_b64 s[44:45], 0x6000
	s_waitcnt vmcnt(2)
	s_barrier
	global_load_lds_dwordx4 v[4:5], off
	v_lshl_add_u64 v[4:5], v[0:1], 0, s[44:45]
	s_add_i32 m0, s23, 0x1a000
	s_add_i32 s36, s23, 0x8000
	global_load_lds_dwordx4 v[4:5], off
	v_lshl_add_u64 v[4:5], v[2:3], 0, s[16:17]
	s_mov_b32 m0, s36
	s_add_i32 s37, s23, 0xa000
	global_load_lds_dwordx4 v[4:5], off
	v_lshl_add_u64 v[2:3], v[2:3], 0, s[44:45]
	s_mov_b32 m0, s37
	s_mov_b64 s[46:47], 0x44000
	global_load_lds_dwordx4 v[2:3], off
	s_add_i32 m0, s23, 0x1c000
	v_lshl_add_u64 v[2:3], v[0:1], 0, s[46:47]
	s_mov_b64 s[48:49], 0x46000
	global_load_lds_dwordx4 v[2:3], off
	v_lshl_add_u64 v[0:1], v[0:1], 0, s[48:49]
	s_add_i32 m0, s23, 0x1e000
	v_and_b32_e32 v142, 15, v208
	global_load_lds_dwordx4 v[0:1], off
	v_and_b32_e32 v143, 48, v208
	v_lshlrev_b32_e32 v1, 2, v142
	s_lshl_b32 s39, s4, 13
	v_lshl_or_b32 v0, v142, 6, v143
	v_and_b32_e32 v2, 32, v1
	s_and_b32 s5, s5, 3
	v_bitop3_b32 v0, v0, s39, v2 bitop3:0xde
	v_lshlrev_b32_e32 v2, 6, v208
	s_movk_i32 s40, 0x3c0
	v_lshlrev_b32_e32 v3, 2, v208
	s_lshl_b32 s39, s5, 5
	s_lshl_b32 s5, s5, 12
	v_and_or_b32 v2, v2, s40, v143
	v_and_b32_e32 v4, 32, v3
	s_lshl_b32 s38, s4, 6
	v_bitop3_b32 v144, s5, v2, v4 bitop3:0xf6
	s_add_i32 s5, 0, 0x20400
	s_cmpk_lt_u32 s41, 0x100
	s_cselect_b64 s[50:51], -1, 0
	s_lshl_b32 s4, s4, 3
	s_and_b32 s42, s41, 0xffffff00
	s_bfe_u32 s41, s41, 0x10006
	s_and_b32 s4, s4, 8
	s_waitcnt vmcnt(6)
	v_add_u32_e32 v145, s5, v3
	s_add_i32 s5, s5, s42
	s_or_b32 s4, s4, s41
	v_add_u32_e32 v146, s5, v1
	s_lshl_b32 s42, s4, 10
	v_readlane_b32 s4, v255, 4
	s_add_i32 s76, 0, 0x10000
	s_add_i32 s77, 0, 0x14000
	s_mov_b32 s61, 0
	s_ashr_i32 s43, s4, 31
	s_mov_b32 s74, s4
	v_mov_b64_e32 v[132:133], 0xb00
	v_mov_b64_e32 v[134:135], 0xaff
	s_movk_i32 s75, 0x161
	v_add_u32_e32 v147, s76, v144
	v_add_u32_e32 v148, s77, v144
	v_add_u32_e32 v149, 0, v0
	v_mov_b32_e32 v150, 0x358637bd
	s_barrier
	v_readlane_b32 s5, v255, 5
	s_branch .LBB0_787

; __device__ __forceinline__ void xcd_barrier(const XcdBarrier& b) {
;     asm volatile("s_waitcnt vmcnt(0)" ::: "memory");
;     __syncthreads();
;     if (threadIdx.x == 0) {
;         unsigned* bar = b.bar;
;         __builtin_amdgcn_s_waitcnt(0);
;         unsigned nloc = b.st[0], nx = b.st[1];
;         if (nloc == 0u) { xcd_barrier_complete(bar, b.x, nloc, nx); b.st[0] = nloc; b.st[1] = nx; }
.LBB0_799:
	s_cmp_gt_i32 s37, 5
	s_cselect_b64 s[2:3], -1, 0
	s_and_b64 s[0:1], s[0:1], s[2:3]
	s_andn2_b64 vcc, exec, s[0:1]
	s_cbranch_vccnz .LBB0_853
	s_waitcnt vmcnt(0)
	s_waitcnt vmcnt(0) lgkmcnt(0)
	s_barrier
	s_mov_b64 s[0:1], exec
	v_readlane_b32 s4, v255, 9
	v_readlane_b32 s5, v255, 10
	s_and_b64 s[4:5], s[0:1], s[4:5]
	s_mov_b64 exec, s[4:5]
	s_cbranch_execz .LBB0_852
	s_add_i32 s4, 0, 0x20040
	v_mov_b32_e32 v0, s4
	s_waitcnt vmcnt(0) expcnt(0) lgkmcnt(0)
	ds_read_b32 v2, v0
	s_add_i32 s4, 0, 0x20044
	v_mov_b32_e32 v0, s4
	ds_read_b32 v0, v0
	s_waitcnt lgkmcnt(1)
	v_cmp_ne_u32_e32 vcc, 0, v2
	s_cbranch_vccnz .LBB0_816
	v_readlane_b32 s4, v255, 4
	v_readlane_b32 s5, v255, 5
	v_readlane_b32 s6, v255, 7
	s_mul_i32 s18, s5, s6
	s_mul_i32 s18, s18, s4
	s_add_u32 s4, s28, 0x1000
	s_addc_u32 s5, s29, 0
	s_add_u32 s6, s28, 0x1100
	s_addc_u32 s7, s29, 0
	s_add_u32 s8, s28, 0x1200
	s_addc_u32 s9, s29, 0
	s_add_u32 s10, s28, 0x1300
	s_addc_u32 s11, s29, 0
	s_mov_b32 s19, 1
	v_mov_b32_e32 v16, 0
	s_branch .LBB0_804

; #define PG8_STAGE(bufoff, gbase, voff) do { _Pragma("unroll") for (int _i = 0; _i < 2; ++_i) \
;         __builtin_amdgcn_global_load_lds((const unsigned*)((const char*)(gbase) + (voff)[_i]), (PG8_LAS unsigned*)(lds + (bufoff) + ldsw + _i * 8192), 16, 0, 0); } while (0)
; #define PG8_WAIT_V(n) asm volatile("s_waitcnt vmcnt(" #n ")" ::: "memory")
; #define PG8_BAR __builtin_amdgcn_s_barrier()
; template <class Epi, class Sched, bool ALIGN_EPI = false, bool SP2 = false, bool TA = true>
; __device__ __forceinline__ void gemm_phase(PG8_LAS unsigned char* lds, const Gemm g, const Sched& S, const Epi& E) {
;     ...
;     const unsigned ldsw = (unsigned)wid * 1024u;
;     const int aoff = lds_byte(wr * 64 + fr, fq * 8), boff = lds_byte(wc * 32 + fr, fq * 8);
;     ...
;         PG8_WAIT_V(2); PG8_BAR;
;         PG8_STAGE(PG8_SB(1, 0), cB + kstepB, voffB); PG8_STAGE(PG8_SA(1, 0), cA + kstep, voffA); PG8_STAGE(PG8_SB(1, 1), cB + hstep + kstepB, voffB);
;         PG8_WAIT_V(6); PG8_BAR;
.LBB0_863:
	s_mov_b64 s[46:47], 0x4000
	s_add_i32 m0, s30, 0x18000
	v_lshl_add_u64 v[4:5], v[0:1], 0, s[46:47]
	s_mov_b64 s[48:49], 0x6000
	s_waitcnt vmcnt(2)
	s_barrier
	global_load_lds_dwordx4 v[4:5], off
	v_lshl_add_u64 v[4:5], v[0:1], 0, s[48:49]
	s_add_i32 m0, s30, 0x1a000
	s_add_i32 s37, s30, 0x8000
	global_load_lds_dwordx4 v[4:5], off
	v_lshl_add_u64 v[4:5], v[2:3], 0, s[46:47]
	s_mov_b32 m0, s37
	s_add_i32 s38, s30, 0xa000
	global_load_lds_dwordx4 v[4:5], off
	v_lshl_add_u64 v[2:3], v[2:3], 0, s[48:49]
	s_mov_b32 m0, s38
	s_mov_b64 s[50:51], 0xb4000
	global_load_lds_dwordx4 v[2:3], off
	s_add_i32 m0, s30, 0x1c000
	v_lshl_add_u64 v[2:3], v[0:1], 0, s[50:51]
	s_mov_b64 s[52:53], 0xb6000
	global_load_lds_dwordx4 v[2:3], off
	v_lshl_add_u64 v[0:1], v[0:1], 0, s[52:53]
	s_add_i32 m0, s30, 0x1e000
	s_and_b32 s39, s1, 3
	global_load_lds_dwordx4 v[0:1], off
	s_lshl_b32 s40, s0, 6
	s_lshl_b32 s1, s0, 13
	s_lshl_b32 s41, s39, 5
	v_lshlrev_b32_e32 v1, 2, v146
	s_cmpk_lt_u32 s6, 0x100
	v_lshl_or_b32 v0, v146, 6, v147
	v_and_b32_e32 v1, 32, v1
	s_cselect_b64 s[54:55], -1, 0
	s_lshl_b32 s0, s0, 3
	v_bitop3_b32 v0, v0, s1, v1 bitop3:0xde
	s_waitcnt vmcnt(6)
	s_and_b32 s0, s0, 8
	s_bfe_u32 s77, s6, 0x10006
	v_lshl_or_b32 v149, s39, 12, v148
	v_readlane_b32 s56, v255, 4
	s_or_b32 s0, s0, s77
	s_add_i32 s79, 0, 0x10000
	s_add_i32 s80, 0, 0x14000
	v_add_u32_e32 v152, 0, v0
	v_mbcnt_lo_u32_b32 v0, -1, 0
	v_cmp_eq_u32_e64 s[4:5], 0, v147
	s_ashr_i32 s42, s56, 31
	s_mov_b32 s43, s56
	s_ashr_i32 s76, s20, 31
	s_lshl_b32 s78, s0, 10
	v_mov_b64_e32 v[138:139], 0x200
	v_mov_b64_e32 v[140:141], 0x1ff
	v_add_u32_e32 v150, s79, v149
	v_add_u32_e32 v151, s80, v149
	s_movk_i32 s81, 0x3c0
	v_mbcnt_hi_u32_b32 v153, -1, v0
	s_mov_b32 s82, 0
	s_barrier
	v_readlane_b32 s57, v255, 5
	s_branch .LBB0_866

; #define PG8_STAGE(bufoff, gbase, voff) do { _Pragma("unroll") for (int _i = 0; _i < 2; ++_i) \
;         __builtin_amdgcn_global_load_lds((const unsigned*)((const char*)(gbase) + (voff)[_i]), (PG8_LAS unsigned*)(lds + (bufoff) + ldsw + _i * 8192), 16, 0, 0); } while (0)
; #define PG8_WAIT_V(n) asm volatile("s_waitcnt vmcnt(" #n ")" ::: "memory")
; #define PG8_BAR __builtin_amdgcn_s_barrier()
; template <class Epi, class Sched, bool ALIGN_EPI = false, bool SP2 = false, bool TA = true>
; __device__ __forceinline__ void gemm_phase(PG8_LAS unsigned char* lds, const Gemm g, const Sched& S, const Epi& E) {
;     ...
;     const unsigned ldsw = (unsigned)wid * 1024u;
;     const int aoff = lds_byte(wr * 64 + fr, fq * 8), boff = lds_byte(wc * 32 + fr, fq * 8);
;     ...
;         PG8_WAIT_V(2); PG8_BAR;
;         PG8_STAGE(PG8_SB(1, 0), cB + kstepB, voffB); PG8_STAGE(PG8_SA(1, 0), cA + kstep, voffA); PG8_STAGE(PG8_SB(1, 1), cB + hstep + kstepB, voffB);
;         PG8_WAIT_V(6); PG8_BAR;
.LBB0_907:
	s_add_u32 s12, s28, 0x1a000000
	s_mov_b64 s[14:15], 0x4000
	s_addc_u32 s13, s29, 0
	s_add_i32 m0, s31, 0x18000
	v_lshl_add_u64 v[4:5], v[0:1], 0, s[14:15]
	s_mov_b64 s[16:17], 0x6000
	s_waitcnt vmcnt(2)
	s_barrier
	global_load_lds_dwordx4 v[4:5], off
	v_lshl_add_u64 v[4:5], v[0:1], 0, s[16:17]
	s_add_i32 m0, s31, 0x1a000
	s_add_i32 s39, s31, 0x8000
	global_load_lds_dwordx4 v[4:5], off
	v_lshl_add_u64 v[4:5], v[2:3], 0, s[14:15]
	s_mov_b32 m0, s39
	s_add_i32 s40, s31, 0xa000
	global_load_lds_dwordx4 v[4:5], off
	v_lshl_add_u64 v[2:3], v[2:3], 0, s[16:17]
	s_mov_b32 m0, s40
	s_mov_b64 s[44:45], 0x14000
	global_load_lds_dwordx4 v[2:3], off
	s_add_i32 m0, s31, 0x1c000
	v_lshl_add_u64 v[2:3], v[0:1], 0, s[44:45]
	s_mov_b64 s[46:47], 0x16000
	global_load_lds_dwordx4 v[2:3], off
	v_lshl_add_u64 v[0:1], v[0:1], 0, s[46:47]
	s_add_i32 m0, s31, 0x1e000
	s_sext_i32_i8 s59, s2
	global_load_lds_dwordx4 v[0:1], off
	v_lshlrev_b32_e32 v1, 2, v146
	s_and_b32 s2, s41, 3
	s_lshl_b32 s42, s50, 13
	v_lshl_or_b32 v0, v146, 6, v147
	v_and_b32_e32 v1, 32, v1
	s_lshl_b32 s41, s50, 6
	v_bitop3_b32 v0, v0, s42, v1 bitop3:0xde
	s_lshl_b32 s42, s2, 5
	s_cmpk_lt_u32 s3, 0x100
	v_lshl_or_b32 v136, s2, 12, v148
	s_cselect_b64 s[48:49], -1, 0
	s_lshl_b32 s2, s50, 3
	s_bfe_u32 s43, s3, 0x10006
	s_and_b32 s2, s2, 8
	s_waitcnt vmcnt(6)
	s_or_b32 s2, s2, s43
	s_lshl_b32 s80, s2, 10
	v_readlane_b32 s2, v255, 4
	s_add_i32 s83, 0, 0x10000
	s_add_i32 s84, 0, 0x14000
	s_ashr_i32 s81, s2, 31
	s_mov_b32 s82, s2
	v_mov_b64_e32 v[130:131], 0x200
	v_mov_b64_e32 v[132:133], 0x1ff
	v_add_u32_e32 v137, s83, v136
	v_add_u32_e32 v138, s84, v136
	v_add_u32_e32 v139, 0, v0
	s_movk_i32 s85, 0x3c0
	s_barrier
	v_readlane_b32 s3, v255, 5
	s_branch .LBB0_910

; __device__ __forceinline__ void xcd_barrier(const XcdBarrier& b) {
;     asm volatile("s_waitcnt vmcnt(0)" ::: "memory");
;     __syncthreads();
;     if (threadIdx.x == 0) {
;         unsigned* bar = b.bar;
;         __builtin_amdgcn_s_waitcnt(0);
;         unsigned nloc = b.st[0], nx = b.st[1];
;         if (nloc == 0u) { xcd_barrier_complete(bar, b.x, nloc, nx); b.st[0] = nloc; b.st[1] = nx; }
.LBB0_924:
	s_cmp_gt_i32 s37, 6
	s_cselect_b64 s[0:1], -1, 0
	s_and_b64 s[2:3], s[8:9], s[0:1]
	s_andn2_b64 vcc, exec, s[2:3]
	s_cbranch_vccnz .LBB0_978
	s_waitcnt vmcnt(0)
	s_waitcnt vmcnt(0) lgkmcnt(0)
	s_barrier
	s_mov_b64 s[2:3], exec
	v_readlane_b32 s4, v255, 9
	v_readlane_b32 s5, v255, 10
	s_and_b64 s[4:5], s[2:3], s[4:5]
	s_mov_b64 exec, s[4:5]
	s_cbranch_execz .LBB0_977
	s_add_i32 s4, 0, 0x20040
	v_mov_b32_e32 v0, s4
	s_waitcnt vmcnt(0) expcnt(0) lgkmcnt(0)
	ds_read_b32 v2, v0
	s_add_i32 s4, 0, 0x20044
	v_mov_b32_e32 v0, s4
	ds_read_b32 v0, v0
	s_waitcnt lgkmcnt(1)
	v_cmp_ne_u32_e32 vcc, 0, v2
	s_cbranch_vccnz .LBB0_941
	v_readlane_b32 s4, v255, 4
	v_readlane_b32 s5, v255, 5
	v_readlane_b32 s6, v255, 7
	s_mul_i32 s18, s5, s6
	s_mul_i32 s18, s18, s4
	s_add_u32 s4, s28, 0x1000
	s_addc_u32 s5, s29, 0
	s_add_u32 s6, s28, 0x1100
	s_addc_u32 s7, s29, 0
	s_add_u32 s8, s28, 0x1200
	s_addc_u32 s9, s29, 0
	s_add_u32 s10, s28, 0x1300
	s_addc_u32 s11, s29, 0
	s_mov_b32 s19, 1
	v_mov_b32_e32 v16, 0
	s_branch .LBB0_929

; #define PG8_STAGE(bufoff, gbase, voff) do { _Pragma("unroll") for (int _i = 0; _i < 2; ++_i) \
;         __builtin_amdgcn_global_load_lds((const unsigned*)((const char*)(gbase) + (voff)[_i]), (PG8_LAS unsigned*)(lds + (bufoff) + ldsw + _i * 8192), 16, 0, 0); } while (0)
; #define PG8_WAIT_V(n) asm volatile("s_waitcnt vmcnt(" #n ")" ::: "memory")
; #define PG8_BAR __builtin_amdgcn_s_barrier()
; template <class Epi, class Sched, bool ALIGN_EPI = false, bool SP2 = false, bool TA = true>
; __device__ __forceinline__ void gemm_phase(PG8_LAS unsigned char* lds, const Gemm g, const Sched& S, const Epi& E) {
;     ...
;     const unsigned ldsw = (unsigned)wid * 1024u;
;     const int aoff = lds_byte(wr * 64 + fr, fq * 8), boff = lds_byte(wc * 32 + fr, fq * 8);
;     ...
;         PG8_WAIT_V(2); PG8_BAR;
;         PG8_STAGE(PG8_SB(1, 0), cB + kstepB, voffB); PG8_STAGE(PG8_SA(1, 0), cA + kstep, voffA); PG8_STAGE(PG8_SB(1, 1), cB + hstep + kstepB, voffB);
;         PG8_WAIT_V(6); PG8_BAR;
.LBB0_990:
	s_add_u32 s48, s28, 0x1a000000
	s_mov_b64 s[50:51], 0x4000
	s_addc_u32 s49, s29, 0
	s_add_i32 m0, s95, 0x18000
	v_lshl_add_u64 v[4:5], v[0:1], 0, s[50:51]
	s_mov_b64 s[52:53], 0x6000
	s_waitcnt vmcnt(2)
	s_barrier
	global_load_lds_dwordx4 v[4:5], off
	v_lshl_add_u64 v[4:5], v[0:1], 0, s[52:53]
	s_add_i32 m0, s95, 0x1a000
	s_add_i32 s18, s95, 0x8000
	global_load_lds_dwordx4 v[4:5], off
	v_lshl_add_u64 v[4:5], v[2:3], 0, s[50:51]
	s_mov_b32 m0, s18
	s_add_i32 s19, s95, 0xa000
	global_load_lds_dwordx4 v[4:5], off
	v_lshl_add_u64 v[2:3], v[2:3], 0, s[52:53]
	s_mov_b32 m0, s19
	s_mov_b64 s[54:55], 0x44000
	global_load_lds_dwordx4 v[2:3], off
	s_add_i32 m0, s95, 0x1c000
	v_lshl_add_u64 v[2:3], v[0:1], 0, s[54:55]
	s_mov_b64 s[56:57], 0x46000
	global_load_lds_dwordx4 v[2:3], off
	v_lshl_add_u64 v[0:1], v[0:1], 0, s[56:57]
	s_add_i32 m0, s95, 0x1e000
	v_and_b32_e32 v158, 15, v208
	global_load_lds_dwordx4 v[0:1], off
	v_and_b32_e32 v1, 48, v208
	v_lshlrev_b32_e32 v3, 2, v158
	s_and_b32 s21, s5, 3
	s_lshl_b32 s5, s4, 13
	v_lshl_or_b32 v2, v158, 6, v1
	v_and_b32_e32 v4, 32, v3
	v_bitop3_b32 v2, v2, s5, v4 bitop3:0xde
	v_lshlrev_b32_e32 v4, 6, v208
	s_movk_i32 s36, 0x3c0
	v_and_or_b32 v1, v4, s36, v1
	v_lshlrev_b32_e32 v4, 2, v208
	s_lshl_b32 s5, s21, 12
	v_and_b32_e32 v5, 32, v4
	v_bitop3_b32 v159, s5, v1, v5 bitop3:0xf6
	s_lshl_b32 s5, s4, 8
	s_add_i32 s7, 0, 0x20400
	s_lshl_b32 s30, s4, 6
	s_lshl_b32 s31, s21, 5
	s_add_i32 s22, s7, s5
	s_cmpk_lt_u32 s6, 0x100
	s_cselect_b64 s[58:59], -1, 0
	s_lshl_b32 s4, s4, 3
	s_and_b32 s4, s4, 8
	s_bfe_u32 s37, s6, 0x10006
	v_bfe_u32 v0, v208, 4, 2
	s_waitcnt vmcnt(6)
	s_or_b32 s4, s4, s37
	v_add_u32_e32 v160, s7, v4
	v_lshlrev_b32_e32 v161, 4, v0
	s_lshl_b32 s38, s4, 10
	v_cmp_eq_u32_e64 s[4:5], 0, v0
	v_readlane_b32 s6, v255, 4
	s_add_i32 s42, 0, 0x10000
	s_add_i32 s43, 0, 0x14000
	v_mbcnt_lo_u32_b32 v0, -1, 0
	s_ashr_i32 s39, s6, 31
	s_mov_b32 s40, s6
	s_ashr_i32 s41, s20, 31
	v_add_u32_e32 v162, s22, v3
	v_mov_b64_e32 v[148:149], 0x200
	v_mov_b64_e32 v[150:151], 0x1ff
	v_add_u32_e32 v163, s42, v159
	v_add_u32_e32 v164, s43, v159
	v_add_u32_e32 v165, 0, v2
	v_mbcnt_hi_u32_b32 v166, -1, v0
	v_mov_b32_e32 v167, 0x358637bd
	s_mov_b32 s23, 0
	s_barrier
	v_readlane_b32 s7, v255, 5
	s_branch .LBB0_993

; __device__ __forceinline__ void xcd_barrier(const XcdBarrier& b) {
;     asm volatile("s_waitcnt vmcnt(0)" ::: "memory");
;     __syncthreads();
;     if (threadIdx.x == 0) {
;         unsigned* bar = b.bar;
;         __builtin_amdgcn_s_waitcnt(0);
;         unsigned nloc = b.st[0], nx = b.st[1];
;         if (nloc == 0u) { xcd_barrier_complete(bar, b.x, nloc, nx); b.st[0] = nloc; b.st[1] = nx; }
.LBB0_1025:
	s_cmp_gt_i32 s37, 7
	s_cselect_b64 s[2:3], -1, 0
	s_and_b64 s[0:1], s[0:1], s[2:3]
	s_andn2_b64 vcc, exec, s[0:1]
	s_cbranch_vccnz .LBB0_1079
	s_waitcnt vmcnt(0)
	s_waitcnt vmcnt(0) lgkmcnt(0)
	s_barrier
	s_mov_b64 s[0:1], exec
	v_readlane_b32 s4, v255, 9
	v_readlane_b32 s5, v255, 10
	s_and_b64 s[4:5], s[0:1], s[4:5]
	s_mov_b64 exec, s[4:5]
	s_cbranch_execz .LBB0_1078
	s_add_i32 s4, 0, 0x20040
	v_mov_b32_e32 v0, s4
	s_waitcnt vmcnt(0) expcnt(0) lgkmcnt(0)
	ds_read_b32 v2, v0
	s_add_i32 s4, 0, 0x20044
	v_mov_b32_e32 v0, s4
	ds_read_b32 v0, v0
	s_waitcnt lgkmcnt(1)
	v_cmp_ne_u32_e32 vcc, 0, v2
	s_cbranch_vccnz .LBB0_1042
	v_readlane_b32 s4, v255, 4
	v_readlane_b32 s5, v255, 5
	v_readlane_b32 s6, v255, 7
	s_mul_i32 s18, s5, s6
	s_mul_i32 s18, s18, s4
	s_add_u32 s4, s28, 0x1000
	s_addc_u32 s5, s29, 0
	s_add_u32 s6, s28, 0x1100
	s_addc_u32 s7, s29, 0
	s_add_u32 s12, s28, 0x1200
	s_addc_u32 s13, s29, 0
	s_add_u32 s14, s28, 0x1300
	s_addc_u32 s15, s29, 0
	s_mov_b32 s19, 1
	v_mov_b32_e32 v16, 0
	s_branch .LBB0_1030

; __device__ __forceinline__ unsigned xb_add(unsigned* p, unsigned v) { return __hip_atomic_fetch_add(p, v, __ATOMIC_RELAXED, __HIP_MEMORY_SCOPE_AGENT); }
; __device__ __forceinline__ void xcd_barrier(const XcdBarrier& b) {
;     ...
;         const unsigned old = xb_add(&bar[XB_XSUB(b.x)], 1u);
;         const unsigned gen = old / nloc;
;         if (old + 1u == (gen + 1u) * nloc) {
.LBB0_1042:
	s_mov_b64 s[6:7], exec
	v_readlane_b32 s4, v255, 8
	s_lshl_b32 s4, s4, 8
	v_mbcnt_lo_u32_b32 v1, s6, 0
	s_add_u32 s4, s28, s4
	v_mbcnt_hi_u32_b32 v1, s7, v1
	s_addc_u32 s5, s29, 0
	v_cmp_eq_u32_e32 vcc, 0, v1
	s_and_saveexec_b64 s[12:13], vcc
	s_cbranch_execz .LBB0_1044
	s_bcnt1_i32_b64 s6, s[6:7]
	v_mov_b32_e32 v3, 0x1000
	v_mov_b32_e32 v4, s6
	global_atomic_add v3, v3, v4, s[4:5] offset:1024 sc0

; #define PG8_STAGE(bufoff, gbase, voff) do { _Pragma("unroll") for (int _i = 0; _i < 2; ++_i) \
;         __builtin_amdgcn_global_load_lds((const unsigned*)((const char*)(gbase) + (voff)[_i]), (PG8_LAS unsigned*)(lds + (bufoff) + ldsw + _i * 8192), 16, 0, 0); } while (0)
; #define PG8_WAIT_V(n) asm volatile("s_waitcnt vmcnt(" #n ")" ::: "memory")
; #define PG8_BAR __builtin_amdgcn_s_barrier()
; template <class Epi, class Sched, bool ALIGN_EPI = false, bool SP2 = false, bool TA = true>
; __device__ __forceinline__ void gemm_phase(PG8_LAS unsigned char* lds, const Gemm g, const Sched& S, const Epi& E) {
;     ...
;     const unsigned ldsw = (unsigned)wid * 1024u;
;     const int aoff = lds_byte(wr * 64 + fr, fq * 8), boff = lds_byte(wc * 32 + fr, fq * 8);
;     ...
;         PG8_WAIT_V(2); PG8_BAR;
;         PG8_STAGE(PG8_SB(1, 0), cB + kstepB, voffB); PG8_STAGE(PG8_SA(1, 0), cA + kstep, voffA); PG8_STAGE(PG8_SB(1, 1), cB + hstep + kstepB, voffB);
;         PG8_WAIT_V(6); PG8_BAR;
.LBB0_1087:
	s_mov_b64 s[44:45], 0x4000
	s_add_i32 m0, s22, 0x18000
	v_lshl_add_u64 v[4:5], v[0:1], 0, s[44:45]
	s_mov_b64 s[46:47], 0x6000
	s_waitcnt vmcnt(2)
	s_barrier
	global_load_lds_dwordx4 v[4:5], off
	v_lshl_add_u64 v[4:5], v[0:1], 0, s[46:47]
	s_add_i32 m0, s22, 0x1a000
	s_add_i32 s33, s22, 0x8000
	global_load_lds_dwordx4 v[4:5], off
	v_lshl_add_u64 v[4:5], v[2:3], 0, s[44:45]
	s_mov_b32 m0, s33
	s_add_i32 s36, s22, 0xa000
	global_load_lds_dwordx4 v[4:5], off
	v_lshl_add_u64 v[2:3], v[2:3], 0, s[46:47]
	s_mov_b32 m0, s36
	s_mov_b64 s[48:49], 0x44000
	global_load_lds_dwordx4 v[2:3], off
	s_add_i32 m0, s22, 0x1c000
	v_lshl_add_u64 v[2:3], v[0:1], 0, s[48:49]
	s_mov_b64 s[50:51], 0x46000
	global_load_lds_dwordx4 v[2:3], off
	v_lshl_add_u64 v[0:1], v[0:1], 0, s[50:51]
	s_add_i32 m0, s22, 0x1e000
	v_and_b32_e32 v145, 15, v208
	global_load_lds_dwordx4 v[0:1], off
	v_lshlrev_b32_e32 v0, 2, v145
	v_lshlrev_b32_e32 v142, 6, v145
	s_and_b32 s37, s5, 3
	s_lshl_b32 s38, s4, 6
	s_lshl_b32 s4, s4, 13
	v_and_b32_e32 v1, 32, v0
	v_and_or_b32 v3, v208, 48, v142
	v_bitop3_b32 v4, v3, s4, v1 bitop3:0xde
	s_lshl_b32 s4, s37, 12
	s_add_i32 s5, 0, 0x20400
	s_cmpk_lt_u32 s39, 0x100
	v_readlane_b32 s40, v255, 4
	v_lshlrev_b32_e32 v1, 2, v208
	s_cselect_b64 s[52:53], -1, 0
	s_and_b32 s39, s39, 0xffffff00
	v_readlane_b32 s41, v255, 5
	v_and_b32_e32 v5, 32, v1
	v_add_u32_e32 v149, s5, v1
	s_add_i32 s5, s5, s39
	s_ashr_i32 s39, s40, 31
	s_ashr_i32 s41, s20, 31
	v_bitop3_b32 v147, s4, v3, v5 bitop3:0xf6
	s_add_u32 s4, s28, s4
	v_bfe_u32 v2, v208, 4, 2
	v_add_u32_e32 v188, s5, v0
	s_addc_u32 s5, s29, 0
	v_lshl_add_u64 v[0:1], s[4:5], 0, v[142:143]
	v_lshlrev_b32_e32 v142, 4, v2
	s_waitcnt vmcnt(6)
	v_lshl_add_u64 v[0:1], v[0:1], 0, v[142:143]
	s_mov_b64 s[4:5], 0x16000000
	v_lshlrev_b32_e32 v144, 3, v2
	v_lshl_add_u64 v[150:151], v[0:1], 0, s[4:5]
	s_add_i32 s43, 0, 0x10000
	s_add_i32 s74, 0, 0x14000
	v_mbcnt_lo_u32_b32 v0, -1, 0
	v_lshlrev_b32_e32 v146, 9, v2
	v_lshlrev_b32_e32 v148, 3, v145
	v_mov_b64_e32 v[152:153], 0x600
	v_mov_b64_e32 v[154:155], 0x5ff
	s_movk_i32 s42, 0xc1
	v_add_u32_e32 v189, s43, v147
	v_add_u32_e32 v190, s74, v147
	v_add_u32_e32 v191, 0, v4
	s_mov_b32 s75, 0xe000000
	v_lshlrev_b32_e32 v192, 2, v144
	v_mov_b32_e32 v193, 0x358637bd
	v_mov_b32_e32 v194, 0x3e38aa3b
	v_mbcnt_hi_u32_b32 v195, -1, v0
	s_barrier
	s_branch .LBB0_1090

; __device__ __forceinline__ unsigned cvt_pk_bf16(float lo, float hi) { unsigned r; asm volatile("v_cvt_pk_bf16_f32 %0, %1, %2" : "=v"(r) : "v"(lo), "v"(hi)); return r; }
;     __device__ __forceinline__ void operator()(const f32x4 (&acc)[2][2][4][2], const Unit& u, int wr, int wc, int fr, int fq, const PG8_LAS float* rtab) const {
;     ...
;             bf16_t* O = sec == 0 ? Q : K; const float* g = sec == 0 ? qg : kg; const float sc = sec == 0 ? c2 : 1.0f;
;             f32x4 gv[2][2];
; #pragma unroll
;             for (int bj = 0; bj < 2; ++bj)
; #pragma unroll
;                 for (int n = 0; n < 2; ++n) gv[bj][n] = *(const f32x4*)(g + 32 * bj + 8 * fq + 4 * n) * sc;
;             const int lcol = 64 * (4 * pt + wc) + 8 * fq;
; #pragma unroll
;             for (int ai = 0; ai < 2; ++ai)
; #pragma unroll
;                 for (int m = 0; m < 4; ++m) { const float r = rs[ai][m]; float ssq = 0.f;
; #pragma unroll
;                     for (int bj = 0; bj < 2; ++bj)
; #pragma unroll
;                         for (int n = 0; n < 2; ++n) { const f32x4 a = acc[ai][bj][m][n]; ssq += (a[0] * a[0] + a[1] * a[1]) + (a[2] * a[2] + a[3] * a[3]); }
;                     ssq += __shfl_xor(ssq, 16); ssq += __shfl_xor(ssq, 32);
;                     const float s = r * __builtin_amdgcn_rsqf(r * r * ssq * (1.0f / 64.0f) + 1e-6f);
; #pragma unroll
;                     for (int bj = 0; bj < 2; ++bj) { const f32x4 v0 = acc[ai][bj][m][0] * s * gv[bj][0], v1 = acc[ai][bj][m][1] * s * gv[bj][1];
;                         u32x4 w; w.x = cvt_pk_bf16(v0[0], v0[1]); w.y = cvt_pk_bf16(v0[2], v0[3]); w.z = cvt_pk_bf16(v1[0], v1[1]); w.w = cvt_pk_bf16(v1[2], v1[3]);
;                         const int row = row0 + ai * HALF + m * 16;
;                         if (sec == 0) *(u32x4*)(O + (size_t)row * 1024 + lcol + 32 * bj) = w;
;                         else { const int b_ = row >> 13, s_ = row & 8191; *(u32x4*)(O + ((size_t)((b_ * 16 + 4 * pt + wc) * 128 + (s_ >> 6))) * 4096 + (4 * bj + fq) * 512 + (s_ & 63) * 8) = w; } } }
.LBB0_1099:
	s_cmp_gt_u32 s6, 3
	s_cselect_b64 s[72:73], -1, 0
	s_cmp_lt_u32 s6, 4
	v_readlane_b32 s80, v255, 27
	s_cselect_b64 vcc, -1, 0
	v_readlane_b32 s90, v255, 37
	v_readlane_b32 s91, v255, 38
	v_readlane_b32 s92, v255, 39
	v_readlane_b32 s93, v255, 40
	s_and_b64 s[6:7], vcc, exec
	v_readlane_b32 s94, v255, 41
	v_readlane_b32 s95, v255, 42
	s_mov_b64 s[64:65], s[92:93]
	s_mov_b64 s[62:63], s[90:91]
	s_cselect_b32 s7, s63, s65
	s_cselect_b32 s6, s62, s64
	global_load_dwordx4 v[136:139], v192, s[6:7]
	global_load_dwordx4 v[166:169], v192, s[6:7] offset:16
	global_load_dwordx4 v[128:131], v192, s[6:7] offset:144
	global_load_dwordx4 v[132:135], v192, s[6:7] offset:128
	v_pk_mul_f32 v[170:171], v[126:127], v[126:127]
	v_pk_mul_f32 v[172:173], v[124:125], v[124:125]
	v_pk_mul_f32 v[174:175], v[122:123], v[122:123]
	v_pk_mul_f32 v[176:177], v[120:121], v[120:121]
	v_pk_mov_b32 v[184:185], v[172:173], v[170:171] op_sel:[1,0]
	v_mov_b32_e32 v173, v171
	v_pk_mov_b32 v[170:171], v[176:177], v[174:175] op_sel:[1,0]
	v_mov_b32_e32 v177, v175
	v_mul_f32_e32 v142, v117, v117
	v_mul_f32_e32 v182, v119, v119
	v_pk_add_f32 v[172:173], v[184:185], v[172:173]
	v_pk_add_f32 v[170:171], v[170:171], v[176:177]
	v_and_b32_e32 v181, 64, v195
	v_mul_f32_e32 v187, v108, v108
	v_mul_f32_e32 v198, v109, v109
	v_mul_f32_e32 v196, v110, v110
	v_mul_f32_e32 v197, v111, v111
	v_pk_fma_f32 v[174:175], v[116:117], v[116:117], v[142:143] op_sel_hi:[1,1,0]
	v_pk_fma_f32 v[182:183], v[118:119], v[118:119], v[182:183] op_sel_hi:[1,1,0]
	v_pk_add_f32 v[172:173], v[172:173], v[172:173] op_sel:[0,1] op_sel_hi:[1,0]
	v_pk_add_f32 v[170:171], v[170:171], v[170:171] op_sel:[0,1] op_sel_hi:[1,0]
	v_xor_b32_e32 v161, 16, v195
	v_add_u32_e32 v181, 64, v181
	v_mov_b32_e32 v175, v196
	v_mov_b32_e32 v183, v197
	v_mov_b32_e32 v173, v187
	v_mov_b32_e32 v171, v198
	v_cndmask_b32_e32 v180, 1.0, v194, vcc
	v_xor_b32_e32 v186, 32, v195
	v_cmp_lt_i32_e32 vcc, v161, v181
	v_pk_add_f32 v[174:175], v[174:175], v[182:183]
	v_pk_add_f32 v[170:171], v[172:173], v[170:171]
	v_cndmask_b32_e32 v142, v195, v161, vcc
	v_cmp_lt_i32_e32 vcc, v186, v181
	v_pk_add_f32 v[170:171], v[170:171], v[174:175]
	v_lshlrev_b32_e32 v197, 2, v142
	v_cndmask_b32_e32 v161, v195, v186, vcc
	v_add_f32_e32 v142, v170, v171
	v_lshlrev_b32_e32 v196, 2, v161
	ds_bpermute_b32 v161, v197, v142
	s_cselect_b32 s6, s75, 0x12000000
	s_waitcnt lgkmcnt(0)
	v_mul_f32_e32 v199, v164, v164
	s_add_u32 s68, s28, s6
	s_addc_u32 s69, s29, 0
	v_add_f32_e32 v142, v142, v161
	ds_bpermute_b32 v161, v196, v142
	s_lshl_b32 s77, s57, 2
	s_ashr_i32 s6, s55, 9
	s_or_b32 s78, s77, s37
	s_and_b32 s6, s6, 0x1fffff0
	s_waitcnt lgkmcnt(0)
	v_add_f32_e32 v142, v142, v161
	v_mul_f32_e32 v142, v199, v142
	v_fmamk_f32 v142, v142, 0x3c800000, v193
	s_or_b32 s6, s78, s6
	v_rsq_f32_e32 v142, v142
	s_bfe_u32 s7, s55, 0x70006
	s_lshl_b32 s6, s6, 7
	s_or_b32 s6, s6, s7
	s_ashr_i32 s7, s6, 31
	s_lshl_b64 s[6:7], s[6:7], 13
	v_mul_f32_e32 v184, v164, v142
	s_add_u32 s70, s68, s6
	v_pk_mul_f32 v[172:173], v[124:125], v[184:185] op_sel_hi:[1,0]
	v_pk_mul_f32 v[186:187], v[126:127], v[184:185] op_sel_hi:[1,0]
	v_pk_mul_f32 v[200:201], v[122:123], v[184:185] op_sel_hi:[1,0]
	v_lshlrev_b32_e32 v178, 1, v148
	v_mov_b32_e32 v179, v143
	s_addc_u32 s71, s69, s7
	v_pk_mul_f32 v[198:199], v[120:121], v[184:185] op_sel_hi:[1,0]
	v_lshl_add_u64 v[182:183], s[70:71], 0, v[178:179]
	s_mov_b64 s[6:7], -1
	s_and_b64 vcc, exec, s[72:73]
	v_readlane_b32 s81, v255, 28
	v_readlane_b32 s82, v255, 29
	v_readlane_b32 s83, v255, 30
	v_readlane_b32 s84, v255, 31
	v_readlane_b32 s85, v255, 32
	s_waitcnt vmcnt(0)
	v_pk_mul_f32 v[174:175], v[180:181], v[138:139] op_sel_hi:[0,1]
	v_pk_mul_f32 v[176:177], v[180:181], v[136:137] op_sel_hi:[0,1]
	v_pk_mul_f32 v[168:169], v[180:181], v[168:169] op_sel_hi:[0,1]
	v_pk_mul_f32 v[170:171], v[180:181], v[166:167] op_sel_hi:[0,1]
	v_pk_mul_f32 v[138:139], v[174:175], v[186:187]
	v_pk_mul_f32 v[136:137], v[176:177], v[172:173]
	v_pk_mul_f32 v[166:167], v[168:169], v[200:201]
	v_pk_mul_f32 v[172:173], v[170:171], v[198:199]
	v_cvt_pk_bf16_f32 v136, v136, v137
	v_cvt_pk_bf16_f32 v137, v138, v139
	v_readlane_b32 s86, v255, 33
	v_cvt_pk_bf16_f32 v138, v172, v173
	v_cvt_pk_bf16_f32 v139, v166, v167
	v_lshlrev_b32_e32 v166, 1, v146
	v_readlane_b32 s87, v255, 34
	v_readlane_b32 s88, v255, 35
	v_readlane_b32 s89, v255, 36
	s_mov_b64 s[66:67], s[94:95]
	s_cbranch_vccz .LBB0_1101
	v_mov_b32_e32 v167, v143
	v_lshl_add_u64 v[172:173], v[182:183], 0, v[166:167]
	global_store_dwordx4 v[172:173], v[136:139], off
	s_mov_b64 s[6:7], 0

; __device__ __forceinline__ void xcd_barrier(const XcdBarrier& b) {
;     asm volatile("s_waitcnt vmcnt(0)" ::: "memory");
;     __syncthreads();
;     if (threadIdx.x == 0) {
;         unsigned* bar = b.bar;
;         __builtin_amdgcn_s_waitcnt(0);
;         unsigned nloc = b.st[0], nx = b.st[1];
;         if (nloc == 0u) { xcd_barrier_complete(bar, b.x, nloc, nx); b.st[0] = nloc; b.st[1] = nx; }
.LBB0_1170:
	s_cmp_gt_i32 s37, 8
	s_cselect_b64 s[2:3], -1, 0
	s_and_b64 s[0:1], s[0:1], s[2:3]
	s_andn2_b64 vcc, exec, s[0:1]
	s_cbranch_vccnz .LBB0_1224
	s_waitcnt vmcnt(0)
	s_waitcnt vmcnt(0) lgkmcnt(0)
	s_barrier
	s_mov_b64 s[0:1], exec
	v_readlane_b32 s4, v255, 9
	v_readlane_b32 s5, v255, 10
	s_and_b64 s[4:5], s[0:1], s[4:5]
	s_mov_b64 exec, s[4:5]
	s_cbranch_execz .LBB0_1223
	s_add_i32 s4, 0, 0x20040
	v_mov_b32_e32 v0, s4
	s_waitcnt vmcnt(0) expcnt(0) lgkmcnt(0)
	ds_read_b32 v2, v0
	s_add_i32 s4, 0, 0x20044
	v_mov_b32_e32 v0, s4
	ds_read_b32 v0, v0
	s_waitcnt lgkmcnt(1)
	v_cmp_ne_u32_e32 vcc, 0, v2
	s_cbranch_vccnz .LBB0_1187
	v_readlane_b32 s4, v255, 4
	v_readlane_b32 s5, v255, 5
	v_readlane_b32 s6, v255, 7
	s_mul_i32 s18, s5, s6
	s_mul_i32 s18, s18, s4
	s_add_u32 s4, s28, 0x1000
	s_addc_u32 s5, s29, 0
	s_add_u32 s6, s28, 0x1100
	s_addc_u32 s7, s29, 0
	s_add_u32 s12, s28, 0x1200
	s_addc_u32 s13, s29, 0
	s_add_u32 s14, s28, 0x1300
	s_addc_u32 s15, s29, 0
	s_mov_b32 s19, 1
	v_mov_b32_e32 v16, 0
	s_branch .LBB0_1175

; #define LAS __attribute__((address_space(3)))
; __global__ void __launch_bounds__(NWAVES * 64, 2) mega_fwd(Args args) {
;     ...
;         __syncthreads();
;         { const float* bt = (const float*)(ws + WS_BT) + ((vcu >> 3) & 7) * 128; LAS float* dst = (LAS float*)(lds + attn_body::LDS_BIAS);
;           for (int i = tid; i < 1024; i += NWAVES * 64) { const int d = i - 256; dst[i] = d < 0 ? -__builtin_inff() : bt[d > 127 ? 127 : d]; } }
;         asm volatile("s_waitcnt vmcnt(0) lgkmcnt(0)" ::: "memory"); __syncthreads();
.LBB0_1224:
	s_cmp_lt_i32 s36, 9
	s_cselect_b64 s[0:1], -1, 0
	s_and_b64 s[4:5], s[0:1], s[2:3]
	s_andn2_b64 vcc, exec, s[4:5]
	s_cbranch_vccnz .LBB0_1462
	v_readlane_b32 s0, v255, 6
	s_lshl_b32 s0, s0, 6
	s_and_b32 s0, s0, 0xe00
	s_add_u32 s0, s28, s0
	v_lshl_add_u32 v0, v208, 2, 0
	s_addc_u32 s1, s29, 0
	v_add_u32_e32 v2, 0x1a800, v0
	s_mov_b64 s[2:3], 0
	s_movk_i32 s12, 0xff
	s_waitcnt lgkmcnt(0)
	v_mov_b32_e32 v1, 0
	s_movk_i32 s13, 0x1ff
	v_mov_b32_e32 v3, v208
	s_waitcnt vmcnt(0)
	s_barrier
	s_branch .LBB0_1227

;   #define DMA_K(t,slot) glds16(ksrc+(long)(t)*4096,(unsigned)__builtin_amdgcn_readfirstlane(kdst+(slot)))
;   #define DMA_V(t,slot) do{ glds16(vsrc+(long)(t)*8192,(unsigned)__builtin_amdgcn_readfirstlane(vdst+2*(slot))); glds16(vsrc+(long)(t)*8192+4096,(unsigned)__builtin_amdgcn_readfirstlane(vdst+2*(slot)+8192)); }while(0)
; template<int THRL> __device__ __forceinline__ void attn_unit(int b,int hc,int qb,const bf16*Q,const bf16*__restrict__ K,const bf16*__restrict__ V,bf16*O,char*shm){
;   const int tid=threadIdx.x,lane=tid&63,r32=lane&31,hi=lane>>5; const int wid=__builtin_amdgcn_readfirstlane(tid>>6);
;   const long rowbase=(long)b*SEQ; const int q0=qb*QB;
;   const bf16*Qw=Q+(rowbase+q0+wid*QBLK)*DM+hc*D;
;   const lds_cfptr btab=(lds_cfptr)((lds_cptr)shm+LDS_BIAS);
;   const unsigned lds0=(unsigned)(uintptr_t)shm;
;   float*wsf=(float*)(shm+LDS_WS)+wid*64;
;   const bf16*ksrc=K+(long)((b*16+hc)*128)*4096+wid*512+lane*8;
;   const bf16*vsrc=V+(long)((b*8+(hc>>1))*128)*8192+wid*512+lane*8;
;   const unsigned kdst=lds0+LDS_K+wid*1024, vdst=lds0+LDS_V+wid*1024;
;     ...
;   const int vb0=(int)(lds0+LDS_V)+((lane>>4)&1)*32+(lane&3)*8+(4*hi+((lane&15)>>2))*64;
;   const char*Kbase=shm+LDS_K; bf16x8 kf[8];
;   const lds_cptr shm3=(lds_cptr)shm; const lds_cptr kp0=shm3+LDS_K+hi*1024+r32*16; const lds_cptr vp0=shm3+LDS_V+((lane>>4)&1)*32+(lane&3)*8+(4*hi+((lane&15)>>2))*64;
;   const int NT=(q0+QB)/KVBLK;
;   DMA_K(0,0);DMA_V(0,0);DMA_K(1,SLOTB);
;   bf16x8 qr[4];
;   #pragma unroll
;   for(int d0=0;d0<4;++d0)qr[d0]=*reinterpret_cast<const bf16x8*>(&Qw[(long)r32*DM+d0*16+hi*8]);
;   float mhat=0.f,l_reg=0.f;f32x16 o[4];o[0]=f32x16{};o[1]=f32x16{};o[2]=f32x16{};o[3]=f32x16{};
;   const f32x16 zero16=f32x16{};
;   const int qrel=wid*QBLK+r32;
.LBB0_1229:
	s_or_b64 exec, exec, s[2:3]
	s_add_u32 s33, s28, 0xe000000
	s_addc_u32 s58, s29, 0
	s_add_u32 s59, s28, 0x12000000
	s_addc_u32 s60, s29, 0
	s_add_u32 s61, s28, 0x16000000
	s_addc_u32 s62, s29, 0
	s_add_u32 s6, s28, 0x1a000000
	s_addc_u32 s7, s29, 0
	v_readlane_b32 s2, v255, 4
	s_ashr_i32 s1, s20, 31
	s_ashr_i32 s0, s2, 31
	s_lshr_b32 s1, s1, 29
	s_lshr_b32 s0, s0, 29
	s_add_i32 s1, s20, s1
	s_add_i32 s0, s2, s0
	s_and_b32 s2, s1, -8
	s_ashr_i32 s0, s0, 3
	s_sub_i32 s2, s20, s2
	s_mul_i32 s0, s0, s2
	s_ashr_i32 s1, s1, 3
	s_add_i32 s0, s0, s1
	s_and_b32 s63, s0, 7
	s_ashr_i32 s1, s0, 2
	s_lshr_b32 s0, s0, 2
	s_and_b32 s1, s1, -16
	s_and_b32 s0, s0, 14
	v_lshlrev_b32_e32 v2, 1, v208
	v_lshlrev_b32_e32 v211, 4, v208
	s_or_b32 s64, s1, s0
	s_xor_b32 s65, s63, 15
	s_or_b32 s68, s63, 16
	s_xor_b32 s69, s63, 31
	v_and_b32_e32 v212, 31, v208
	v_lshrrev_b32_e32 v1, 5, v209
	v_and_b32_e32 v3, 32, v2
	v_lshlrev_b32_e32 v4, 3, v208
	v_and_b32_e32 v2, 0xc0, v211
	s_cmp_lg_u32 0, -1
	v_and_b32_e32 v5, 24, v4
	v_lshl_or_b32 v6, v1, 8, v2
	v_lshlrev_b32_e32 v2, 10, v212
	s_cselect_b32 s0, 0, 0
	v_lshlrev_b32_e32 v7, 10, v1
	v_lshl_or_b32 v2, v1, 3, v2
	v_lshlrev_b32_e32 v215, 2, v1
	v_lshlrev_b32_e32 v216, 4, v1
	v_lshlrev_b32_e32 v217, 9, v1
	v_or_b32_e32 v1, v5, v6
	s_addk_i32 s0, 0x6000
	v_add3_u32 v228, v3, s0, v1
	v_sub_u32_e32 v1, v212, v215
	v_mov_b32_e32 v197, 0
	v_add_u32_e32 v9, 0, v3
	v_lshlrev_b32_e32 v196, 4, v209
	v_add_u32_e32 v229, 0xfffffec0, v1
	v_lshlrev_b32_e32 v1, 2, v212
	s_waitcnt vmcnt(0) lgkmcnt(0)
	v_add3_u32 v214, v9, v5, v6
	v_lshrrev_b32_e32 v210, 3, v209
	v_and_b32_e32 v218, 56, v4
	v_bfe_u32 v219, v4, 5, 1
	v_lshl_add_u64 v[4:5], s[28:29], 0, v[196:197]
	s_mov_b64 s[0:1], 0x1600c000
	v_sub_u32_e32 v1, v1, v216
	v_readlane_b32 s3, v255, 5
	v_lshlrev_b32_e32 v0, 3, v209
	v_lshlrev_b32_e32 v8, 4, v212
	v_or_b32_e32 v222, 8, v210
	v_or_b32_e32 v224, 16, v210
	v_or_b32_e32 v226, 24, v210
	v_lshl_add_u64 v[198:199], v[4:5], 0, s[0:1]
	v_add_u32_e32 v1, 0, v1
	s_mov_b64 s[0:1], 0x16004000
	s_movk_i32 s44, 0xe000
	s_mov_b32 s13, 0
	v_add3_u32 v213, 0, v7, v8
	v_cmp_gt_u32_e64 s[2:3], 32, v209
	v_and_b32_e32 v220, 48, v211
	v_lshlrev_b32_e32 v221, 7, v210
	v_lshlrev_b32_e32 v223, 7, v222
	v_lshlrev_b32_e32 v225, 7, v224
	v_lshlrev_b32_e32 v227, 7, v226
	v_add_u32_e32 v230, 0x1a614, v1
	v_lshl_add_u64 v[200:201], v[4:5], 0, s[0:1]
	v_lshlrev_b32_e32 v196, 1, v0
	s_mov_b64 s[14:15], 0x2000
	v_lshlrev_b32_e32 v231, 1, v2
	s_mov_b64 s[16:17], 0x4000
	s_add_i32 s70, 0, 0x1a800
	s_mov_b64 s[24:25], 0x6000
	s_mov_b32 s45, -1
	s_mov_b32 s71, 0x41000000
	s_mov_b64 s[46:47], 0x8000
	s_movk_i32 s72, 0xef
	s_movk_i32 s73, 0xf0
	s_movk_i32 s74, 0xf1
	s_movk_i32 s75, 0xf2
	s_movk_i32 s76, 0xf7
	s_movk_i32 s77, 0xf8
	s_movk_i32 s78, 0xf9
	s_movk_i32 s79, 0xfa
	s_movk_i32 s80, 0x3c0
	v_mov_b32_e32 v232, 0xff800000
	s_mov_b32 s81, 0
	s_waitcnt lgkmcnt(0)
	s_barrier
	s_branch .LBB0_1232

; #define WAIT_BAR(N) asm volatile("s_waitcnt vmcnt(" #N ") lgkmcnt(0)\n\ts_barrier":::"memory")
;   #define DMA_K(t,slot) glds16(ksrc+(long)(t)*4096,(unsigned)__builtin_amdgcn_readfirstlane(kdst+(slot)))
;   #define DMA_V(t,slot) do{ glds16(vsrc+(long)(t)*8192,(unsigned)__builtin_amdgcn_readfirstlane(vdst+2*(slot))); glds16(vsrc+(long)(t)*8192+4096,(unsigned)__builtin_amdgcn_readfirstlane(vdst+2*(slot)+8192)); }while(0)
;   #define CMASK(P0,P1,t) do{int jb_=(t)-(NT-4); if(jb_>=-2&&(32*wid-64*jb_<176||64*jb_+63>32*wid))cmask(P0,P1,jb_,qrel,hi,btab);}while(0)
;   #define ROT() do{sl_prev=sl_cur;sl_cur=sl_next;sl_next=(sl_next==(NSLOT-1)*SLOTB)?0:sl_next+SLOTB;}while(0)
;   #define CMASK(P0,P1,t) do{}while(0)
;   #define CMASK(P0,P1,t) do{int jb_=(t)-(NT-4); if(jb_>=-2&&(32*wid-64*jb_<176||64*jb_+63>32*wid))cmask(P0,P1,jb_,qrel,hi,btab);}while(0)
; template<int THRL> __device__ __forceinline__ void attn_unit(int b,int hc,int qb,const bf16*Q,const bf16*__restrict__ K,const bf16*__restrict__ V,bf16*O,char*shm){
;     ...
;   qkt(pA0,pA1,Kbase,qr,zero16,r32,hi);asm volatile("s_nop 15\n\ts_nop 7":"+v"(pA0),"+v"(pA1));CMASK(pA0,pA1,0);
;   { const float rm=rowmax(pA0,pA1); mhat=rm;
;     _Pragma("unroll") for(int r=0;r<16;++r){pA0[r]=__builtin_amdgcn_exp2f(pA0[r]-mhat);pA1[r]=__builtin_amdgcn_exp2f(pA1[r]-mhat);} }
;   WAIT_BAR(0);
;   DMA_K(3,0);DMA_V(1,SLOTB);
;   ROT();
;   kload8(kf,kp0+sl_cur);
;   WAIT_BAR(3);
.LBB0_1275:
	v_max3_f32 v34, v16, v17, v0
	v_max3_f32 v35, v18, v19, v1
	s_and_b32 s18, s87, 0x3fffffc0
	v_max3_f32 v34, v34, v2, v3
	v_max3_f32 v35, v35, v22, v23
	s_lshl_b32 s18, s18, 2
	v_max3_f32 v34, v34, v20, v21
	v_max3_f32 v35, v35, v6, v7
	s_add_i32 s49, s18, 0
	v_max3_f32 v34, v34, v4, v5
	v_max3_f32 v35, v35, v26, v27
	s_add_i32 s49, s49, 0x12000
	v_max3_f32 v34, v34, v24, v25
	v_max3_f32 v35, v35, v10, v11
	s_waitcnt vmcnt(0) lgkmcnt(0)
	s_barrier
	s_cmp_lg_u32 0, -1
	v_max3_f32 v34, v34, v8, v9
	v_max3_f32 v35, v35, v30, v31
	s_mov_b32 s37, 0
	v_max3_f32 v34, v34, v28, v29
	v_max3_f32 v35, v35, v14, v15
	v_lshl_add_u32 v233, v212, 2, s49
	v_max3_f32 v34, v34, v12, v13
	s_nop 0
	v_max_f32_e32 v34, v34, v35
	s_nop 0
	v_mov_b32_e32 v35, v34
	s_nop 1
	v_permlane32_swap_b32_e32 v34, v35
	v_max_f32_e32 v235, v34, v35
	s_nop 0
	v_sub_f32_e32 v0, v0, v235
	v_exp_f32_e32 v64, v0
	v_sub_f32_e32 v0, v17, v235
	v_exp_f32_e32 v81, v0
	v_sub_f32_e32 v0, v1, v235
	v_exp_f32_e32 v65, v0
	v_sub_f32_e32 v0, v18, v235
	v_exp_f32_e32 v82, v0
	v_sub_f32_e32 v0, v2, v235
	v_exp_f32_e32 v66, v0
	v_sub_f32_e32 v0, v19, v235
	v_exp_f32_e32 v83, v0
	v_sub_f32_e32 v0, v3, v235
	v_exp_f32_e32 v67, v0
	v_sub_f32_e32 v0, v20, v235
	v_exp_f32_e32 v84, v0
	v_sub_f32_e32 v0, v4, v235
	v_exp_f32_e32 v68, v0
	v_sub_f32_e32 v0, v21, v235
	v_exp_f32_e32 v85, v0
	v_sub_f32_e32 v0, v5, v235
	v_exp_f32_e32 v69, v0
	v_sub_f32_e32 v0, v22, v235
	v_exp_f32_e32 v86, v0
	v_sub_f32_e32 v0, v6, v235
	v_exp_f32_e32 v70, v0
	v_sub_f32_e32 v0, v23, v235
	v_exp_f32_e32 v87, v0
	v_sub_f32_e32 v0, v7, v235
	v_exp_f32_e32 v71, v0
	v_sub_f32_e32 v0, v24, v235
	v_exp_f32_e32 v88, v0
	v_sub_f32_e32 v0, v8, v235
	v_exp_f32_e32 v72, v0
	v_sub_f32_e32 v0, v25, v235
	v_exp_f32_e32 v89, v0
	v_sub_f32_e32 v0, v9, v235
	v_exp_f32_e32 v73, v0
	v_sub_f32_e32 v0, v26, v235
	v_exp_f32_e32 v90, v0
	v_sub_f32_e32 v0, v10, v235
	v_exp_f32_e32 v74, v0
	v_sub_f32_e32 v0, v27, v235
	v_exp_f32_e32 v91, v0
	v_sub_f32_e32 v0, v11, v235
	v_exp_f32_e32 v75, v0
	v_sub_f32_e32 v0, v28, v235
	v_exp_f32_e32 v92, v0
	v_sub_f32_e32 v0, v12, v235
	v_exp_f32_e32 v76, v0
	v_sub_f32_e32 v0, v29, v235
	v_exp_f32_e32 v93, v0
	v_sub_f32_e32 v0, v13, v235
	v_exp_f32_e32 v77, v0
	v_sub_f32_e32 v0, v30, v235
	v_exp_f32_e32 v94, v0
	v_sub_f32_e32 v0, v14, v235
	v_exp_f32_e32 v78, v0
	v_sub_f32_e32 v0, v31, v235
	v_exp_f32_e32 v95, v0
	v_sub_f32_e32 v0, v15, v235
	v_exp_f32_e32 v79, v0
	v_lshl_add_u64 v[0:1], v[202:203], 0, s[24:25]
	s_mov_b32 s18, m0
	s_mov_b32 m0, s89
	s_nop 0
	global_load_lds_dwordx4 v[0:1], off
	s_mov_b32 m0, s18
	s_cselect_b32 s18, 0, 0
	s_add_i32 s12, s18, s12
	v_lshl_add_u64 v[0:1], v[32:33], 0, s[16:17]
	s_add_i32 s18, s12, 0xa000
	s_mov_b32 s22, m0
	s_mov_b32 m0, s18
	s_nop 0
	global_load_lds_dwordx4 v[0:1], off
	s_mov_b32 m0, s22
	v_lshl_add_u64 v[0:1], v[32:33], 0, s[24:25]
	s_add_i32 s12, s12, 0xc000
	s_mov_b32 s18, m0
	s_mov_b32 m0, s12
	s_nop 0
	global_load_lds_dwordx4 v[0:1], off
	s_mov_b32 m0, s18
	ds_read_b128 v[188:191], v213 offset:8192
	ds_read_b128 v[184:187], v213 offset:8704
	ds_read_b128 v[180:183], v213 offset:10240
	ds_read_b128 v[176:179], v213 offset:10752
	ds_read_b128 v[172:175], v213 offset:12288
	ds_read_b128 v[168:171], v213 offset:12800
	ds_read_b128 v[164:167], v213 offset:14336
	ds_read_b128 v[160:163], v213 offset:14848
	v_sub_f32_e32 v16, v16, v235
	v_exp_f32_e32 v80, v16
	s_waitcnt vmcnt(3) lgkmcnt(0)
	s_barrier
	s_cmp_lt_i32 s91, 9
	s_cbranch_scc1 .LBB0_1291
	s_add_i32 s30, s19, s21
	s_ashr_i32 s31, s30, 31
	s_add_i32 s22, s91, -7
	s_lshl_b64 s[30:31], s[30:31], 14
	s_add_u32 s30, s30, s0
	s_addc_u32 s31, s31, s1
	v_mov_b32_e32 v32, v197
	v_mov_b32_e32 v33, v197
	v_mov_b32_e32 v46, v197
	v_mov_b32_e32 v47, v197
	v_lshl_add_u64 v[204:205], v[198:199], 0, s[30:31]
	s_mov_b64 s[30:31], 0xa000
	v_mov_b32_e32 v34, v197
	v_mov_b32_e32 v35, v197
	v_mov_b32_e32 v36, v197
	v_mov_b32_e32 v37, v197
	v_mov_b32_e32 v38, v197
	v_mov_b32_e32 v39, v197
	v_mov_b32_e32 v40, v197
	v_mov_b32_e32 v41, v197
	v_mov_b32_e32 v42, v197
	v_mov_b32_e32 v43, v197
	v_mov_b32_e32 v44, v197
	v_mov_b32_e32 v45, v197
	v_mov_b64_e32 v[62:63], v[46:47]
	v_mov_b64_e32 v[16:17], v[32:33]
	v_mov_b64_e32 v[0:1], v[32:33]
	s_mov_b32 s12, 1
	v_lshl_add_u64 v[206:207], v[202:203], 0, s[30:31]
	s_mov_b32 s23, 0
	s_movk_i32 s37, 0x4000
	s_movk_i32 s86, 0x2000
	v_mov_b32_e32 v236, 0
	v_mov_b64_e32 v[60:61], v[44:45]
	v_mov_b64_e32 v[58:59], v[42:43]
	v_mov_b64_e32 v[56:57], v[40:41]
	v_mov_b64_e32 v[54:55], v[38:39]
	v_mov_b64_e32 v[52:53], v[36:37]
	v_mov_b64_e32 v[50:51], v[34:35]
	v_mov_b64_e32 v[48:49], v[32:33]
	v_mov_b64_e32 v[18:19], v[34:35]
	v_mov_b64_e32 v[20:21], v[36:37]
	v_mov_b64_e32 v[22:23], v[38:39]
	v_mov_b64_e32 v[24:25], v[40:41]
	v_mov_b64_e32 v[26:27], v[42:43]
	v_mov_b64_e32 v[28:29], v[44:45]
	v_mov_b64_e32 v[30:31], v[46:47]
	v_mov_b64_e32 v[2:3], v[34:35]
	v_mov_b64_e32 v[4:5], v[36:37]
	v_mov_b64_e32 v[6:7], v[38:39]
	v_mov_b64_e32 v[8:9], v[40:41]
	v_mov_b64_e32 v[10:11], v[42:43]
	v_mov_b64_e32 v[12:13], v[44:45]
	v_mov_b64_e32 v[14:15], v[46:47]
	v_xor_b32_e32 v238, 0x80000000, v235
	v_mov_b32_e32 v239, v238
	v_mov_b64_e32 v[240:241], v[238:239]
	v_mov_b64_e32 v[242:243], v[238:239]
	v_mov_b64_e32 v[244:245], v[238:239]
	v_mov_b64_e32 v[246:247], v[238:239]
	v_mov_b64_e32 v[248:249], v[238:239]
	v_mov_b64_e32 v[250:251], v[238:239]
	v_mov_b64_e32 v[252:253], v[238:239]
.LBB0_1277:
	s_lshl_b32 s18, s23, 1
	v_add_u32_e32 v237, s18, v214
	ds_read_b64_tr_b16 v[192:193], v237 offset:24576
	v_add_f32_e32 v112, v80, v81
	v_add_f32_e32 v112, v82, v112
	v_add_f32_e32 v112, v83, v112
	v_add_f32_e32 v112, v84, v112
	v_add_f32_e32 v128, v85, v112
	s_waitcnt lgkmcnt(8)
	v_mfma_f32_32x32x16_bf16 v[112:127], v[188:191], v[156:159], v[238:253]
	v_cvt_pk_bf16_f32 v148, v80, v81
	v_cvt_pk_bf16_f32 v149, v82, v83
	ds_read_b64_tr_b16 v[194:195], v237 offset:25088
	s_waitcnt lgkmcnt(8)
	v_mfma_f32_32x32x16_bf16 v[96:111], v[184:187], v[156:159], v[238:253]
	v_add_f32_e32 v80, v86, v128
	v_add_f32_e32 v80, v87, v80
	v_add_f32_e32 v80, v88, v80
	v_add_f32_e32 v82, v89, v80
	v_cvt_pk_bf16_f32 v150, v84, v85
	v_cvt_pk_bf16_f32 v151, v86, v87
	ds_read_b64_tr_b16 v[80:81], v237 offset:28672
	s_waitcnt lgkmcnt(8)
	v_mfma_f32_32x32x16_bf16 v[112:127], v[180:183], v[152:155], v[112:127]
	v_add_f32_e32 v82, v90, v82
	v_add_f32_e32 v82, v91, v82
	v_add_f32_e32 v82, v92, v82
	v_add_f32_e32 v84, v93, v82
	v_cvt_pk_bf16_f32 v140, v88, v89
	v_cvt_pk_bf16_f32 v141, v90, v91
	ds_read_b64_tr_b16 v[82:83], v237 offset:29184
	s_waitcnt lgkmcnt(8)
	v_mfma_f32_32x32x16_bf16 v[96:111], v[176:179], v[152:155], v[96:111]
	v_add_f32_e32 v84, v94, v84
	v_add_f32_e32 v84, v95, v84
	v_add_f32_e32 v84, v64, v84
	v_add_f32_e32 v86, v65, v84
	v_cvt_pk_bf16_f32 v142, v92, v93
	v_cvt_pk_bf16_f32 v143, v94, v95
	ds_read_b64_tr_b16 v[84:85], v237 offset:32768
	s_waitcnt lgkmcnt(8)
	v_mfma_f32_32x32x16_bf16 v[112:127], v[172:175], v[144:147], v[112:127]
	v_add_f32_e32 v86, v66, v86
	v_add_f32_e32 v86, v67, v86
	v_add_f32_e32 v86, v68, v86
	v_add_f32_e32 v88, v69, v86
	v_cvt_pk_bf16_f32 v132, v64, v65
	v_cvt_pk_bf16_f32 v133, v66, v67
	ds_read_b64_tr_b16 v[86:87], v237 offset:33280
	s_waitcnt lgkmcnt(8)
	v_mfma_f32_32x32x16_bf16 v[96:111], v[168:171], v[144:147], v[96:111]
	v_add_f32_e32 v64, v70, v88
	v_add_f32_e32 v64, v71, v64
	v_add_f32_e32 v64, v72, v64
	v_add_f32_e32 v66, v73, v64
	v_cvt_pk_bf16_f32 v134, v68, v69
	v_cvt_pk_bf16_f32 v135, v70, v71
	ds_read_b64_tr_b16 v[64:65], v237 offset:36864
	s_waitcnt lgkmcnt(8)
	v_mfma_f32_32x32x16_bf16 v[112:127], v[164:167], v[136:139], v[112:127]
	v_add_f32_e32 v66, v74, v66
	v_add_f32_e32 v66, v75, v66
	v_add_f32_e32 v66, v76, v66
	v_add_f32_e32 v68, v77, v66
	v_cvt_pk_bf16_f32 v128, v72, v73
	v_cvt_pk_bf16_f32 v129, v74, v75
	ds_read_b64_tr_b16 v[66:67], v237 offset:37376
	s_waitcnt lgkmcnt(8)
	v_mfma_f32_32x32x16_bf16 v[96:111], v[160:163], v[136:139], v[96:111]
	v_add_f32_e32 v68, v78, v68
	v_add_f32_e32 v68, v79, v68
	v_add_f32_e32 v70, 0, v68
	v_cvt_pk_bf16_f32 v130, v76, v77
	v_cvt_pk_bf16_f32 v131, v78, v79
	s_movk_i32 s30, 0xc000
	v_lshl_add_u64 v[68:69], v[206:207], 0, s[44:45]
	s_add_i32 s18, s86, s89
	s_mov_b32 s31, -1
	s_mov_b32 s23, m0
	s_mov_b32 m0, s18
	s_nop 0
	global_load_lds_dwordx4 v[68:69], off
	s_mov_b32 m0, s23
	v_lshl_add_u64 v[68:69], v[204:205], 0, s[30:31]
	s_lshl_b32 s18, s37, 1
	s_add_i32 s18, s18, s90
	s_mov_b32 s23, m0
	s_mov_b32 m0, s18
	s_nop 0
	global_load_lds_dwordx4 v[68:69], off
	s_mov_b32 m0, s23
	v_lshl_add_u64 v[68:69], v[204:205], 0, s[44:45]
	s_addk_i32 s18, 0x2000
	s_mov_b32 s23, m0
	s_mov_b32 m0, s18
	s_nop 0
	global_load_lds_dwordx4 v[68:69], off
	s_mov_b32 m0, s23
	v_max_f32_e32 v68, v113, v113
	v_max_f32_e32 v69, v112, v112
	v_max_f32_e32 v68, v69, v68
	v_max3_f32 v69, v114, v115, v97
	v_max3_f32 v68, v68, v96, v98
	v_max3_f32 v68, v68, v99, v116
	v_max3_f32 v69, v69, v118, v119
	v_max3_f32 v68, v68, v117, v100
	v_max3_f32 v69, v69, v102, v103
	v_max3_f32 v68, v68, v101, v120
	v_max3_f32 v69, v69, v122, v123
	v_max3_f32 v68, v68, v121, v104
	v_max3_f32 v69, v69, v106, v107
	v_max3_f32 v68, v68, v105, v124
	v_max3_f32 v69, v69, v126, v127
	v_max3_f32 v68, v68, v125, v108
	v_max3_f32 v69, v69, v110, v111
	v_max3_f32 v68, v68, v109, v69
	v_mov_b32_e32 v69, v68
	s_nop 1
	v_permlane32_swap_b32_e32 v68, v69
	v_max_f32_e32 v69, v69, v69
	v_max_f32_e32 v68, v68, v68
	v_max_f32_e32 v68, v68, v69
	v_cmp_lt_f32_e32 vcc, s71, v68
	s_cmp_lg_u64 vcc, 0
	v_add_f32_e32 v236, v236, v70
	s_cselect_b64 s[50:51], -1, 0
	s_cbranch_vccnz .LBB0_1285

.LBB0_1280:
	s_add_i32 s18, s37, 0x2000
	s_lshl_b32 s23, s86, 1
	v_add_u32_e32 v237, s23, v214
	ds_read_b64_tr_b16 v[180:181], v237 offset:24576
	s_cmpk_lg_i32 s37, 0x4000
	s_cselect_b32 s86, s18, 0
	v_add_f32_e32 v80, v112, v113
	v_add_f32_e32 v80, v114, v80
	v_add_f32_e32 v80, v115, v80
	v_add_f32_e32 v80, v116, v80
	v_add_f32_e32 v128, v117, v80
	s_waitcnt lgkmcnt(8)
	v_mfma_f32_32x32x16_bf16 v[80:95], v[192:195], v[156:159], v[238:253]
	v_cvt_pk_bf16_f32 v148, v112, v113
	v_cvt_pk_bf16_f32 v149, v114, v115
	ds_read_b64_tr_b16 v[182:183], v237 offset:25088
	s_waitcnt lgkmcnt(8)
	v_mfma_f32_32x32x16_bf16 v[64:79], v[188:191], v[156:159], v[238:253]
	v_add_f32_e32 v112, v118, v128
	v_add_f32_e32 v112, v119, v112
	v_add_f32_e32 v112, v120, v112
	v_add_f32_e32 v114, v121, v112
	v_cvt_pk_bf16_f32 v150, v116, v117
	v_cvt_pk_bf16_f32 v151, v118, v119
	ds_read_b64_tr_b16 v[112:113], v237 offset:28672
	s_waitcnt lgkmcnt(8)
	v_mfma_f32_32x32x16_bf16 v[80:95], v[184:187], v[152:155], v[80:95]
	v_add_f32_e32 v114, v122, v114
	v_add_f32_e32 v114, v123, v114
	v_add_f32_e32 v114, v124, v114
	v_add_f32_e32 v116, v125, v114
	v_cvt_pk_bf16_f32 v140, v120, v121
	v_cvt_pk_bf16_f32 v141, v122, v123
	ds_read_b64_tr_b16 v[114:115], v237 offset:29184
	s_waitcnt lgkmcnt(8)
	v_mfma_f32_32x32x16_bf16 v[64:79], v[176:179], v[152:155], v[64:79]
	v_add_f32_e32 v116, v126, v116
	v_add_f32_e32 v116, v127, v116
	v_add_f32_e32 v116, v96, v116
	v_add_f32_e32 v118, v97, v116
	v_cvt_pk_bf16_f32 v142, v124, v125
	v_cvt_pk_bf16_f32 v143, v126, v127
	ds_read_b64_tr_b16 v[116:117], v237 offset:32768
	s_waitcnt lgkmcnt(8)
	v_mfma_f32_32x32x16_bf16 v[80:95], v[172:175], v[144:147], v[80:95]
	v_add_f32_e32 v118, v98, v118
	v_add_f32_e32 v118, v99, v118
	v_add_f32_e32 v118, v100, v118
	v_add_f32_e32 v120, v101, v118
	v_cvt_pk_bf16_f32 v132, v96, v97
	v_cvt_pk_bf16_f32 v133, v98, v99
	ds_read_b64_tr_b16 v[118:119], v237 offset:33280
	s_waitcnt lgkmcnt(8)
	v_mfma_f32_32x32x16_bf16 v[64:79], v[168:171], v[144:147], v[64:79]
	v_add_f32_e32 v96, v102, v120
	v_add_f32_e32 v96, v103, v96
	v_add_f32_e32 v96, v104, v96
	v_add_f32_e32 v98, v105, v96
	v_cvt_pk_bf16_f32 v134, v100, v101
	v_cvt_pk_bf16_f32 v135, v102, v103
	ds_read_b64_tr_b16 v[96:97], v237 offset:36864
	s_waitcnt lgkmcnt(8)
	v_mfma_f32_32x32x16_bf16 v[80:95], v[164:167], v[136:139], v[80:95]
	v_add_f32_e32 v98, v106, v98
	v_add_f32_e32 v98, v107, v98
	v_add_f32_e32 v98, v108, v98
	v_add_f32_e32 v100, v109, v98
	v_cvt_pk_bf16_f32 v128, v104, v105
	v_cvt_pk_bf16_f32 v129, v106, v107
	ds_read_b64_tr_b16 v[98:99], v237 offset:37376
	s_waitcnt lgkmcnt(8)
	v_mfma_f32_32x32x16_bf16 v[64:79], v[160:163], v[136:139], v[64:79]
	v_add_f32_e32 v100, v110, v100
	v_add_f32_e32 v100, v111, v100
	v_add_f32_e32 v102, 0, v100
	v_cvt_pk_bf16_f32 v130, v108, v109
	v_cvt_pk_bf16_f32 v131, v110, v111
	s_add_i32 s18, s37, s89
	s_mov_b32 s23, m0
	s_mov_b32 m0, s18
	s_nop 0
	global_load_lds_dwordx4 v[206:207], off
	s_mov_b32 m0, s23
	s_lshl_b32 s18, s86, 1
	s_add_i32 s18, s18, s90
	s_mov_b32 s23, m0
	s_mov_b32 m0, s18
	s_nop 0
	global_load_lds_dwordx4 v[204:205], off
	s_mov_b32 m0, s23
	v_lshl_add_u64 v[100:101], v[204:205], 0, s[14:15]
	s_addk_i32 s18, 0x2000
	s_mov_b32 s23, m0
	s_mov_b32 m0, s18
	s_nop 0
	global_load_lds_dwordx4 v[100:101], off
	s_mov_b32 m0, s23
	v_max_f32_e32 v100, v81, v81
	v_max_f32_e32 v101, v80, v80
	v_max_f32_e32 v100, v101, v100
	v_max3_f32 v101, v82, v83, v65
	v_max3_f32 v100, v100, v64, v66
	v_max3_f32 v100, v100, v67, v84
	v_max3_f32 v101, v101, v86, v87
	v_max3_f32 v100, v100, v85, v68
	v_max3_f32 v101, v101, v70, v71
	v_max3_f32 v100, v100, v69, v88
	v_max3_f32 v101, v101, v90, v91
	v_max3_f32 v100, v100, v89, v72
	v_max3_f32 v101, v101, v74, v75
	v_max3_f32 v100, v100, v73, v92
	v_max3_f32 v101, v101, v94, v95
	v_max3_f32 v100, v100, v93, v76
	v_max3_f32 v101, v101, v78, v79
	v_max3_f32 v100, v100, v77, v101
	v_mov_b32_e32 v101, v100
	s_nop 1
	v_permlane32_swap_b32_e32 v100, v101
	v_max_f32_e32 v101, v101, v101
	v_max_f32_e32 v100, v100, v100
	v_max_f32_e32 v100, v100, v101
	v_cmp_lt_f32_e32 vcc, s71, v100
	s_cmp_lg_u64 vcc, 0
	v_add_f32_e32 v236, v236, v102
	s_cselect_b64 s[50:51], -1, 0
	s_cbranch_vccnz .LBB0_1288

.LBB0_1285:
	v_max_f32_e32 v68, v68, v68
	v_max_f32_e32 v69, 0, v68
	v_exp_f32_e64 v68, -v69
	s_and_saveexec_b64 s[52:53], s[2:3]
	ds_write_b32 v233, v68
	s_or_b64 exec, exec, s[52:53]
	v_sub_f32_e32 v127, v127, v69
	v_sub_f32_e32 v126, v126, v69
	v_sub_f32_e32 v125, v125, v69
	v_sub_f32_e32 v124, v124, v69
	v_sub_f32_e32 v123, v123, v69
	v_sub_f32_e32 v122, v122, v69
	v_sub_f32_e32 v121, v121, v69
	v_sub_f32_e32 v120, v120, v69
	v_sub_f32_e32 v119, v119, v69
	v_sub_f32_e32 v118, v118, v69
	v_sub_f32_e32 v117, v117, v69
	v_sub_f32_e32 v116, v116, v69
	v_sub_f32_e32 v115, v115, v69
	v_sub_f32_e32 v114, v114, v69
	v_sub_f32_e32 v113, v113, v69
	v_sub_f32_e32 v112, v112, v69
	v_sub_f32_e32 v111, v111, v69
	v_sub_f32_e32 v110, v110, v69
	v_sub_f32_e32 v109, v109, v69
	v_sub_f32_e32 v108, v108, v69
	v_sub_f32_e32 v107, v107, v69
	v_sub_f32_e32 v106, v106, v69
	v_sub_f32_e32 v105, v105, v69
	v_sub_f32_e32 v104, v104, v69
	v_sub_f32_e32 v103, v103, v69
	v_sub_f32_e32 v102, v102, v69
	v_sub_f32_e32 v101, v101, v69
	v_sub_f32_e32 v100, v100, v69
	v_sub_f32_e32 v99, v99, v69
	v_sub_f32_e32 v98, v98, v69
	v_sub_f32_e32 v97, v97, v69
	v_sub_f32_e32 v96, v96, v69
	v_add_f32_e32 v235, v235, v69
	v_xor_b32_e32 v238, 0x80000000, v235
	v_mov_b32_e32 v239, v238
	v_mov_b64_e32 v[240:241], v[238:239]
	v_mov_b64_e32 v[242:243], v[238:239]
	v_mov_b64_e32 v[244:245], v[238:239]
	v_mov_b64_e32 v[246:247], v[238:239]
	v_mov_b64_e32 v[248:249], v[238:239]
	v_mov_b64_e32 v[250:251], v[238:239]
	v_mov_b64_e32 v[252:253], v[238:239]
	v_mul_f32_e32 v236, v236, v68
	s_branch .LBB0_1278
.LBB0_1288:
	v_max_f32_e32 v100, v100, v100
	v_max_f32_e32 v101, 0, v100
	v_exp_f32_e64 v100, -v101
	s_and_saveexec_b64 s[52:53], s[2:3]
	ds_write_b32 v233, v100
	s_or_b64 exec, exec, s[52:53]
	v_sub_f32_e32 v95, v95, v101
	v_sub_f32_e32 v94, v94, v101
	v_sub_f32_e32 v93, v93, v101
	v_sub_f32_e32 v92, v92, v101
	v_sub_f32_e32 v91, v91, v101
	v_sub_f32_e32 v90, v90, v101
	v_sub_f32_e32 v89, v89, v101
	v_sub_f32_e32 v88, v88, v101
	v_sub_f32_e32 v87, v87, v101
	v_sub_f32_e32 v86, v86, v101
	v_sub_f32_e32 v85, v85, v101
	v_sub_f32_e32 v84, v84, v101
	v_sub_f32_e32 v83, v83, v101
	v_sub_f32_e32 v82, v82, v101
	v_sub_f32_e32 v81, v81, v101
	v_sub_f32_e32 v80, v80, v101
	v_sub_f32_e32 v79, v79, v101
	v_sub_f32_e32 v78, v78, v101
	v_sub_f32_e32 v77, v77, v101
	v_sub_f32_e32 v76, v76, v101
	v_sub_f32_e32 v75, v75, v101
	v_sub_f32_e32 v74, v74, v101
	v_sub_f32_e32 v73, v73, v101
	v_sub_f32_e32 v72, v72, v101
	v_sub_f32_e32 v71, v71, v101
	v_sub_f32_e32 v70, v70, v101
	v_sub_f32_e32 v69, v69, v101
	v_sub_f32_e32 v68, v68, v101
	v_sub_f32_e32 v67, v67, v101
	v_sub_f32_e32 v66, v66, v101
	v_sub_f32_e32 v65, v65, v101
	v_sub_f32_e32 v64, v64, v101
	v_add_f32_e32 v235, v235, v101
	v_xor_b32_e32 v238, 0x80000000, v235
	v_mov_b32_e32 v239, v238
	v_mov_b64_e32 v[240:241], v[238:239]
	v_mov_b64_e32 v[242:243], v[238:239]
	v_mov_b64_e32 v[244:245], v[238:239]
	v_mov_b64_e32 v[246:247], v[238:239]
	v_mov_b64_e32 v[248:249], v[238:239]
	v_mov_b64_e32 v[250:251], v[238:239]
	v_mov_b64_e32 v[252:253], v[238:239]
	v_mul_f32_e32 v236, v236, v100
	s_branch .LBB0_1281

.LBB0_1410:
	v_add_u32_e32 v202, s36, v214
	ds_read_b64_tr_b16 v[192:193], v202 offset:24576
	v_xor_b32_e32 v96, 0x80000000, v235
	v_mov_b32_e32 v97, v96
	v_mov_b64_e32 v[98:99], v[96:97]
	v_mov_b64_e32 v[100:101], v[96:97]
	v_mov_b64_e32 v[102:103], v[96:97]
	v_mov_b64_e32 v[104:105], v[96:97]
	v_mov_b64_e32 v[106:107], v[96:97]
	v_mov_b64_e32 v[108:109], v[96:97]
	v_mov_b64_e32 v[110:111], v[96:97]
	v_add_f32_e32 v112, v80, v81
	v_add_f32_e32 v112, v82, v112
	v_add_f32_e32 v112, v83, v112
	v_add_f32_e32 v112, v84, v112
	v_add_f32_e32 v128, v85, v112
	s_waitcnt lgkmcnt(8)
	v_mfma_f32_32x32x16_bf16 v[112:127], v[188:191], v[156:159], v[96:111]
	v_cvt_pk_bf16_f32 v148, v80, v81
	v_cvt_pk_bf16_f32 v149, v82, v83
	ds_read_b64_tr_b16 v[194:195], v202 offset:25088
	s_waitcnt lgkmcnt(8)
	v_mfma_f32_32x32x16_bf16 v[96:111], v[184:187], v[156:159], v[96:111]
	v_add_f32_e32 v80, v86, v128
	v_add_f32_e32 v80, v87, v80
	v_add_f32_e32 v80, v88, v80
	v_add_f32_e32 v82, v89, v80
	v_cvt_pk_bf16_f32 v150, v84, v85
	v_cvt_pk_bf16_f32 v151, v86, v87
	ds_read_b64_tr_b16 v[80:81], v202 offset:28672
	s_waitcnt lgkmcnt(8)
	v_mfma_f32_32x32x16_bf16 v[112:127], v[180:183], v[152:155], v[112:127]
	v_add_f32_e32 v82, v90, v82
	v_add_f32_e32 v82, v91, v82
	v_add_f32_e32 v82, v92, v82
	v_add_f32_e32 v84, v93, v82
	v_cvt_pk_bf16_f32 v140, v88, v89
	v_cvt_pk_bf16_f32 v141, v90, v91
	ds_read_b64_tr_b16 v[82:83], v202 offset:29184
	s_waitcnt lgkmcnt(8)
	v_mfma_f32_32x32x16_bf16 v[96:111], v[176:179], v[152:155], v[96:111]
	v_add_f32_e32 v84, v94, v84
	v_add_f32_e32 v84, v95, v84
	v_add_f32_e32 v84, v64, v84
	v_add_f32_e32 v86, v65, v84
	v_cvt_pk_bf16_f32 v142, v92, v93
	v_cvt_pk_bf16_f32 v143, v94, v95
	ds_read_b64_tr_b16 v[84:85], v202 offset:32768
	s_waitcnt lgkmcnt(8)
	v_mfma_f32_32x32x16_bf16 v[112:127], v[172:175], v[144:147], v[112:127]
	v_add_f32_e32 v86, v66, v86
	v_add_f32_e32 v86, v67, v86
	v_add_f32_e32 v86, v68, v86
	v_add_f32_e32 v88, v69, v86
	v_cvt_pk_bf16_f32 v132, v64, v65
	v_cvt_pk_bf16_f32 v133, v66, v67
	ds_read_b64_tr_b16 v[86:87], v202 offset:33280
	s_waitcnt lgkmcnt(8)
	v_mfma_f32_32x32x16_bf16 v[96:111], v[168:171], v[144:147], v[96:111]
	v_add_f32_e32 v64, v70, v88
	v_add_f32_e32 v64, v71, v64
	v_add_f32_e32 v64, v72, v64
	v_add_f32_e32 v66, v73, v64
	v_cvt_pk_bf16_f32 v134, v68, v69
	v_cvt_pk_bf16_f32 v135, v70, v71
	ds_read_b64_tr_b16 v[64:65], v202 offset:36864
	s_waitcnt lgkmcnt(8)
	v_mfma_f32_32x32x16_bf16 v[112:127], v[164:167], v[136:139], v[112:127]
	v_add_f32_e32 v66, v74, v66
	v_add_f32_e32 v66, v75, v66
	v_add_f32_e32 v66, v76, v66
	v_add_f32_e32 v68, v77, v66
	v_cvt_pk_bf16_f32 v128, v72, v73
	v_cvt_pk_bf16_f32 v129, v74, v75
	ds_read_b64_tr_b16 v[66:67], v202 offset:37376
	s_waitcnt lgkmcnt(8)
	v_mfma_f32_32x32x16_bf16 v[96:111], v[160:163], v[136:139], v[96:111]
	v_add_f32_e32 v68, v78, v68
	v_add_f32_e32 v68, v79, v68
	v_add_f32_e32 v68, 0, v68
	v_cvt_pk_bf16_f32 v130, v76, v77
	v_cvt_pk_bf16_f32 v131, v78, v79
	s_cmpk_gt_u32 s87, 0x2ff
	s_cbranch_scc1 .LBB0_1444
; __device__ __forceinline__ void cmask(f32x16&p0,f32x16&p1,int jb,int qrel,int hi,lds_cfptr bt){
;   const lds_cfptr t=bt+(qrel-64*jb-4*hi+256);
;   const int dq=qrel-64*jb-4*hi;
;   #pragma unroll
;   for(int r=0;r<16;++r){const int off=(r&3)+8*(r>>2); const float b0=t[-off],b1=t[-off-32]; p0[r]=(dq-off<0)?(p0[r]-INFINITY):p0[r]+b0; p1[r]=(dq-off-32<0)?(p1[r]-INFINITY):p1[r]+b1;}
; }
	v_sub_u32_e32 v69, v234, v215
	v_lshl_add_u32 v72, v69, 2, s70
	ds_read_b32 v70, v72 offset:128
	s_movk_i32 s0, 0xbf
	v_cmp_lt_i32_e32 vcc, s0, v69
	v_mov_b32_e32 v71, 0xff800000
	v_mov_b32_e32 v73, 0xff800000
	s_and_saveexec_b64 s[0:1], vcc
	v_readlane_b32 s36, v254, 4
	v_readlane_b32 s37, v254, 5
	ds_read_b32 v73, v72 offset:256
	s_or_b64 exec, exec, s[0:1]
	ds_read_b32 v74, v72 offset:124
	s_movk_i32 s0, 0xc0
	v_cmp_lt_i32_e32 vcc, s0, v69
	s_and_saveexec_b64 s[0:1], vcc
	ds_read_b32 v71, v72 offset:252
	s_or_b64 exec, exec, s[0:1]
	ds_read_b32 v75, v72 offset:120
	s_movk_i32 s0, 0xc1
	v_cmp_lt_i32_e32 vcc, s0, v69
	v_mov_b32_e32 v76, 0xff800000
	v_mov_b32_e32 v77, 0xff800000
	s_and_saveexec_b64 s[0:1], vcc
	ds_read_b32 v77, v72 offset:248
	s_or_b64 exec, exec, s[0:1]
	ds_read_b32 v78, v72 offset:116
	s_movk_i32 s0, 0xc2
	v_cmp_lt_i32_e32 vcc, s0, v69
	s_and_saveexec_b64 s[0:1], vcc
	ds_read_b32 v76, v72 offset:244
	s_or_b64 exec, exec, s[0:1]
	ds_read_b32 v79, v72 offset:96
	s_movk_i32 s0, 0xc7
	v_cmp_lt_i32_e32 vcc, s0, v69
	v_mov_b32_e32 v88, 0xff800000
	v_mov_b32_e32 v89, 0xff800000
	s_and_saveexec_b64 s[0:1], vcc
	ds_read_b32 v89, v72 offset:224
	s_or_b64 exec, exec, s[0:1]
	ds_read_b32 v90, v72 offset:92
	s_movk_i32 s0, 0xc8
	v_cmp_lt_i32_e32 vcc, s0, v69
	s_and_saveexec_b64 s[0:1], vcc
	ds_read_b32 v88, v72 offset:220
	s_or_b64 exec, exec, s[0:1]
	ds_read_b32 v91, v72 offset:88
	s_movk_i32 s0, 0xc9
	v_cmp_lt_i32_e32 vcc, s0, v69
	v_mov_b32_e32 v92, 0xff800000
	v_mov_b32_e32 v93, 0xff800000
	s_and_saveexec_b64 s[0:1], vcc
	ds_read_b32 v93, v72 offset:216
	s_or_b64 exec, exec, s[0:1]
	ds_read_b32 v94, v72 offset:84
	s_movk_i32 s0, 0xca
	v_cmp_lt_i32_e32 vcc, s0, v69
	s_and_saveexec_b64 s[0:1], vcc
	ds_read_b32 v92, v72 offset:212
	s_or_b64 exec, exec, s[0:1]
	ds_read_b32 v95, v72 offset:64
	s_movk_i32 s0, 0xcf
	v_cmp_lt_i32_e32 vcc, s0, v69
	v_mov_b32_e32 v136, 0xff800000
	v_mov_b32_e32 v137, 0xff800000
	s_and_saveexec_b64 s[0:1], vcc
	ds_read_b32 v137, v72 offset:192
	s_or_b64 exec, exec, s[0:1]
	ds_read_b32 v138, v72 offset:60
	s_movk_i32 s0, 0xd0
	v_cmp_lt_i32_e32 vcc, s0, v69
	s_and_saveexec_b64 s[0:1], vcc
	ds_read_b32 v136, v72 offset:188
	s_or_b64 exec, exec, s[0:1]
	ds_read_b32 v139, v72 offset:56
	s_movk_i32 s0, 0xd1
	v_cmp_lt_i32_e32 vcc, s0, v69
	v_mov_b32_e32 v144, 0xff800000
	v_mov_b32_e32 v145, 0xff800000
	s_and_saveexec_b64 s[0:1], vcc
	ds_read_b32 v145, v72 offset:184
	s_or_b64 exec, exec, s[0:1]
	ds_read_b32 v146, v72 offset:52
	s_movk_i32 s0, 0xd2
	v_cmp_lt_i32_e32 vcc, s0, v69
	s_and_saveexec_b64 s[0:1], vcc
	ds_read_b32 v144, v72 offset:180
	s_or_b64 exec, exec, s[0:1]
	ds_read_b32 v147, v72 offset:32
	s_movk_i32 s0, 0xd7
	v_cmp_lt_i32_e32 vcc, s0, v69
	v_mov_b32_e32 v152, 0xff800000
	v_mov_b32_e32 v153, 0xff800000
	s_and_saveexec_b64 s[0:1], vcc
	ds_read_b32 v153, v72 offset:160
	s_or_b64 exec, exec, s[0:1]
	ds_read_b32 v154, v72 offset:28
	s_movk_i32 s0, 0xd8
	v_cmp_lt_i32_e32 vcc, s0, v69
	s_and_saveexec_b64 s[0:1], vcc
	ds_read_b32 v152, v72 offset:156
	s_or_b64 exec, exec, s[0:1]
	ds_read_b32 v156, v72 offset:24
	s_movk_i32 s0, 0xd9
	v_cmp_lt_i32_e32 vcc, s0, v69
	v_mov_b32_e32 v157, 0xff800000
	v_mov_b32_e32 v158, 0xff800000
	s_and_saveexec_b64 s[0:1], vcc
	ds_read_b32 v158, v72 offset:152
	s_or_b64 exec, exec, s[0:1]
	ds_read_b32 v155, v72 offset:20
	s_movk_i32 s0, 0xda
	v_cmp_lt_i32_e32 vcc, s0, v69
	s_and_saveexec_b64 s[0:1], vcc
	ds_read_b32 v157, v72 offset:148
	s_or_b64 exec, exec, s[0:1]
	s_movk_i32 s0, 0xdf
	v_cmp_lt_i32_e32 vcc, s0, v69
	s_movk_i32 s0, 0xe0
	s_waitcnt lgkmcnt(14)
	v_add_f32_e32 v112, v112, v73
	v_cndmask_b32_e32 v70, v232, v70, vcc
	v_cmp_lt_i32_e32 vcc, s0, v69
	s_movk_i32 s0, 0xe1
	v_add_f32_e32 v96, v96, v70
	v_cndmask_b32_e32 v70, v232, v74, vcc
	v_cmp_lt_i32_e32 vcc, s0, v69
	s_movk_i32 s0, 0xe2
	v_add_f32_e32 v97, v97, v70
	s_waitcnt lgkmcnt(13)
	v_cndmask_b32_e32 v70, v232, v75, vcc
	v_cmp_lt_i32_e32 vcc, s0, v69
	s_movk_i32 s0, 0xe7
	v_add_f32_e32 v98, v98, v70
	s_waitcnt lgkmcnt(12)
	v_cndmask_b32_e32 v70, v232, v78, vcc
	v_cmp_lt_i32_e32 vcc, s0, v69
	s_movk_i32 s0, 0xe8
	v_add_f32_e32 v99, v99, v70
	s_waitcnt lgkmcnt(11)
	v_cndmask_b32_e32 v70, v232, v79, vcc
	v_cmp_lt_i32_e32 vcc, s0, v69
	s_movk_i32 s0, 0xe9
	v_add_f32_e32 v100, v100, v70
	s_waitcnt lgkmcnt(10)
	v_cndmask_b32_e32 v70, v232, v90, vcc
	v_cmp_lt_i32_e32 vcc, s0, v69
	s_movk_i32 s0, 0xea
	v_add_f32_e32 v101, v101, v70
	s_waitcnt lgkmcnt(9)
	v_cndmask_b32_e32 v70, v232, v91, vcc
	v_cmp_lt_i32_e32 vcc, s0, v69
	v_add_f32_e32 v102, v102, v70
	v_add_f32_e32 v113, v113, v71
	s_waitcnt lgkmcnt(8)
	v_cndmask_b32_e32 v70, v232, v94, vcc
	v_cmp_lt_i32_e32 vcc, s72, v69
	v_add_f32_e32 v103, v103, v70
	v_add_f32_e32 v114, v114, v77
	s_waitcnt lgkmcnt(7)
	v_cndmask_b32_e32 v70, v232, v95, vcc
	v_cmp_lt_i32_e32 vcc, s73, v69
	v_add_f32_e32 v104, v104, v70
	v_add_f32_e32 v115, v115, v76
	s_waitcnt lgkmcnt(6)
	v_cndmask_b32_e32 v70, v232, v138, vcc
	v_cmp_lt_i32_e32 vcc, s74, v69
	v_add_f32_e32 v105, v105, v70
	v_add_f32_e32 v116, v116, v89
	s_waitcnt lgkmcnt(5)
	v_cndmask_b32_e32 v70, v232, v139, vcc
	v_cmp_lt_i32_e32 vcc, s75, v69
	v_add_f32_e32 v106, v106, v70
	v_add_f32_e32 v117, v117, v88
	s_waitcnt lgkmcnt(4)
	v_cndmask_b32_e32 v70, v232, v146, vcc
	v_cmp_lt_i32_e32 vcc, s76, v69
	v_add_f32_e32 v107, v107, v70
	v_add_f32_e32 v118, v118, v93
	s_waitcnt lgkmcnt(3)
	v_cndmask_b32_e32 v70, v232, v147, vcc
	v_cmp_lt_i32_e32 vcc, s77, v69
	v_add_f32_e32 v108, v108, v70
	v_add_f32_e32 v119, v119, v92
	s_waitcnt lgkmcnt(2)
	v_cndmask_b32_e32 v70, v232, v154, vcc
	v_cmp_lt_i32_e32 vcc, s78, v69
	v_add_f32_e32 v109, v109, v70
	v_add_f32_e32 v120, v120, v137
	s_waitcnt lgkmcnt(1)
	v_cndmask_b32_e32 v70, v232, v156, vcc
	v_cmp_lt_i32_e32 vcc, s79, v69
	v_add_f32_e32 v121, v121, v136
	v_add_f32_e32 v122, v122, v145
	s_waitcnt lgkmcnt(0)
	v_cndmask_b32_e32 v69, v232, v155, vcc
	v_add_f32_e32 v123, v123, v144
	v_add_f32_e32 v124, v124, v153
	v_add_f32_e32 v125, v125, v152
	v_add_f32_e32 v126, v126, v158
	v_add_f32_e32 v110, v110, v70
	v_add_f32_e32 v127, v127, v157
	v_add_f32_e32 v111, v111, v69
	s_branch .LBB0_1445
.LBB0_1444:
	v_readlane_b32 s36, v254, 4
	v_readlane_b32 s37, v254, 5

; __device__ __forceinline__ void combine_local(const Args& a, int vcu, int wave, int lane) {
;     constexpr float LINIT = 0.35550906759f;
;     bf16* O0 = (bf16*)(a.ws + WS_HBA); const bf16* O1 = (const bf16*)(a.ws + WS_O1);
;     const float d1 = wave_sum(a.in[I_LQ1][lane] * a.in[I_LK1][lane]), d2 = wave_sum(a.in[I_LQ2][lane] * a.in[I_LK2][lane]);
;     const float lam = __expf(d1) - __expf(d2) + LINIT;
;     float g[16];
; #pragma unroll
;     for (int e = 0; e < 16; ++e) g[e] = a.in[I_ASG][(lane & 7) * 16 + e] * (1.0f - LINIT);
.LBB0_1453:
	v_readlane_b32 s40, v255, 27
	v_lshlrev_b32_e32 v0, 2, v209
	v_readlane_b32 s41, v255, 28
	v_readlane_b32 s42, v255, 29
	v_readlane_b32 s43, v255, 30
	v_readlane_b32 s44, v255, 31
	v_readlane_b32 s45, v255, 32
	v_readlane_b32 s46, v255, 33
	v_readlane_b32 s47, v255, 34
	v_readlane_b32 s48, v255, 35
	v_readlane_b32 s49, v255, 36
	v_readlane_b32 s50, v255, 37
	v_readlane_b32 s51, v255, 38
	v_readlane_b32 s52, v255, 39
	v_readlane_b32 s53, v255, 40
	v_readlane_b32 s54, v255, 41
	v_readlane_b32 s55, v255, 42
	s_waitcnt vmcnt(0)
	s_barrier
	s_mov_b64 s[22:23], s[54:55]
	s_nop 2
	global_load_dword v1, v0, s[54:55]
	v_readlane_b32 s40, v255, 43
	v_readlane_b32 s41, v255, 44
	v_readlane_b32 s42, v255, 45
	v_readlane_b32 s43, v255, 46
	v_readlane_b32 s44, v255, 47
	v_readlane_b32 s45, v255, 48
	v_readlane_b32 s46, v255, 49
	v_readlane_b32 s47, v255, 50
	s_mov_b64 s[12:13], s[40:41]
	s_mov_b64 s[14:15], s[42:43]
	s_mov_b64 s[16:17], s[44:45]
	global_load_dword v20, v0, s[12:13]
	global_load_dword v22, v0, s[14:15]
	global_load_dword v23, v0, s[16:17]
	v_and_b32_e32 v0, 0x70, v211
	s_mov_b64 s[18:19], s[46:47]
	v_lshlrev_b32_e32 v0, 2, v0
	global_load_dwordx4 v[2:5], v0, s[18:19]
	global_load_dwordx4 v[6:9], v0, s[18:19] offset:16
	global_load_dwordx4 v[10:13], v0, s[18:19] offset:32
	global_load_dwordx4 v[14:17], v0, s[18:19] offset:48
	v_mbcnt_lo_u32_b32 v0, -1, 0
	v_lshlrev_b32_e32 v18, 11, v208
	v_mbcnt_hi_u32_b32 v27, -1, v0
	v_lshlrev_b32_e32 v19, 5, v208
	v_and_b32_e32 v0, 0x2000, v18
	v_and_b32_e32 v18, 64, v27
	v_and_b32_e32 v25, 32, v19
	v_xor_b32_e32 v19, 1, v27
	v_add_u32_e32 v18, 64, v18
	v_xor_b32_e32 v28, 2, v27
	v_cmp_lt_i32_e32 vcc, v19, v18
	v_xor_b32_e32 v29, 4, v27
	v_xor_b32_e32 v30, 8, v27
	v_cndmask_b32_e32 v19, v27, v19, vcc
	v_cmp_lt_i32_e32 vcc, v28, v18
	v_xor_b32_e32 v31, 16, v27
	v_xor_b32_e32 v32, 32, v27
	v_cndmask_b32_e32 v28, v27, v28, vcc
	v_cmp_lt_i32_e32 vcc, v29, v18
	v_lshlrev_b32_e32 v28, 2, v28
	v_readlane_b32 s12, v255, 6
	v_cndmask_b32_e32 v29, v27, v29, vcc
	v_cmp_lt_i32_e32 vcc, v30, v18
	v_lshlrev_b32_e32 v29, 2, v29
	s_lshl_b32 s1, s12, 7
	v_cndmask_b32_e32 v30, v27, v30, vcc
	v_cmp_lt_i32_e32 vcc, v31, v18
	s_mov_b32 s0, 0x3f24fd5c
	s_and_b32 s1, s1, 0xffffe000
	v_cndmask_b32_e32 v31, v27, v31, vcc
	v_cmp_lt_i32_e32 vcc, v32, v18
	v_lshlrev_b32_e32 v34, 2, v31
	v_readlane_b32 s13, v255, 59
	v_cndmask_b32_e32 v18, v27, v32, vcc
	v_lshlrev_b32_e32 v27, 2, v19
	v_lshlrev_b32_e32 v32, 2, v30
	v_lshlrev_b32_e32 v35, 2, v18
	s_lshl_b32 s18, s12, 13
	s_lshl_b32 s14, s12, 11
	s_lshl_b32 s19, s13, 11
	s_and_b32 s18, s18, 0xfff80000
	s_and_b32 s3, s12, 7
	s_lshl_b32 s17, s13, 5
	s_and_b32 s21, s14, 0x1c000
	s_add_i32 s18, s18, s19
	s_mov_b32 s2, 0
	v_bfe_u32 v21, v208, 1, 1
	s_movk_i32 s12, 0x3c0
	s_mov_b32 s13, 0xffff0000
	v_mov_b32_e32 v24, 0x358637bd
	s_xor_b32 s14, s3, 15
	s_or_b32 s15, s3, 16
	s_xor_b32 s16, s3, 31
	s_add_i32 s17, s1, s17
	v_or_b32_e32 v0, s21, v0
	v_lshl_or_b32 v26, v210, 6, s18
	s_movk_i32 s18, 0x7fff
	v_readlane_b32 s48, v255, 51
	v_readlane_b32 s49, v255, 52
	v_readlane_b32 s50, v255, 53
	v_readlane_b32 s51, v255, 54
	v_readlane_b32 s52, v255, 55
	v_readlane_b32 s53, v255, 56
	v_readlane_b32 s54, v255, 57
	v_readlane_b32 s55, v255, 58
	s_waitcnt vmcnt(6)
	v_mul_f32_e32 v19, v1, v20
	ds_bpermute_b32 v31, v27, v19
	s_waitcnt vmcnt(4)
	v_mul_f32_e32 v30, v22, v23
	ds_bpermute_b32 v30, v27, v30
	s_waitcnt vmcnt(3)
	v_mov_b32_e32 v18, v2
	v_mov_b32_e32 v19, v4
	s_waitcnt lgkmcnt(1)
	v_fmac_f32_e32 v31, v1, v20
	ds_bpermute_b32 v1, v28, v31
	s_waitcnt lgkmcnt(1)
	v_fmac_f32_e32 v30, v22, v23
	ds_bpermute_b32 v2, v28, v30
	v_mov_b32_e32 v4, v3
	s_waitcnt vmcnt(2)
	v_mov_b32_e32 v22, v6
	s_waitcnt lgkmcnt(1)
	v_add_f32_e32 v1, v31, v1
	ds_bpermute_b32 v3, v29, v1
	s_waitcnt lgkmcnt(1)
	v_add_f32_e32 v2, v30, v2
	ds_bpermute_b32 v6, v29, v2
	v_mov_b32_e32 v23, v8
	v_mov_b32_e32 v8, v7
	s_waitcnt lgkmcnt(1)
	v_add_f32_e32 v1, v1, v3
	ds_bpermute_b32 v3, v32, v1
	s_waitcnt lgkmcnt(1)
	v_add_f32_e32 v2, v2, v6
	ds_bpermute_b32 v6, v32, v2
	s_waitcnt vmcnt(1)
	v_mov_b32_e32 v30, v10
	s_waitcnt vmcnt(0)
	v_mov_b32_e32 v32, v14
	s_waitcnt lgkmcnt(1)
	v_add_f32_e32 v1, v1, v3
	ds_bpermute_b32 v7, v34, v1
	s_waitcnt lgkmcnt(1)
	v_add_f32_e32 v6, v2, v6
	ds_bpermute_b32 v10, v34, v6
	v_mov_b32_e32 v33, v16
	v_mov_b32_e32 v16, v15
	s_waitcnt lgkmcnt(1)
	v_add_f32_e32 v1, v1, v7
	v_pk_mul_f32 v[2:3], v[18:19], s[0:1] op_sel_hi:[1,0]
	s_waitcnt lgkmcnt(0)
	v_add_f32_e32 v14, v6, v10
	ds_bpermute_b32 v15, v35, v1
	ds_bpermute_b32 v18, v35, v14
	v_mov_b32_e32 v31, v12
	v_mov_b32_e32 v12, v11
	v_pk_mul_f32 v[4:5], v[4:5], s[0:1] op_sel_hi:[1,0]
	s_waitcnt lgkmcnt(1)
	v_add_f32_e32 v1, v1, v15
	s_waitcnt lgkmcnt(0)
	v_add_f32_e32 v14, v14, v18
	v_mul_f32_e32 v1, 0x3fb8aa3b, v1
	v_mul_f32_e32 v14, 0x3fb8aa3b, v14
	v_exp_f32_e32 v1, v1
	v_exp_f32_e32 v18, v14
	v_pk_mul_f32 v[6:7], v[22:23], s[0:1] op_sel_hi:[1,0]
	v_pk_mul_f32 v[8:9], v[8:9], s[0:1] op_sel_hi:[1,0]
	v_pk_mul_f32 v[10:11], v[30:31], s[0:1] op_sel_hi:[1,0]
	v_sub_f32_e32 v1, v1, v18
	v_add_f32_e32 v18, 0x3eb60549, v1
	v_pk_mul_f32 v[12:13], v[12:13], s[0:1] op_sel_hi:[1,0]
	v_pk_mul_f32 v[14:15], v[32:33], s[0:1] op_sel_hi:[1,0]
	v_pk_mul_f32 v[16:17], v[16:17], s[0:1] op_sel_hi:[1,0]
	v_mov_b32_e32 v19, v18

; __device__ __forceinline__ void xcd_barrier(const XcdBarrier& b) {
;     asm volatile("s_waitcnt vmcnt(0)" ::: "memory");
;     __syncthreads();
;     if (threadIdx.x == 0) {
;         unsigned* bar = b.bar;
;         __builtin_amdgcn_s_waitcnt(0);
;         unsigned nloc = b.st[0], nx = b.st[1];
;         if (nloc == 0u) { xcd_barrier_complete(bar, b.x, nloc, nx); b.st[0] = nloc; b.st[1] = nx; }
.LBB0_1462:
	s_cmp_gt_u32 s37, 9
	s_cselect_b64 s[0:1], -1, 0
	s_and_b64 s[0:1], s[4:5], s[0:1]
	s_andn2_b64 vcc, exec, s[0:1]
	s_cbranch_vccnz .LBB0_1516
	s_waitcnt vmcnt(0)
	s_waitcnt vmcnt(0) lgkmcnt(0)
	s_barrier
	s_mov_b64 s[0:1], exec
	v_readlane_b32 s2, v255, 9
	v_readlane_b32 s3, v255, 10
	s_and_b64 s[2:3], s[0:1], s[2:3]
	s_mov_b64 exec, s[2:3]
	s_cbranch_execz .LBB0_1515
	s_add_i32 s2, 0, 0x20040
	v_mov_b32_e32 v0, s2
	s_waitcnt vmcnt(0) expcnt(0) lgkmcnt(0)
	ds_read_b32 v2, v0
	s_add_i32 s2, 0, 0x20044
	v_mov_b32_e32 v0, s2
	ds_read_b32 v0, v0
	s_waitcnt lgkmcnt(1)
	v_cmp_ne_u32_e32 vcc, 0, v2
	s_cbranch_vccnz .LBB0_1479
	v_readlane_b32 s2, v255, 4
	v_readlane_b32 s3, v255, 5
	v_readlane_b32 s4, v255, 7
	s_mul_i32 s18, s3, s4
	s_mul_i32 s18, s18, s2
	s_add_u32 s2, s28, 0x1000
	s_addc_u32 s3, s29, 0
	s_add_u32 s4, s28, 0x1100
	s_addc_u32 s5, s29, 0
	s_add_u32 s6, s28, 0x1200
	s_addc_u32 s7, s29, 0
	s_add_u32 s12, s28, 0x1300
	s_addc_u32 s13, s29, 0
	s_mov_b32 s19, 1
	v_mov_b32_e32 v16, 0
	s_branch .LBB0_1467

; __device__ __forceinline__ unsigned xb_ld(unsigned* p)              { return __hip_atomic_load(p, __ATOMIC_RELAXED, __HIP_MEMORY_SCOPE_AGENT); }
; __device__ __forceinline__ unsigned xb_add(unsigned* p, unsigned v) { return __hip_atomic_fetch_add(p, v, __ATOMIC_RELAXED, __HIP_MEMORY_SCOPE_AGENT); }
; __device__ __forceinline__ void xcd_barrier_complete(unsigned* bar, unsigned x, unsigned& nloc, unsigned& nx) {
;     ...
;         sum = 0u; cnt = 0u; mine = 0u;
; #pragma unroll
;         for (unsigned j = 0; j < 16; ++j) { const unsigned c = xb_ld(&bar[XB_XCNT(j)]); sum += c; cnt += (c > 0u) ? 1u : 0u; mine = (j == x) ? c : mine; }
;         if (sum == G) break;
;         __builtin_amdgcn_s_sleep(1);
;         if ((++sp & 255u) == 0u) { if (xb_ld(&bar[XB_TMO])) break; if (sp > XB_SPIN_CAP) { atomicAdd(&bar[XB_TMO], 1u); break; } }
;     }
;     nloc = mine > 0u ? mine : 1u; nx = cnt > 0u ? cnt : 1u;
; }
; __device__ __forceinline__ void xcd_barrier(const XcdBarrier& b) {
;     asm volatile("s_waitcnt vmcnt(0)" ::: "memory");
;     __syncthreads();
;     if (threadIdx.x == 0) {
;         unsigned* bar = b.bar;
;         __builtin_amdgcn_s_waitcnt(0);
;         unsigned nloc = b.st[0], nx = b.st[1];
;         if (nloc == 0u) { xcd_barrier_complete(bar, b.x, nloc, nx); b.st[0] = nloc; b.st[1] = nx; }
;         const unsigned old = xb_add(&bar[XB_XSUB(b.x)], 1u);
.LBB0_1478:
	v_readlane_b32 s2, v255, 8
	s_cmp_eq_u32 s2, 0
	s_cselect_b64 vcc, -1, 0
	s_cmp_eq_u32 s2, 1
	v_cndmask_b32_e32 v16, 0, v15, vcc
	s_cselect_b64 vcc, -1, 0
	s_cmp_eq_u32 s2, 2
	v_cndmask_b32_e32 v16, v16, v0, vcc
	s_cselect_b64 vcc, -1, 0
	s_cmp_eq_u32 s2, 3
	v_cndmask_b32_e32 v16, v16, v1, vcc
	s_cselect_b64 vcc, -1, 0
	s_cmp_eq_u32 s2, 4
	v_cndmask_b32_e32 v16, v16, v2, vcc
	s_cselect_b64 vcc, -1, 0
	s_cmp_eq_u32 s2, 5
	v_cndmask_b32_e32 v16, v16, v3, vcc
	s_cselect_b64 vcc, -1, 0
	s_cmp_eq_u32 s2, 6
	v_cndmask_b32_e32 v16, v16, v4, vcc
	s_cselect_b64 vcc, -1, 0
	s_cmp_eq_u32 s2, 7
	v_cndmask_b32_e32 v16, v16, v5, vcc
	s_cselect_b64 vcc, -1, 0
	s_cmp_eq_u32 s2, 8
	v_cndmask_b32_e32 v16, v16, v6, vcc
	s_cselect_b64 vcc, -1, 0
	s_cmp_eq_u32 s2, 9
	v_cndmask_b32_e32 v16, v16, v7, vcc
	s_cselect_b64 vcc, -1, 0
	s_cmp_eq_u32 s2, 10
	v_cndmask_b32_e32 v16, v16, v8, vcc
	s_cselect_b64 vcc, -1, 0
	s_cmp_eq_u32 s2, 11
	v_cndmask_b32_e32 v16, v16, v9, vcc
	s_cselect_b64 vcc, -1, 0
	s_cmp_eq_u32 s2, 12
	v_cndmask_b32_e32 v16, v16, v10, vcc
	s_cselect_b64 vcc, -1, 0
	s_cmp_eq_u32 s2, 13
	v_cndmask_b32_e32 v16, v16, v11, vcc
	s_cselect_b64 vcc, -1, 0
	s_cmp_eq_u32 s2, 14
	v_cndmask_b32_e32 v16, v16, v12, vcc
	s_cselect_b64 vcc, -1, 0
	s_cmp_eq_u32 s2, 15
	v_cndmask_b32_e32 v16, v16, v13, vcc
	s_cselect_b64 vcc, -1, 0
	v_cndmask_b32_e32 v16, v16, v14, vcc
	v_cmp_ne_u32_e32 vcc, 0, v15
	s_add_i32 s2, 0, 0x20040
	s_nop 0
	v_cndmask_b32_e64 v15, 0, 1, vcc
	v_cmp_ne_u32_e32 vcc, 0, v0
	s_nop 1
	v_addc_co_u32_e32 v0, vcc, 0, v15, vcc
	v_cmp_ne_u32_e32 vcc, 0, v1
	s_nop 1
	v_cndmask_b32_e64 v1, 0, 1, vcc
	v_cmp_ne_u32_e32 vcc, 0, v2
	v_max_u32_e32 v2, 1, v16
	s_nop 0
	v_addc_co_u32_e32 v0, vcc, v0, v1, vcc
	v_cmp_ne_u32_e32 vcc, 0, v3
	s_nop 1
	v_cndmask_b32_e64 v1, 0, 1, vcc
	v_cmp_ne_u32_e32 vcc, 0, v4
	s_nop 1
	v_addc_co_u32_e32 v0, vcc, v0, v1, vcc
	v_cmp_ne_u32_e32 vcc, 0, v5
	s_nop 1
	v_cndmask_b32_e64 v1, 0, 1, vcc
	v_cmp_ne_u32_e32 vcc, 0, v6
	s_nop 1
	v_addc_co_u32_e32 v0, vcc, v0, v1, vcc
	v_cmp_ne_u32_e32 vcc, 0, v7
	s_nop 1
	v_cndmask_b32_e64 v1, 0, 1, vcc
	v_cmp_ne_u32_e32 vcc, 0, v8
	s_nop 1
	v_addc_co_u32_e32 v0, vcc, v0, v1, vcc
	v_cmp_ne_u32_e32 vcc, 0, v9
	s_nop 1
	v_cndmask_b32_e64 v1, 0, 1, vcc
	v_cmp_ne_u32_e32 vcc, 0, v10
	s_nop 1
	v_addc_co_u32_e32 v0, vcc, v0, v1, vcc
	v_cmp_ne_u32_e32 vcc, 0, v11
	s_nop 1
	v_cndmask_b32_e64 v1, 0, 1, vcc
	v_cmp_ne_u32_e32 vcc, 0, v12
	s_nop 1
	v_addc_co_u32_e32 v0, vcc, v0, v1, vcc
	v_cmp_ne_u32_e32 vcc, 0, v13
	s_nop 1
	v_cndmask_b32_e64 v1, 0, 1, vcc
	v_cmp_ne_u32_e32 vcc, 0, v14
	s_nop 1
	v_addc_co_u32_e32 v0, vcc, v0, v1, vcc
	v_mov_b32_e32 v1, s2
	s_add_i32 s2, 0, 0x20044
	v_max_u32_e32 v0, 1, v0
	ds_write_b32 v1, v2
	v_mov_b32_e32 v1, s2
	ds_write_b32 v1, v0
.LBB0_1479:
	s_mov_b64 s[4:5], exec
	v_readlane_b32 s2, v255, 8
	s_lshl_b32 s2, s2, 8
	v_mbcnt_lo_u32_b32 v1, s4, 0
	s_add_u32 s2, s28, s2
	v_mbcnt_hi_u32_b32 v1, s5, v1
	s_addc_u32 s3, s29, 0
	v_cmp_eq_u32_e32 vcc, 0, v1
	s_and_saveexec_b64 s[6:7], vcc
	s_cbranch_execz .LBB0_1481
	s_bcnt1_i32_b64 s4, s[4:5]
	v_mov_b32_e32 v3, 0x1000
	v_mov_b32_e32 v4, s4
	global_atomic_add v3, v3, v4, s[2:3] offset:1024 sc0

.LBB0_1491:
	s_or_b64 exec, exec, s[14:15]
	s_xor_b64 s[12:13], s[16:17], -1
	s_and_saveexec_b64 s[14:15], s[12:13]
	v_readlane_b32 s36, v254, 4
	v_readlane_b32 s37, v254, 5
	s_xor_b64 s[14:15], exec, s[14:15]
	s_cbranch_execz .LBB0_1494
	s_mov_b64 s[12:13], exec
	v_mbcnt_lo_u32_b32 v0, s12, 0
	v_mbcnt_hi_u32_b32 v0, s13, v0
	v_cmp_eq_u32_e32 vcc, 0, v0
	s_and_b64 s[14:15], exec, vcc
	s_mov_b64 exec, s[14:15]
	s_cbranch_execz .LBB0_1494
	s_bcnt1_i32_b64 s12, s[12:13]
	v_mov_b32_e32 v0, 0
	v_mov_b32_e32 v1, s12
	global_atomic_add v0, v1, s[28:29] offset:512

; __device__ __forceinline__ unsigned xb_ld(unsigned* p)              { return __hip_atomic_load(p, __ATOMIC_RELAXED, __HIP_MEMORY_SCOPE_AGENT); }
; __device__ __forceinline__ unsigned xb_add(unsigned* p, unsigned v) { return __hip_atomic_fetch_add(p, v, __ATOMIC_RELAXED, __HIP_MEMORY_SCOPE_AGENT); }
; #define XB_SPIN(cond, bar) do { unsigned _sp = 0; while (cond) { __builtin_amdgcn_s_sleep(1); \
;     if ((++_sp & 255u) == 0u) { if (xb_ld(&(bar)[XB_TMO])) break; if (_sp > XB_SPIN_CAP) { atomicAdd(&(bar)[XB_TMO], 1u); break; } } } } while (0)
; __device__ __forceinline__ void xcd_barrier(const XcdBarrier& b) {
;     ...
;             const unsigned og = xb_add(&bar[XB_TOP], 1u);
;             const unsigned tg = og / nx;
;             if (og + 1u == (tg + 1u) * nx) xb_add(&bar[XB_TOPGEN], 1u);
;             else XB_SPIN(xb_ld(&bar[XB_TOPGEN]) == tg, bar);
;             __builtin_amdgcn_fence(__ATOMIC_ACQUIRE, "agent");
;             xb_add(&bar[XB_XGEN(b.x)], 1u);
;             asm volatile("s_waitcnt vmcnt(0)" ::: "memory");
;         } else {
;             XB_SPIN(xb_ld(&bar[XB_XGEN(b.x)]) == gen, bar);
;             __builtin_amdgcn_fence(__ATOMIC_ACQUIRE, "agent");
;             asm volatile("s_waitcnt vmcnt(0)" ::: "memory");
;         }
.LBB0_1508:
	s_or_b64 exec, exec, s[16:17]
	v_readlane_b32 s36, v254, 4
	s_and_b64 s[16:17], s[24:25], exec
	v_readlane_b32 s37, v254, 5

; #define PG8_STAGE(bufoff, gbase, voff) do { _Pragma("unroll") for (int _i = 0; _i < 2; ++_i) \
;         __builtin_amdgcn_global_load_lds((const unsigned*)((const char*)(gbase) + (voff)[_i]), (PG8_LAS unsigned*)(lds + (bufoff) + ldsw + _i * 8192), 16, 0, 0); } while (0)
; #define PG8_WAIT_V(n) asm volatile("s_waitcnt vmcnt(" #n ")" ::: "memory")
; #define PG8_BAR __builtin_amdgcn_s_barrier()
; template <class Epi, class Sched, bool ALIGN_EPI = false, bool SP2 = false, bool TA = true>
; __device__ __forceinline__ void gemm_phase(PG8_LAS unsigned char* lds, const Gemm g, const Sched& S, const Epi& E) {
;     ...
;     const unsigned ldsw = (unsigned)wid * 1024u;
;     const int aoff = lds_byte(wr * 64 + fr, fq * 8), boff = lds_byte(wc * 32 + fr, fq * 8);
;     ...
;         PG8_WAIT_V(2); PG8_BAR;
;         PG8_STAGE(PG8_SB(1, 0), cB + kstepB, voffB); PG8_STAGE(PG8_SA(1, 0), cA + kstep, voffA); PG8_STAGE(PG8_SB(1, 1), cB + hstep + kstepB, voffB);
;         PG8_WAIT_V(6); PG8_BAR;
.LBB0_1526:
	s_mov_b64 s[36:37], 0x4000
	s_add_i32 m0, s22, 0x18000
	v_lshl_add_u64 v[4:5], v[0:1], 0, s[36:37]
	s_mov_b64 s[38:39], 0x6000
	s_waitcnt vmcnt(2)
	s_barrier
	global_load_lds_dwordx4 v[4:5], off
	v_lshl_add_u64 v[4:5], v[0:1], 0, s[38:39]
	s_add_i32 m0, s22, 0x1a000
	s_add_i32 s33, s22, 0x8000
	global_load_lds_dwordx4 v[4:5], off
	v_lshl_add_u64 v[4:5], v[2:3], 0, s[36:37]
	s_mov_b32 m0, s33
	s_add_i32 s66, s22, 0xa000
	global_load_lds_dwordx4 v[4:5], off
	v_lshl_add_u64 v[2:3], v[2:3], 0, s[38:39]
	s_mov_b32 m0, s66
	s_mov_b64 s[40:41], 0x44000
	global_load_lds_dwordx4 v[2:3], off
	s_add_i32 m0, s22, 0x1c000
	v_lshl_add_u64 v[2:3], v[0:1], 0, s[40:41]
	s_mov_b64 s[42:43], 0x46000
	global_load_lds_dwordx4 v[2:3], off
	v_lshl_add_u64 v[0:1], v[0:1], 0, s[42:43]
	s_add_i32 m0, s22, 0x1e000
	v_and_b32_e32 v146, 15, v208
	global_load_lds_dwordx4 v[0:1], off
	v_and_b32_e32 v147, 48, v208
	v_lshlrev_b32_e32 v1, 2, v208
	s_and_b32 s67, s3, 3
	s_lshl_b32 s3, s2, 13
	v_lshl_or_b32 v0, v146, 6, v147
	v_and_b32_e32 v1, 32, v1
	s_lshl_b32 s68, s2, 6
	v_bitop3_b32 v0, v0, s3, v1 bitop3:0xde
	s_lshl_b32 s69, s67, 5
	s_lshl_b32 s3, s67, 12
	s_cmpk_lt_u32 s46, 0x100
	v_lshlrev_b32_e32 v2, 6, v208
	s_movk_i32 s70, 0x3c0
	s_cselect_b64 s[44:45], -1, 0
	s_lshl_b32 s2, s2, 3
	v_and_or_b32 v2, v2, s70, v147
	s_waitcnt vmcnt(6)
	s_and_b32 s4, s2, 8
	s_bfe_u32 s74, s46, 0x10006
	v_bitop3_b32 v148, s3, v2, v1 bitop3:0xf6
	v_readlane_b32 s48, v255, 4
	s_or_b32 s4, s4, s74
	s_add_i32 s76, 0, 0x10000
	s_add_i32 s77, 0, 0x14000
	v_add_u32_e32 v151, 0, v0
	v_mbcnt_lo_u32_b32 v0, -1, 0
	v_cmp_eq_u32_e64 s[2:3], 0, v147
	s_ashr_i32 s71, s48, 31
	s_mov_b32 s72, s48
	s_ashr_i32 s73, s20, 31
	s_lshl_b32 s75, s4, 10
	v_mov_b64_e32 v[138:139], 0x200
	v_mov_b64_e32 v[140:141], 0x1ff
	v_add_u32_e32 v149, s76, v148
	v_add_u32_e32 v150, s77, v148
	v_mbcnt_hi_u32_b32 v152, -1, v0
	s_mov_b32 s78, 0
	s_barrier
	v_readlane_b32 s49, v255, 5
	s_branch .LBB0_1529

; __device__ __forceinline__ void xcd_barrier(const XcdBarrier& b) {
;     asm volatile("s_waitcnt vmcnt(0)" ::: "memory");
;     __syncthreads();
;     if (threadIdx.x == 0) {
;         unsigned* bar = b.bar;
;         __builtin_amdgcn_s_waitcnt(0);
;         unsigned nloc = b.st[0], nx = b.st[1];
;         if (nloc == 0u) { xcd_barrier_complete(bar, b.x, nloc, nx); b.st[0] = nloc; b.st[1] = nx; }
.LBB0_1559:
	s_cmp_gt_i32 s37, 11
	s_cselect_b64 s[2:3], -1, 0
	s_and_b64 s[0:1], s[0:1], s[2:3]
	s_andn2_b64 vcc, exec, s[0:1]
	s_cbranch_vccnz .LBB0_1613
	s_waitcnt vmcnt(0)
	s_waitcnt vmcnt(0) lgkmcnt(0)
	s_barrier
	s_mov_b64 s[0:1], exec
	v_readlane_b32 s4, v255, 9
	v_readlane_b32 s5, v255, 10
	s_and_b64 s[4:5], s[0:1], s[4:5]
	s_mov_b64 exec, s[4:5]
	s_cbranch_execz .LBB0_1612
	s_add_i32 s4, 0, 0x20040
	v_mov_b32_e32 v0, s4
	s_waitcnt vmcnt(0) expcnt(0) lgkmcnt(0)
	ds_read_b32 v2, v0
	s_add_i32 s4, 0, 0x20044
	v_mov_b32_e32 v0, s4
	ds_read_b32 v0, v0
	s_waitcnt lgkmcnt(1)
	v_cmp_ne_u32_e32 vcc, 0, v2
	s_cbranch_vccnz .LBB0_1576
	v_readlane_b32 s4, v255, 4
	v_readlane_b32 s5, v255, 5
	v_readlane_b32 s6, v255, 7
	s_mul_i32 s18, s5, s6
	s_mul_i32 s18, s18, s4
	s_add_u32 s4, s28, 0x1000
	s_addc_u32 s5, s29, 0
	s_add_u32 s6, s28, 0x1100
	s_addc_u32 s7, s29, 0
	s_add_u32 s12, s28, 0x1200
	s_addc_u32 s13, s29, 0
	s_add_u32 s14, s28, 0x1300
	s_addc_u32 s15, s29, 0
	s_mov_b32 s19, 1
	v_mov_b32_e32 v16, 0
	s_branch .LBB0_1564

.LBB0_1588:
	s_or_b64 exec, exec, s[16:17]
	s_xor_b64 s[14:15], s[24:25], -1
	s_and_saveexec_b64 s[16:17], s[14:15]
	v_readlane_b32 s36, v254, 4
	v_readlane_b32 s37, v254, 5
	s_xor_b64 s[16:17], exec, s[16:17]
	s_cbranch_execz .LBB0_1591
	s_mov_b64 s[14:15], exec
	v_mbcnt_lo_u32_b32 v0, s14, 0
	v_mbcnt_hi_u32_b32 v0, s15, v0
	v_cmp_eq_u32_e32 vcc, 0, v0
	s_and_b64 s[16:17], exec, vcc
	s_mov_b64 exec, s[16:17]
	s_cbranch_execz .LBB0_1591
	s_bcnt1_i32_b64 s14, s[14:15]
	v_mov_b32_e32 v0, 0
	v_mov_b32_e32 v1, s14
	global_atomic_add v0, v1, s[28:29] offset:512

; __device__ __forceinline__ unsigned xb_ld(unsigned* p)              { return __hip_atomic_load(p, __ATOMIC_RELAXED, __HIP_MEMORY_SCOPE_AGENT); }
; __device__ __forceinline__ unsigned xb_add(unsigned* p, unsigned v) { return __hip_atomic_fetch_add(p, v, __ATOMIC_RELAXED, __HIP_MEMORY_SCOPE_AGENT); }
; #define XB_SPIN(cond, bar) do { unsigned _sp = 0; while (cond) { __builtin_amdgcn_s_sleep(1); \
;     if ((++_sp & 255u) == 0u) { if (xb_ld(&(bar)[XB_TMO])) break; if (_sp > XB_SPIN_CAP) { atomicAdd(&(bar)[XB_TMO], 1u); break; } } } } while (0)
; __device__ __forceinline__ void xcd_barrier(const XcdBarrier& b) {
;     ...
;             const unsigned og = xb_add(&bar[XB_TOP], 1u);
;             const unsigned tg = og / nx;
;             if (og + 1u == (tg + 1u) * nx) xb_add(&bar[XB_TOPGEN], 1u);
;             else XB_SPIN(xb_ld(&bar[XB_TOPGEN]) == tg, bar);
;             __builtin_amdgcn_fence(__ATOMIC_ACQUIRE, "agent");
;             xb_add(&bar[XB_XGEN(b.x)], 1u);
;             asm volatile("s_waitcnt vmcnt(0)" ::: "memory");
;         } else {
;             XB_SPIN(xb_ld(&bar[XB_XGEN(b.x)]) == gen, bar);
;             __builtin_amdgcn_fence(__ATOMIC_ACQUIRE, "agent");
;             asm volatile("s_waitcnt vmcnt(0)" ::: "memory");
;         }
.LBB0_1605:
	s_or_b64 exec, exec, s[24:25]
	v_readlane_b32 s36, v254, 4
	s_and_b64 s[24:25], s[34:35], exec
	v_readlane_b32 s37, v254, 5

; #define PG8_STAGE(bufoff, gbase, voff) do { _Pragma("unroll") for (int _i = 0; _i < 2; ++_i) \
;         __builtin_amdgcn_global_load_lds((const unsigned*)((const char*)(gbase) + (voff)[_i]), (PG8_LAS unsigned*)(lds + (bufoff) + ldsw + _i * 8192), 16, 0, 0); } while (0)
; #define PG8_WAIT_V(n) asm volatile("s_waitcnt vmcnt(" #n ")" ::: "memory")
; #define PG8_BAR __builtin_amdgcn_s_barrier()
; template <class Epi, class Sched, bool ALIGN_EPI = false, bool SP2 = false, bool TA = true>
; __device__ __forceinline__ void gemm_phase(PG8_LAS unsigned char* lds, const Gemm g, const Sched& S, const Epi& E) {
;     ...
;     const unsigned ldsw = (unsigned)wid * 1024u;
;     const int aoff = lds_byte(wr * 64 + fr, fq * 8), boff = lds_byte(wc * 32 + fr, fq * 8);
;     ...
;         PG8_WAIT_V(2); PG8_BAR;
;         PG8_STAGE(PG8_SB(1, 0), cB + kstepB, voffB); PG8_STAGE(PG8_SA(1, 0), cA + kstep, voffA); PG8_STAGE(PG8_SB(1, 1), cB + hstep + kstepB, voffB);
;         PG8_WAIT_V(6); PG8_BAR;
.LBB0_1619:
	s_add_u32 s24, s28, 0xe000000
	s_mov_b64 s[34:35], 0x4000
	s_addc_u32 s25, s29, 0
	s_add_i32 m0, s23, 0x18000
	v_lshl_add_u64 v[4:5], v[0:1], 0, s[34:35]
	s_mov_b64 s[36:37], 0x6000
	s_waitcnt vmcnt(2)
	s_barrier
	global_load_lds_dwordx4 v[4:5], off
	v_lshl_add_u64 v[4:5], v[0:1], 0, s[36:37]
	s_add_i32 m0, s23, 0x1a000
	s_add_i32 s60, s23, 0x8000
	global_load_lds_dwordx4 v[4:5], off
	v_lshl_add_u64 v[4:5], v[2:3], 0, s[34:35]
	s_mov_b32 m0, s60
	s_add_i32 s61, s23, 0xa000
	global_load_lds_dwordx4 v[4:5], off
	v_lshl_add_u64 v[2:3], v[2:3], 0, s[36:37]
	s_mov_b32 m0, s61
	s_mov_b64 s[38:39], 0x44000
	global_load_lds_dwordx4 v[2:3], off
	s_add_i32 m0, s23, 0x1c000
	v_lshl_add_u64 v[2:3], v[0:1], 0, s[38:39]
	s_mov_b64 s[40:41], 0x46000
	global_load_lds_dwordx4 v[2:3], off
	v_lshl_add_u64 v[0:1], v[0:1], 0, s[40:41]
	s_add_i32 m0, s23, 0x1e000
	v_and_b32_e32 v142, 15, v208
	global_load_lds_dwordx4 v[0:1], off
	v_and_b32_e32 v143, 48, v208
	v_lshlrev_b32_e32 v1, 2, v142
	s_lshl_b32 s42, s4, 13
	v_lshl_or_b32 v0, v142, 6, v143
	v_and_b32_e32 v2, 32, v1
	s_and_b32 s5, s5, 3
	v_bitop3_b32 v0, v0, s42, v2 bitop3:0xde
	v_lshlrev_b32_e32 v2, 6, v208
	s_movk_i32 s64, 0x3c0
	v_lshlrev_b32_e32 v3, 2, v208
	s_lshl_b32 s63, s5, 5
	s_lshl_b32 s5, s5, 12
	v_and_or_b32 v2, v2, s64, v143
	v_and_b32_e32 v4, 32, v3
	s_lshl_b32 s62, s4, 6
	v_bitop3_b32 v144, s5, v2, v4 bitop3:0xf6
	s_add_i32 s5, 0, 0x20400
	s_cmpk_lt_u32 s44, 0x100
	s_cselect_b64 s[42:43], -1, 0
	s_lshl_b32 s4, s4, 3
	s_and_b32 s45, s44, 0xffffff00
	s_bfe_u32 s65, s44, 0x10006
	s_and_b32 s4, s4, 8
	s_waitcnt vmcnt(6)
	v_add_u32_e32 v145, s5, v3
	s_add_i32 s5, s5, s45
	s_or_b32 s4, s4, s65
	v_add_u32_e32 v146, s5, v1
	s_lshl_b32 s66, s4, 10
	v_readlane_b32 s4, v255, 4
	s_add_i32 s70, 0, 0x10000
	s_add_i32 s71, 0, 0x14000
	s_mov_b32 s53, 0
	s_ashr_i32 s67, s4, 31
	s_mov_b32 s68, s4
	v_mov_b64_e32 v[132:133], 0xb00
	v_mov_b64_e32 v[134:135], 0xaff
	s_movk_i32 s69, 0x161
	v_add_u32_e32 v147, s70, v144
	v_add_u32_e32 v148, s71, v144
	v_add_u32_e32 v149, 0, v0
	v_mov_b32_e32 v150, 0x358637bd
	s_barrier
	v_readlane_b32 s5, v255, 5
	s_branch .LBB0_1622

; __device__ __forceinline__ void xcd_barrier(const XcdBarrier& b) {
;     asm volatile("s_waitcnt vmcnt(0)" ::: "memory");
;     __syncthreads();
;     if (threadIdx.x == 0) {
;         unsigned* bar = b.bar;
;         __builtin_amdgcn_s_waitcnt(0);
;         unsigned nloc = b.st[0], nx = b.st[1];
;         if (nloc == 0u) { xcd_barrier_complete(bar, b.x, nloc, nx); b.st[0] = nloc; b.st[1] = nx; }
.LBB0_1634:
	s_cmp_gt_i32 s37, 12
	s_cselect_b64 s[2:3], -1, 0
	s_and_b64 s[0:1], s[0:1], s[2:3]
	s_andn2_b64 vcc, exec, s[0:1]
	s_cbranch_vccnz .LBB0_1688
	s_waitcnt vmcnt(0)
	s_waitcnt vmcnt(0) lgkmcnt(0)
	s_barrier
	s_mov_b64 s[0:1], exec
	v_readlane_b32 s4, v255, 9
	v_readlane_b32 s5, v255, 10
	s_and_b64 s[4:5], s[0:1], s[4:5]
	s_mov_b64 exec, s[4:5]
	s_cbranch_execz .LBB0_1687
	s_add_i32 s4, 0, 0x20040
	v_mov_b32_e32 v0, s4
	s_waitcnt vmcnt(0) expcnt(0) lgkmcnt(0)
	ds_read_b32 v2, v0
	s_add_i32 s4, 0, 0x20044
	v_mov_b32_e32 v0, s4
	ds_read_b32 v0, v0
	s_waitcnt lgkmcnt(1)
	v_cmp_ne_u32_e32 vcc, 0, v2
	s_cbranch_vccnz .LBB0_1651
	v_readlane_b32 s4, v255, 4
	v_readlane_b32 s5, v255, 5
	v_readlane_b32 s6, v255, 7
	s_mul_i32 s18, s5, s6
	s_mul_i32 s18, s18, s4
	s_add_u32 s4, s28, 0x1000
	s_addc_u32 s5, s29, 0
	s_add_u32 s6, s28, 0x1100
	s_addc_u32 s7, s29, 0
	s_add_u32 s12, s28, 0x1200
	s_addc_u32 s13, s29, 0
	s_add_u32 s14, s28, 0x1300
	s_addc_u32 s15, s29, 0
	s_mov_b32 s19, 1
	v_mov_b32_e32 v16, 0
	s_branch .LBB0_1639

; #define PG8_STAGE(bufoff, gbase, voff) do { _Pragma("unroll") for (int _i = 0; _i < 2; ++_i) \
;         __builtin_amdgcn_global_load_lds((const unsigned*)((const char*)(gbase) + (voff)[_i]), (PG8_LAS unsigned*)(lds + (bufoff) + ldsw + _i * 8192), 16, 0, 0); } while (0)
; #define PG8_WAIT_V(n) asm volatile("s_waitcnt vmcnt(" #n ")" ::: "memory")
; #define PG8_BAR __builtin_amdgcn_s_barrier()
; template <class Epi, class Sched, bool ALIGN_EPI = false, bool SP2 = false, bool TA = true>
; __device__ __forceinline__ void gemm_phase(PG8_LAS unsigned char* lds, const Gemm g, const Sched& S, const Epi& E) {
;     ...
;     const unsigned ldsw = (unsigned)wid * 1024u;
;     const int aoff = lds_byte(wr * 64 + fr, fq * 8), boff = lds_byte(wc * 32 + fr, fq * 8);
;     ...
;         PG8_WAIT_V(2); PG8_BAR;
;         PG8_STAGE(PG8_SB(1, 0), cB + kstepB, voffB); PG8_STAGE(PG8_SA(1, 0), cA + kstep, voffA); PG8_STAGE(PG8_SB(1, 1), cB + hstep + kstepB, voffB);
;         PG8_WAIT_V(6); PG8_BAR;
.LBB0_1698:
	s_mov_b64 s[38:39], 0x4000
	s_add_i32 m0, s30, 0x18000
	v_lshl_add_u64 v[4:5], v[0:1], 0, s[38:39]
	s_mov_b64 s[40:41], 0x6000
	s_waitcnt vmcnt(2)
	s_barrier
	global_load_lds_dwordx4 v[4:5], off
	v_lshl_add_u64 v[4:5], v[0:1], 0, s[40:41]
	s_add_i32 m0, s30, 0x1a000
	s_add_i32 s63, s30, 0x8000
	global_load_lds_dwordx4 v[4:5], off
	v_lshl_add_u64 v[4:5], v[2:3], 0, s[38:39]
	s_mov_b32 m0, s63
	s_add_i32 s64, s30, 0xa000
	global_load_lds_dwordx4 v[4:5], off
	v_lshl_add_u64 v[2:3], v[2:3], 0, s[40:41]
	s_mov_b32 m0, s64
	s_mov_b64 s[42:43], 0xb4000
	global_load_lds_dwordx4 v[2:3], off
	s_add_i32 m0, s30, 0x1c000
	v_lshl_add_u64 v[2:3], v[0:1], 0, s[42:43]
	s_mov_b64 s[44:45], 0xb6000
	global_load_lds_dwordx4 v[2:3], off
	v_lshl_add_u64 v[0:1], v[0:1], 0, s[44:45]
	s_add_i32 m0, s30, 0x1e000
	s_and_b32 s65, s1, 3
	global_load_lds_dwordx4 v[0:1], off
	s_lshl_b32 s66, s0, 6
	s_lshl_b32 s1, s0, 13
	s_lshl_b32 s67, s65, 5
	v_lshlrev_b32_e32 v1, 2, v146
	s_cmpk_lt_u32 s6, 0x100
	v_lshl_or_b32 v0, v146, 6, v147
	v_and_b32_e32 v1, 32, v1
	s_cselect_b64 s[46:47], -1, 0
	s_lshl_b32 s0, s0, 3
	v_bitop3_b32 v0, v0, s1, v1 bitop3:0xde
	s_waitcnt vmcnt(6)
	s_and_b32 s0, s0, 8
	s_bfe_u32 s71, s6, 0x10006
	v_lshl_or_b32 v149, s65, 12, v148
	v_readlane_b32 s48, v255, 4
	s_or_b32 s0, s0, s71
	s_add_i32 s73, 0, 0x10000
	s_add_i32 s74, 0, 0x14000
	v_add_u32_e32 v152, 0, v0
	v_mbcnt_lo_u32_b32 v0, -1, 0
	v_cmp_eq_u32_e64 s[4:5], 0, v147
	s_ashr_i32 s68, s48, 31
	s_mov_b32 s69, s48
	s_ashr_i32 s70, s20, 31
	s_lshl_b32 s72, s0, 10
	v_mov_b64_e32 v[138:139], 0x200
	v_mov_b64_e32 v[140:141], 0x1ff
	v_add_u32_e32 v150, s73, v149
	v_add_u32_e32 v151, s74, v149
	s_movk_i32 s75, 0x3c0
	v_mbcnt_hi_u32_b32 v153, -1, v0
	s_mov_b32 s76, 0
	s_barrier
	v_readlane_b32 s49, v255, 5
	s_branch .LBB0_1701

;   __device__ __forceinline__ bool next(int i,AttnUnit&u)const{ if(i>=8)return false; const int s=vcu&7,k=i&3; { const int p_=vcu>>3; u.bh=(p_>>3)*16+(p_&7)*2+(i>>2); } u.qb=(k==0)?s:(k==1)?15-s:(k==2)?16+s:31-s; return true; }
;     __host__ __device__ bool next(int i, Unit& u) const {
;         const long L = (long)i * G + c; if (L >= nwg) return false;
;         int wgid = (int)L; { const int q = nwg / NXCD, r = nwg % NXCD, xcd = wgid % NXCD, off = wgid / NXCD; wgid = (xcd < r ? xcd * (q + 1) : r * (q + 1) + (xcd - r) * q) + off; }
;         const int nig = WGM * nN, gid = wgid / nig, fm = gid * WGM, gsz = (nM - fm) < WGM ? (nM - fm) : WGM;
;         u.pm = fm + ((wgid % nig) % gsz); u.pn = (wgid % nig) / gsz; return true;
.LBB0_1735:
	v_readlane_b32 s36, v254, 4
	s_and_b64 vcc, exec, s[2:3]
	v_readfirstlane_b32 s3, v208
	v_readlane_b32 s37, v254, 5
	s_cbranch_vccnz .LBB0_1759
	s_ashr_i32 s18, s20, 31
	s_lshr_b32 s0, s18, 29
	s_add_i32 s2, s20, s0
	s_and_b32 s0, s2, -8
	s_sub_i32 s5, s20, s0
	s_cmp_gt_i32 s5, -1
	s_cbranch_scc0 .LBB0_1738
	s_lshl_b32 s4, s5, 6
	s_cbranch_execz .LBB0_1739
	s_branch .LBB0_1740

; #define PG8_STAGE(bufoff, gbase, voff) do { _Pragma("unroll") for (int _i = 0; _i < 2; ++_i) \
;         __builtin_amdgcn_global_load_lds((const unsigned*)((const char*)(gbase) + (voff)[_i]), (PG8_LAS unsigned*)(lds + (bufoff) + ldsw + _i * 8192), 16, 0, 0); } while (0)
; #define PG8_WAIT_V(n) asm volatile("s_waitcnt vmcnt(" #n ")" ::: "memory")
; #define PG8_BAR __builtin_amdgcn_s_barrier()
; template <class Epi, class Sched, bool ALIGN_EPI = false, bool SP2 = false, bool TA = true>
; __device__ __forceinline__ void gemm_phase(PG8_LAS unsigned char* lds, const Gemm g, const Sched& S, const Epi& E) {
;     ...
;     const unsigned ldsw = (unsigned)wid * 1024u;
;     const int aoff = lds_byte(wr * 64 + fr, fq * 8), boff = lds_byte(wc * 32 + fr, fq * 8);
;     ...
;         PG8_WAIT_V(2); PG8_BAR;
;         PG8_STAGE(PG8_SB(1, 0), cB + kstepB, voffB); PG8_STAGE(PG8_SA(1, 0), cA + kstep, voffA); PG8_STAGE(PG8_SB(1, 1), cB + hstep + kstepB, voffB);
;         PG8_WAIT_V(6); PG8_BAR;
.LBB0_1742:
	s_add_u32 s16, s28, 0x1a000000
	s_mov_b64 s[24:25], 0x4000
	s_addc_u32 s17, s29, 0
	s_add_i32 m0, s31, 0x18000
	v_lshl_add_u64 v[4:5], v[0:1], 0, s[24:25]
	s_mov_b64 s[34:35], 0x6000
	s_waitcnt vmcnt(2)
	s_barrier
	global_load_lds_dwordx4 v[4:5], off
	v_lshl_add_u64 v[4:5], v[0:1], 0, s[34:35]
	s_add_i32 m0, s31, 0x1a000
	s_add_i32 s69, s31, 0x8000
	global_load_lds_dwordx4 v[4:5], off
	v_lshl_add_u64 v[4:5], v[2:3], 0, s[24:25]
	s_mov_b32 m0, s69
	s_add_i32 s70, s31, 0xa000
	global_load_lds_dwordx4 v[4:5], off
	v_lshl_add_u64 v[2:3], v[2:3], 0, s[34:35]
	s_mov_b32 m0, s70
	s_mov_b64 s[36:37], 0x14000
	global_load_lds_dwordx4 v[2:3], off
	s_add_i32 m0, s31, 0x1c000
	v_lshl_add_u64 v[2:3], v[0:1], 0, s[36:37]
	s_mov_b64 s[38:39], 0x16000
	global_load_lds_dwordx4 v[2:3], off
	v_lshl_add_u64 v[0:1], v[0:1], 0, s[38:39]
	s_add_i32 m0, s31, 0x1e000
	s_sext_i32_i8 s51, s2
	global_load_lds_dwordx4 v[0:1], off
	s_and_b32 s2, s40, 3
	s_lshl_b32 s71, s42, 6
	s_lshl_b32 s40, s42, 13
	v_lshlrev_b32_e32 v1, 2, v146
	s_lshl_b32 s72, s2, 5
	v_lshl_or_b32 v0, v146, 6, v147
	v_and_b32_e32 v1, 32, v1
	s_cmpk_lt_u32 s3, 0x100
	v_bitop3_b32 v0, v0, s40, v1 bitop3:0xde
	v_lshl_or_b32 v136, s2, 12, v148
	s_cselect_b64 s[40:41], -1, 0
	s_lshl_b32 s2, s42, 3
	s_bfe_u32 s73, s3, 0x10006
	s_and_b32 s2, s2, 8
	s_waitcnt vmcnt(6)
	s_or_b32 s2, s2, s73
	s_lshl_b32 s74, s2, 10
	v_readlane_b32 s2, v255, 4
	s_add_i32 s77, 0, 0x10000
	s_add_i32 s78, 0, 0x14000
	s_ashr_i32 s75, s2, 31
	s_mov_b32 s76, s2
	v_mov_b64_e32 v[130:131], 0x200
	v_mov_b64_e32 v[132:133], 0x1ff
	v_add_u32_e32 v137, s77, v136
	v_add_u32_e32 v138, s78, v136
	v_add_u32_e32 v139, 0, v0
	s_movk_i32 s79, 0x3c0
	s_barrier
	v_readlane_b32 s3, v255, 5
	s_branch .LBB0_1745

; __device__ __forceinline__ void xcd_barrier(const XcdBarrier& b) {
;     asm volatile("s_waitcnt vmcnt(0)" ::: "memory");
;     __syncthreads();
;     if (threadIdx.x == 0) {
;         unsigned* bar = b.bar;
;         __builtin_amdgcn_s_waitcnt(0);
;         unsigned nloc = b.st[0], nx = b.st[1];
;         if (nloc == 0u) { xcd_barrier_complete(bar, b.x, nloc, nx); b.st[0] = nloc; b.st[1] = nx; }
.LBB0_1759:
	s_cmp_gt_i32 s37, 13
	s_cselect_b64 s[0:1], -1, 0
	s_and_b64 s[2:3], s[12:13], s[0:1]
	s_andn2_b64 vcc, exec, s[2:3]
	s_cbranch_vccnz .LBB0_1813
	s_waitcnt vmcnt(0)
	s_waitcnt vmcnt(0) lgkmcnt(0)
	s_barrier
	s_mov_b64 s[2:3], exec
	v_readlane_b32 s4, v255, 9
	v_readlane_b32 s5, v255, 10
	s_and_b64 s[4:5], s[2:3], s[4:5]
	s_mov_b64 exec, s[4:5]
	s_cbranch_execz .LBB0_1812
	s_add_i32 s4, 0, 0x20040
	v_mov_b32_e32 v0, s4
	s_waitcnt vmcnt(0) expcnt(0) lgkmcnt(0)
	ds_read_b32 v2, v0
	s_add_i32 s4, 0, 0x20044
	v_mov_b32_e32 v0, s4
	ds_read_b32 v0, v0
	s_waitcnt lgkmcnt(1)
	v_cmp_ne_u32_e32 vcc, 0, v2
	s_cbranch_vccnz .LBB0_1776
	v_readlane_b32 s4, v255, 4
	v_readlane_b32 s5, v255, 5
	v_readlane_b32 s6, v255, 7
	s_mul_i32 s21, s5, s6
	s_mul_i32 s21, s21, s4
	s_add_u32 s4, s28, 0x1000
	s_addc_u32 s5, s29, 0
	s_add_u32 s6, s28, 0x1100
	s_addc_u32 s7, s29, 0
	s_add_u32 s12, s28, 0x1200
	s_addc_u32 s13, s29, 0
	s_add_u32 s14, s28, 0x1300
	s_addc_u32 s15, s29, 0
	s_mov_b32 s22, 1
	v_mov_b32_e32 v16, 0
	s_branch .LBB0_1764

.LBB0_1788:
	s_or_b64 exec, exec, s[16:17]
	s_xor_b64 s[14:15], s[18:19], -1
	s_and_saveexec_b64 s[16:17], s[14:15]
	v_readlane_b32 s36, v254, 4
	s_xor_b64 s[16:17], exec, s[16:17]
	v_readlane_b32 s37, v254, 5
	s_cbranch_execz .LBB0_1791
	s_mov_b64 s[14:15], exec
	v_mbcnt_lo_u32_b32 v0, s14, 0
	v_mbcnt_hi_u32_b32 v0, s15, v0
	v_cmp_eq_u32_e32 vcc, 0, v0
	s_and_b64 s[16:17], exec, vcc
	s_mov_b64 exec, s[16:17]
	s_cbranch_execz .LBB0_1791
	s_bcnt1_i32_b64 s14, s[14:15]
	v_mov_b32_e32 v0, 0
	v_mov_b32_e32 v1, s14
	global_atomic_add v0, v1, s[28:29] offset:512

; __device__ __forceinline__ unsigned xb_ld(unsigned* p)              { return __hip_atomic_load(p, __ATOMIC_RELAXED, __HIP_MEMORY_SCOPE_AGENT); }
; __device__ __forceinline__ unsigned xb_add(unsigned* p, unsigned v) { return __hip_atomic_fetch_add(p, v, __ATOMIC_RELAXED, __HIP_MEMORY_SCOPE_AGENT); }
; #define XB_SPIN(cond, bar) do { unsigned _sp = 0; while (cond) { __builtin_amdgcn_s_sleep(1); \
;     if ((++_sp & 255u) == 0u) { if (xb_ld(&(bar)[XB_TMO])) break; if (_sp > XB_SPIN_CAP) { atomicAdd(&(bar)[XB_TMO], 1u); break; } } } } while (0)
; __device__ __forceinline__ void xcd_barrier(const XcdBarrier& b) {
;     ...
;             const unsigned og = xb_add(&bar[XB_TOP], 1u);
;             const unsigned tg = og / nx;
;             if (og + 1u == (tg + 1u) * nx) xb_add(&bar[XB_TOPGEN], 1u);
;             else XB_SPIN(xb_ld(&bar[XB_TOPGEN]) == tg, bar);
;             __builtin_amdgcn_fence(__ATOMIC_ACQUIRE, "agent");
;             xb_add(&bar[XB_XGEN(b.x)], 1u);
;             asm volatile("s_waitcnt vmcnt(0)" ::: "memory");
;         } else {
;             XB_SPIN(xb_ld(&bar[XB_XGEN(b.x)]) == gen, bar);
;             __builtin_amdgcn_fence(__ATOMIC_ACQUIRE, "agent");
;             asm volatile("s_waitcnt vmcnt(0)" ::: "memory");
;         }
.LBB0_1805:
	s_or_b64 exec, exec, s[18:19]
	v_readlane_b32 s36, v254, 4
	s_and_b64 s[18:19], s[24:25], exec
	v_readlane_b32 s37, v254, 5

; #define PG8_STAGE(bufoff, gbase, voff) do { _Pragma("unroll") for (int _i = 0; _i < 2; ++_i) \
;         __builtin_amdgcn_global_load_lds((const unsigned*)((const char*)(gbase) + (voff)[_i]), (PG8_LAS unsigned*)(lds + (bufoff) + ldsw + _i * 8192), 16, 0, 0); } while (0)
; #define PG8_WAIT_V(n) asm volatile("s_waitcnt vmcnt(" #n ")" ::: "memory")
; #define PG8_BAR __builtin_amdgcn_s_barrier()
; template <class Epi, class Sched, bool ALIGN_EPI = false, bool SP2 = false, bool TA = true>
; __device__ __forceinline__ void gemm_phase(PG8_LAS unsigned char* lds, const Gemm g, const Sched& S, const Epi& E) {
;     ...
;     const unsigned ldsw = (unsigned)wid * 1024u;
;     const int aoff = lds_byte(wr * 64 + fr, fq * 8), boff = lds_byte(wc * 32 + fr, fq * 8);
;     ...
;         PG8_WAIT_V(2); PG8_BAR;
;         PG8_STAGE(PG8_SB(1, 0), cB + kstepB, voffB); PG8_STAGE(PG8_SA(1, 0), cA + kstep, voffA); PG8_STAGE(PG8_SB(1, 1), cB + hstep + kstepB, voffB);
;         PG8_WAIT_V(6); PG8_BAR;
.LBB0_1823:
	s_add_u32 s16, s28, 0x1a000000
	s_addc_u32 s17, s29, 0
	s_lshl_b32 s3, s3, 5
	s_mov_b64 s[18:19], 0x4000
	s_and_b32 s57, s3, 0x60
	s_add_i32 m0, s52, 0x18000
	v_lshl_add_u64 v[2:3], v[0:1], 0, s[18:19]
	s_lshl_b32 s56, s2, 6
	s_lshl_b32 s36, s2, 13
	s_lshl_b32 s3, s57, 7
	s_waitcnt vmcnt(2)
	s_barrier
	global_load_lds_dwordx4 v[2:3], off
	s_add_i32 m0, s52, 0x1a000
	s_mov_b64 s[24:25], 0x6000
	s_add_u32 s28, s48, 0x4000
	v_lshl_add_u64 v[2:3], v[0:1], 0, s[24:25]
	s_addc_u32 s29, s49, 0
	s_add_i32 s58, s52, 0x8000
	global_load_lds_dwordx4 v[2:3], off
	v_lshl_add_u64 v[2:3], s[28:29], 0, v[144:145]
	s_mov_b32 m0, s58
	s_add_i32 s59, s52, 0xa000
	global_load_lds_dwordx4 v[2:3], off
	v_lshl_add_u64 v[2:3], s[28:29], 0, v[146:147]
	s_mov_b32 m0, s59
	s_mov_b64 s[28:29], 0x44000
	global_load_lds_dwordx4 v[2:3], off
	s_add_i32 m0, s52, 0x1c000
	v_lshl_add_u64 v[2:3], v[0:1], 0, s[28:29]
	s_mov_b64 s[30:31], 0x46000
	global_load_lds_dwordx4 v[2:3], off
	v_lshl_add_u64 v[0:1], v[0:1], 0, s[30:31]
	s_add_i32 m0, s52, 0x1e000
	v_and_b32_e32 v160, 15, v208
	global_load_lds_dwordx4 v[0:1], off
	v_lshrrev_b32_e32 v0, 1, v208
	v_and_b32_e32 v161, 24, v0
	v_lshlrev_b32_e32 v0, 1, v161
	v_lshlrev_b32_e32 v2, 2, v160
	v_lshl_or_b32 v1, v160, 6, v0
	v_and_b32_e32 v3, 32, v2
	v_bitop3_b32 v1, v1, s36, v3 bitop3:0xde
	v_lshlrev_b32_e32 v3, 6, v208
	s_movk_i32 s60, 0x3c0
	v_and_or_b32 v0, v3, s60, v0
	v_lshlrev_b32_e32 v3, 2, v208
	v_and_b32_e32 v4, 32, v3
	s_sext_i32_i8 s45, s35
	v_bitop3_b32 v162, s3, v0, v4 bitop3:0xf6
	s_lshl_b32 s3, s2, 8
	s_add_i32 s35, 0, 0x20400
	s_add_i32 s3, s35, s3
	s_waitcnt vmcnt(6)
	s_cmpk_lt_u32 s34, 0x100
	v_add_u32_e32 v163, s35, v3
	s_cselect_b64 s[34:35], -1, 0
	s_lshl_b32 s2, s2, 3
	v_readlane_b32 s36, v255, 4
	s_add_i32 s63, 0, 0x10000
	s_add_i32 s64, 0, 0x14000
	s_and_b32 s61, s2, 8
	s_ashr_i32 s62, s36, 31
	v_add_u32_e32 v164, s3, v2
	v_mov_b64_e32 v[148:149], 0x200
	v_mov_b64_e32 v[150:151], 0x1ff
	v_add_u32_e32 v165, s63, v162
	v_add_u32_e32 v166, s64, v162
	v_add_u32_e32 v167, 0, v1
	v_mov_b32_e32 v168, 0x358637bd
	s_barrier
	v_readlane_b32 s37, v255, 5
	s_branch .LBB0_1826

;   __device__ __forceinline__ bool next(int i,AttnUnit&u)const{ if(i>=8)return false; const int s=vcu&7,k=i&3; { const int p_=vcu>>3; u.bh=(p_>>3)*16+(p_&7)*2+(i>>2); } u.qb=(k==0)?s:(k==1)?15-s:(k==2)?16+s:31-s; return true; }
;     __host__ __device__ bool next(int i, Unit& u) const {
;         const long L = (long)i * G + c; if (L >= nwg) return false;
;         int wgid = (int)L; { const int q = nwg / NXCD, r = nwg % NXCD, xcd = wgid % NXCD, off = wgid / NXCD; wgid = (xcd < r ? xcd * (q + 1) : r * (q + 1) + (xcd - r) * q) + off; }
; template <class Epi, class Sched, bool ALIGN_EPI = false, bool SP2 = false, bool TA = true>
; __device__ __forceinline__ void gemm_phase(PG8_LAS unsigned char* lds, const Gemm g, const Sched& S, const Epi& E) {
;     ...
;         const bool has_next = S.next(ui + 1, nxt);
;         const char* nA = has_next ? (const char*)g.A + (size_t)nxt.pm * tstep : cA; const char* nB = has_next ? (const char*)g.Bt + (size_t)nxt.pn * tstep : cB;
.LBB0_1826:
	s_add_i32 s65, s47, 1
	v_readlane_b32 s40, v255, 4
	s_mul_i32 s2, s65, s62
	s_mul_hi_u32 s3, s65, s40
	s_add_i32 s3, s3, s2
	s_mul_i32 s2, s65, s40
	v_readlane_b32 s41, v255, 5
	s_add_u32 s40, s2, s20
	s_addc_u32 s41, s3, s21
	v_cmp_gt_i64_e32 vcc, s[40:41], v[150:151]
	v_cmp_lt_i64_e64 s[2:3], s[40:41], v[148:149]
	s_cbranch_vccnz .LBB0_1832
	s_ashr_i32 s36, s40, 31
	s_lshr_b32 s36, s36, 29
	s_add_i32 s38, s40, s36
	s_and_b32 s36, s38, -8
	s_sub_i32 s39, s40, s36
	s_cmp_gt_i32 s39, -1
	s_mov_b64 s[36:37], -1
	s_cbranch_scc0 .LBB0_1829
	s_lshl_b32 s40, s39, 6
	s_mov_b64 s[36:37], 0

; #define PG8_LAS __attribute__((address_space(3)))
;     __device__ __forceinline__ void load_grp(Grp& g, int row, int col0) const {
; #pragma unroll
;         for (int bj = 0; bj < 2; ++bj) { const size_t off = (size_t)row * 1024 + col0 + bj * HALF;
;             if (BASEF32) { g.b[bj][0] = *(const f32x4*)(base + off); g.b[bj][1] = *(const f32x4*)(base + off + 4); }
;             else g.h[bj] = *(const u32x4*)(baseh + tiled_off(row, col0 + bj * HALF, 1024));
;             if (MODE == 1) g.p[bj] = *(const u32x4*)(pp + tiled_off(row, col0 + bj * HALF, 1024)); }
;     }
;     __device__ __forceinline__ void operator()(const f32x4 (&acc)[2][2][4][2], const Unit& u, int wr, int wc, int fr, int fq, const PG8_LAS float* rtab) const {
;         const int row0 = u.pm * BM + wr * 64 + fr, col0 = u.pn * BM + wc * 32 + 8 * fq;
;         f32x4 bv[2][2];
; #pragma unroll
;         for (int bj = 0; bj < 2; ++bj)
; #pragma unroll
;             for (int n = 0; n < 2; ++n) bv[bj][n] = (MODE == 0 && bias) ? *(const f32x4*)(bias + col0 + bj * HALF + 4 * n) : (f32x4){0.f, 0.f, 0.f, 0.f};
;         Grp cur, nxt; load_grp(cur, row0, col0);
; #pragma unroll
;         for (int gi = 0; gi < 8; ++gi) { const int ai = gi >> 2, m = gi & 3; const int row = row0 + ai * HALF + m * 16; float ssq = 0.f;
;             if (gi < 7) load_grp(nxt, row0 + ((gi + 1) >> 2) * HALF + ((gi + 1) & 3) * 16, col0);
;             float rsr = 0.f;
;             if (MODE == 1) rsr = rtab[ai * HALF + wr * 64 + m * 16 + fr];
; #pragma unroll
;             for (int bj = 0; bj < 2; ++bj) { const size_t off = (size_t)row * 1024 + col0 + bj * HALF;
;                 f32x4 v0, v1;
;                 if (BASEF32) { v0 = cur.b[bj][0]; v1 = cur.b[bj][1]; }
;                 else { const u32x4 hw = cur.h[bj];
;                     v0 = (f32x4){__uint_as_float(hw.x << 16), __uint_as_float(hw.x & 0xffff0000u), __uint_as_float(hw.y << 16), __uint_as_float(hw.y & 0xffff0000u)};
;                     v1 = (f32x4){__uint_as_float(hw.z << 16), __uint_as_float(hw.z & 0xffff0000u), __uint_as_float(hw.w << 16), __uint_as_float(hw.w & 0xffff0000u)}; }
;                 if (MODE == 0) { v0 += acc[ai][bj][m][0] + bv[bj][0]; v1 += acc[ai][bj][m][1] + bv[bj][1]; }
;                 else { const u32x4 pw = cur.p[bj]; const f32x4 a0 = acc[ai][bj][m][0] * rsr, a1 = acc[ai][bj][m][1] * rsr;
.LBB0_1836:
	s_lshl_b32 s39, s45, 8
	s_lshl_b32 s37, s44, 8
	s_or_b32 s46, s39, s57
	s_add_i32 s37, s37, s56
	v_or_b32_e32 v152, s46, v161
	v_or_b32_e32 v154, s37, v160
	v_lshlrev_b32_e32 v129, 1, v152
	s_ashr_i32 s44, s37, 7
	s_bfe_u32 s37, s57, 0x10005
	v_lshlrev_b32_e32 v128, 6, v154
	v_and_b32_e32 v170, 48, v129
	s_or_b32 s39, s37, s61
	v_and_or_b32 v159, v128, s60, v170
	v_lshlrev_b32_e32 v128, 2, v154
	s_lshl_b32 s39, s39, 10
	v_and_b32_e32 v171, 32, v128
	s_ashr_i32 s45, s44, 31
	v_bitop3_b32 v128, v159, s39, v171 bitop3:0xde
	s_ashr_i32 s50, s46, 6
	s_lshl_b64 s[48:49], s[44:45], 17
	v_lshrrev_b32_e32 v146, 1, v128
	s_ashr_i32 s51, s50, 31
	v_lshl_add_u64 v[136:137], s[48:49], 0, v[146:147]
	s_lshl_b64 s[44:45], s[50:51], 13
	v_lshl_add_u64 v[128:129], v[136:137], 0, s[44:45]
	v_lshlrev_b64 v[132:133], 1, v[128:129]
	v_lshl_add_u64 v[128:129], s[8:9], 0, v[132:133]
	v_lshl_add_u64 v[132:133], s[16:17], 0, v[132:133]
	global_load_dwordx4 v[128:131], v[128:129], off
	s_lshl_b32 s46, s47, 10
	global_load_dwordx4 v[132:135], v[132:133], off
	s_and_b32 s46, s46, 0x400
	v_add_u32_e32 v169, s46, v164
	ds_read_b32 v158, v169
	s_or_b32 s46, s50, 2
	s_ashr_i32 s47, s46, 31
	s_lshl_b64 s[46:47], s[46:47], 13
	v_or_b32_e32 v156, 16, v154
	s_waitcnt lgkmcnt(0)
	v_pk_mul_f32 v[182:183], v[120:121], v[158:159] op_sel_hi:[1,0]
	v_lshl_add_u64 v[120:121], v[136:137], 0, s[46:47]
	v_pk_mul_f32 v[124:125], v[124:125], v[158:159] op_sel_hi:[1,0]
	v_lshlrev_b64 v[120:121], 1, v[120:121]
	v_mul_f32_e32 v136, 0xbfb8aa3b, v124
	v_mul_f32_e32 v137, 0xbfb8aa3b, v125
	v_lshl_add_u64 v[124:125], s[8:9], 0, v[120:121]
	v_lshl_add_u64 v[120:121], s[16:17], 0, v[120:121]
	global_load_dwordx4 v[172:175], v[124:125], off
	global_load_dwordx4 v[176:179], v[120:121], off
	v_lshrrev_b32_e32 v138, 3, v156
	v_and_or_b32 v138, v138, 10, s37
	v_lshlrev_b32_e32 v138, 10, v138
	v_bitop3_b32 v138, v159, v138, v171 bitop3:0xde
	v_lshrrev_b32_e32 v146, 1, v138
	v_pk_mul_f32 v[184:185], v[122:123], v[158:159] op_sel_hi:[1,0]
	v_lshl_add_u64 v[122:123], s[48:49], 0, v[146:147]
	v_pk_mul_f32 v[126:127], v[126:127], v[158:159] op_sel_hi:[1,0]
	v_lshl_add_u64 v[120:121], v[122:123], 0, s[44:45]
	v_lshl_add_u64 v[122:123], v[122:123], 0, s[46:47]
	v_mul_f32_e32 v126, 0xbfb8aa3b, v126
	v_mul_f32_e32 v127, 0xbfb8aa3b, v127
	v_lshlrev_b64 v[120:121], 1, v[120:121]
	v_lshlrev_b64 v[122:123], 1, v[122:123]
	v_mul_f32_e32 v146, 0xbfb8aa3b, v182
	v_exp_f32_e32 v181, v126
	v_exp_f32_e32 v182, v127
	v_lshl_add_u64 v[124:125], s[8:9], 0, v[120:121]
	v_lshl_add_u64 v[120:121], s[16:17], 0, v[120:121]
	v_lshl_add_u64 v[126:127], s[8:9], 0, v[122:123]
	v_lshl_add_u64 v[122:123], s[16:17], 0, v[122:123]
	v_exp_f32_e32 v157, v136
	v_exp_f32_e32 v180, v137
	global_load_dwordx4 v[140:143], v[124:125], off
	global_load_dwordx4 v[136:139], v[120:121], off
	s_nop 0
	global_load_dwordx4 v[124:127], v[126:127], off
	s_nop 0
	global_load_dwordx4 v[120:123], v[122:123], off
	v_add_f32_e32 v187, 1.0, v181
	v_add_f32_e32 v157, 1.0, v157
	v_add_f32_e32 v186, 1.0, v180
	v_add_f32_e32 v182, 1.0, v182
	v_rcp_f32_e32 v180, v157
	v_rcp_f32_e32 v181, v186
	v_rcp_f32_e32 v186, v187
	v_rcp_f32_e32 v187, v182
	v_mul_f32_e32 v157, 0xbfb8aa3b, v183
	v_exp_f32_e32 v146, v146
	v_exp_f32_e32 v157, v157
	v_readlane_b32 s68, v255, 0
	v_ashrrev_i32_e32 v155, 31, v154
	v_readlane_b32 s70, v255, 2
	v_readlane_b32 s71, v255, 3
	v_ashrrev_i32_e32 v153, 31, v152
	s_mov_b64 s[26:27], s[70:71]
	v_lshlrev_b64 v[152:153], 2, v[152:153]
	v_pk_mul_f32 v[116:117], v[116:117], v[158:159] op_sel_hi:[1,0]
	v_pk_mul_f32 v[118:119], v[118:119], v[158:159] op_sel_hi:[1,0]
	s_andn2_b64 vcc, exec, s[2:3]
	v_mul_f32_e32 v118, 0xbfb8aa3b, v118
	v_mul_f32_e32 v119, 0xbfb8aa3b, v119
	v_exp_f32_e32 v118, v118
	v_exp_f32_e32 v119, v119
	s_mov_b64 s[2:3], -1
	v_readlane_b32 s69, v255, 1
	s_waitcnt vmcnt(0)
	v_lshlrev_b32_e32 v188, 16, v128
	v_and_b32_e32 v189, 0xffff0000, v128
	v_lshlrev_b32_e32 v190, 16, v132
	v_and_b32_e32 v191, 0xffff0000, v132
	v_lshlrev_b32_e32 v128, 16, v129
	v_and_b32_e32 v129, 0xffff0000, v129
	v_lshlrev_b32_e32 v132, 16, v133
	v_and_b32_e32 v133, 0xffff0000, v133
	v_pk_fma_f32 v[182:183], v[186:187], v[132:133], v[128:129]
	v_lshlrev_b32_e32 v132, 16, v130
	v_and_b32_e32 v133, 0xffff0000, v130
	v_mul_f32_e32 v130, 0xbfb8aa3b, v184
	v_add_f32_e32 v128, 1.0, v146
	v_add_f32_e32 v129, 1.0, v157
	v_lshlrev_b32_e32 v186, 16, v134
	v_and_b32_e32 v187, 0xffff0000, v134
	v_exp_f32_e32 v130, v130
	v_mul_f32_e32 v134, 0xbfb8aa3b, v185
	v_rcp_f32_e32 v128, v128
	v_rcp_f32_e32 v129, v129
	v_exp_f32_e32 v134, v134
	v_add_f32_e32 v130, 1.0, v130
	v_pk_fma_f32 v[180:181], v[180:181], v[190:191], v[188:189]
	v_pk_fma_f32 v[128:129], v[128:129], v[186:187], v[132:133]
	v_rcp_f32_e32 v132, v130
	v_add_f32_e32 v130, 1.0, v134
	v_rcp_f32_e32 v133, v130
	v_lshlrev_b32_e32 v130, 16, v131
	v_and_b32_e32 v131, 0xffff0000, v131
	v_lshlrev_b32_e32 v134, 16, v135
	v_and_b32_e32 v135, 0xffff0000, v135
	v_pk_fma_f32 v[130:131], v[132:133], v[134:135], v[130:131]
	v_lshlrev_b64 v[132:133], 12, v[154:155]
	v_lshl_add_u64 v[132:133], s[26:27], 0, v[132:133]
	v_lshl_add_u64 v[132:133], v[132:133], 0, v[152:153]
	global_store_dwordx4 v[132:133], v[180:183], off
	global_store_dwordx4 v[132:133], v[128:131], off offset:16
	v_ashrrev_i32_e32 v157, 31, v156
	s_nop 0
	v_pk_mul_f32 v[128:129], v[114:115], v[158:159] op_sel_hi:[1,0]
	v_mul_f32_e32 v114, 0xbfb8aa3b, v116
	v_exp_f32_e32 v116, v114
	v_mul_f32_e32 v114, 0xbfb8aa3b, v117
	v_exp_f32_e32 v117, v114
	v_pk_mul_f32 v[114:115], v[112:113], v[158:159] op_sel_hi:[1,0]
	v_add_f32_e32 v112, 1.0, v116
; __device__ __forceinline__ float fast_sigmoid(float x) { return __builtin_amdgcn_rcpf(1.0f + __builtin_amdgcn_exp2f(x * -1.4426950408889634f)); }
;     __device__ __forceinline__ void operator()(const f32x4 (&acc)[2][2][4][2], const Unit& u, int wr, int wc, int fr, int fq, const PG8_LAS float* rtab) const {
;     ...
;         for (int gi = 0; gi < 8; ++gi) { const int ai = gi >> 2, m = gi & 3; const int row = row0 + ai * HALF + m * 16; float ssq = 0.f;
;             if (gi < 7) load_grp(nxt, row0 + ((gi + 1) >> 2) * HALF + ((gi + 1) & 3) * 16, col0);
;             float rsr = 0.f;
;             if (MODE == 1) rsr = rtab[ai * HALF + wr * 64 + m * 16 + fr];
; #pragma unroll
;             for (int bj = 0; bj < 2; ++bj) { const size_t off = (size_t)row * 1024 + col0 + bj * HALF;
;                 f32x4 v0, v1;
;                 if (BASEF32) { v0 = cur.b[bj][0]; v1 = cur.b[bj][1]; }
;                 else { const u32x4 hw = cur.h[bj];
;                     v0 = (f32x4){__uint_as_float(hw.x << 16), __uint_as_float(hw.x & 0xffff0000u), __uint_as_float(hw.y << 16), __uint_as_float(hw.y & 0xffff0000u)};
;                     v1 = (f32x4){__uint_as_float(hw.z << 16), __uint_as_float(hw.z & 0xffff0000u), __uint_as_float(hw.w << 16), __uint_as_float(hw.w & 0xffff0000u)}; }
;                 if (MODE == 0) { v0 += acc[ai][bj][m][0] + bv[bj][0]; v1 += acc[ai][bj][m][1] + bv[bj][1]; }
;                 else { const u32x4 pw = cur.p[bj]; const f32x4 a0 = acc[ai][bj][m][0] * rsr, a1 = acc[ai][bj][m][1] * rsr;
;                     v0[0] += fast_sigmoid(a0[0]) * __uint_as_float(pw.x << 16); v0[1] += fast_sigmoid(a0[1]) * __uint_as_float(pw.x & 0xffff0000u);
;                     v0[2] += fast_sigmoid(a0[2]) * __uint_as_float(pw.y << 16); v0[3] += fast_sigmoid(a0[3]) * __uint_as_float(pw.y & 0xffff0000u);
;                     v1[0] += fast_sigmoid(a1[0]) * __uint_as_float(pw.z << 16); v1[1] += fast_sigmoid(a1[1]) * __uint_as_float(pw.z & 0xffff0000u);
;                     v1[2] += fast_sigmoid(a1[2]) * __uint_as_float(pw.w << 16); v1[3] += fast_sigmoid(a1[3]) * __uint_as_float(pw.w & 0xffff0000u); }
;                 if (OUTF32) { *(f32x4*)(out + off) = v0; *(f32x4*)(out + off + 4) = v1; }
	v_rcp_f32_e32 v112, v112
	v_add_f32_e32 v113, 1.0, v117
	v_rcp_f32_e32 v113, v113
	v_lshlrev_b32_e32 v116, 16, v172
	v_and_b32_e32 v117, 0xffff0000, v172
	v_lshlrev_b32_e32 v130, 16, v176
	v_and_b32_e32 v131, 0xffff0000, v176
	v_mul_f32_e32 v114, 0xbfb8aa3b, v114
	v_pk_fma_f32 v[112:113], v[112:113], v[130:131], v[116:117]
	v_add_f32_e32 v116, 1.0, v118
	v_add_f32_e32 v117, 1.0, v119
	v_exp_f32_e32 v134, v114
	v_mul_f32_e32 v114, 0xbfb8aa3b, v115
	v_rcp_f32_e32 v116, v116
	v_rcp_f32_e32 v117, v117
	v_exp_f32_e32 v135, v114
	v_lshlrev_b32_e32 v118, 16, v173
	v_and_b32_e32 v119, 0xffff0000, v173
	v_lshlrev_b32_e32 v130, 16, v177
	v_and_b32_e32 v131, 0xffff0000, v177
	v_pk_fma_f32 v[114:115], v[116:117], v[130:131], v[118:119]
	v_add_f32_e32 v116, 1.0, v134
	v_add_f32_e32 v117, 1.0, v135
	v_mul_f32_e32 v128, 0xbfb8aa3b, v128
	v_mul_f32_e32 v129, 0xbfb8aa3b, v129
	v_rcp_f32_e32 v116, v116
	v_rcp_f32_e32 v117, v117
	v_exp_f32_e32 v128, v128
	v_exp_f32_e32 v129, v129
	v_lshlrev_b32_e32 v118, 16, v174
	v_and_b32_e32 v119, 0xffff0000, v174
	v_lshlrev_b32_e32 v130, 16, v178
	v_and_b32_e32 v131, 0xffff0000, v178
	v_pk_fma_f32 v[116:117], v[116:117], v[130:131], v[118:119]
	v_add_f32_e32 v118, 1.0, v128
	v_add_f32_e32 v119, 1.0, v129
	v_rcp_f32_e32 v118, v118
	v_rcp_f32_e32 v119, v119
	v_lshlrev_b32_e32 v128, 16, v175
	v_and_b32_e32 v129, 0xffff0000, v175
	v_lshlrev_b32_e32 v130, 16, v179
	v_and_b32_e32 v131, 0xffff0000, v179
	v_or_b32_e32 v158, 32, v154
	v_pk_fma_f32 v[118:119], v[118:119], v[130:131], v[128:129]
	global_store_dwordx4 v[132:133], v[112:115], off offset:512
	global_store_dwordx4 v[132:133], v[116:119], off offset:528
	v_lshlrev_b32_e32 v174, 16, v136
	v_lshrrev_b32_e32 v112, 3, v158
	v_and_or_b32 v112, v112, 12, s37
	v_lshlrev_b32_e32 v112, 10, v112
	v_bitop3_b32 v112, v159, v112, v171 bitop3:0xde
	v_lshrrev_b32_e32 v146, 1, v112
	v_lshl_add_u64 v[112:113], s[48:49], 0, v[146:147]
	v_lshl_add_u64 v[114:115], v[112:113], 0, s[44:45]
	v_lshlrev_b64 v[114:115], 1, v[114:115]
	v_lshl_add_u64 v[116:117], s[8:9], 0, v[114:115]
	v_lshl_add_u64 v[114:115], s[16:17], 0, v[114:115]
	global_load_dwordx4 v[132:135], v[116:117], off
	global_load_dwordx4 v[128:131], v[114:115], off
	ds_read_b32 v146, v169 offset:64
	v_and_b32_e32 v175, 0xffff0000, v136
	v_lshlrev_b32_e32 v136, 16, v137
	v_and_b32_e32 v137, 0xffff0000, v137
	v_lshl_add_u64 v[112:113], v[112:113], 0, s[46:47]
	s_waitcnt lgkmcnt(0)
	v_pk_mul_f32 v[108:109], v[108:109], v[146:147] op_sel_hi:[1,0]
	v_pk_mul_f32 v[172:173], v[106:107], v[146:147] op_sel_hi:[1,0]
	v_mul_f32_e32 v106, 0xbfb8aa3b, v108
	v_exp_f32_e32 v108, v106
	v_mul_f32_e32 v106, 0xbfb8aa3b, v109
	v_exp_f32_e32 v109, v106
	v_pk_mul_f32 v[110:111], v[110:111], v[146:147] op_sel_hi:[1,0]
	v_pk_mul_f32 v[106:107], v[104:105], v[146:147] op_sel_hi:[1,0]
	v_add_f32_e32 v104, 1.0, v108
	v_add_f32_e32 v105, 1.0, v109
	v_mul_f32_e32 v110, 0xbfb8aa3b, v110
	v_mul_f32_e32 v111, 0xbfb8aa3b, v111
	v_rcp_f32_e32 v104, v104
	v_rcp_f32_e32 v105, v105
	v_exp_f32_e32 v110, v110
	v_exp_f32_e32 v111, v111
	v_lshlrev_b32_e32 v108, 16, v140
	v_and_b32_e32 v109, 0xffff0000, v140
	v_mul_f32_e32 v106, 0xbfb8aa3b, v106
	v_pk_fma_f32 v[104:105], v[104:105], v[174:175], v[108:109]
	v_add_f32_e32 v108, 1.0, v110
	v_add_f32_e32 v109, 1.0, v111
	v_exp_f32_e32 v140, v106
	v_mul_f32_e32 v106, 0xbfb8aa3b, v107
	v_rcp_f32_e32 v108, v108
	v_rcp_f32_e32 v109, v109
	v_lshlrev_b32_e32 v110, 16, v141
	v_and_b32_e32 v111, 0xffff0000, v141
	v_exp_f32_e32 v141, v106
	v_pk_fma_f32 v[106:107], v[108:109], v[136:137], v[110:111]
	v_add_f32_e32 v108, 1.0, v140
	v_lshlrev_b32_e32 v136, 16, v138
	v_add_f32_e32 v109, 1.0, v141
	v_and_b32_e32 v137, 0xffff0000, v138
	v_mul_f32_e32 v138, 0xbfb8aa3b, v172
	v_mul_f32_e32 v140, 0xbfb8aa3b, v173
	v_rcp_f32_e32 v108, v108
	v_rcp_f32_e32 v109, v109
	v_exp_f32_e32 v138, v138
	v_exp_f32_e32 v140, v140
	v_lshlrev_b32_e32 v110, 16, v142
	v_and_b32_e32 v111, 0xffff0000, v142
	v_pk_fma_f32 v[108:109], v[108:109], v[136:137], v[110:111]
	v_add_f32_e32 v110, 1.0, v138
	v_add_f32_e32 v111, 1.0, v140
	v_rcp_f32_e32 v110, v110
	v_rcp_f32_e32 v111, v111
	v_lshlrev_b32_e32 v136, 16, v143
	v_and_b32_e32 v137, 0xffff0000, v143
	v_lshlrev_b32_e32 v138, 16, v139
	v_and_b32_e32 v139, 0xffff0000, v139
	v_pk_fma_f32 v[110:111], v[110:111], v[138:139], v[136:137]
	v_lshlrev_b64 v[136:137], 12, v[156:157]
	v_lshlrev_b64 v[112:113], 1, v[112:113]
	v_lshl_add_u64 v[136:137], s[26:27], 0, v[136:137]
	v_lshl_add_u64 v[114:115], s[8:9], 0, v[112:113]
	v_lshl_add_u64 v[112:113], s[16:17], 0, v[112:113]
	v_lshl_add_u64 v[136:137], v[136:137], 0, v[152:153]
	v_pk_mul_f32 v[100:101], v[100:101], v[146:147] op_sel_hi:[1,0]
	global_load_dwordx4 v[116:119], v[114:115], off
	s_nop 0
	global_load_dwordx4 v[112:115], v[112:113], off
	s_nop 0
	global_store_dwordx4 v[136:137], v[104:107], off
	global_store_dwordx4 v[136:137], v[108:111], off offset:16
	v_pk_mul_f32 v[102:103], v[102:103], v[146:147] op_sel_hi:[1,0]
	v_pk_mul_f32 v[104:105], v[98:99], v[146:147] op_sel_hi:[1,0]
	v_mul_f32_e32 v98, 0xbfb8aa3b, v100
	v_exp_f32_e32 v100, v98
	v_mul_f32_e32 v98, 0xbfb8aa3b, v101
	v_exp_f32_e32 v101, v98
	v_pk_mul_f32 v[98:99], v[96:97], v[146:147] op_sel_hi:[1,0]
	v_add_f32_e32 v96, 1.0, v100
	v_mul_f32_e32 v102, 0xbfb8aa3b, v102
	v_add_f32_e32 v97, 1.0, v101
	v_mul_f32_e32 v103, 0xbfb8aa3b, v103
	v_rcp_f32_e32 v96, v96
	v_rcp_f32_e32 v97, v97
	v_exp_f32_e32 v102, v102
	v_exp_f32_e32 v103, v103
	v_lshlrev_b32_e32 v100, 16, v124
	v_and_b32_e32 v101, 0xffff0000, v124
	v_lshlrev_b32_e32 v106, 16, v120
	v_and_b32_e32 v107, 0xffff0000, v120
	v_mul_f32_e32 v98, 0xbfb8aa3b, v98
	v_pk_fma_f32 v[96:97], v[96:97], v[106:107], v[100:101]
	v_add_f32_e32 v100, 1.0, v102
	v_add_f32_e32 v101, 1.0, v103
	v_exp_f32_e32 v108, v98
	v_mul_f32_e32 v98, 0xbfb8aa3b, v99
	v_rcp_f32_e32 v100, v100
	v_rcp_f32_e32 v101, v101
	v_exp_f32_e32 v109, v98
	v_lshlrev_b32_e32 v102, 16, v125
	v_and_b32_e32 v103, 0xffff0000, v125
	v_lshlrev_b32_e32 v106, 16, v121
	v_and_b32_e32 v107, 0xffff0000, v121
	v_pk_fma_f32 v[98:99], v[100:101], v[106:107], v[102:103]
	v_add_f32_e32 v100, 1.0, v108
	v_add_f32_e32 v101, 1.0, v109
	v_mul_f32_e32 v104, 0xbfb8aa3b, v104
	v_mul_f32_e32 v105, 0xbfb8aa3b, v105
	v_rcp_f32_e32 v100, v100
	v_rcp_f32_e32 v101, v101
	v_exp_f32_e32 v104, v104
	v_exp_f32_e32 v105, v105
	v_lshlrev_b32_e32 v102, 16, v126
	v_and_b32_e32 v103, 0xffff0000, v126
	v_lshlrev_b32_e32 v106, 16, v122
	v_and_b32_e32 v107, 0xffff0000, v122
	v_pk_fma_f32 v[100:101], v[100:101], v[106:107], v[102:103]
	v_add_f32_e32 v102, 1.0, v104
	v_add_f32_e32 v103, 1.0, v105
	v_rcp_f32_e32 v102, v102
	v_rcp_f32_e32 v103, v103
	v_lshlrev_b32_e32 v104, 16, v127
	v_and_b32_e32 v105, 0xffff0000, v127
	v_lshlrev_b32_e32 v106, 16, v123
	v_and_b32_e32 v107, 0xffff0000, v123
	v_or_b32_e32 v120, 48, v154
	v_pk_fma_f32 v[102:103], v[102:103], v[106:107], v[104:105]
	global_store_dwordx4 v[136:137], v[96:99], off offset:512
	global_store_dwordx4 v[136:137], v[100:103], off offset:528
	s_waitcnt vmcnt(6)
; __device__ __forceinline__ float fast_sigmoid(float x) { return __builtin_amdgcn_rcpf(1.0f + __builtin_amdgcn_exp2f(x * -1.4426950408889634f)); }
;     __device__ __forceinline__ void operator()(const f32x4 (&acc)[2][2][4][2], const Unit& u, int wr, int wc, int fr, int fq, const PG8_LAS float* rtab) const {
;     ...
;         for (int gi = 0; gi < 8; ++gi) { const int ai = gi >> 2, m = gi & 3; const int row = row0 + ai * HALF + m * 16; float ssq = 0.f;
;             if (gi < 7) load_grp(nxt, row0 + ((gi + 1) >> 2) * HALF + ((gi + 1) & 3) * 16, col0);
;             float rsr = 0.f;
;             if (MODE == 1) rsr = rtab[ai * HALF + wr * 64 + m * 16 + fr];
; #pragma unroll
;             for (int bj = 0; bj < 2; ++bj) { const size_t off = (size_t)row * 1024 + col0 + bj * HALF;
;                 f32x4 v0, v1;
;                 if (BASEF32) { v0 = cur.b[bj][0]; v1 = cur.b[bj][1]; }
;                 else { const u32x4 hw = cur.h[bj];
;                     v0 = (f32x4){__uint_as_float(hw.x << 16), __uint_as_float(hw.x & 0xffff0000u), __uint_as_float(hw.y << 16), __uint_as_float(hw.y & 0xffff0000u)};
;                     v1 = (f32x4){__uint_as_float(hw.z << 16), __uint_as_float(hw.z & 0xffff0000u), __uint_as_float(hw.w << 16), __uint_as_float(hw.w & 0xffff0000u)}; }
;                 if (MODE == 0) { v0 += acc[ai][bj][m][0] + bv[bj][0]; v1 += acc[ai][bj][m][1] + bv[bj][1]; }
;                 else { const u32x4 pw = cur.p[bj]; const f32x4 a0 = acc[ai][bj][m][0] * rsr, a1 = acc[ai][bj][m][1] * rsr;
;                     v0[0] += fast_sigmoid(a0[0]) * __uint_as_float(pw.x << 16); v0[1] += fast_sigmoid(a0[1]) * __uint_as_float(pw.x & 0xffff0000u);
;                     v0[2] += fast_sigmoid(a0[2]) * __uint_as_float(pw.y << 16); v0[3] += fast_sigmoid(a0[3]) * __uint_as_float(pw.y & 0xffff0000u);
;                     v1[0] += fast_sigmoid(a1[0]) * __uint_as_float(pw.z << 16); v1[1] += fast_sigmoid(a1[1]) * __uint_as_float(pw.z & 0xffff0000u);
;                     v1[2] += fast_sigmoid(a1[2]) * __uint_as_float(pw.w << 16); v1[3] += fast_sigmoid(a1[3]) * __uint_as_float(pw.w & 0xffff0000u); }
;                 if (OUTF32) { *(f32x4*)(out + off) = v0; *(f32x4*)(out + off + 4) = v1; }
	v_lshlrev_b32_e32 v126, 16, v128
	v_lshrrev_b32_e32 v96, 3, v120
	v_and_or_b32 v96, v96, 14, s37
	v_lshlrev_b32_e32 v96, 10, v96
	v_bitop3_b32 v96, v159, v96, v171 bitop3:0xde
	v_lshrrev_b32_e32 v146, 1, v96
	v_lshl_add_u64 v[96:97], s[48:49], 0, v[146:147]
	v_lshl_add_u64 v[98:99], v[96:97], 0, s[44:45]
	v_lshlrev_b64 v[98:99], 1, v[98:99]
	v_lshl_add_u64 v[100:101], s[8:9], 0, v[98:99]
	v_lshl_add_u64 v[98:99], s[16:17], 0, v[98:99]
	global_load_dwordx4 v[108:111], v[100:101], off
	global_load_dwordx4 v[104:107], v[98:99], off
	ds_read_b32 v122, v169 offset:128
	v_and_b32_e32 v127, 0xffff0000, v128
	v_ashrrev_i32_e32 v159, 31, v158
	v_lshl_add_u64 v[96:97], v[96:97], 0, s[46:47]
	v_lshlrev_b64 v[96:97], 1, v[96:97]
	s_waitcnt lgkmcnt(0)
	v_pk_mul_f32 v[92:93], v[92:93], v[122:123] op_sel_hi:[1,0]
	v_pk_mul_f32 v[124:125], v[90:91], v[122:123] op_sel_hi:[1,0]
	v_mul_f32_e32 v90, 0xbfb8aa3b, v92
	v_exp_f32_e32 v92, v90
	v_mul_f32_e32 v90, 0xbfb8aa3b, v93
	v_exp_f32_e32 v93, v90
	v_pk_mul_f32 v[94:95], v[94:95], v[122:123] op_sel_hi:[1,0]
	v_pk_mul_f32 v[90:91], v[88:89], v[122:123] op_sel_hi:[1,0]
	v_add_f32_e32 v88, 1.0, v92
	v_add_f32_e32 v89, 1.0, v93
	v_mul_f32_e32 v94, 0xbfb8aa3b, v94
	v_mul_f32_e32 v95, 0xbfb8aa3b, v95
	v_rcp_f32_e32 v88, v88
	v_rcp_f32_e32 v89, v89
	v_exp_f32_e32 v94, v94
	v_exp_f32_e32 v95, v95
	v_lshlrev_b32_e32 v92, 16, v132
	v_and_b32_e32 v93, 0xffff0000, v132
	v_mul_f32_e32 v90, 0xbfb8aa3b, v90
	v_pk_fma_f32 v[88:89], v[88:89], v[126:127], v[92:93]
	v_add_f32_e32 v92, 1.0, v94
	v_add_f32_e32 v93, 1.0, v95
	v_exp_f32_e32 v121, v90
	v_mul_f32_e32 v90, 0xbfb8aa3b, v91
	v_rcp_f32_e32 v92, v92
	v_rcp_f32_e32 v93, v93
	v_exp_f32_e32 v123, v90
	v_lshlrev_b32_e32 v94, 16, v133
	v_and_b32_e32 v95, 0xffff0000, v133
	v_lshlrev_b32_e32 v126, 16, v129
	v_and_b32_e32 v127, 0xffff0000, v129
	v_pk_fma_f32 v[90:91], v[92:93], v[126:127], v[94:95]
	v_add_f32_e32 v92, 1.0, v121
	v_add_f32_e32 v93, 1.0, v123
	v_mul_f32_e32 v121, 0xbfb8aa3b, v124
	v_mul_f32_e32 v123, 0xbfb8aa3b, v125
	v_rcp_f32_e32 v92, v92
	v_rcp_f32_e32 v93, v93
	v_exp_f32_e32 v121, v121
	v_exp_f32_e32 v123, v123
	v_lshlrev_b32_e32 v94, 16, v134
	v_and_b32_e32 v95, 0xffff0000, v134
	v_lshlrev_b32_e32 v126, 16, v130
	v_and_b32_e32 v127, 0xffff0000, v130
	v_pk_fma_f32 v[92:93], v[92:93], v[126:127], v[94:95]
	v_add_f32_e32 v94, 1.0, v121
	v_add_f32_e32 v95, 1.0, v123
	v_rcp_f32_e32 v94, v94
	v_rcp_f32_e32 v95, v95
	v_lshlrev_b32_e32 v124, 16, v135
	v_and_b32_e32 v125, 0xffff0000, v135
	v_lshlrev_b32_e32 v126, 16, v131
	v_and_b32_e32 v127, 0xffff0000, v131
	v_pk_fma_f32 v[94:95], v[94:95], v[126:127], v[124:125]
	v_lshlrev_b64 v[124:125], 12, v[158:159]
	v_lshl_add_u64 v[124:125], s[26:27], 0, v[124:125]
	v_lshl_add_u64 v[98:99], s[8:9], 0, v[96:97]
	v_lshl_add_u64 v[96:97], s[16:17], 0, v[96:97]
	v_lshl_add_u64 v[124:125], v[124:125], 0, v[152:153]
	v_pk_mul_f32 v[84:85], v[84:85], v[122:123] op_sel_hi:[1,0]
	global_load_dwordx4 v[100:103], v[98:99], off
	s_nop 0
	global_load_dwordx4 v[96:99], v[96:97], off
	s_nop 0
	global_store_dwordx4 v[124:125], v[88:91], off
	global_store_dwordx4 v[124:125], v[92:95], off offset:16
	v_pk_mul_f32 v[86:87], v[86:87], v[122:123] op_sel_hi:[1,0]
	v_pk_mul_f32 v[88:89], v[82:83], v[122:123] op_sel_hi:[1,0]
	v_mul_f32_e32 v82, 0xbfb8aa3b, v84
	v_exp_f32_e32 v84, v82
	v_mul_f32_e32 v82, 0xbfb8aa3b, v85
	v_exp_f32_e32 v85, v82
	v_pk_mul_f32 v[82:83], v[80:81], v[122:123] op_sel_hi:[1,0]
	v_add_f32_e32 v80, 1.0, v84
	v_mul_f32_e32 v86, 0xbfb8aa3b, v86
	v_add_f32_e32 v81, 1.0, v85
	v_mul_f32_e32 v87, 0xbfb8aa3b, v87
	v_rcp_f32_e32 v80, v80
	v_rcp_f32_e32 v81, v81
	v_exp_f32_e32 v86, v86
	v_exp_f32_e32 v87, v87
	s_waitcnt vmcnt(11)
	v_lshlrev_b32_e32 v84, 16, v116
	v_and_b32_e32 v85, 0xffff0000, v116
	s_waitcnt vmcnt(10)
	v_lshlrev_b32_e32 v90, 16, v112
	v_and_b32_e32 v91, 0xffff0000, v112
	v_mul_f32_e32 v82, 0xbfb8aa3b, v82
	v_pk_fma_f32 v[80:81], v[80:81], v[90:91], v[84:85]
	v_add_f32_e32 v84, 1.0, v86
	v_add_f32_e32 v85, 1.0, v87
	v_exp_f32_e32 v92, v82
	v_mul_f32_e32 v82, 0xbfb8aa3b, v83
	v_rcp_f32_e32 v84, v84
	v_rcp_f32_e32 v85, v85
	v_exp_f32_e32 v93, v82
	v_lshlrev_b32_e32 v86, 16, v117
	v_and_b32_e32 v87, 0xffff0000, v117
	v_lshlrev_b32_e32 v90, 16, v113
	v_and_b32_e32 v91, 0xffff0000, v113
	v_pk_fma_f32 v[82:83], v[84:85], v[90:91], v[86:87]
	v_add_f32_e32 v84, 1.0, v92
	v_add_f32_e32 v85, 1.0, v93
	v_mul_f32_e32 v88, 0xbfb8aa3b, v88
	v_mul_f32_e32 v89, 0xbfb8aa3b, v89
	v_rcp_f32_e32 v84, v84
	v_rcp_f32_e32 v85, v85
	v_exp_f32_e32 v88, v88
	v_exp_f32_e32 v89, v89
	v_lshlrev_b32_e32 v86, 16, v118
	v_and_b32_e32 v87, 0xffff0000, v118
	v_lshlrev_b32_e32 v90, 16, v114
	v_and_b32_e32 v91, 0xffff0000, v114
	v_pk_fma_f32 v[84:85], v[84:85], v[90:91], v[86:87]
	v_add_f32_e32 v86, 1.0, v88
	v_add_f32_e32 v87, 1.0, v89
	v_rcp_f32_e32 v86, v86
	v_rcp_f32_e32 v87, v87
	v_lshlrev_b32_e32 v88, 16, v119
	v_and_b32_e32 v89, 0xffff0000, v119
	v_lshlrev_b32_e32 v90, 16, v115
	v_and_b32_e32 v91, 0xffff0000, v115
	v_add_u32_e32 v114, 0x80, v154
	v_pk_fma_f32 v[86:87], v[86:87], v[90:91], v[88:89]
	global_store_dwordx4 v[124:125], v[80:83], off offset:512
	global_store_dwordx4 v[124:125], v[84:87], off offset:528
	s_waitcnt vmcnt(6)
; __device__ __forceinline__ float fast_sigmoid(float x) { return __builtin_amdgcn_rcpf(1.0f + __builtin_amdgcn_exp2f(x * -1.4426950408889634f)); }
;     __device__ __forceinline__ void operator()(const f32x4 (&acc)[2][2][4][2], const Unit& u, int wr, int wc, int fr, int fq, const PG8_LAS float* rtab) const {
;     ...
;         for (int gi = 0; gi < 8; ++gi) { const int ai = gi >> 2, m = gi & 3; const int row = row0 + ai * HALF + m * 16; float ssq = 0.f;
;             if (gi < 7) load_grp(nxt, row0 + ((gi + 1) >> 2) * HALF + ((gi + 1) & 3) * 16, col0);
;             float rsr = 0.f;
;             if (MODE == 1) rsr = rtab[ai * HALF + wr * 64 + m * 16 + fr];
; #pragma unroll
;             for (int bj = 0; bj < 2; ++bj) { const size_t off = (size_t)row * 1024 + col0 + bj * HALF;
;                 f32x4 v0, v1;
;                 if (BASEF32) { v0 = cur.b[bj][0]; v1 = cur.b[bj][1]; }
;                 else { const u32x4 hw = cur.h[bj];
;                     v0 = (f32x4){__uint_as_float(hw.x << 16), __uint_as_float(hw.x & 0xffff0000u), __uint_as_float(hw.y << 16), __uint_as_float(hw.y & 0xffff0000u)};
;                     v1 = (f32x4){__uint_as_float(hw.z << 16), __uint_as_float(hw.z & 0xffff0000u), __uint_as_float(hw.w << 16), __uint_as_float(hw.w & 0xffff0000u)}; }
;                 if (MODE == 0) { v0 += acc[ai][bj][m][0] + bv[bj][0]; v1 += acc[ai][bj][m][1] + bv[bj][1]; }
;                 else { const u32x4 pw = cur.p[bj]; const f32x4 a0 = acc[ai][bj][m][0] * rsr, a1 = acc[ai][bj][m][1] * rsr;
;                     v0[0] += fast_sigmoid(a0[0]) * __uint_as_float(pw.x << 16); v0[1] += fast_sigmoid(a0[1]) * __uint_as_float(pw.x & 0xffff0000u);
;                     v0[2] += fast_sigmoid(a0[2]) * __uint_as_float(pw.y << 16); v0[3] += fast_sigmoid(a0[3]) * __uint_as_float(pw.y & 0xffff0000u);
;                     v1[0] += fast_sigmoid(a1[0]) * __uint_as_float(pw.z << 16); v1[1] += fast_sigmoid(a1[1]) * __uint_as_float(pw.z & 0xffff0000u);
;                     v1[2] += fast_sigmoid(a1[2]) * __uint_as_float(pw.w << 16); v1[3] += fast_sigmoid(a1[3]) * __uint_as_float(pw.w & 0xffff0000u); }
;                 if (OUTF32) { *(f32x4*)(out + off) = v0; *(f32x4*)(out + off + 4) = v1; }
	v_lshlrev_b32_e32 v124, 16, v104
	v_ashrrev_i32_e32 v80, 7, v114
	v_ashrrev_i32_e32 v81, 31, v80
	v_lshlrev_b64 v[112:113], 17, v[80:81]
	v_lshlrev_b32_e32 v80, 6, v114
	v_and_or_b32 v116, v80, s60, v170
	v_lshlrev_b32_e32 v80, 2, v114
	v_and_b32_e32 v117, 32, v80
	v_bitop3_b32 v80, v116, s39, v117 bitop3:0xde
	v_lshrrev_b32_e32 v146, 1, v80
	v_lshl_add_u64 v[80:81], v[112:113], 0, v[146:147]
	v_lshl_add_u64 v[82:83], v[80:81], 0, s[44:45]
	v_lshlrev_b64 v[82:83], 1, v[82:83]
	v_lshl_add_u64 v[84:85], s[8:9], 0, v[82:83]
	v_lshl_add_u64 v[82:83], s[16:17], 0, v[82:83]
	global_load_dwordx4 v[92:95], v[84:85], off
	global_load_dwordx4 v[88:91], v[82:83], off
	ds_read_b32 v118, v169 offset:192
	v_and_b32_e32 v125, 0xffff0000, v104
	v_lshlrev_b32_e32 v104, 16, v105
	v_and_b32_e32 v105, 0xffff0000, v105
	v_ashrrev_i32_e32 v121, 31, v120
	s_waitcnt lgkmcnt(0)
	v_pk_mul_f32 v[76:77], v[76:77], v[118:119] op_sel_hi:[1,0]
	v_pk_mul_f32 v[122:123], v[74:75], v[118:119] op_sel_hi:[1,0]
	v_mul_f32_e32 v74, 0xbfb8aa3b, v76
	v_exp_f32_e32 v76, v74
	v_mul_f32_e32 v74, 0xbfb8aa3b, v77
	v_exp_f32_e32 v77, v74
	v_pk_mul_f32 v[78:79], v[78:79], v[118:119] op_sel_hi:[1,0]
	v_pk_mul_f32 v[74:75], v[72:73], v[118:119] op_sel_hi:[1,0]
	v_add_f32_e32 v72, 1.0, v76
	v_add_f32_e32 v73, 1.0, v77
	v_mul_f32_e32 v78, 0xbfb8aa3b, v78
	v_mul_f32_e32 v79, 0xbfb8aa3b, v79
	v_rcp_f32_e32 v72, v72
	v_rcp_f32_e32 v73, v73
	v_exp_f32_e32 v78, v78
	v_exp_f32_e32 v79, v79
	v_lshlrev_b32_e32 v76, 16, v108
	v_and_b32_e32 v77, 0xffff0000, v108
	v_mul_f32_e32 v74, 0xbfb8aa3b, v74
	v_pk_fma_f32 v[72:73], v[72:73], v[124:125], v[76:77]
	v_add_f32_e32 v76, 1.0, v78
	v_add_f32_e32 v77, 1.0, v79
	v_exp_f32_e32 v108, v74
	v_mul_f32_e32 v74, 0xbfb8aa3b, v75
	v_rcp_f32_e32 v76, v76
	v_rcp_f32_e32 v77, v77
	v_lshlrev_b32_e32 v78, 16, v109
	v_and_b32_e32 v79, 0xffff0000, v109
	v_exp_f32_e32 v109, v74
	v_pk_fma_f32 v[74:75], v[76:77], v[104:105], v[78:79]
	v_add_f32_e32 v76, 1.0, v108
	v_lshlrev_b32_e32 v104, 16, v106
	v_add_f32_e32 v77, 1.0, v109
	v_and_b32_e32 v105, 0xffff0000, v106
	v_mul_f32_e32 v106, 0xbfb8aa3b, v122
	v_mul_f32_e32 v108, 0xbfb8aa3b, v123
	v_rcp_f32_e32 v76, v76
	v_rcp_f32_e32 v77, v77
	v_exp_f32_e32 v106, v106
	v_exp_f32_e32 v108, v108
	v_lshlrev_b32_e32 v78, 16, v110
	v_and_b32_e32 v79, 0xffff0000, v110
	v_pk_fma_f32 v[76:77], v[76:77], v[104:105], v[78:79]
	v_add_f32_e32 v78, 1.0, v106
	v_add_f32_e32 v79, 1.0, v108
	v_rcp_f32_e32 v78, v78
	v_rcp_f32_e32 v79, v79
	v_lshlrev_b32_e32 v104, 16, v111
	v_and_b32_e32 v105, 0xffff0000, v111
	v_lshlrev_b32_e32 v106, 16, v107
	v_and_b32_e32 v107, 0xffff0000, v107
	v_lshl_add_u64 v[80:81], v[80:81], 0, s[46:47]
	v_pk_fma_f32 v[78:79], v[78:79], v[106:107], v[104:105]
	v_lshlrev_b64 v[104:105], 12, v[120:121]
	v_lshlrev_b64 v[80:81], 1, v[80:81]
	v_lshl_add_u64 v[104:105], s[26:27], 0, v[104:105]
	v_lshl_add_u64 v[82:83], s[8:9], 0, v[80:81]
	v_lshl_add_u64 v[80:81], s[16:17], 0, v[80:81]
	v_lshl_add_u64 v[104:105], v[104:105], 0, v[152:153]
	v_pk_mul_f32 v[68:69], v[68:69], v[118:119] op_sel_hi:[1,0]
	global_load_dwordx4 v[84:87], v[82:83], off
	s_nop 0
	global_load_dwordx4 v[80:83], v[80:81], off
	s_nop 0
	global_store_dwordx4 v[104:105], v[72:75], off
	global_store_dwordx4 v[104:105], v[76:79], off offset:16
	v_pk_mul_f32 v[70:71], v[70:71], v[118:119] op_sel_hi:[1,0]
	v_pk_mul_f32 v[72:73], v[66:67], v[118:119] op_sel_hi:[1,0]
	v_mul_f32_e32 v66, 0xbfb8aa3b, v68
	v_exp_f32_e32 v68, v66
	v_mul_f32_e32 v66, 0xbfb8aa3b, v69
	v_exp_f32_e32 v69, v66
	v_pk_mul_f32 v[66:67], v[64:65], v[118:119] op_sel_hi:[1,0]
	v_add_f32_e32 v64, 1.0, v68
	v_mul_f32_e32 v70, 0xbfb8aa3b, v70
	v_add_f32_e32 v65, 1.0, v69
	v_mul_f32_e32 v71, 0xbfb8aa3b, v71
	v_rcp_f32_e32 v64, v64
	v_rcp_f32_e32 v65, v65
	v_exp_f32_e32 v70, v70
	v_exp_f32_e32 v71, v71
	s_waitcnt vmcnt(11)
	v_lshlrev_b32_e32 v68, 16, v100
	v_and_b32_e32 v69, 0xffff0000, v100
	s_waitcnt vmcnt(10)
	v_lshlrev_b32_e32 v74, 16, v96
	v_and_b32_e32 v75, 0xffff0000, v96
	v_mul_f32_e32 v66, 0xbfb8aa3b, v66
	v_pk_fma_f32 v[64:65], v[64:65], v[74:75], v[68:69]
	v_add_f32_e32 v68, 1.0, v70
	v_add_f32_e32 v69, 1.0, v71
	v_exp_f32_e32 v76, v66
	v_mul_f32_e32 v66, 0xbfb8aa3b, v67
	v_rcp_f32_e32 v68, v68
	v_rcp_f32_e32 v69, v69
	v_exp_f32_e32 v77, v66
	v_lshlrev_b32_e32 v70, 16, v101
	v_and_b32_e32 v71, 0xffff0000, v101
	v_lshlrev_b32_e32 v74, 16, v97
	v_and_b32_e32 v75, 0xffff0000, v97
	v_pk_fma_f32 v[66:67], v[68:69], v[74:75], v[70:71]
	v_add_f32_e32 v68, 1.0, v76
	v_add_f32_e32 v69, 1.0, v77
	v_mul_f32_e32 v72, 0xbfb8aa3b, v72
	v_mul_f32_e32 v73, 0xbfb8aa3b, v73
	v_rcp_f32_e32 v68, v68
	v_rcp_f32_e32 v69, v69
	v_exp_f32_e32 v72, v72
	v_exp_f32_e32 v73, v73
	v_lshlrev_b32_e32 v70, 16, v102
	v_and_b32_e32 v71, 0xffff0000, v102
	v_lshlrev_b32_e32 v74, 16, v98
	v_and_b32_e32 v75, 0xffff0000, v98
	v_pk_fma_f32 v[68:69], v[68:69], v[74:75], v[70:71]
	v_add_f32_e32 v70, 1.0, v72
	v_add_f32_e32 v71, 1.0, v73
	v_rcp_f32_e32 v70, v70
	v_rcp_f32_e32 v71, v71
	v_lshlrev_b32_e32 v72, 16, v103
	v_and_b32_e32 v73, 0xffff0000, v103
	v_lshlrev_b32_e32 v74, 16, v99
	v_and_b32_e32 v75, 0xffff0000, v99
	v_add_u32_e32 v96, 0x90, v154
	v_pk_fma_f32 v[70:71], v[70:71], v[74:75], v[72:73]
	global_store_dwordx4 v[104:105], v[64:67], off offset:512
	global_store_dwordx4 v[104:105], v[68:71], off offset:528
	s_waitcnt vmcnt(6)
; __device__ __forceinline__ float fast_sigmoid(float x) { return __builtin_amdgcn_rcpf(1.0f + __builtin_amdgcn_exp2f(x * -1.4426950408889634f)); }
;     __device__ __forceinline__ void operator()(const f32x4 (&acc)[2][2][4][2], const Unit& u, int wr, int wc, int fr, int fq, const PG8_LAS float* rtab) const {
;     ...
;         for (int gi = 0; gi < 8; ++gi) { const int ai = gi >> 2, m = gi & 3; const int row = row0 + ai * HALF + m * 16; float ssq = 0.f;
;             if (gi < 7) load_grp(nxt, row0 + ((gi + 1) >> 2) * HALF + ((gi + 1) & 3) * 16, col0);
;             float rsr = 0.f;
;             if (MODE == 1) rsr = rtab[ai * HALF + wr * 64 + m * 16 + fr];
; #pragma unroll
;             for (int bj = 0; bj < 2; ++bj) { const size_t off = (size_t)row * 1024 + col0 + bj * HALF;
;                 f32x4 v0, v1;
;                 if (BASEF32) { v0 = cur.b[bj][0]; v1 = cur.b[bj][1]; }
;                 else { const u32x4 hw = cur.h[bj];
;                     v0 = (f32x4){__uint_as_float(hw.x << 16), __uint_as_float(hw.x & 0xffff0000u), __uint_as_float(hw.y << 16), __uint_as_float(hw.y & 0xffff0000u)};
;                     v1 = (f32x4){__uint_as_float(hw.z << 16), __uint_as_float(hw.z & 0xffff0000u), __uint_as_float(hw.w << 16), __uint_as_float(hw.w & 0xffff0000u)}; }
;                 if (MODE == 0) { v0 += acc[ai][bj][m][0] + bv[bj][0]; v1 += acc[ai][bj][m][1] + bv[bj][1]; }
;                 else { const u32x4 pw = cur.p[bj]; const f32x4 a0 = acc[ai][bj][m][0] * rsr, a1 = acc[ai][bj][m][1] * rsr;
;                     v0[0] += fast_sigmoid(a0[0]) * __uint_as_float(pw.x << 16); v0[1] += fast_sigmoid(a0[1]) * __uint_as_float(pw.x & 0xffff0000u);
;                     v0[2] += fast_sigmoid(a0[2]) * __uint_as_float(pw.y << 16); v0[3] += fast_sigmoid(a0[3]) * __uint_as_float(pw.y & 0xffff0000u);
;                     v1[0] += fast_sigmoid(a1[0]) * __uint_as_float(pw.z << 16); v1[1] += fast_sigmoid(a1[1]) * __uint_as_float(pw.z & 0xffff0000u);
;                     v1[2] += fast_sigmoid(a1[2]) * __uint_as_float(pw.w << 16); v1[3] += fast_sigmoid(a1[3]) * __uint_as_float(pw.w & 0xffff0000u); }
;                 if (OUTF32) { *(f32x4*)(out + off) = v0; *(f32x4*)(out + off + 4) = v1; }
	v_lshlrev_b32_e32 v102, 16, v88
	v_lshrrev_b32_e32 v64, 3, v96
	v_and_or_b32 v64, v64, 14, s37
	v_lshlrev_b32_e32 v64, 10, v64
	v_bitop3_b32 v64, v116, v64, v117 bitop3:0xde
	v_lshrrev_b32_e32 v146, 1, v64
	v_lshl_add_u64 v[64:65], v[112:113], 0, v[146:147]
	v_lshl_add_u64 v[66:67], v[64:65], 0, s[44:45]
	v_lshlrev_b64 v[66:67], 1, v[66:67]
	v_lshl_add_u64 v[68:69], s[8:9], 0, v[66:67]
	v_lshl_add_u64 v[66:67], s[16:17], 0, v[66:67]
	global_load_dwordx4 v[76:79], v[68:69], off
	global_load_dwordx4 v[72:75], v[66:67], off
	ds_read_b32 v98, v169 offset:512
	v_and_b32_e32 v103, 0xffff0000, v88
	v_lshlrev_b32_e32 v88, 16, v89
	v_and_b32_e32 v89, 0xffff0000, v89
	v_ashrrev_i32_e32 v115, 31, v114
	s_waitcnt lgkmcnt(0)
	v_pk_mul_f32 v[60:61], v[60:61], v[98:99] op_sel_hi:[1,0]
	v_pk_mul_f32 v[100:101], v[58:59], v[98:99] op_sel_hi:[1,0]
	v_mul_f32_e32 v58, 0xbfb8aa3b, v60
	v_exp_f32_e32 v60, v58
	v_mul_f32_e32 v58, 0xbfb8aa3b, v61
	v_exp_f32_e32 v61, v58
	v_pk_mul_f32 v[62:63], v[62:63], v[98:99] op_sel_hi:[1,0]
	v_pk_mul_f32 v[58:59], v[56:57], v[98:99] op_sel_hi:[1,0]
	v_add_f32_e32 v56, 1.0, v60
	v_add_f32_e32 v57, 1.0, v61
	v_mul_f32_e32 v62, 0xbfb8aa3b, v62
	v_mul_f32_e32 v63, 0xbfb8aa3b, v63
	v_rcp_f32_e32 v56, v56
	v_rcp_f32_e32 v57, v57
	v_exp_f32_e32 v62, v62
	v_exp_f32_e32 v63, v63
	v_lshlrev_b32_e32 v60, 16, v92
	v_and_b32_e32 v61, 0xffff0000, v92
	v_mul_f32_e32 v58, 0xbfb8aa3b, v58
	v_pk_fma_f32 v[56:57], v[56:57], v[102:103], v[60:61]
	v_add_f32_e32 v60, 1.0, v62
	v_add_f32_e32 v61, 1.0, v63
	v_exp_f32_e32 v92, v58
	v_mul_f32_e32 v58, 0xbfb8aa3b, v59
	v_rcp_f32_e32 v60, v60
	v_rcp_f32_e32 v61, v61
	v_lshlrev_b32_e32 v62, 16, v93
	v_and_b32_e32 v63, 0xffff0000, v93
	v_exp_f32_e32 v93, v58
	v_pk_fma_f32 v[58:59], v[60:61], v[88:89], v[62:63]
	v_add_f32_e32 v60, 1.0, v92
	v_lshlrev_b32_e32 v88, 16, v90
	v_add_f32_e32 v61, 1.0, v93
	v_and_b32_e32 v89, 0xffff0000, v90
	v_mul_f32_e32 v90, 0xbfb8aa3b, v100
	v_mul_f32_e32 v92, 0xbfb8aa3b, v101
	v_rcp_f32_e32 v60, v60
	v_rcp_f32_e32 v61, v61
	v_exp_f32_e32 v90, v90
	v_exp_f32_e32 v92, v92
	v_lshlrev_b32_e32 v62, 16, v94
	v_and_b32_e32 v63, 0xffff0000, v94
	v_pk_fma_f32 v[60:61], v[60:61], v[88:89], v[62:63]
	v_add_f32_e32 v62, 1.0, v90
	v_add_f32_e32 v63, 1.0, v92
	v_rcp_f32_e32 v62, v62
	v_rcp_f32_e32 v63, v63
	v_lshlrev_b32_e32 v88, 16, v95
	v_and_b32_e32 v89, 0xffff0000, v95
	v_lshlrev_b32_e32 v90, 16, v91
	v_and_b32_e32 v91, 0xffff0000, v91
	v_lshl_add_u64 v[64:65], v[64:65], 0, s[46:47]
	v_pk_fma_f32 v[62:63], v[62:63], v[90:91], v[88:89]
	v_lshlrev_b64 v[88:89], 12, v[114:115]
	v_lshlrev_b64 v[64:65], 1, v[64:65]
	v_lshl_add_u64 v[88:89], s[26:27], 0, v[88:89]
	v_lshl_add_u64 v[66:67], s[8:9], 0, v[64:65]
	v_lshl_add_u64 v[64:65], s[16:17], 0, v[64:65]
	v_lshl_add_u64 v[88:89], v[88:89], 0, v[152:153]
	v_pk_mul_f32 v[52:53], v[52:53], v[98:99] op_sel_hi:[1,0]
	global_load_dwordx4 v[68:71], v[66:67], off
	s_nop 0
	global_load_dwordx4 v[64:67], v[64:65], off
	s_nop 0
	global_store_dwordx4 v[88:89], v[56:59], off
	global_store_dwordx4 v[88:89], v[60:63], off offset:16
	v_pk_mul_f32 v[54:55], v[54:55], v[98:99] op_sel_hi:[1,0]
	v_pk_mul_f32 v[56:57], v[50:51], v[98:99] op_sel_hi:[1,0]
	v_mul_f32_e32 v50, 0xbfb8aa3b, v52
	v_exp_f32_e32 v52, v50
	v_mul_f32_e32 v50, 0xbfb8aa3b, v53
	v_exp_f32_e32 v53, v50
	v_pk_mul_f32 v[50:51], v[48:49], v[98:99] op_sel_hi:[1,0]
	v_add_f32_e32 v48, 1.0, v52
	v_mul_f32_e32 v54, 0xbfb8aa3b, v54
	v_add_f32_e32 v49, 1.0, v53
	v_mul_f32_e32 v55, 0xbfb8aa3b, v55
	v_rcp_f32_e32 v48, v48
	v_rcp_f32_e32 v49, v49
	v_exp_f32_e32 v54, v54
	v_exp_f32_e32 v55, v55
	s_waitcnt vmcnt(11)
	v_lshlrev_b32_e32 v52, 16, v84
	v_and_b32_e32 v53, 0xffff0000, v84
	s_waitcnt vmcnt(10)
	v_lshlrev_b32_e32 v58, 16, v80
	v_and_b32_e32 v59, 0xffff0000, v80
	v_mul_f32_e32 v50, 0xbfb8aa3b, v50
	v_pk_fma_f32 v[48:49], v[48:49], v[58:59], v[52:53]
	v_add_f32_e32 v52, 1.0, v54
	v_add_f32_e32 v53, 1.0, v55
	v_exp_f32_e32 v60, v50
	v_mul_f32_e32 v50, 0xbfb8aa3b, v51
	v_rcp_f32_e32 v52, v52
	v_rcp_f32_e32 v53, v53
	v_exp_f32_e32 v61, v50
	v_lshlrev_b32_e32 v54, 16, v85
	v_and_b32_e32 v55, 0xffff0000, v85
	v_lshlrev_b32_e32 v58, 16, v81
	v_and_b32_e32 v59, 0xffff0000, v81
	v_pk_fma_f32 v[50:51], v[52:53], v[58:59], v[54:55]
	v_add_f32_e32 v52, 1.0, v60
	v_add_f32_e32 v53, 1.0, v61
	v_mul_f32_e32 v56, 0xbfb8aa3b, v56
	v_mul_f32_e32 v57, 0xbfb8aa3b, v57
	v_rcp_f32_e32 v52, v52
	v_rcp_f32_e32 v53, v53
	v_exp_f32_e32 v56, v56
	v_exp_f32_e32 v57, v57
	v_lshlrev_b32_e32 v54, 16, v86
	v_and_b32_e32 v55, 0xffff0000, v86
	v_lshlrev_b32_e32 v58, 16, v82
	v_and_b32_e32 v59, 0xffff0000, v82
	v_pk_fma_f32 v[52:53], v[52:53], v[58:59], v[54:55]
	v_add_f32_e32 v54, 1.0, v56
	v_add_f32_e32 v55, 1.0, v57
	v_rcp_f32_e32 v54, v54
	v_rcp_f32_e32 v55, v55
	v_lshlrev_b32_e32 v56, 16, v87
	v_and_b32_e32 v57, 0xffff0000, v87
	v_lshlrev_b32_e32 v58, 16, v83
	v_and_b32_e32 v59, 0xffff0000, v83
	v_add_u32_e32 v80, 0xa0, v154
	v_pk_fma_f32 v[54:55], v[54:55], v[58:59], v[56:57]
	global_store_dwordx4 v[88:89], v[48:51], off offset:512
	global_store_dwordx4 v[88:89], v[52:55], off offset:528
	s_waitcnt vmcnt(6)
	v_lshlrev_b32_e32 v86, 16, v72
	v_lshrrev_b32_e32 v48, 3, v80
	v_and_or_b32 v48, v48, 14, s37
	v_lshlrev_b32_e32 v48, 10, v48
	v_bitop3_b32 v48, v116, v48, v117 bitop3:0xde
	v_lshrrev_b32_e32 v146, 1, v48
	v_lshl_add_u64 v[48:49], v[112:113], 0, v[146:147]
	v_lshl_add_u64 v[50:51], v[48:49], 0, s[44:45]
	v_lshlrev_b64 v[50:51], 1, v[50:51]
	v_lshl_add_u64 v[52:53], s[8:9], 0, v[50:51]
	v_lshl_add_u64 v[50:51], s[16:17], 0, v[50:51]
	global_load_dwordx4 v[60:63], v[52:53], off
	global_load_dwordx4 v[56:59], v[50:51], off
	ds_read_b32 v82, v169 offset:576
	v_and_b32_e32 v87, 0xffff0000, v72
	v_lshlrev_b32_e32 v72, 16, v73
	v_and_b32_e32 v73, 0xffff0000, v73
	v_ashrrev_i32_e32 v97, 31, v96
	s_waitcnt lgkmcnt(0)
; __device__ __forceinline__ float fast_sigmoid(float x) { return __builtin_amdgcn_rcpf(1.0f + __builtin_amdgcn_exp2f(x * -1.4426950408889634f)); }
;     __device__ __forceinline__ void operator()(const f32x4 (&acc)[2][2][4][2], const Unit& u, int wr, int wc, int fr, int fq, const PG8_LAS float* rtab) const {
;     ...
;         for (int gi = 0; gi < 8; ++gi) { const int ai = gi >> 2, m = gi & 3; const int row = row0 + ai * HALF + m * 16; float ssq = 0.f;
;             if (gi < 7) load_grp(nxt, row0 + ((gi + 1) >> 2) * HALF + ((gi + 1) & 3) * 16, col0);
;             float rsr = 0.f;
;             if (MODE == 1) rsr = rtab[ai * HALF + wr * 64 + m * 16 + fr];
; #pragma unroll
;             for (int bj = 0; bj < 2; ++bj) { const size_t off = (size_t)row * 1024 + col0 + bj * HALF;
;                 f32x4 v0, v1;
;                 if (BASEF32) { v0 = cur.b[bj][0]; v1 = cur.b[bj][1]; }
;                 else { const u32x4 hw = cur.h[bj];
;                     v0 = (f32x4){__uint_as_float(hw.x << 16), __uint_as_float(hw.x & 0xffff0000u), __uint_as_float(hw.y << 16), __uint_as_float(hw.y & 0xffff0000u)};
;                     v1 = (f32x4){__uint_as_float(hw.z << 16), __uint_as_float(hw.z & 0xffff0000u), __uint_as_float(hw.w << 16), __uint_as_float(hw.w & 0xffff0000u)}; }
;                 if (MODE == 0) { v0 += acc[ai][bj][m][0] + bv[bj][0]; v1 += acc[ai][bj][m][1] + bv[bj][1]; }
;                 else { const u32x4 pw = cur.p[bj]; const f32x4 a0 = acc[ai][bj][m][0] * rsr, a1 = acc[ai][bj][m][1] * rsr;
;                     v0[0] += fast_sigmoid(a0[0]) * __uint_as_float(pw.x << 16); v0[1] += fast_sigmoid(a0[1]) * __uint_as_float(pw.x & 0xffff0000u);
;                     v0[2] += fast_sigmoid(a0[2]) * __uint_as_float(pw.y << 16); v0[3] += fast_sigmoid(a0[3]) * __uint_as_float(pw.y & 0xffff0000u);
;                     v1[0] += fast_sigmoid(a1[0]) * __uint_as_float(pw.z << 16); v1[1] += fast_sigmoid(a1[1]) * __uint_as_float(pw.z & 0xffff0000u);
;                     v1[2] += fast_sigmoid(a1[2]) * __uint_as_float(pw.w << 16); v1[3] += fast_sigmoid(a1[3]) * __uint_as_float(pw.w & 0xffff0000u); }
;                 if (OUTF32) { *(f32x4*)(out + off) = v0; *(f32x4*)(out + off + 4) = v1; }
	v_pk_mul_f32 v[44:45], v[44:45], v[82:83] op_sel_hi:[1,0]
	v_pk_mul_f32 v[84:85], v[42:43], v[82:83] op_sel_hi:[1,0]
	v_mul_f32_e32 v42, 0xbfb8aa3b, v44
	v_exp_f32_e32 v44, v42
	v_mul_f32_e32 v42, 0xbfb8aa3b, v45
	v_exp_f32_e32 v45, v42
	v_pk_mul_f32 v[46:47], v[46:47], v[82:83] op_sel_hi:[1,0]
	v_pk_mul_f32 v[42:43], v[40:41], v[82:83] op_sel_hi:[1,0]
	v_add_f32_e32 v40, 1.0, v44
	v_add_f32_e32 v41, 1.0, v45
	v_mul_f32_e32 v46, 0xbfb8aa3b, v46
	v_mul_f32_e32 v47, 0xbfb8aa3b, v47
	v_rcp_f32_e32 v40, v40
	v_rcp_f32_e32 v41, v41
	v_exp_f32_e32 v46, v46
	v_exp_f32_e32 v47, v47
	v_lshlrev_b32_e32 v44, 16, v76
	v_and_b32_e32 v45, 0xffff0000, v76
	v_mul_f32_e32 v42, 0xbfb8aa3b, v42
	v_pk_fma_f32 v[40:41], v[40:41], v[86:87], v[44:45]
	v_add_f32_e32 v44, 1.0, v46
	v_add_f32_e32 v45, 1.0, v47
	v_exp_f32_e32 v76, v42
	v_mul_f32_e32 v42, 0xbfb8aa3b, v43
	v_rcp_f32_e32 v44, v44
	v_rcp_f32_e32 v45, v45
	v_lshlrev_b32_e32 v46, 16, v77
	v_and_b32_e32 v47, 0xffff0000, v77
	v_exp_f32_e32 v77, v42
	v_pk_fma_f32 v[42:43], v[44:45], v[72:73], v[46:47]
	v_add_f32_e32 v44, 1.0, v76
	v_lshlrev_b32_e32 v72, 16, v74
	v_add_f32_e32 v45, 1.0, v77
	v_and_b32_e32 v73, 0xffff0000, v74
	v_mul_f32_e32 v74, 0xbfb8aa3b, v84
	v_mul_f32_e32 v76, 0xbfb8aa3b, v85
	v_rcp_f32_e32 v44, v44
	v_rcp_f32_e32 v45, v45
	v_exp_f32_e32 v74, v74
	v_exp_f32_e32 v76, v76
	v_lshlrev_b32_e32 v46, 16, v78
	v_and_b32_e32 v47, 0xffff0000, v78
	v_pk_fma_f32 v[44:45], v[44:45], v[72:73], v[46:47]
	v_add_f32_e32 v46, 1.0, v74
	v_add_f32_e32 v47, 1.0, v76
	v_rcp_f32_e32 v46, v46
	v_rcp_f32_e32 v47, v47
	v_lshlrev_b32_e32 v72, 16, v79
	v_and_b32_e32 v73, 0xffff0000, v79
	v_lshlrev_b32_e32 v74, 16, v75
	v_and_b32_e32 v75, 0xffff0000, v75
	v_lshl_add_u64 v[48:49], v[48:49], 0, s[46:47]
	v_pk_fma_f32 v[46:47], v[46:47], v[74:75], v[72:73]
	v_lshlrev_b64 v[72:73], 12, v[96:97]
	v_lshlrev_b64 v[48:49], 1, v[48:49]
	v_lshl_add_u64 v[72:73], s[26:27], 0, v[72:73]
	v_lshl_add_u64 v[50:51], s[8:9], 0, v[48:49]
	v_lshl_add_u64 v[48:49], s[16:17], 0, v[48:49]
	v_lshl_add_u64 v[72:73], v[72:73], 0, v[152:153]
	v_pk_mul_f32 v[36:37], v[36:37], v[82:83] op_sel_hi:[1,0]
	global_load_dwordx4 v[52:55], v[50:51], off
	s_nop 0
	global_load_dwordx4 v[48:51], v[48:49], off
	s_nop 0
	global_store_dwordx4 v[72:73], v[40:43], off
	global_store_dwordx4 v[72:73], v[44:47], off offset:16
	v_pk_mul_f32 v[38:39], v[38:39], v[82:83] op_sel_hi:[1,0]
	v_pk_mul_f32 v[40:41], v[34:35], v[82:83] op_sel_hi:[1,0]
	v_mul_f32_e32 v34, 0xbfb8aa3b, v36
	v_exp_f32_e32 v36, v34
	v_mul_f32_e32 v34, 0xbfb8aa3b, v37
	v_exp_f32_e32 v37, v34
	v_pk_mul_f32 v[34:35], v[32:33], v[82:83] op_sel_hi:[1,0]
	v_add_f32_e32 v32, 1.0, v36
	v_mul_f32_e32 v38, 0xbfb8aa3b, v38
	v_add_f32_e32 v33, 1.0, v37
	v_mul_f32_e32 v39, 0xbfb8aa3b, v39
	v_rcp_f32_e32 v32, v32
	v_rcp_f32_e32 v33, v33
	v_exp_f32_e32 v38, v38
	v_exp_f32_e32 v39, v39
	s_waitcnt vmcnt(11)
	v_lshlrev_b32_e32 v36, 16, v68
	v_and_b32_e32 v37, 0xffff0000, v68
	s_waitcnt vmcnt(10)
	v_lshlrev_b32_e32 v42, 16, v64
	v_and_b32_e32 v43, 0xffff0000, v64
	v_mul_f32_e32 v34, 0xbfb8aa3b, v34
	v_pk_fma_f32 v[32:33], v[32:33], v[42:43], v[36:37]
	v_add_f32_e32 v36, 1.0, v38
	v_add_f32_e32 v37, 1.0, v39
	v_exp_f32_e32 v44, v34
	v_mul_f32_e32 v34, 0xbfb8aa3b, v35
	v_rcp_f32_e32 v36, v36
	v_rcp_f32_e32 v37, v37
	v_exp_f32_e32 v45, v34
	v_lshlrev_b32_e32 v38, 16, v69
	v_and_b32_e32 v39, 0xffff0000, v69
	v_lshlrev_b32_e32 v42, 16, v65
	v_and_b32_e32 v43, 0xffff0000, v65
	v_pk_fma_f32 v[34:35], v[36:37], v[42:43], v[38:39]
	v_add_f32_e32 v36, 1.0, v44
	v_add_f32_e32 v37, 1.0, v45
	v_mul_f32_e32 v40, 0xbfb8aa3b, v40
	v_mul_f32_e32 v41, 0xbfb8aa3b, v41
	v_rcp_f32_e32 v36, v36
	v_rcp_f32_e32 v37, v37
	v_exp_f32_e32 v40, v40
	v_exp_f32_e32 v41, v41
	v_lshlrev_b32_e32 v38, 16, v70
	v_and_b32_e32 v39, 0xffff0000, v70
	v_lshlrev_b32_e32 v42, 16, v66
	v_and_b32_e32 v43, 0xffff0000, v66
	v_pk_fma_f32 v[36:37], v[36:37], v[42:43], v[38:39]
	v_add_f32_e32 v38, 1.0, v40
	v_add_f32_e32 v39, 1.0, v41
	v_rcp_f32_e32 v38, v38
	v_rcp_f32_e32 v39, v39
	v_lshlrev_b32_e32 v40, 16, v71
	v_and_b32_e32 v41, 0xffff0000, v71
	v_lshlrev_b32_e32 v42, 16, v67
	v_and_b32_e32 v43, 0xffff0000, v67
	v_add_u32_e32 v64, 0xb0, v154
	v_pk_fma_f32 v[38:39], v[38:39], v[42:43], v[40:41]
	global_store_dwordx4 v[72:73], v[32:35], off offset:512
	global_store_dwordx4 v[72:73], v[36:39], off offset:528
	s_waitcnt vmcnt(6)
	v_lshlrev_b32_e32 v70, 16, v56
	v_lshrrev_b32_e32 v32, 3, v64
	v_and_or_b32 v32, v32, 14, s37
	v_lshlrev_b32_e32 v32, 10, v32
	v_bitop3_b32 v32, v116, v32, v117 bitop3:0xde
	v_lshrrev_b32_e32 v146, 1, v32
	v_lshl_add_u64 v[32:33], v[112:113], 0, v[146:147]
	v_lshl_add_u64 v[34:35], v[32:33], 0, s[44:45]
	v_lshlrev_b64 v[34:35], 1, v[34:35]
	v_lshl_add_u64 v[36:37], s[8:9], 0, v[34:35]
	v_lshl_add_u64 v[34:35], s[16:17], 0, v[34:35]
	global_load_dwordx4 v[44:47], v[36:37], off
	global_load_dwordx4 v[40:43], v[34:35], off
	ds_read_b32 v66, v169 offset:640
	v_and_b32_e32 v71, 0xffff0000, v56
	v_lshlrev_b32_e32 v56, 16, v57
	v_and_b32_e32 v57, 0xffff0000, v57
	v_lshl_add_u64 v[32:33], v[32:33], 0, s[46:47]
	s_waitcnt lgkmcnt(0)
; __device__ __forceinline__ float fast_sigmoid(float x) { return __builtin_amdgcn_rcpf(1.0f + __builtin_amdgcn_exp2f(x * -1.4426950408889634f)); }
;     __device__ __forceinline__ void operator()(const f32x4 (&acc)[2][2][4][2], const Unit& u, int wr, int wc, int fr, int fq, const PG8_LAS float* rtab) const {
;     ...
;         for (int gi = 0; gi < 8; ++gi) { const int ai = gi >> 2, m = gi & 3; const int row = row0 + ai * HALF + m * 16; float ssq = 0.f;
;             if (gi < 7) load_grp(nxt, row0 + ((gi + 1) >> 2) * HALF + ((gi + 1) & 3) * 16, col0);
;             float rsr = 0.f;
;             if (MODE == 1) rsr = rtab[ai * HALF + wr * 64 + m * 16 + fr];
; #pragma unroll
;             for (int bj = 0; bj < 2; ++bj) { const size_t off = (size_t)row * 1024 + col0 + bj * HALF;
;                 f32x4 v0, v1;
;                 if (BASEF32) { v0 = cur.b[bj][0]; v1 = cur.b[bj][1]; }
;                 else { const u32x4 hw = cur.h[bj];
;                     v0 = (f32x4){__uint_as_float(hw.x << 16), __uint_as_float(hw.x & 0xffff0000u), __uint_as_float(hw.y << 16), __uint_as_float(hw.y & 0xffff0000u)};
;                     v1 = (f32x4){__uint_as_float(hw.z << 16), __uint_as_float(hw.z & 0xffff0000u), __uint_as_float(hw.w << 16), __uint_as_float(hw.w & 0xffff0000u)}; }
;                 if (MODE == 0) { v0 += acc[ai][bj][m][0] + bv[bj][0]; v1 += acc[ai][bj][m][1] + bv[bj][1]; }
;                 else { const u32x4 pw = cur.p[bj]; const f32x4 a0 = acc[ai][bj][m][0] * rsr, a1 = acc[ai][bj][m][1] * rsr;
;                     v0[0] += fast_sigmoid(a0[0]) * __uint_as_float(pw.x << 16); v0[1] += fast_sigmoid(a0[1]) * __uint_as_float(pw.x & 0xffff0000u);
;                     v0[2] += fast_sigmoid(a0[2]) * __uint_as_float(pw.y << 16); v0[3] += fast_sigmoid(a0[3]) * __uint_as_float(pw.y & 0xffff0000u);
;                     v1[0] += fast_sigmoid(a1[0]) * __uint_as_float(pw.z << 16); v1[1] += fast_sigmoid(a1[1]) * __uint_as_float(pw.z & 0xffff0000u);
;                     v1[2] += fast_sigmoid(a1[2]) * __uint_as_float(pw.w << 16); v1[3] += fast_sigmoid(a1[3]) * __uint_as_float(pw.w & 0xffff0000u); }
;                 if (OUTF32) { *(f32x4*)(out + off) = v0; *(f32x4*)(out + off + 4) = v1; }
	v_pk_mul_f32 v[28:29], v[28:29], v[66:67] op_sel_hi:[1,0]
	v_pk_mul_f32 v[68:69], v[26:27], v[66:67] op_sel_hi:[1,0]
	v_mul_f32_e32 v26, 0xbfb8aa3b, v28
	v_exp_f32_e32 v28, v26
	v_mul_f32_e32 v26, 0xbfb8aa3b, v29
	v_exp_f32_e32 v29, v26
	v_pk_mul_f32 v[30:31], v[30:31], v[66:67] op_sel_hi:[1,0]
	v_pk_mul_f32 v[26:27], v[24:25], v[66:67] op_sel_hi:[1,0]
	v_add_f32_e32 v24, 1.0, v28
	v_add_f32_e32 v25, 1.0, v29
	v_mul_f32_e32 v30, 0xbfb8aa3b, v30
	v_mul_f32_e32 v31, 0xbfb8aa3b, v31
	v_rcp_f32_e32 v24, v24
	v_rcp_f32_e32 v25, v25
	v_exp_f32_e32 v30, v30
	v_exp_f32_e32 v31, v31
	v_lshlrev_b32_e32 v28, 16, v60
	v_and_b32_e32 v29, 0xffff0000, v60
	v_mul_f32_e32 v26, 0xbfb8aa3b, v26
	v_pk_fma_f32 v[24:25], v[24:25], v[70:71], v[28:29]
	v_add_f32_e32 v28, 1.0, v30
	v_add_f32_e32 v29, 1.0, v31
	v_exp_f32_e32 v60, v26
	v_mul_f32_e32 v26, 0xbfb8aa3b, v27
	v_rcp_f32_e32 v28, v28
	v_rcp_f32_e32 v29, v29
	v_lshlrev_b32_e32 v30, 16, v61
	v_and_b32_e32 v31, 0xffff0000, v61
	v_exp_f32_e32 v61, v26
	v_pk_fma_f32 v[26:27], v[28:29], v[56:57], v[30:31]
	v_add_f32_e32 v28, 1.0, v60
	v_lshlrev_b32_e32 v56, 16, v58
	v_add_f32_e32 v29, 1.0, v61
	v_and_b32_e32 v57, 0xffff0000, v58
	v_mul_f32_e32 v58, 0xbfb8aa3b, v68
	v_mul_f32_e32 v60, 0xbfb8aa3b, v69
	v_rcp_f32_e32 v28, v28
	v_rcp_f32_e32 v29, v29
	v_exp_f32_e32 v58, v58
	v_exp_f32_e32 v60, v60
	v_lshlrev_b64 v[32:33], 1, v[32:33]
	v_lshlrev_b32_e32 v30, 16, v62
	v_and_b32_e32 v31, 0xffff0000, v62
	v_lshl_add_u64 v[34:35], s[8:9], 0, v[32:33]
	v_lshl_add_u64 v[32:33], s[16:17], 0, v[32:33]
	v_pk_fma_f32 v[28:29], v[28:29], v[56:57], v[30:31]
	v_add_f32_e32 v30, 1.0, v58
	v_add_f32_e32 v31, 1.0, v60
	global_load_dwordx4 v[36:39], v[34:35], off
	s_nop 0
	global_load_dwordx4 v[32:35], v[32:33], off
	v_rcp_f32_e32 v30, v30
	v_rcp_f32_e32 v31, v31
	v_ashrrev_i32_e32 v81, 31, v80
	v_lshlrev_b32_e32 v56, 16, v63
	v_and_b32_e32 v57, 0xffff0000, v63
	v_lshlrev_b32_e32 v58, 16, v59
	v_and_b32_e32 v59, 0xffff0000, v59
	v_pk_fma_f32 v[30:31], v[30:31], v[58:59], v[56:57]
	v_lshlrev_b64 v[56:57], 12, v[80:81]
	v_lshl_add_u64 v[56:57], s[26:27], 0, v[56:57]
	v_lshl_add_u64 v[56:57], v[56:57], 0, v[152:153]
	v_pk_mul_f32 v[20:21], v[20:21], v[66:67] op_sel_hi:[1,0]
	global_store_dwordx4 v[56:57], v[24:27], off
	global_store_dwordx4 v[56:57], v[28:31], off offset:16
	v_pk_mul_f32 v[22:23], v[22:23], v[66:67] op_sel_hi:[1,0]
	v_pk_mul_f32 v[24:25], v[18:19], v[66:67] op_sel_hi:[1,0]
	v_mul_f32_e32 v18, 0xbfb8aa3b, v20
	v_exp_f32_e32 v20, v18
	v_mul_f32_e32 v18, 0xbfb8aa3b, v21
	v_exp_f32_e32 v21, v18
	v_pk_mul_f32 v[18:19], v[16:17], v[66:67] op_sel_hi:[1,0]
	v_add_f32_e32 v16, 1.0, v20
	v_mul_f32_e32 v22, 0xbfb8aa3b, v22
	v_add_f32_e32 v17, 1.0, v21
	v_mul_f32_e32 v23, 0xbfb8aa3b, v23
	v_rcp_f32_e32 v16, v16
	v_rcp_f32_e32 v17, v17
	v_exp_f32_e32 v22, v22
	v_exp_f32_e32 v23, v23
	s_waitcnt vmcnt(11)
	v_lshlrev_b32_e32 v20, 16, v52
	v_and_b32_e32 v21, 0xffff0000, v52
	s_waitcnt vmcnt(10)
	v_lshlrev_b32_e32 v26, 16, v48
	v_and_b32_e32 v27, 0xffff0000, v48
	v_mul_f32_e32 v18, 0xbfb8aa3b, v18
	v_pk_fma_f32 v[16:17], v[16:17], v[26:27], v[20:21]
	v_add_f32_e32 v20, 1.0, v22
	v_add_f32_e32 v21, 1.0, v23
	v_exp_f32_e32 v28, v18
	v_mul_f32_e32 v18, 0xbfb8aa3b, v19
	v_rcp_f32_e32 v20, v20
	v_rcp_f32_e32 v21, v21
	v_exp_f32_e32 v29, v18
	v_lshlrev_b32_e32 v22, 16, v53
	v_and_b32_e32 v23, 0xffff0000, v53
	v_lshlrev_b32_e32 v26, 16, v49
	v_and_b32_e32 v27, 0xffff0000, v49
	v_pk_fma_f32 v[18:19], v[20:21], v[26:27], v[22:23]
	v_add_f32_e32 v20, 1.0, v28
	v_add_f32_e32 v21, 1.0, v29
	v_mul_f32_e32 v24, 0xbfb8aa3b, v24
	v_mul_f32_e32 v25, 0xbfb8aa3b, v25
	v_rcp_f32_e32 v20, v20
	v_rcp_f32_e32 v21, v21
	v_exp_f32_e32 v24, v24
	v_exp_f32_e32 v25, v25
	v_lshlrev_b32_e32 v22, 16, v54
	v_and_b32_e32 v23, 0xffff0000, v54
	v_lshlrev_b32_e32 v26, 16, v50
	v_and_b32_e32 v27, 0xffff0000, v50
	v_pk_fma_f32 v[20:21], v[20:21], v[26:27], v[22:23]
	v_add_f32_e32 v22, 1.0, v24
	v_add_f32_e32 v23, 1.0, v25
	v_rcp_f32_e32 v22, v22
	v_rcp_f32_e32 v23, v23
	v_lshlrev_b32_e32 v24, 16, v55
	v_and_b32_e32 v25, 0xffff0000, v55
	v_lshlrev_b32_e32 v26, 16, v51
	v_and_b32_e32 v27, 0xffff0000, v51
	v_pk_fma_f32 v[22:23], v[22:23], v[26:27], v[24:25]
	global_store_dwordx4 v[56:57], v[16:19], off offset:512
	global_store_dwordx4 v[56:57], v[20:23], off offset:528
	ds_read_b32 v16, v169 offset:704
	v_ashrrev_i32_e32 v65, 31, v64
	s_waitcnt vmcnt(6)
	v_lshlrev_b32_e32 v20, 16, v40
	v_and_b32_e32 v21, 0xffff0000, v40
	s_waitcnt lgkmcnt(0)
; __host__ __device__ __forceinline__ size_t tiled_off(int row, int col, int K) { return ((size_t)(row >> 7) * (K >> 6) + (col >> 6)) * 8192 + (lds_byte(row & 127, col & 63) >> 1); }
; __device__ __forceinline__ unsigned cvt_pk_bf16(float lo, float hi) { unsigned r; asm volatile("v_cvt_pk_bf16_f32 %0, %1, %2" : "=v"(r) : "v"(lo), "v"(hi)); return r; }
; __device__ __forceinline__ float fast_sigmoid(float x) { return __builtin_amdgcn_rcpf(1.0f + __builtin_amdgcn_exp2f(x * -1.4426950408889634f)); }
;     __device__ __forceinline__ void operator()(const f32x4 (&acc)[2][2][4][2], const Unit& u, int wr, int wc, int fr, int fq, const PG8_LAS float* rtab) const {
;     ...
;                 else { const u32x4 pw = cur.p[bj]; const f32x4 a0 = acc[ai][bj][m][0] * rsr, a1 = acc[ai][bj][m][1] * rsr;
;                     v0[0] += fast_sigmoid(a0[0]) * __uint_as_float(pw.x << 16); v0[1] += fast_sigmoid(a0[1]) * __uint_as_float(pw.x & 0xffff0000u);
;                     v0[2] += fast_sigmoid(a0[2]) * __uint_as_float(pw.y << 16); v0[3] += fast_sigmoid(a0[3]) * __uint_as_float(pw.y & 0xffff0000u);
;                     v1[0] += fast_sigmoid(a1[0]) * __uint_as_float(pw.z << 16); v1[1] += fast_sigmoid(a1[1]) * __uint_as_float(pw.z & 0xffff0000u);
;                     v1[2] += fast_sigmoid(a1[2]) * __uint_as_float(pw.w << 16); v1[3] += fast_sigmoid(a1[3]) * __uint_as_float(pw.w & 0xffff0000u); }
;                 if (OUTF32) { *(f32x4*)(out + off) = v0; *(f32x4*)(out + off + 4) = v1; }
;                 else { u32x4 w; w.x = cvt_pk_bf16(v0[0], v0[1]); w.y = cvt_pk_bf16(v0[2], v0[3]); w.z = cvt_pk_bf16(v1[0], v1[1]); w.w = cvt_pk_bf16(v1[2], v1[3]);
;                     *(u32x4*)(hb + tiled_off(row, col0 + bj * HALF, 1024)) = w;
;                     ssq += (v0[0] * v0[0] + v0[1] * v0[1]) + (v0[2] * v0[2] + v0[3] * v0[3]) + (v1[0] * v1[0] + v1[1] * v1[1]) + (v1[2] * v1[2] + v1[3] * v1[3]); } }
;             if (!OUTF32) { ssq += __shfl_xor(ssq, 16); ssq += __shfl_xor(ssq, 32);
;                 if (fq == 0) SSout[(size_t)row * 16 + u.pn * 4 + wc] = ssq; }
;             asm volatile("" ::: "memory");
;             cur = nxt; }
	v_pk_mul_f32 v[12:13], v[12:13], v[16:17] op_sel_hi:[1,0]
	v_pk_mul_f32 v[18:19], v[10:11], v[16:17] op_sel_hi:[1,0]
	v_mul_f32_e32 v10, 0xbfb8aa3b, v12
	v_exp_f32_e32 v12, v10
	v_mul_f32_e32 v10, 0xbfb8aa3b, v13
	v_exp_f32_e32 v13, v10
	v_pk_mul_f32 v[14:15], v[14:15], v[16:17] op_sel_hi:[1,0]
	v_pk_mul_f32 v[10:11], v[8:9], v[16:17] op_sel_hi:[1,0]
	v_add_f32_e32 v8, 1.0, v12
	v_add_f32_e32 v9, 1.0, v13
	v_mul_f32_e32 v14, 0xbfb8aa3b, v14
	v_mul_f32_e32 v15, 0xbfb8aa3b, v15
	v_rcp_f32_e32 v8, v8
	v_rcp_f32_e32 v9, v9
	v_exp_f32_e32 v14, v14
	v_exp_f32_e32 v15, v15
	v_lshlrev_b32_e32 v12, 16, v44
	v_and_b32_e32 v13, 0xffff0000, v44
	v_mul_f32_e32 v10, 0xbfb8aa3b, v10
	v_pk_fma_f32 v[8:9], v[8:9], v[20:21], v[12:13]
	v_add_f32_e32 v12, 1.0, v14
	v_add_f32_e32 v13, 1.0, v15
	v_exp_f32_e32 v17, v10
	v_mul_f32_e32 v10, 0xbfb8aa3b, v11
	v_rcp_f32_e32 v12, v12
	v_rcp_f32_e32 v13, v13
	v_exp_f32_e32 v22, v10
	v_lshlrev_b32_e32 v14, 16, v45
	v_and_b32_e32 v15, 0xffff0000, v45
	v_lshlrev_b32_e32 v20, 16, v41
	v_and_b32_e32 v21, 0xffff0000, v41
	v_pk_fma_f32 v[10:11], v[12:13], v[20:21], v[14:15]
	v_add_f32_e32 v12, 1.0, v17
	v_add_f32_e32 v13, 1.0, v22
	v_mul_f32_e32 v17, 0xbfb8aa3b, v18
	v_mul_f32_e32 v18, 0xbfb8aa3b, v19
	v_rcp_f32_e32 v12, v12
	v_rcp_f32_e32 v13, v13
	v_exp_f32_e32 v17, v17
	v_exp_f32_e32 v18, v18
	v_lshlrev_b32_e32 v14, 16, v46
	v_and_b32_e32 v15, 0xffff0000, v46
	v_lshlrev_b32_e32 v20, 16, v42
	v_and_b32_e32 v21, 0xffff0000, v42
	v_pk_fma_f32 v[12:13], v[12:13], v[20:21], v[14:15]
	v_add_f32_e32 v14, 1.0, v17
	v_add_f32_e32 v15, 1.0, v18
	v_rcp_f32_e32 v14, v14
	v_rcp_f32_e32 v15, v15
	v_lshlrev_b32_e32 v18, 16, v47
	v_and_b32_e32 v19, 0xffff0000, v47
	v_lshlrev_b32_e32 v20, 16, v43
	v_and_b32_e32 v21, 0xffff0000, v43
	v_pk_fma_f32 v[14:15], v[14:15], v[20:21], v[18:19]
	v_lshlrev_b64 v[18:19], 12, v[64:65]
	v_lshl_add_u64 v[18:19], s[26:27], 0, v[18:19]
	v_lshl_add_u64 v[18:19], v[18:19], 0, v[152:153]
	v_pk_mul_f32 v[4:5], v[4:5], v[16:17] op_sel_hi:[1,0]
	global_store_dwordx4 v[18:19], v[8:11], off
	global_store_dwordx4 v[18:19], v[12:15], off offset:16
	v_pk_mul_f32 v[6:7], v[6:7], v[16:17] op_sel_hi:[1,0]
	v_pk_mul_f32 v[8:9], v[2:3], v[16:17] op_sel_hi:[1,0]
	v_mul_f32_e32 v2, 0xbfb8aa3b, v4
	v_exp_f32_e32 v4, v2
	v_mul_f32_e32 v2, 0xbfb8aa3b, v5
	v_exp_f32_e32 v5, v2
	v_pk_mul_f32 v[2:3], v[0:1], v[16:17] op_sel_hi:[1,0]
	v_add_f32_e32 v0, 1.0, v4
	v_mul_f32_e32 v6, 0xbfb8aa3b, v6
	v_add_f32_e32 v1, 1.0, v5
	v_mul_f32_e32 v7, 0xbfb8aa3b, v7
	v_rcp_f32_e32 v0, v0
	v_rcp_f32_e32 v1, v1
	v_exp_f32_e32 v6, v6
	v_exp_f32_e32 v7, v7
	s_waitcnt vmcnt(7)
	v_lshlrev_b32_e32 v4, 16, v36
	v_and_b32_e32 v5, 0xffff0000, v36
	s_waitcnt vmcnt(6)
	v_lshlrev_b32_e32 v10, 16, v32
	v_and_b32_e32 v11, 0xffff0000, v32
	v_mul_f32_e32 v2, 0xbfb8aa3b, v2
	v_pk_fma_f32 v[0:1], v[0:1], v[10:11], v[4:5]
	v_add_f32_e32 v4, 1.0, v6
	v_add_f32_e32 v5, 1.0, v7
	v_exp_f32_e32 v12, v2
	v_mul_f32_e32 v2, 0xbfb8aa3b, v3
	v_rcp_f32_e32 v4, v4
	v_rcp_f32_e32 v5, v5
	v_exp_f32_e32 v13, v2
	v_lshlrev_b32_e32 v6, 16, v37
	v_and_b32_e32 v7, 0xffff0000, v37
	v_lshlrev_b32_e32 v10, 16, v33
	v_and_b32_e32 v11, 0xffff0000, v33
	v_pk_fma_f32 v[2:3], v[4:5], v[10:11], v[6:7]
	v_add_f32_e32 v4, 1.0, v12
	v_add_f32_e32 v5, 1.0, v13
	v_mul_f32_e32 v8, 0xbfb8aa3b, v8
	v_mul_f32_e32 v9, 0xbfb8aa3b, v9
	v_rcp_f32_e32 v4, v4
	v_rcp_f32_e32 v5, v5
	v_exp_f32_e32 v8, v8
	v_exp_f32_e32 v9, v9
	v_lshlrev_b32_e32 v6, 16, v38
	v_and_b32_e32 v7, 0xffff0000, v38
	v_lshlrev_b32_e32 v10, 16, v34
	v_and_b32_e32 v11, 0xffff0000, v34
	v_pk_fma_f32 v[4:5], v[4:5], v[10:11], v[6:7]
	v_add_f32_e32 v6, 1.0, v8
	v_add_f32_e32 v7, 1.0, v9
	v_rcp_f32_e32 v6, v6
	v_rcp_f32_e32 v7, v7
	v_lshlrev_b32_e32 v8, 16, v39
	v_and_b32_e32 v9, 0xffff0000, v39
	v_lshlrev_b32_e32 v10, 16, v35
	v_and_b32_e32 v11, 0xffff0000, v35
	v_pk_fma_f32 v[6:7], v[6:7], v[10:11], v[8:9]
	global_store_dwordx4 v[18:19], v[0:3], off offset:512
	global_store_dwordx4 v[18:19], v[4:7], off offset:528
	s_cbranch_vccnz .LBB0_1825
	s_and_saveexec_b64 s[2:3], s[0:1]
	s_cbranch_execz .LBB0_1839
	v_lshl_or_b32 v0, s38, 8, v208
	v_ashrrev_i32_e32 v1, 31, v0
	v_lshlrev_b64 v[0:1], 6, v[0:1]
	v_lshl_add_u64 v[12:13], s[10:11], 0, v[0:1]
	global_load_dwordx4 v[0:3], v[12:13], off
	global_load_dwordx4 v[4:7], v[12:13], off offset:16
	global_load_dwordx4 v[8:11], v[12:13], off offset:32
	s_nop 0
	global_load_dwordx4 v[12:15], v[12:13], off offset:48
	s_lshl_b32 s37, s65, 10
	s_and_b32 s37, s37, 0x400
	s_waitcnt vmcnt(2)
	v_pk_add_f32 v[2:3], v[2:3], v[6:7]
	v_pk_add_f32 v[0:1], v[0:1], v[4:5]
	s_waitcnt vmcnt(0)
	v_pk_add_f32 v[4:5], v[10:11], v[14:15]
	v_pk_add_f32 v[6:7], v[8:9], v[12:13]
	v_pk_add_f32 v[2:3], v[2:3], v[4:5]
	v_pk_add_f32 v[0:1], v[0:1], v[6:7]
	s_nop 0
	v_pk_mov_b32 v[4:5], v[0:1], v[2:3] op_sel:[1,0]
	v_mov_b32_e32 v1, v3
	v_pk_add_f32 v[0:1], v[4:5], v[0:1]
	s_nop 0
	v_add_f32_e32 v0, v0, v1
	v_fmamk_f32 v0, v0, 0x3a800000, v168
	v_rsq_f32_e32 v0, v0
	v_add_u32_e32 v1, s37, v163
	ds_write_b32 v1, v0

; __global__ void __launch_bounds__(NWAVES * 64, 2) mega_fwd(Args args) {
	.amdhsa_kernel _Z8mega_fwd4Args
		.amdhsa_group_segment_fixed_size 0
		.amdhsa_private_segment_fixed_size 0
		.amdhsa_kernarg_size 512
		.amdhsa_user_sgpr_count 2
		.amdhsa_user_sgpr_dispatch_ptr 0
		.amdhsa_user_sgpr_queue_ptr 0
		.amdhsa_user_sgpr_kernarg_segment_ptr 1
		.amdhsa_user_sgpr_dispatch_id 0
		.amdhsa_user_sgpr_kernarg_preload_length 0
		.amdhsa_user_sgpr_kernarg_preload_offset 0
		.amdhsa_user_sgpr_private_segment_size 0
		.amdhsa_uses_dynamic_stack 0
		.amdhsa_enable_private_segment 0
		.amdhsa_system_sgpr_workgroup_id_x 1
		.amdhsa_system_sgpr_workgroup_id_y 0
		.amdhsa_system_sgpr_workgroup_id_z 0
		.amdhsa_system_sgpr_workgroup_info 0
		.amdhsa_system_vgpr_workitem_id 2
		.amdhsa_next_free_vgpr 256
		.amdhsa_next_free_sgpr 98
		.amdhsa_accum_offset 256
		.amdhsa_reserve_vcc 1
		.amdhsa_float_round_mode_32 0
		.amdhsa_float_round_mode_16_64 0
		.amdhsa_float_denorm_mode_32 3
		.amdhsa_float_denorm_mode_16_64 3
		.amdhsa_dx10_clamp 1
		.amdhsa_ieee_mode 1
		.amdhsa_fp16_overflow 0
		.amdhsa_tg_split 0
		.amdhsa_exception_fp_ieee_invalid_op 0
		.amdhsa_exception_fp_denorm_src 0
		.amdhsa_exception_fp_ieee_div_zero 0
		.amdhsa_exception_fp_ieee_overflow 0
		.amdhsa_exception_fp_ieee_underflow 0
		.amdhsa_exception_fp_ieee_inexact 0
		.amdhsa_exception_int_div_zero 0
	.end_amdhsa_kernel

; __global__ void __launch_bounds__(NWAVES * 64, 2) mega_fwd(Args args) {
amdhsa.kernels:
  - .agpr_count:     0
    .args:
      - .offset:         0
        .size:           256
        .value_kind:     by_value
      - .offset:         256
        .size:           4
        .value_kind:     hidden_block_count_x
      - .offset:         260
        .size:           4
        .value_kind:     hidden_block_count_y
      - .offset:         264
        .size:           4
        .value_kind:     hidden_block_count_z
      - .offset:         268
        .size:           2
        .value_kind:     hidden_group_size_x
      - .offset:         270
        .size:           2
        .value_kind:     hidden_group_size_y
      - .offset:         272
        .size:           2
        .value_kind:     hidden_group_size_z
      - .offset:         274
        .size:           2
        .value_kind:     hidden_remainder_x
      - .offset:         276
        .size:           2
        .value_kind:     hidden_remainder_y
      - .offset:         278
        .size:           2
        .value_kind:     hidden_remainder_z
      - .offset:         296
        .size:           8
        .value_kind:     hidden_global_offset_x
      - .offset:         304
        .size:           8
        .value_kind:     hidden_global_offset_y
      - .offset:         312
        .size:           8
        .value_kind:     hidden_global_offset_z
      - .offset:         320
        .size:           2
        .value_kind:     hidden_grid_dims
      - .offset:         344
        .size:           8
        .value_kind:     hidden_multigrid_sync_arg
      - .offset:         376
        .size:           4
        .value_kind:     hidden_dynamic_lds_size
    .group_segment_fixed_size: 0
    .kernarg_segment_align: 8
    .kernarg_segment_size: 512
    .language:       OpenCL C
    .language_version:
      - 2
      - 0
    .max_flat_workgroup_size: 512
    .name:           _Z8mega_fwd4Args
    .private_segment_fixed_size: 0
    .sgpr_count:     104
    .sgpr_spill_count: 76
    .symbol:         _Z8mega_fwd4Args.kd
    .uniform_work_group_size: 1
    .uses_dynamic_stack: false
    .vgpr_count:     256
    .vgpr_spill_count: 0
    .wavefront_size: 64
